# MFMA issue order k-inner: the two MFMAs of each accumulator back to back (accumulate chain), all GEMM K-loops
# speedup vs baseline: 1.0174x; 1.0108x over previous
.LBB0_114:
	s_lshl_b32 s26, s20, 20
	s_and_b64 s[50:51], s[22:23], exec
	s_cselect_b32 s50, s26, s55
	s_lshl_b32 s27, s48, 20
	s_and_b64 s[56:57], s[22:23], exec
	s_cselect_b32 s51, s27, s52
	s_addk_i32 s52, 0x100
	s_add_i32 s53, s55, 0x100
	s_mov_b32 s54, -2
	s_waitcnt vmcnt(0)
	v_add_u32_e32 v132, s55, v143
	v_add_u32_e32 v133, s55, v144
	ds_read_b128 v[150:153], v145
	ds_read_b128 v[154:157], v145 offset:1024
	ds_read_b128 v[158:161], v145 offset:2048
	ds_read_b128 v[162:165], v145 offset:3072
	ds_read_b128 v[166:169], v146
	ds_read_b128 v[170:173], v146 offset:1024
	ds_read_b128 v[174:177], v146 offset:2048
	ds_read_b128 v[178:181], v146 offset:3072
	s_cmp_eq_u32 s54, 28
	s_cselect_b32 s57, s50, s53
	s_cselect_b32 s56, s51, s52
	s_or_b32 s55, s57, 0x80
	s_add_i32 m0, s35, 0xc000
	ds_read_b128 v[182:185], v147
	ds_read_b128 v[186:189], v147 offset:1024
	ds_read_b128 v[190:193], v147 offset:2048
	ds_read_b128 v[194:197], v147 offset:3072
	ds_read_b128 v[198:201], v147 offset:4096
	ds_read_b128 v[212:215], v147 offset:5120
	ds_read_b128 v[218:221], v147 offset:6144
	ds_read_b128 v[222:225], v147 offset:7168
	global_load_lds_dwordx4 v133, s[4:5]
	s_add_i32 m0, s35, 0xe000
	s_nop 0
	global_load_lds_dwordx4 v132, s[4:5]
	s_waitcnt vmcnt(8)
	s_waitcnt lgkmcnt(0)
	s_setprio 1
	s_barrier
	v_mfma_f32_16x16x32_bf16 v[126:129], v[150:153], v[182:185], 0
	v_mfma_f32_16x16x32_bf16 v[126:129], v[154:157], v[186:189], v[126:129]
	v_mfma_f32_16x16x32_bf16 v[122:125], v[158:161], v[182:185], 0
	v_mfma_f32_16x16x32_bf16 v[122:125], v[162:165], v[186:189], v[122:125]
	v_mfma_f32_16x16x32_bf16 v[110:113], v[150:153], v[190:193], 0
	v_mfma_f32_16x16x32_bf16 v[110:113], v[154:157], v[194:197], v[110:113]
	v_mfma_f32_16x16x32_bf16 v[106:109], v[158:161], v[190:193], 0
	v_mfma_f32_16x16x32_bf16 v[106:109], v[162:165], v[194:197], v[106:109]
	v_mfma_f32_16x16x32_bf16 v[94:97], v[150:153], v[198:201], 0
	v_mfma_f32_16x16x32_bf16 v[94:97], v[154:157], v[212:215], v[94:97]
	v_mfma_f32_16x16x32_bf16 v[90:93], v[158:161], v[198:201], 0
	v_mfma_f32_16x16x32_bf16 v[90:93], v[162:165], v[212:215], v[90:93]
	v_mfma_f32_16x16x32_bf16 v[78:81], v[150:153], v[218:221], 0
	v_mfma_f32_16x16x32_bf16 v[78:81], v[154:157], v[222:225], v[78:81]
	v_mfma_f32_16x16x32_bf16 v[74:77], v[158:161], v[218:221], 0
	v_mfma_f32_16x16x32_bf16 v[74:77], v[162:165], v[222:225], v[74:77]
	s_setprio 0
	s_setprio 1
	v_mfma_f32_16x16x32_bf16 v[118:121], v[166:169], v[182:185], 0
	v_mfma_f32_16x16x32_bf16 v[118:121], v[170:173], v[186:189], v[118:121]
	v_mfma_f32_16x16x32_bf16 v[114:117], v[174:177], v[182:185], 0
	v_mfma_f32_16x16x32_bf16 v[114:117], v[178:181], v[186:189], v[114:117]
	v_mfma_f32_16x16x32_bf16 v[102:105], v[166:169], v[190:193], 0
	v_mfma_f32_16x16x32_bf16 v[102:105], v[170:173], v[194:197], v[102:105]
	v_mfma_f32_16x16x32_bf16 v[98:101], v[174:177], v[190:193], 0
	v_mfma_f32_16x16x32_bf16 v[98:101], v[178:181], v[194:197], v[98:101]
	v_mfma_f32_16x16x32_bf16 v[86:89], v[166:169], v[198:201], 0
	v_mfma_f32_16x16x32_bf16 v[86:89], v[170:173], v[212:215], v[86:89]
	v_mfma_f32_16x16x32_bf16 v[82:85], v[174:177], v[198:201], 0
	v_mfma_f32_16x16x32_bf16 v[82:85], v[178:181], v[212:215], v[82:85]
	v_mfma_f32_16x16x32_bf16 v[70:73], v[166:169], v[218:221], 0
	v_mfma_f32_16x16x32_bf16 v[70:73], v[170:173], v[222:225], v[70:73]
	v_mfma_f32_16x16x32_bf16 v[66:69], v[174:177], v[218:221], 0
	v_mfma_f32_16x16x32_bf16 v[66:69], v[178:181], v[222:225], v[66:69]
	s_setprio 0
	s_barrier
	s_mov_b32 m0, s25
	v_add_u32_e32 v134, s56, v137
	ds_read_b128 v[182:185], v147 offset:16384
	ds_read_b128 v[186:189], v147 offset:17408
	ds_read_b128 v[190:193], v147 offset:18432
	ds_read_b128 v[194:197], v147 offset:19456
	ds_read_b128 v[198:201], v147 offset:20480
	ds_read_b128 v[212:215], v147 offset:21504
	ds_read_b128 v[218:221], v147 offset:22528
	ds_read_b128 v[222:225], v147 offset:23552
	global_load_lds_dwordx4 v134, s[6:7]
	v_add_u32_e32 v134, s56, v139
	s_mov_b32 m0, s30
	s_add_i32 s58, s56, 0x80000
	global_load_lds_dwordx4 v134, s[6:7]
	v_add_u32_e32 v134, s58, v137
	s_mov_b32 m0, s31
	s_nop 0
	global_load_lds_dwordx4 v134, s[6:7]
	v_add_u32_e32 v134, s58, v139
	s_mov_b32 m0, s34
	s_nop 0
	global_load_lds_dwordx4 v134, s[6:7]
	v_add_u32_e32 v134, s57, v136
	s_mov_b32 m0, s35
	s_nop 0
	global_load_lds_dwordx4 v134, s[4:5]
	v_add_u32_e32 v134, s57, v138
	s_mov_b32 m0, s36
	s_nop 0
	global_load_lds_dwordx4 v134, s[4:5]
	s_waitcnt vmcnt(8)
	s_waitcnt lgkmcnt(0)
	s_setprio 1
	s_barrier
	v_mfma_f32_16x16x32_bf16 v[62:65], v[150:153], v[182:185], 0
	v_mfma_f32_16x16x32_bf16 v[62:65], v[154:157], v[186:189], v[62:65]
	v_mfma_f32_16x16x32_bf16 v[58:61], v[158:161], v[182:185], 0
	v_mfma_f32_16x16x32_bf16 v[58:61], v[162:165], v[186:189], v[58:61]
	v_mfma_f32_16x16x32_bf16 v[46:49], v[150:153], v[190:193], 0
	v_mfma_f32_16x16x32_bf16 v[46:49], v[154:157], v[194:197], v[46:49]
	v_mfma_f32_16x16x32_bf16 v[42:45], v[158:161], v[190:193], 0
	v_mfma_f32_16x16x32_bf16 v[42:45], v[162:165], v[194:197], v[42:45]
	v_mfma_f32_16x16x32_bf16 v[30:33], v[150:153], v[198:201], 0
	v_mfma_f32_16x16x32_bf16 v[30:33], v[154:157], v[212:215], v[30:33]
	v_mfma_f32_16x16x32_bf16 v[26:29], v[158:161], v[198:201], 0
	v_mfma_f32_16x16x32_bf16 v[26:29], v[162:165], v[212:215], v[26:29]
	v_mfma_f32_16x16x32_bf16 v[14:17], v[150:153], v[218:221], 0
	v_mfma_f32_16x16x32_bf16 v[14:17], v[154:157], v[222:225], v[14:17]
	v_mfma_f32_16x16x32_bf16 v[10:13], v[158:161], v[218:221], 0
	v_mfma_f32_16x16x32_bf16 v[10:13], v[162:165], v[222:225], v[10:13]
	s_setprio 0
	s_setprio 1
	v_mfma_f32_16x16x32_bf16 v[54:57], v[166:169], v[182:185], 0
	v_mfma_f32_16x16x32_bf16 v[54:57], v[170:173], v[186:189], v[54:57]
	v_mfma_f32_16x16x32_bf16 v[50:53], v[174:177], v[182:185], 0
	v_mfma_f32_16x16x32_bf16 v[50:53], v[178:181], v[186:189], v[50:53]
	v_mfma_f32_16x16x32_bf16 v[38:41], v[166:169], v[190:193], 0
	v_mfma_f32_16x16x32_bf16 v[38:41], v[170:173], v[194:197], v[38:41]
	v_mfma_f32_16x16x32_bf16 v[34:37], v[174:177], v[190:193], 0
	v_mfma_f32_16x16x32_bf16 v[34:37], v[178:181], v[194:197], v[34:37]
	v_mfma_f32_16x16x32_bf16 v[22:25], v[166:169], v[198:201], 0
	v_mfma_f32_16x16x32_bf16 v[22:25], v[170:173], v[212:215], v[22:25]
	v_mfma_f32_16x16x32_bf16 v[18:21], v[174:177], v[198:201], 0
	v_mfma_f32_16x16x32_bf16 v[18:21], v[178:181], v[212:215], v[18:21]
	v_mfma_f32_16x16x32_bf16 v[6:9], v[166:169], v[218:221], 0
	v_mfma_f32_16x16x32_bf16 v[6:9], v[170:173], v[222:225], v[6:9]
	v_mfma_f32_16x16x32_bf16 v[2:5], v[174:177], v[218:221], 0
	v_mfma_f32_16x16x32_bf16 v[2:5], v[178:181], v[222:225], v[2:5]
	s_setprio 0
	s_barrier
	ds_read_b128 v[150:153], v148
	ds_read_b128 v[154:157], v148 offset:1024
	ds_read_b128 v[158:161], v148 offset:2048
	ds_read_b128 v[162:165], v148 offset:3072
	ds_read_b128 v[166:169], v149
	ds_read_b128 v[170:173], v149 offset:1024
	ds_read_b128 v[174:177], v149 offset:2048
	ds_read_b128 v[178:181], v149 offset:3072
	s_add_i32 s57, s57, 0x80000
	s_mov_b32 m0, s37
	v_add_u32_e32 v134, s57, v136
	ds_read_b128 v[182:185], v147 offset:32768
	ds_read_b128 v[186:189], v147 offset:33792
	ds_read_b128 v[190:193], v147 offset:34816
	ds_read_b128 v[194:197], v147 offset:35840
	ds_read_b128 v[198:201], v147 offset:36864
	ds_read_b128 v[212:215], v147 offset:37888
	ds_read_b128 v[218:221], v147 offset:38912
	ds_read_b128 v[222:225], v147 offset:39936
	global_load_lds_dwordx4 v134, s[4:5]
	v_add_u32_e32 v134, s57, v138
	s_mov_b32 m0, s38
	s_nop 0
	global_load_lds_dwordx4 v134, s[4:5]
	s_waitcnt vmcnt(8)
	s_waitcnt lgkmcnt(0)
	s_setprio 1
	s_barrier
	v_mfma_f32_16x16x32_bf16 v[126:129], v[150:153], v[182:185], v[126:129]
	v_mfma_f32_16x16x32_bf16 v[126:129], v[154:157], v[186:189], v[126:129]
	v_mfma_f32_16x16x32_bf16 v[122:125], v[158:161], v[182:185], v[122:125]
	v_mfma_f32_16x16x32_bf16 v[122:125], v[162:165], v[186:189], v[122:125]
	v_mfma_f32_16x16x32_bf16 v[110:113], v[150:153], v[190:193], v[110:113]
	v_mfma_f32_16x16x32_bf16 v[110:113], v[154:157], v[194:197], v[110:113]
	v_mfma_f32_16x16x32_bf16 v[106:109], v[158:161], v[190:193], v[106:109]
	v_mfma_f32_16x16x32_bf16 v[106:109], v[162:165], v[194:197], v[106:109]
	v_mfma_f32_16x16x32_bf16 v[94:97], v[150:153], v[198:201], v[94:97]
	v_mfma_f32_16x16x32_bf16 v[94:97], v[154:157], v[212:215], v[94:97]
	v_mfma_f32_16x16x32_bf16 v[90:93], v[158:161], v[198:201], v[90:93]
	v_mfma_f32_16x16x32_bf16 v[90:93], v[162:165], v[212:215], v[90:93]
	v_mfma_f32_16x16x32_bf16 v[78:81], v[150:153], v[218:221], v[78:81]
	v_mfma_f32_16x16x32_bf16 v[78:81], v[154:157], v[222:225], v[78:81]
	v_mfma_f32_16x16x32_bf16 v[74:77], v[158:161], v[218:221], v[74:77]
	v_mfma_f32_16x16x32_bf16 v[74:77], v[162:165], v[222:225], v[74:77]
	s_setprio 0
	s_setprio 1
	v_mfma_f32_16x16x32_bf16 v[118:121], v[166:169], v[182:185], v[118:121]
	v_mfma_f32_16x16x32_bf16 v[118:121], v[170:173], v[186:189], v[118:121]
	v_mfma_f32_16x16x32_bf16 v[114:117], v[174:177], v[182:185], v[114:117]
	v_mfma_f32_16x16x32_bf16 v[114:117], v[178:181], v[186:189], v[114:117]
	v_mfma_f32_16x16x32_bf16 v[102:105], v[166:169], v[190:193], v[102:105]
	v_mfma_f32_16x16x32_bf16 v[102:105], v[170:173], v[194:197], v[102:105]
	v_mfma_f32_16x16x32_bf16 v[98:101], v[174:177], v[190:193], v[98:101]
	v_mfma_f32_16x16x32_bf16 v[98:101], v[178:181], v[194:197], v[98:101]
	v_mfma_f32_16x16x32_bf16 v[86:89], v[166:169], v[198:201], v[86:89]
	v_mfma_f32_16x16x32_bf16 v[86:89], v[170:173], v[212:215], v[86:89]
	v_mfma_f32_16x16x32_bf16 v[82:85], v[174:177], v[198:201], v[82:85]
	v_mfma_f32_16x16x32_bf16 v[82:85], v[178:181], v[212:215], v[82:85]
	v_mfma_f32_16x16x32_bf16 v[70:73], v[166:169], v[218:221], v[70:73]
	v_mfma_f32_16x16x32_bf16 v[70:73], v[170:173], v[222:225], v[70:73]
	v_mfma_f32_16x16x32_bf16 v[66:69], v[174:177], v[218:221], v[66:69]
	v_mfma_f32_16x16x32_bf16 v[66:69], v[178:181], v[222:225], v[66:69]
	s_setprio 0
	s_barrier
	s_or_b32 s57, s56, 0x80
	s_mov_b32 m0, s39
	v_add_u32_e32 v134, s57, v137
	ds_read_b128 v[182:185], v147 offset:49152
	ds_read_b128 v[186:189], v147 offset:50176
	ds_read_b128 v[190:193], v147 offset:51200
	ds_read_b128 v[194:197], v147 offset:52224
	ds_read_b128 v[198:201], v147 offset:53248
	ds_read_b128 v[212:215], v147 offset:54272
	ds_read_b128 v[218:221], v147 offset:55296
	ds_read_b128 v[222:225], v147 offset:56320
	global_load_lds_dwordx4 v134, s[6:7]
	v_add_u32_e32 v134, s57, v139
	s_mov_b32 m0, s40
	s_add_i32 s56, s56, 0x80080
	global_load_lds_dwordx4 v134, s[6:7]
	v_add_u32_e32 v134, s56, v137
	s_mov_b32 m0, s43
	s_nop 0
	global_load_lds_dwordx4 v134, s[6:7]
	v_add_u32_e32 v134, s56, v139
	s_mov_b32 m0, s44
	s_nop 0
	global_load_lds_dwordx4 v134, s[6:7]
	v_add_u32_e32 v134, s55, v136
	s_mov_b32 m0, s41
	s_nop 0
	global_load_lds_dwordx4 v134, s[4:5]
	v_add_u32_e32 v134, s55, v138
	s_mov_b32 m0, s42
	s_nop 0
	global_load_lds_dwordx4 v134, s[4:5]
	s_waitcnt vmcnt(8)
	s_waitcnt lgkmcnt(0)
	s_setprio 1
	s_barrier
	v_mfma_f32_16x16x32_bf16 v[62:65], v[150:153], v[182:185], v[62:65]
	v_mfma_f32_16x16x32_bf16 v[62:65], v[154:157], v[186:189], v[62:65]
	v_mfma_f32_16x16x32_bf16 v[58:61], v[158:161], v[182:185], v[58:61]
	v_mfma_f32_16x16x32_bf16 v[58:61], v[162:165], v[186:189], v[58:61]
	v_mfma_f32_16x16x32_bf16 v[46:49], v[150:153], v[190:193], v[46:49]
	v_mfma_f32_16x16x32_bf16 v[46:49], v[154:157], v[194:197], v[46:49]
	v_mfma_f32_16x16x32_bf16 v[42:45], v[158:161], v[190:193], v[42:45]
	v_mfma_f32_16x16x32_bf16 v[42:45], v[162:165], v[194:197], v[42:45]
	v_mfma_f32_16x16x32_bf16 v[30:33], v[150:153], v[198:201], v[30:33]
	v_mfma_f32_16x16x32_bf16 v[30:33], v[154:157], v[212:215], v[30:33]
	v_mfma_f32_16x16x32_bf16 v[26:29], v[158:161], v[198:201], v[26:29]
	v_mfma_f32_16x16x32_bf16 v[26:29], v[162:165], v[212:215], v[26:29]
	v_mfma_f32_16x16x32_bf16 v[14:17], v[150:153], v[218:221], v[14:17]
	v_mfma_f32_16x16x32_bf16 v[14:17], v[154:157], v[222:225], v[14:17]
	v_mfma_f32_16x16x32_bf16 v[10:13], v[158:161], v[218:221], v[10:13]
	v_mfma_f32_16x16x32_bf16 v[10:13], v[162:165], v[222:225], v[10:13]
	s_setprio 0
	s_setprio 1
	v_mfma_f32_16x16x32_bf16 v[54:57], v[166:169], v[182:185], v[54:57]
	v_mfma_f32_16x16x32_bf16 v[54:57], v[170:173], v[186:189], v[54:57]
	v_mfma_f32_16x16x32_bf16 v[50:53], v[174:177], v[182:185], v[50:53]
	v_mfma_f32_16x16x32_bf16 v[50:53], v[178:181], v[186:189], v[50:53]
	v_mfma_f32_16x16x32_bf16 v[38:41], v[166:169], v[190:193], v[38:41]
	v_mfma_f32_16x16x32_bf16 v[38:41], v[170:173], v[194:197], v[38:41]
	v_mfma_f32_16x16x32_bf16 v[34:37], v[174:177], v[190:193], v[34:37]
	v_mfma_f32_16x16x32_bf16 v[34:37], v[178:181], v[194:197], v[34:37]
	v_mfma_f32_16x16x32_bf16 v[22:25], v[166:169], v[198:201], v[22:25]
	v_mfma_f32_16x16x32_bf16 v[22:25], v[170:173], v[212:215], v[22:25]
	v_mfma_f32_16x16x32_bf16 v[18:21], v[174:177], v[198:201], v[18:21]
	v_mfma_f32_16x16x32_bf16 v[18:21], v[178:181], v[212:215], v[18:21]
	v_mfma_f32_16x16x32_bf16 v[6:9], v[166:169], v[218:221], v[6:9]
	v_mfma_f32_16x16x32_bf16 v[6:9], v[170:173], v[222:225], v[6:9]
	v_mfma_f32_16x16x32_bf16 v[2:5], v[174:177], v[218:221], v[2:5]
	v_mfma_f32_16x16x32_bf16 v[2:5], v[178:181], v[222:225], v[2:5]
	s_setprio 0
	s_barrier
	s_add_i32 s54, s54, 2
	s_addk_i32 s52, 0x100
	s_addk_i32 s53, 0x100
	v_add_u32_e32 v132, 0x100, v132
	s_cmp_gt_u32 s54, 29
	v_add_u32_e32 v133, 0x100, v133
.LBB0_115:
	ds_read_b128 v[150:153], v145
	ds_read_b128 v[154:157], v145 offset:1024
	ds_read_b128 v[158:161], v145 offset:2048
	ds_read_b128 v[162:165], v145 offset:3072
	ds_read_b128 v[166:169], v146
	ds_read_b128 v[170:173], v146 offset:1024
	ds_read_b128 v[174:177], v146 offset:2048
	ds_read_b128 v[178:181], v146 offset:3072
	s_cmp_eq_u32 s54, 28
	s_cselect_b32 s57, s50, s53
	s_cselect_b32 s56, s51, s52
	s_or_b32 s55, s57, 0x80
	s_add_i32 m0, s35, 0xc000
	ds_read_b128 v[182:185], v147
	ds_read_b128 v[186:189], v147 offset:1024
	ds_read_b128 v[190:193], v147 offset:2048
	ds_read_b128 v[194:197], v147 offset:3072
	ds_read_b128 v[198:201], v147 offset:4096
	ds_read_b128 v[212:215], v147 offset:5120
	ds_read_b128 v[218:221], v147 offset:6144
	ds_read_b128 v[222:225], v147 offset:7168
	global_load_lds_dwordx4 v133, s[4:5]
	s_add_i32 m0, s35, 0xe000
	s_nop 0
	global_load_lds_dwordx4 v132, s[4:5]
	s_waitcnt vmcnt(8)
	s_waitcnt lgkmcnt(0)
	s_setprio 1
	s_barrier
	v_mfma_f32_16x16x32_bf16 v[126:129], v[150:153], v[182:185], v[126:129]
	v_mfma_f32_16x16x32_bf16 v[126:129], v[154:157], v[186:189], v[126:129]
	v_mfma_f32_16x16x32_bf16 v[122:125], v[158:161], v[182:185], v[122:125]
	v_mfma_f32_16x16x32_bf16 v[122:125], v[162:165], v[186:189], v[122:125]
	v_mfma_f32_16x16x32_bf16 v[110:113], v[150:153], v[190:193], v[110:113]
	v_mfma_f32_16x16x32_bf16 v[110:113], v[154:157], v[194:197], v[110:113]
	v_mfma_f32_16x16x32_bf16 v[106:109], v[158:161], v[190:193], v[106:109]
	v_mfma_f32_16x16x32_bf16 v[106:109], v[162:165], v[194:197], v[106:109]
	v_mfma_f32_16x16x32_bf16 v[94:97], v[150:153], v[198:201], v[94:97]
	v_mfma_f32_16x16x32_bf16 v[94:97], v[154:157], v[212:215], v[94:97]
	v_mfma_f32_16x16x32_bf16 v[90:93], v[158:161], v[198:201], v[90:93]
	v_mfma_f32_16x16x32_bf16 v[90:93], v[162:165], v[212:215], v[90:93]
	v_mfma_f32_16x16x32_bf16 v[78:81], v[150:153], v[218:221], v[78:81]
	v_mfma_f32_16x16x32_bf16 v[78:81], v[154:157], v[222:225], v[78:81]
	v_mfma_f32_16x16x32_bf16 v[74:77], v[158:161], v[218:221], v[74:77]
	v_mfma_f32_16x16x32_bf16 v[74:77], v[162:165], v[222:225], v[74:77]
	s_setprio 0
	s_setprio 1
	v_mfma_f32_16x16x32_bf16 v[118:121], v[166:169], v[182:185], v[118:121]
	v_mfma_f32_16x16x32_bf16 v[118:121], v[170:173], v[186:189], v[118:121]
	v_mfma_f32_16x16x32_bf16 v[114:117], v[174:177], v[182:185], v[114:117]
	v_mfma_f32_16x16x32_bf16 v[114:117], v[178:181], v[186:189], v[114:117]
	v_mfma_f32_16x16x32_bf16 v[102:105], v[166:169], v[190:193], v[102:105]
	v_mfma_f32_16x16x32_bf16 v[102:105], v[170:173], v[194:197], v[102:105]
	v_mfma_f32_16x16x32_bf16 v[98:101], v[174:177], v[190:193], v[98:101]
	v_mfma_f32_16x16x32_bf16 v[98:101], v[178:181], v[194:197], v[98:101]
	v_mfma_f32_16x16x32_bf16 v[86:89], v[166:169], v[198:201], v[86:89]
	v_mfma_f32_16x16x32_bf16 v[86:89], v[170:173], v[212:215], v[86:89]
	v_mfma_f32_16x16x32_bf16 v[82:85], v[174:177], v[198:201], v[82:85]
	v_mfma_f32_16x16x32_bf16 v[82:85], v[178:181], v[212:215], v[82:85]
	v_mfma_f32_16x16x32_bf16 v[70:73], v[166:169], v[218:221], v[70:73]
	v_mfma_f32_16x16x32_bf16 v[70:73], v[170:173], v[222:225], v[70:73]
	v_mfma_f32_16x16x32_bf16 v[66:69], v[174:177], v[218:221], v[66:69]
	v_mfma_f32_16x16x32_bf16 v[66:69], v[178:181], v[222:225], v[66:69]
	s_setprio 0
	s_barrier
	s_mov_b32 m0, s25
	v_add_u32_e32 v134, s56, v137
	ds_read_b128 v[182:185], v147 offset:16384
	ds_read_b128 v[186:189], v147 offset:17408
	ds_read_b128 v[190:193], v147 offset:18432
	ds_read_b128 v[194:197], v147 offset:19456
	ds_read_b128 v[198:201], v147 offset:20480
	ds_read_b128 v[212:215], v147 offset:21504
	ds_read_b128 v[218:221], v147 offset:22528
	ds_read_b128 v[222:225], v147 offset:23552
	global_load_lds_dwordx4 v134, s[6:7]
	v_add_u32_e32 v134, s56, v139
	s_mov_b32 m0, s30
	s_add_i32 s58, s56, 0x80000
	global_load_lds_dwordx4 v134, s[6:7]
	v_add_u32_e32 v134, s58, v137
	s_mov_b32 m0, s31
	s_nop 0
	global_load_lds_dwordx4 v134, s[6:7]
	v_add_u32_e32 v134, s58, v139
	s_mov_b32 m0, s34
	s_nop 0
	global_load_lds_dwordx4 v134, s[6:7]
	v_add_u32_e32 v134, s57, v136
	s_mov_b32 m0, s35
	s_nop 0
	global_load_lds_dwordx4 v134, s[4:5]
	v_add_u32_e32 v134, s57, v138
	s_mov_b32 m0, s36
	s_nop 0
	global_load_lds_dwordx4 v134, s[4:5]
	s_waitcnt vmcnt(8)
	s_waitcnt lgkmcnt(0)
	s_setprio 1
	s_barrier
	v_mfma_f32_16x16x32_bf16 v[62:65], v[150:153], v[182:185], v[62:65]
	v_mfma_f32_16x16x32_bf16 v[62:65], v[154:157], v[186:189], v[62:65]
	v_mfma_f32_16x16x32_bf16 v[58:61], v[158:161], v[182:185], v[58:61]
	v_mfma_f32_16x16x32_bf16 v[58:61], v[162:165], v[186:189], v[58:61]
	v_mfma_f32_16x16x32_bf16 v[46:49], v[150:153], v[190:193], v[46:49]
	v_mfma_f32_16x16x32_bf16 v[46:49], v[154:157], v[194:197], v[46:49]
	v_mfma_f32_16x16x32_bf16 v[42:45], v[158:161], v[190:193], v[42:45]
	v_mfma_f32_16x16x32_bf16 v[42:45], v[162:165], v[194:197], v[42:45]
	v_mfma_f32_16x16x32_bf16 v[30:33], v[150:153], v[198:201], v[30:33]
	v_mfma_f32_16x16x32_bf16 v[30:33], v[154:157], v[212:215], v[30:33]
	v_mfma_f32_16x16x32_bf16 v[26:29], v[158:161], v[198:201], v[26:29]
	v_mfma_f32_16x16x32_bf16 v[26:29], v[162:165], v[212:215], v[26:29]
	v_mfma_f32_16x16x32_bf16 v[14:17], v[150:153], v[218:221], v[14:17]
	v_mfma_f32_16x16x32_bf16 v[14:17], v[154:157], v[222:225], v[14:17]
	v_mfma_f32_16x16x32_bf16 v[10:13], v[158:161], v[218:221], v[10:13]
	v_mfma_f32_16x16x32_bf16 v[10:13], v[162:165], v[222:225], v[10:13]
	s_setprio 0
	s_setprio 1
	v_mfma_f32_16x16x32_bf16 v[54:57], v[166:169], v[182:185], v[54:57]
	v_mfma_f32_16x16x32_bf16 v[54:57], v[170:173], v[186:189], v[54:57]
	v_mfma_f32_16x16x32_bf16 v[50:53], v[174:177], v[182:185], v[50:53]
	v_mfma_f32_16x16x32_bf16 v[50:53], v[178:181], v[186:189], v[50:53]
	v_mfma_f32_16x16x32_bf16 v[38:41], v[166:169], v[190:193], v[38:41]
	v_mfma_f32_16x16x32_bf16 v[38:41], v[170:173], v[194:197], v[38:41]
	v_mfma_f32_16x16x32_bf16 v[34:37], v[174:177], v[190:193], v[34:37]
	v_mfma_f32_16x16x32_bf16 v[34:37], v[178:181], v[194:197], v[34:37]
	v_mfma_f32_16x16x32_bf16 v[22:25], v[166:169], v[198:201], v[22:25]
	v_mfma_f32_16x16x32_bf16 v[22:25], v[170:173], v[212:215], v[22:25]
	v_mfma_f32_16x16x32_bf16 v[18:21], v[174:177], v[198:201], v[18:21]
	v_mfma_f32_16x16x32_bf16 v[18:21], v[178:181], v[212:215], v[18:21]
	v_mfma_f32_16x16x32_bf16 v[6:9], v[166:169], v[218:221], v[6:9]
	v_mfma_f32_16x16x32_bf16 v[6:9], v[170:173], v[222:225], v[6:9]
	v_mfma_f32_16x16x32_bf16 v[2:5], v[174:177], v[218:221], v[2:5]
	v_mfma_f32_16x16x32_bf16 v[2:5], v[178:181], v[222:225], v[2:5]
	s_setprio 0
	s_barrier
	ds_read_b128 v[150:153], v148
	ds_read_b128 v[154:157], v148 offset:1024
	ds_read_b128 v[158:161], v148 offset:2048
	ds_read_b128 v[162:165], v148 offset:3072
	ds_read_b128 v[166:169], v149
	ds_read_b128 v[170:173], v149 offset:1024
	ds_read_b128 v[174:177], v149 offset:2048
	ds_read_b128 v[178:181], v149 offset:3072
	s_add_i32 s57, s57, 0x80000
	s_mov_b32 m0, s37
	v_add_u32_e32 v134, s57, v136
	ds_read_b128 v[182:185], v147 offset:32768
	ds_read_b128 v[186:189], v147 offset:33792
	ds_read_b128 v[190:193], v147 offset:34816
	ds_read_b128 v[194:197], v147 offset:35840
	ds_read_b128 v[198:201], v147 offset:36864
	ds_read_b128 v[212:215], v147 offset:37888
	ds_read_b128 v[218:221], v147 offset:38912
	ds_read_b128 v[222:225], v147 offset:39936
	global_load_lds_dwordx4 v134, s[4:5]
	v_add_u32_e32 v134, s57, v138
	s_mov_b32 m0, s38
	s_nop 0
	global_load_lds_dwordx4 v134, s[4:5]
	s_waitcnt vmcnt(8)
	s_waitcnt lgkmcnt(0)
	s_setprio 1
	s_barrier
	v_mfma_f32_16x16x32_bf16 v[126:129], v[150:153], v[182:185], v[126:129]
	v_mfma_f32_16x16x32_bf16 v[126:129], v[154:157], v[186:189], v[126:129]
	v_mfma_f32_16x16x32_bf16 v[122:125], v[158:161], v[182:185], v[122:125]
	v_mfma_f32_16x16x32_bf16 v[122:125], v[162:165], v[186:189], v[122:125]
	v_mfma_f32_16x16x32_bf16 v[110:113], v[150:153], v[190:193], v[110:113]
	v_mfma_f32_16x16x32_bf16 v[110:113], v[154:157], v[194:197], v[110:113]
	v_mfma_f32_16x16x32_bf16 v[106:109], v[158:161], v[190:193], v[106:109]
	v_mfma_f32_16x16x32_bf16 v[106:109], v[162:165], v[194:197], v[106:109]
	v_mfma_f32_16x16x32_bf16 v[94:97], v[150:153], v[198:201], v[94:97]
	v_mfma_f32_16x16x32_bf16 v[94:97], v[154:157], v[212:215], v[94:97]
	v_mfma_f32_16x16x32_bf16 v[90:93], v[158:161], v[198:201], v[90:93]
	v_mfma_f32_16x16x32_bf16 v[90:93], v[162:165], v[212:215], v[90:93]
	v_mfma_f32_16x16x32_bf16 v[78:81], v[150:153], v[218:221], v[78:81]
	v_mfma_f32_16x16x32_bf16 v[78:81], v[154:157], v[222:225], v[78:81]
	v_mfma_f32_16x16x32_bf16 v[74:77], v[158:161], v[218:221], v[74:77]
	v_mfma_f32_16x16x32_bf16 v[74:77], v[162:165], v[222:225], v[74:77]
	s_setprio 0
	s_setprio 1
	v_mfma_f32_16x16x32_bf16 v[118:121], v[166:169], v[182:185], v[118:121]
	v_mfma_f32_16x16x32_bf16 v[118:121], v[170:173], v[186:189], v[118:121]
	v_mfma_f32_16x16x32_bf16 v[114:117], v[174:177], v[182:185], v[114:117]
	v_mfma_f32_16x16x32_bf16 v[114:117], v[178:181], v[186:189], v[114:117]
	v_mfma_f32_16x16x32_bf16 v[102:105], v[166:169], v[190:193], v[102:105]
	v_mfma_f32_16x16x32_bf16 v[102:105], v[170:173], v[194:197], v[102:105]
	v_mfma_f32_16x16x32_bf16 v[98:101], v[174:177], v[190:193], v[98:101]
	v_mfma_f32_16x16x32_bf16 v[98:101], v[178:181], v[194:197], v[98:101]
	v_mfma_f32_16x16x32_bf16 v[86:89], v[166:169], v[198:201], v[86:89]
	v_mfma_f32_16x16x32_bf16 v[86:89], v[170:173], v[212:215], v[86:89]
	v_mfma_f32_16x16x32_bf16 v[82:85], v[174:177], v[198:201], v[82:85]
	v_mfma_f32_16x16x32_bf16 v[82:85], v[178:181], v[212:215], v[82:85]
	v_mfma_f32_16x16x32_bf16 v[70:73], v[166:169], v[218:221], v[70:73]
	v_mfma_f32_16x16x32_bf16 v[70:73], v[170:173], v[222:225], v[70:73]
	v_mfma_f32_16x16x32_bf16 v[66:69], v[174:177], v[218:221], v[66:69]
	v_mfma_f32_16x16x32_bf16 v[66:69], v[178:181], v[222:225], v[66:69]
	s_setprio 0
	s_barrier
	s_or_b32 s57, s56, 0x80
	s_mov_b32 m0, s39
	v_add_u32_e32 v134, s57, v137
	ds_read_b128 v[182:185], v147 offset:49152
	ds_read_b128 v[186:189], v147 offset:50176
	ds_read_b128 v[190:193], v147 offset:51200
	ds_read_b128 v[194:197], v147 offset:52224
	ds_read_b128 v[198:201], v147 offset:53248
	ds_read_b128 v[212:215], v147 offset:54272
	ds_read_b128 v[218:221], v147 offset:55296
	ds_read_b128 v[222:225], v147 offset:56320
	global_load_lds_dwordx4 v134, s[6:7]
	v_add_u32_e32 v134, s57, v139
	s_mov_b32 m0, s40
	s_add_i32 s56, s56, 0x80080
	global_load_lds_dwordx4 v134, s[6:7]
	v_add_u32_e32 v134, s56, v137
	s_mov_b32 m0, s43
	s_nop 0
	global_load_lds_dwordx4 v134, s[6:7]
	v_add_u32_e32 v134, s56, v139
	s_mov_b32 m0, s44
	s_nop 0
	global_load_lds_dwordx4 v134, s[6:7]
	v_add_u32_e32 v134, s55, v136
	s_mov_b32 m0, s41
	s_nop 0
	global_load_lds_dwordx4 v134, s[4:5]
	v_add_u32_e32 v134, s55, v138
	s_mov_b32 m0, s42
	s_nop 0
	global_load_lds_dwordx4 v134, s[4:5]
	s_add_i32 s54, s54, 2
	s_addk_i32 s52, 0x100
	s_addk_i32 s53, 0x100
	v_add_u32_e32 v132, 0x100, v132
	s_cmp_gt_u32 s54, 29
	v_add_u32_e32 v133, 0x100, v133
	s_waitcnt vmcnt(8)
	s_waitcnt lgkmcnt(0)
	s_setprio 1
	s_barrier
	v_mfma_f32_16x16x32_bf16 v[62:65], v[150:153], v[182:185], v[62:65]
	v_mfma_f32_16x16x32_bf16 v[62:65], v[154:157], v[186:189], v[62:65]
	v_mfma_f32_16x16x32_bf16 v[58:61], v[158:161], v[182:185], v[58:61]
	v_mfma_f32_16x16x32_bf16 v[58:61], v[162:165], v[186:189], v[58:61]
	v_mfma_f32_16x16x32_bf16 v[46:49], v[150:153], v[190:193], v[46:49]
	v_mfma_f32_16x16x32_bf16 v[46:49], v[154:157], v[194:197], v[46:49]
	v_mfma_f32_16x16x32_bf16 v[42:45], v[158:161], v[190:193], v[42:45]
	v_mfma_f32_16x16x32_bf16 v[42:45], v[162:165], v[194:197], v[42:45]
	v_mfma_f32_16x16x32_bf16 v[30:33], v[150:153], v[198:201], v[30:33]
	v_mfma_f32_16x16x32_bf16 v[30:33], v[154:157], v[212:215], v[30:33]
	v_mfma_f32_16x16x32_bf16 v[26:29], v[158:161], v[198:201], v[26:29]
	v_mfma_f32_16x16x32_bf16 v[26:29], v[162:165], v[212:215], v[26:29]
	v_mfma_f32_16x16x32_bf16 v[14:17], v[150:153], v[218:221], v[14:17]
	v_mfma_f32_16x16x32_bf16 v[14:17], v[154:157], v[222:225], v[14:17]
	v_mfma_f32_16x16x32_bf16 v[10:13], v[158:161], v[218:221], v[10:13]
	v_mfma_f32_16x16x32_bf16 v[10:13], v[162:165], v[222:225], v[10:13]
	s_setprio 0
	s_setprio 1
	v_mfma_f32_16x16x32_bf16 v[54:57], v[166:169], v[182:185], v[54:57]
	v_mfma_f32_16x16x32_bf16 v[54:57], v[170:173], v[186:189], v[54:57]
	v_mfma_f32_16x16x32_bf16 v[50:53], v[174:177], v[182:185], v[50:53]
	v_mfma_f32_16x16x32_bf16 v[50:53], v[178:181], v[186:189], v[50:53]
	v_mfma_f32_16x16x32_bf16 v[38:41], v[166:169], v[190:193], v[38:41]
	v_mfma_f32_16x16x32_bf16 v[38:41], v[170:173], v[194:197], v[38:41]
	v_mfma_f32_16x16x32_bf16 v[34:37], v[174:177], v[190:193], v[34:37]
	v_mfma_f32_16x16x32_bf16 v[34:37], v[178:181], v[194:197], v[34:37]
	v_mfma_f32_16x16x32_bf16 v[22:25], v[166:169], v[198:201], v[22:25]
	v_mfma_f32_16x16x32_bf16 v[22:25], v[170:173], v[212:215], v[22:25]
	v_mfma_f32_16x16x32_bf16 v[18:21], v[174:177], v[198:201], v[18:21]
	v_mfma_f32_16x16x32_bf16 v[18:21], v[178:181], v[212:215], v[18:21]
	v_mfma_f32_16x16x32_bf16 v[6:9], v[166:169], v[218:221], v[6:9]
	v_mfma_f32_16x16x32_bf16 v[6:9], v[170:173], v[222:225], v[6:9]
	v_mfma_f32_16x16x32_bf16 v[2:5], v[174:177], v[218:221], v[2:5]
	v_mfma_f32_16x16x32_bf16 v[2:5], v[178:181], v[222:225], v[2:5]
	s_setprio 0
	s_barrier
	s_cbranch_scc0 .LBB0_115
	s_and_b64 vcc, exec, s[16:17]
	s_cbranch_vccz .LBB0_118
	s_barrier

.LBB0_135:
	v_lshrrev_b32_e32 v9, 1, v5
	v_and_b32_e32 v135, 24, v9
	v_and_b32_e32 v136, 15, v5
	v_lshlrev_b32_e32 v9, 1, v135
	v_lshlrev_b32_e32 v5, 2, v5
	s_lshl_b32 s27, s27, 5
	s_lshl_b32 s26, s29, 6
	v_lshl_or_b32 v9, v136, 6, v9
	s_lshl_b32 s29, s29, 13
	v_and_b32_e32 v5, 32, v5
	s_and_b32 s27, s27, 0x60
	v_bitop3_b32 v10, v9, s29, v5 bitop3:0xde
	s_lshl_b32 s29, s27, 7
	v_bitop3_b32 v137, v9, s29, v5 bitop3:0xde
	s_add_i32 s29, s28, 0x18000
	s_or_b32 s31, s12, 0x80
	s_add_i32 s30, s29, s37
	v_add_u32_e32 v5, s31, v131
	s_mov_b32 m0, s30
	s_waitcnt vmcnt(2)
	s_barrier
	global_load_lds_dwordx4 v5, s[6:7]
	v_add_u32_e32 v5, s31, v133
	s_add_i32 s31, s30, 0x2000
	s_mov_b32 m0, s31
	s_or_b32 s35, s21, 0x80
	s_add_i32 s34, s22, 0x8000
	global_load_lds_dwordx4 v5, s[6:7]
	v_add_u32_e32 v5, s35, v130
	s_mov_b32 m0, s34
	s_add_i32 s36, s28, 0x1c000
	global_load_lds_dwordx4 v5, s[4:5]
	v_add_u32_e32 v5, s35, v132
	s_add_i32 s35, s22, 0xa000
	s_mov_b32 m0, s35
	s_or_b32 s38, s12, 0x80080
	s_add_i32 s37, s36, s37
	global_load_lds_dwordx4 v5, s[4:5]
	v_add_u32_e32 v5, s38, v131
	s_mov_b32 m0, s37
	s_add_i32 s39, s21, 0x80080
	global_load_lds_dwordx4 v5, s[6:7]
	v_add_u32_e32 v5, s38, v133
	s_add_i32 s38, s37, 0x2000
	s_mov_b32 m0, s38
	v_lshlrev_b32_e32 v7, 12, v7
	global_load_lds_dwordx4 v5, s[6:7]
	v_lshlrev_b32_e32 v5, 15, v6
	v_and_b32_e32 v5, 0xffff0000, v5
	v_and_b32_e32 v6, 1, v6
	v_add3_u32 v5, s39, v5, v7
	v_lshlrev_b32_e32 v6, 6, v6
	v_lshlrev_b32_e32 v7, 1, v8
	v_add3_u32 v138, v5, v6, v7
	v_lshlrev_b32_e32 v5, 15, v2
	v_and_b32_e32 v5, 0xffff0000, v5
	v_lshlrev_b32_e32 v3, 12, v3
	v_and_b32_e32 v2, 1, v2
	s_waitcnt vmcnt(6)
	v_add3_u32 v3, s39, v5, v3
	v_lshlrev_b32_e32 v2, 6, v2
	v_lshlrev_b32_e32 v4, 1, v4
	v_add3_u32 v139, v3, v2, v4
	v_or_b32_e32 v134, s26, v136
	s_mov_b32 s39, -2
	s_mov_b32 s40, 0
	v_add_u32_e32 v140, s28, v10
	s_barrier
	v_add_u32_e32 v141, s13, v137
	ds_read_b128 v[142:145], v141
	ds_read_b128 v[146:149], v141 offset:1024
	ds_read_b128 v[150:153], v141 offset:2048
	ds_read_b128 v[154:157], v141 offset:3072
	v_add_u32_e32 v141, s16, v137
	ds_read_b128 v[158:161], v141
	ds_read_b128 v[162:165], v141 offset:1024
	ds_read_b128 v[166:169], v141 offset:2048
	ds_read_b128 v[170:173], v141 offset:3072
	s_add_i32 s41, s40, 0x100
	s_cmp_lg_u32 s39, 28
	s_cselect_b32 s43, s41, 0
	s_add_i32 s44, s43, s21
	s_or_b32 s42, s44, 0x80
	s_add_i32 s43, s43, s12
	v_add_u32_e32 v141, s40, v139
	s_add_i32 m0, s22, 0xc000
	ds_read_b128 v[174:177], v140
	ds_read_b128 v[178:181], v140 offset:1024
	ds_read_b128 v[182:185], v140 offset:2048
	ds_read_b128 v[186:189], v140 offset:3072
	ds_read_b128 v[190:193], v140 offset:4096
	ds_read_b128 v[194:197], v140 offset:5120
	ds_read_b128 v[198:201], v140 offset:6144
	ds_read_b128 v[212:215], v140 offset:7168
	global_load_lds_dwordx4 v141, s[4:5]
	v_add_u32_e32 v141, s40, v138
	s_add_i32 m0, s22, 0xe000
	s_nop 0
	global_load_lds_dwordx4 v141, s[4:5]
	s_waitcnt vmcnt(8)
	s_waitcnt lgkmcnt(0)
	s_setprio 1
	s_barrier
	v_mfma_f32_16x16x32_bf16 v[126:129], v[142:145], v[174:177], 0
	v_mfma_f32_16x16x32_bf16 v[126:129], v[146:149], v[178:181], v[126:129]
	v_mfma_f32_16x16x32_bf16 v[122:125], v[150:153], v[174:177], 0
	v_mfma_f32_16x16x32_bf16 v[122:125], v[154:157], v[178:181], v[122:125]
	v_mfma_f32_16x16x32_bf16 v[110:113], v[142:145], v[182:185], 0
	v_mfma_f32_16x16x32_bf16 v[110:113], v[146:149], v[186:189], v[110:113]
	v_mfma_f32_16x16x32_bf16 v[106:109], v[150:153], v[182:185], 0
	v_mfma_f32_16x16x32_bf16 v[106:109], v[154:157], v[186:189], v[106:109]
	v_mfma_f32_16x16x32_bf16 v[94:97], v[142:145], v[190:193], 0
	v_mfma_f32_16x16x32_bf16 v[94:97], v[146:149], v[194:197], v[94:97]
	v_mfma_f32_16x16x32_bf16 v[90:93], v[150:153], v[190:193], 0
	v_mfma_f32_16x16x32_bf16 v[90:93], v[154:157], v[194:197], v[90:93]
	v_mfma_f32_16x16x32_bf16 v[78:81], v[142:145], v[198:201], 0
	v_mfma_f32_16x16x32_bf16 v[78:81], v[146:149], v[212:215], v[78:81]
	v_mfma_f32_16x16x32_bf16 v[74:77], v[150:153], v[198:201], 0
	v_mfma_f32_16x16x32_bf16 v[74:77], v[154:157], v[212:215], v[74:77]
	s_setprio 0
	s_setprio 1
	v_mfma_f32_16x16x32_bf16 v[118:121], v[158:161], v[174:177], 0
	v_mfma_f32_16x16x32_bf16 v[118:121], v[162:165], v[178:181], v[118:121]
	v_mfma_f32_16x16x32_bf16 v[114:117], v[166:169], v[174:177], 0
	v_mfma_f32_16x16x32_bf16 v[114:117], v[170:173], v[178:181], v[114:117]
	v_mfma_f32_16x16x32_bf16 v[102:105], v[158:161], v[182:185], 0
	v_mfma_f32_16x16x32_bf16 v[102:105], v[162:165], v[186:189], v[102:105]
	v_mfma_f32_16x16x32_bf16 v[98:101], v[166:169], v[182:185], 0
	v_mfma_f32_16x16x32_bf16 v[98:101], v[170:173], v[186:189], v[98:101]
	v_mfma_f32_16x16x32_bf16 v[86:89], v[158:161], v[190:193], 0
	v_mfma_f32_16x16x32_bf16 v[86:89], v[162:165], v[194:197], v[86:89]
	v_mfma_f32_16x16x32_bf16 v[82:85], v[166:169], v[190:193], 0
	v_mfma_f32_16x16x32_bf16 v[82:85], v[170:173], v[194:197], v[82:85]
	v_mfma_f32_16x16x32_bf16 v[70:73], v[158:161], v[198:201], 0
	v_mfma_f32_16x16x32_bf16 v[70:73], v[162:165], v[212:215], v[70:73]
	v_mfma_f32_16x16x32_bf16 v[66:69], v[166:169], v[198:201], 0
	v_mfma_f32_16x16x32_bf16 v[66:69], v[170:173], v[212:215], v[66:69]
	s_setprio 0
	s_barrier
	s_mov_b32 m0, s14
	v_add_u32_e32 v141, s43, v131
	ds_read_b128 v[174:177], v140 offset:16384
	ds_read_b128 v[178:181], v140 offset:17408
	ds_read_b128 v[182:185], v140 offset:18432
	ds_read_b128 v[186:189], v140 offset:19456
	ds_read_b128 v[190:193], v140 offset:20480
	ds_read_b128 v[194:197], v140 offset:21504
	ds_read_b128 v[198:201], v140 offset:22528
	ds_read_b128 v[212:215], v140 offset:23552
	global_load_lds_dwordx4 v141, s[6:7]
	v_add_u32_e32 v141, s43, v133
	s_mov_b32 m0, s15
	s_add_i32 s40, s43, 0x80000
	global_load_lds_dwordx4 v141, s[6:7]
	v_add_u32_e32 v141, s40, v131
	s_mov_b32 m0, s17
	s_nop 0
	global_load_lds_dwordx4 v141, s[6:7]
	v_add_u32_e32 v141, s40, v133
	s_mov_b32 m0, s20
	s_nop 0
	global_load_lds_dwordx4 v141, s[6:7]
	v_add_u32_e32 v141, s44, v130
	s_mov_b32 m0, s22
	s_nop 0
	global_load_lds_dwordx4 v141, s[4:5]
	v_add_u32_e32 v141, s44, v132
	s_mov_b32 m0, s23
	s_nop 0
	global_load_lds_dwordx4 v141, s[4:5]
	s_waitcnt vmcnt(8)
	s_waitcnt lgkmcnt(0)
	s_setprio 1
	s_barrier
	v_mfma_f32_16x16x32_bf16 v[62:65], v[142:145], v[174:177], 0
	v_mfma_f32_16x16x32_bf16 v[62:65], v[146:149], v[178:181], v[62:65]
	v_mfma_f32_16x16x32_bf16 v[58:61], v[150:153], v[174:177], 0
	v_mfma_f32_16x16x32_bf16 v[58:61], v[154:157], v[178:181], v[58:61]
	v_mfma_f32_16x16x32_bf16 v[46:49], v[142:145], v[182:185], 0
	v_mfma_f32_16x16x32_bf16 v[46:49], v[146:149], v[186:189], v[46:49]
	v_mfma_f32_16x16x32_bf16 v[42:45], v[150:153], v[182:185], 0
	v_mfma_f32_16x16x32_bf16 v[42:45], v[154:157], v[186:189], v[42:45]
	v_mfma_f32_16x16x32_bf16 v[30:33], v[142:145], v[190:193], 0
	v_mfma_f32_16x16x32_bf16 v[30:33], v[146:149], v[194:197], v[30:33]
	v_mfma_f32_16x16x32_bf16 v[26:29], v[150:153], v[190:193], 0
	v_mfma_f32_16x16x32_bf16 v[26:29], v[154:157], v[194:197], v[26:29]
	v_mfma_f32_16x16x32_bf16 v[14:17], v[142:145], v[198:201], 0
	v_mfma_f32_16x16x32_bf16 v[14:17], v[146:149], v[212:215], v[14:17]
	v_mfma_f32_16x16x32_bf16 v[10:13], v[150:153], v[198:201], 0
	v_mfma_f32_16x16x32_bf16 v[10:13], v[154:157], v[212:215], v[10:13]
	s_setprio 0
	s_setprio 1
	v_mfma_f32_16x16x32_bf16 v[54:57], v[158:161], v[174:177], 0
	v_mfma_f32_16x16x32_bf16 v[54:57], v[162:165], v[178:181], v[54:57]
	v_mfma_f32_16x16x32_bf16 v[50:53], v[166:169], v[174:177], 0
	v_mfma_f32_16x16x32_bf16 v[50:53], v[170:173], v[178:181], v[50:53]
	v_mfma_f32_16x16x32_bf16 v[38:41], v[158:161], v[182:185], 0
	v_mfma_f32_16x16x32_bf16 v[38:41], v[162:165], v[186:189], v[38:41]
	v_mfma_f32_16x16x32_bf16 v[34:37], v[166:169], v[182:185], 0
	v_mfma_f32_16x16x32_bf16 v[34:37], v[170:173], v[186:189], v[34:37]
	v_mfma_f32_16x16x32_bf16 v[22:25], v[158:161], v[190:193], 0
	v_mfma_f32_16x16x32_bf16 v[22:25], v[162:165], v[194:197], v[22:25]
	v_mfma_f32_16x16x32_bf16 v[18:21], v[166:169], v[190:193], 0
	v_mfma_f32_16x16x32_bf16 v[18:21], v[170:173], v[194:197], v[18:21]
	v_mfma_f32_16x16x32_bf16 v[6:9], v[158:161], v[198:201], 0
	v_mfma_f32_16x16x32_bf16 v[6:9], v[162:165], v[212:215], v[6:9]
	v_mfma_f32_16x16x32_bf16 v[2:5], v[166:169], v[198:201], 0
	v_mfma_f32_16x16x32_bf16 v[2:5], v[170:173], v[212:215], v[2:5]
	s_setprio 0
	s_barrier
	v_add_u32_e32 v141, s29, v137
	ds_read_b128 v[142:145], v141
	ds_read_b128 v[146:149], v141 offset:1024
	ds_read_b128 v[150:153], v141 offset:2048
	ds_read_b128 v[154:157], v141 offset:3072
	v_add_u32_e32 v141, s36, v137
	ds_read_b128 v[158:161], v141
	ds_read_b128 v[162:165], v141 offset:1024
	ds_read_b128 v[166:169], v141 offset:2048
	ds_read_b128 v[170:173], v141 offset:3072
	s_add_i32 s44, s44, 0x80000
	s_mov_b32 m0, s24
	v_add_u32_e32 v141, s44, v130
	ds_read_b128 v[174:177], v140 offset:32768
	ds_read_b128 v[178:181], v140 offset:33792
	ds_read_b128 v[182:185], v140 offset:34816
	ds_read_b128 v[186:189], v140 offset:35840
	ds_read_b128 v[190:193], v140 offset:36864
	ds_read_b128 v[194:197], v140 offset:37888
	ds_read_b128 v[198:201], v140 offset:38912
	ds_read_b128 v[212:215], v140 offset:39936
	global_load_lds_dwordx4 v141, s[4:5]
	v_add_u32_e32 v141, s44, v132
	s_mov_b32 m0, s25
	s_nop 0
	global_load_lds_dwordx4 v141, s[4:5]
	s_waitcnt vmcnt(8)
	s_waitcnt lgkmcnt(0)
	s_setprio 1
	s_barrier
	v_mfma_f32_16x16x32_bf16 v[126:129], v[142:145], v[174:177], v[126:129]
	v_mfma_f32_16x16x32_bf16 v[126:129], v[146:149], v[178:181], v[126:129]
	v_mfma_f32_16x16x32_bf16 v[122:125], v[150:153], v[174:177], v[122:125]
	v_mfma_f32_16x16x32_bf16 v[122:125], v[154:157], v[178:181], v[122:125]
	v_mfma_f32_16x16x32_bf16 v[110:113], v[142:145], v[182:185], v[110:113]
	v_mfma_f32_16x16x32_bf16 v[110:113], v[146:149], v[186:189], v[110:113]
	v_mfma_f32_16x16x32_bf16 v[106:109], v[150:153], v[182:185], v[106:109]
	v_mfma_f32_16x16x32_bf16 v[106:109], v[154:157], v[186:189], v[106:109]
	v_mfma_f32_16x16x32_bf16 v[94:97], v[142:145], v[190:193], v[94:97]
	v_mfma_f32_16x16x32_bf16 v[94:97], v[146:149], v[194:197], v[94:97]
	v_mfma_f32_16x16x32_bf16 v[90:93], v[150:153], v[190:193], v[90:93]
	v_mfma_f32_16x16x32_bf16 v[90:93], v[154:157], v[194:197], v[90:93]
	v_mfma_f32_16x16x32_bf16 v[78:81], v[142:145], v[198:201], v[78:81]
	v_mfma_f32_16x16x32_bf16 v[78:81], v[146:149], v[212:215], v[78:81]
	v_mfma_f32_16x16x32_bf16 v[74:77], v[150:153], v[198:201], v[74:77]
	v_mfma_f32_16x16x32_bf16 v[74:77], v[154:157], v[212:215], v[74:77]
	s_setprio 0
	s_setprio 1
	v_mfma_f32_16x16x32_bf16 v[118:121], v[158:161], v[174:177], v[118:121]
	v_mfma_f32_16x16x32_bf16 v[118:121], v[162:165], v[178:181], v[118:121]
	v_mfma_f32_16x16x32_bf16 v[114:117], v[166:169], v[174:177], v[114:117]
	v_mfma_f32_16x16x32_bf16 v[114:117], v[170:173], v[178:181], v[114:117]
	v_mfma_f32_16x16x32_bf16 v[102:105], v[158:161], v[182:185], v[102:105]
	v_mfma_f32_16x16x32_bf16 v[102:105], v[162:165], v[186:189], v[102:105]
	v_mfma_f32_16x16x32_bf16 v[98:101], v[166:169], v[182:185], v[98:101]
	v_mfma_f32_16x16x32_bf16 v[98:101], v[170:173], v[186:189], v[98:101]
	v_mfma_f32_16x16x32_bf16 v[86:89], v[158:161], v[190:193], v[86:89]
	v_mfma_f32_16x16x32_bf16 v[86:89], v[162:165], v[194:197], v[86:89]
	v_mfma_f32_16x16x32_bf16 v[82:85], v[166:169], v[190:193], v[82:85]
	v_mfma_f32_16x16x32_bf16 v[82:85], v[170:173], v[194:197], v[82:85]
	v_mfma_f32_16x16x32_bf16 v[70:73], v[158:161], v[198:201], v[70:73]
	v_mfma_f32_16x16x32_bf16 v[70:73], v[162:165], v[212:215], v[70:73]
	v_mfma_f32_16x16x32_bf16 v[66:69], v[166:169], v[198:201], v[66:69]
	v_mfma_f32_16x16x32_bf16 v[66:69], v[170:173], v[212:215], v[66:69]
	s_setprio 0
	s_barrier
	s_or_b32 s40, s43, 0x80
	s_mov_b32 m0, s30
	v_add_u32_e32 v141, s40, v131
	ds_read_b128 v[174:177], v140 offset:49152
	ds_read_b128 v[178:181], v140 offset:50176
	ds_read_b128 v[182:185], v140 offset:51200
	ds_read_b128 v[186:189], v140 offset:52224
	ds_read_b128 v[190:193], v140 offset:53248
	ds_read_b128 v[194:197], v140 offset:54272
	ds_read_b128 v[198:201], v140 offset:55296
	ds_read_b128 v[212:215], v140 offset:56320
	global_load_lds_dwordx4 v141, s[6:7]
	v_add_u32_e32 v141, s40, v133
	s_mov_b32 m0, s31
	s_add_i32 s43, s43, 0x80080
	global_load_lds_dwordx4 v141, s[6:7]
	v_add_u32_e32 v141, s43, v131
	s_mov_b32 m0, s37
	s_nop 0
	global_load_lds_dwordx4 v141, s[6:7]
	v_add_u32_e32 v141, s43, v133
	s_mov_b32 m0, s38
	s_nop 0
	global_load_lds_dwordx4 v141, s[6:7]
	v_add_u32_e32 v141, s42, v130
	s_mov_b32 m0, s34
	s_nop 0
	global_load_lds_dwordx4 v141, s[4:5]
	v_add_u32_e32 v141, s42, v132
	s_mov_b32 m0, s35
	s_nop 0
	global_load_lds_dwordx4 v141, s[4:5]
	s_waitcnt vmcnt(8)
	s_waitcnt lgkmcnt(0)
	s_setprio 1
	s_barrier
	v_mfma_f32_16x16x32_bf16 v[62:65], v[142:145], v[174:177], v[62:65]
	v_mfma_f32_16x16x32_bf16 v[62:65], v[146:149], v[178:181], v[62:65]
	v_mfma_f32_16x16x32_bf16 v[58:61], v[150:153], v[174:177], v[58:61]
	v_mfma_f32_16x16x32_bf16 v[58:61], v[154:157], v[178:181], v[58:61]
	v_mfma_f32_16x16x32_bf16 v[46:49], v[142:145], v[182:185], v[46:49]
	v_mfma_f32_16x16x32_bf16 v[46:49], v[146:149], v[186:189], v[46:49]
	v_mfma_f32_16x16x32_bf16 v[42:45], v[150:153], v[182:185], v[42:45]
	v_mfma_f32_16x16x32_bf16 v[42:45], v[154:157], v[186:189], v[42:45]
	v_mfma_f32_16x16x32_bf16 v[30:33], v[142:145], v[190:193], v[30:33]
	v_mfma_f32_16x16x32_bf16 v[30:33], v[146:149], v[194:197], v[30:33]
	v_mfma_f32_16x16x32_bf16 v[26:29], v[150:153], v[190:193], v[26:29]
	v_mfma_f32_16x16x32_bf16 v[26:29], v[154:157], v[194:197], v[26:29]
	v_mfma_f32_16x16x32_bf16 v[14:17], v[142:145], v[198:201], v[14:17]
	v_mfma_f32_16x16x32_bf16 v[14:17], v[146:149], v[212:215], v[14:17]
	v_mfma_f32_16x16x32_bf16 v[10:13], v[150:153], v[198:201], v[10:13]
	v_mfma_f32_16x16x32_bf16 v[10:13], v[154:157], v[212:215], v[10:13]
	s_setprio 0
	s_setprio 1
	v_mfma_f32_16x16x32_bf16 v[54:57], v[158:161], v[174:177], v[54:57]
	v_mfma_f32_16x16x32_bf16 v[54:57], v[162:165], v[178:181], v[54:57]
	v_mfma_f32_16x16x32_bf16 v[50:53], v[166:169], v[174:177], v[50:53]
	v_mfma_f32_16x16x32_bf16 v[50:53], v[170:173], v[178:181], v[50:53]
	v_mfma_f32_16x16x32_bf16 v[38:41], v[158:161], v[182:185], v[38:41]
	v_mfma_f32_16x16x32_bf16 v[38:41], v[162:165], v[186:189], v[38:41]
	v_mfma_f32_16x16x32_bf16 v[34:37], v[166:169], v[182:185], v[34:37]
	v_mfma_f32_16x16x32_bf16 v[34:37], v[170:173], v[186:189], v[34:37]
	v_mfma_f32_16x16x32_bf16 v[22:25], v[158:161], v[190:193], v[22:25]
	v_mfma_f32_16x16x32_bf16 v[22:25], v[162:165], v[194:197], v[22:25]
	v_mfma_f32_16x16x32_bf16 v[18:21], v[166:169], v[190:193], v[18:21]
	v_mfma_f32_16x16x32_bf16 v[18:21], v[170:173], v[194:197], v[18:21]
	v_mfma_f32_16x16x32_bf16 v[6:9], v[158:161], v[198:201], v[6:9]
	v_mfma_f32_16x16x32_bf16 v[6:9], v[162:165], v[212:215], v[6:9]
	v_mfma_f32_16x16x32_bf16 v[2:5], v[166:169], v[198:201], v[2:5]
	v_mfma_f32_16x16x32_bf16 v[2:5], v[170:173], v[212:215], v[2:5]
	s_setprio 0
	s_barrier
	s_add_i32 s39, s39, 2
	s_cmp_gt_u32 s39, 29
	s_mov_b32 s40, s41
.LBB0_136:
	v_add_u32_e32 v141, s13, v137
	ds_read_b128 v[142:145], v141
	ds_read_b128 v[146:149], v141 offset:1024
	ds_read_b128 v[150:153], v141 offset:2048
	ds_read_b128 v[154:157], v141 offset:3072
	v_add_u32_e32 v141, s16, v137
	ds_read_b128 v[158:161], v141
	ds_read_b128 v[162:165], v141 offset:1024
	ds_read_b128 v[166:169], v141 offset:2048
	ds_read_b128 v[170:173], v141 offset:3072
	s_add_i32 s41, s40, 0x100
	s_cmp_lg_u32 s39, 28
	s_cselect_b32 s43, s41, 0
	s_add_i32 s44, s43, s21
	s_or_b32 s42, s44, 0x80
	s_add_i32 s43, s43, s12
	v_add_u32_e32 v141, s40, v139
	s_add_i32 m0, s22, 0xc000
	ds_read_b128 v[174:177], v140
	ds_read_b128 v[178:181], v140 offset:1024
	ds_read_b128 v[182:185], v140 offset:2048
	ds_read_b128 v[186:189], v140 offset:3072
	ds_read_b128 v[190:193], v140 offset:4096
	ds_read_b128 v[194:197], v140 offset:5120
	ds_read_b128 v[198:201], v140 offset:6144
	ds_read_b128 v[212:215], v140 offset:7168
	global_load_lds_dwordx4 v141, s[4:5]
	v_add_u32_e32 v141, s40, v138
	s_add_i32 m0, s22, 0xe000
	s_nop 0
	global_load_lds_dwordx4 v141, s[4:5]
	s_waitcnt vmcnt(8)
	s_waitcnt lgkmcnt(0)
	s_setprio 1
	s_barrier
	v_mfma_f32_16x16x32_bf16 v[126:129], v[142:145], v[174:177], v[126:129]
	v_mfma_f32_16x16x32_bf16 v[126:129], v[146:149], v[178:181], v[126:129]
	v_mfma_f32_16x16x32_bf16 v[122:125], v[150:153], v[174:177], v[122:125]
	v_mfma_f32_16x16x32_bf16 v[122:125], v[154:157], v[178:181], v[122:125]
	v_mfma_f32_16x16x32_bf16 v[110:113], v[142:145], v[182:185], v[110:113]
	v_mfma_f32_16x16x32_bf16 v[110:113], v[146:149], v[186:189], v[110:113]
	v_mfma_f32_16x16x32_bf16 v[106:109], v[150:153], v[182:185], v[106:109]
	v_mfma_f32_16x16x32_bf16 v[106:109], v[154:157], v[186:189], v[106:109]
	v_mfma_f32_16x16x32_bf16 v[94:97], v[142:145], v[190:193], v[94:97]
	v_mfma_f32_16x16x32_bf16 v[94:97], v[146:149], v[194:197], v[94:97]
	v_mfma_f32_16x16x32_bf16 v[90:93], v[150:153], v[190:193], v[90:93]
	v_mfma_f32_16x16x32_bf16 v[90:93], v[154:157], v[194:197], v[90:93]
	v_mfma_f32_16x16x32_bf16 v[78:81], v[142:145], v[198:201], v[78:81]
	v_mfma_f32_16x16x32_bf16 v[78:81], v[146:149], v[212:215], v[78:81]
	v_mfma_f32_16x16x32_bf16 v[74:77], v[150:153], v[198:201], v[74:77]
	v_mfma_f32_16x16x32_bf16 v[74:77], v[154:157], v[212:215], v[74:77]
	s_setprio 0
	s_setprio 1
	v_mfma_f32_16x16x32_bf16 v[118:121], v[158:161], v[174:177], v[118:121]
	v_mfma_f32_16x16x32_bf16 v[118:121], v[162:165], v[178:181], v[118:121]
	v_mfma_f32_16x16x32_bf16 v[114:117], v[166:169], v[174:177], v[114:117]
	v_mfma_f32_16x16x32_bf16 v[114:117], v[170:173], v[178:181], v[114:117]
	v_mfma_f32_16x16x32_bf16 v[102:105], v[158:161], v[182:185], v[102:105]
	v_mfma_f32_16x16x32_bf16 v[102:105], v[162:165], v[186:189], v[102:105]
	v_mfma_f32_16x16x32_bf16 v[98:101], v[166:169], v[182:185], v[98:101]
	v_mfma_f32_16x16x32_bf16 v[98:101], v[170:173], v[186:189], v[98:101]
	v_mfma_f32_16x16x32_bf16 v[86:89], v[158:161], v[190:193], v[86:89]
	v_mfma_f32_16x16x32_bf16 v[86:89], v[162:165], v[194:197], v[86:89]
	v_mfma_f32_16x16x32_bf16 v[82:85], v[166:169], v[190:193], v[82:85]
	v_mfma_f32_16x16x32_bf16 v[82:85], v[170:173], v[194:197], v[82:85]
	v_mfma_f32_16x16x32_bf16 v[70:73], v[158:161], v[198:201], v[70:73]
	v_mfma_f32_16x16x32_bf16 v[70:73], v[162:165], v[212:215], v[70:73]
	v_mfma_f32_16x16x32_bf16 v[66:69], v[166:169], v[198:201], v[66:69]
	v_mfma_f32_16x16x32_bf16 v[66:69], v[170:173], v[212:215], v[66:69]
	s_setprio 0
	s_barrier
	s_mov_b32 m0, s14
	v_add_u32_e32 v141, s43, v131
	ds_read_b128 v[174:177], v140 offset:16384
	ds_read_b128 v[178:181], v140 offset:17408
	ds_read_b128 v[182:185], v140 offset:18432
	ds_read_b128 v[186:189], v140 offset:19456
	ds_read_b128 v[190:193], v140 offset:20480
	ds_read_b128 v[194:197], v140 offset:21504
	ds_read_b128 v[198:201], v140 offset:22528
	ds_read_b128 v[212:215], v140 offset:23552
	global_load_lds_dwordx4 v141, s[6:7]
	v_add_u32_e32 v141, s43, v133
	s_mov_b32 m0, s15
	s_add_i32 s40, s43, 0x80000
	global_load_lds_dwordx4 v141, s[6:7]
	v_add_u32_e32 v141, s40, v131
	s_mov_b32 m0, s17
	s_nop 0
	global_load_lds_dwordx4 v141, s[6:7]
	v_add_u32_e32 v141, s40, v133
	s_mov_b32 m0, s20
	s_nop 0
	global_load_lds_dwordx4 v141, s[6:7]
	v_add_u32_e32 v141, s44, v130
	s_mov_b32 m0, s22
	s_nop 0
	global_load_lds_dwordx4 v141, s[4:5]
	v_add_u32_e32 v141, s44, v132
	s_mov_b32 m0, s23
	s_nop 0
	global_load_lds_dwordx4 v141, s[4:5]
	s_waitcnt vmcnt(8)
	s_waitcnt lgkmcnt(0)
	s_setprio 1
	s_barrier
	v_mfma_f32_16x16x32_bf16 v[62:65], v[142:145], v[174:177], v[62:65]
	v_mfma_f32_16x16x32_bf16 v[62:65], v[146:149], v[178:181], v[62:65]
	v_mfma_f32_16x16x32_bf16 v[58:61], v[150:153], v[174:177], v[58:61]
	v_mfma_f32_16x16x32_bf16 v[58:61], v[154:157], v[178:181], v[58:61]
	v_mfma_f32_16x16x32_bf16 v[46:49], v[142:145], v[182:185], v[46:49]
	v_mfma_f32_16x16x32_bf16 v[46:49], v[146:149], v[186:189], v[46:49]
	v_mfma_f32_16x16x32_bf16 v[42:45], v[150:153], v[182:185], v[42:45]
	v_mfma_f32_16x16x32_bf16 v[42:45], v[154:157], v[186:189], v[42:45]
	v_mfma_f32_16x16x32_bf16 v[30:33], v[142:145], v[190:193], v[30:33]
	v_mfma_f32_16x16x32_bf16 v[30:33], v[146:149], v[194:197], v[30:33]
	v_mfma_f32_16x16x32_bf16 v[26:29], v[150:153], v[190:193], v[26:29]
	v_mfma_f32_16x16x32_bf16 v[26:29], v[154:157], v[194:197], v[26:29]
	v_mfma_f32_16x16x32_bf16 v[14:17], v[142:145], v[198:201], v[14:17]
	v_mfma_f32_16x16x32_bf16 v[14:17], v[146:149], v[212:215], v[14:17]
	v_mfma_f32_16x16x32_bf16 v[10:13], v[150:153], v[198:201], v[10:13]
	v_mfma_f32_16x16x32_bf16 v[10:13], v[154:157], v[212:215], v[10:13]
	s_setprio 0
	s_setprio 1
	v_mfma_f32_16x16x32_bf16 v[54:57], v[158:161], v[174:177], v[54:57]
	v_mfma_f32_16x16x32_bf16 v[54:57], v[162:165], v[178:181], v[54:57]
	v_mfma_f32_16x16x32_bf16 v[50:53], v[166:169], v[174:177], v[50:53]
	v_mfma_f32_16x16x32_bf16 v[50:53], v[170:173], v[178:181], v[50:53]
	v_mfma_f32_16x16x32_bf16 v[38:41], v[158:161], v[182:185], v[38:41]
	v_mfma_f32_16x16x32_bf16 v[38:41], v[162:165], v[186:189], v[38:41]
	v_mfma_f32_16x16x32_bf16 v[34:37], v[166:169], v[182:185], v[34:37]
	v_mfma_f32_16x16x32_bf16 v[34:37], v[170:173], v[186:189], v[34:37]
	v_mfma_f32_16x16x32_bf16 v[22:25], v[158:161], v[190:193], v[22:25]
	v_mfma_f32_16x16x32_bf16 v[22:25], v[162:165], v[194:197], v[22:25]
	v_mfma_f32_16x16x32_bf16 v[18:21], v[166:169], v[190:193], v[18:21]
	v_mfma_f32_16x16x32_bf16 v[18:21], v[170:173], v[194:197], v[18:21]
	v_mfma_f32_16x16x32_bf16 v[6:9], v[158:161], v[198:201], v[6:9]
	v_mfma_f32_16x16x32_bf16 v[6:9], v[162:165], v[212:215], v[6:9]
	v_mfma_f32_16x16x32_bf16 v[2:5], v[166:169], v[198:201], v[2:5]
	v_mfma_f32_16x16x32_bf16 v[2:5], v[170:173], v[212:215], v[2:5]
	s_setprio 0
	s_barrier
	v_add_u32_e32 v141, s29, v137
	ds_read_b128 v[142:145], v141
	ds_read_b128 v[146:149], v141 offset:1024
	ds_read_b128 v[150:153], v141 offset:2048
	ds_read_b128 v[154:157], v141 offset:3072
	v_add_u32_e32 v141, s36, v137
	ds_read_b128 v[158:161], v141
	ds_read_b128 v[162:165], v141 offset:1024
	ds_read_b128 v[166:169], v141 offset:2048
	ds_read_b128 v[170:173], v141 offset:3072
	s_add_i32 s44, s44, 0x80000
	s_mov_b32 m0, s24
	v_add_u32_e32 v141, s44, v130
	ds_read_b128 v[174:177], v140 offset:32768
	ds_read_b128 v[178:181], v140 offset:33792
	ds_read_b128 v[182:185], v140 offset:34816
	ds_read_b128 v[186:189], v140 offset:35840
	ds_read_b128 v[190:193], v140 offset:36864
	ds_read_b128 v[194:197], v140 offset:37888
	ds_read_b128 v[198:201], v140 offset:38912
	ds_read_b128 v[212:215], v140 offset:39936
	global_load_lds_dwordx4 v141, s[4:5]
	v_add_u32_e32 v141, s44, v132
	s_mov_b32 m0, s25
	s_nop 0
	global_load_lds_dwordx4 v141, s[4:5]
	s_waitcnt vmcnt(8)
	s_waitcnt lgkmcnt(0)
	s_setprio 1
	s_barrier
	v_mfma_f32_16x16x32_bf16 v[126:129], v[142:145], v[174:177], v[126:129]
	v_mfma_f32_16x16x32_bf16 v[126:129], v[146:149], v[178:181], v[126:129]
	v_mfma_f32_16x16x32_bf16 v[122:125], v[150:153], v[174:177], v[122:125]
	v_mfma_f32_16x16x32_bf16 v[122:125], v[154:157], v[178:181], v[122:125]
	v_mfma_f32_16x16x32_bf16 v[110:113], v[142:145], v[182:185], v[110:113]
	v_mfma_f32_16x16x32_bf16 v[110:113], v[146:149], v[186:189], v[110:113]
	v_mfma_f32_16x16x32_bf16 v[106:109], v[150:153], v[182:185], v[106:109]
	v_mfma_f32_16x16x32_bf16 v[106:109], v[154:157], v[186:189], v[106:109]
	v_mfma_f32_16x16x32_bf16 v[94:97], v[142:145], v[190:193], v[94:97]
	v_mfma_f32_16x16x32_bf16 v[94:97], v[146:149], v[194:197], v[94:97]
	v_mfma_f32_16x16x32_bf16 v[90:93], v[150:153], v[190:193], v[90:93]
	v_mfma_f32_16x16x32_bf16 v[90:93], v[154:157], v[194:197], v[90:93]
	v_mfma_f32_16x16x32_bf16 v[78:81], v[142:145], v[198:201], v[78:81]
	v_mfma_f32_16x16x32_bf16 v[78:81], v[146:149], v[212:215], v[78:81]
	v_mfma_f32_16x16x32_bf16 v[74:77], v[150:153], v[198:201], v[74:77]
	v_mfma_f32_16x16x32_bf16 v[74:77], v[154:157], v[212:215], v[74:77]
	s_setprio 0
	s_setprio 1
	v_mfma_f32_16x16x32_bf16 v[118:121], v[158:161], v[174:177], v[118:121]
	v_mfma_f32_16x16x32_bf16 v[118:121], v[162:165], v[178:181], v[118:121]
	v_mfma_f32_16x16x32_bf16 v[114:117], v[166:169], v[174:177], v[114:117]
	v_mfma_f32_16x16x32_bf16 v[114:117], v[170:173], v[178:181], v[114:117]
	v_mfma_f32_16x16x32_bf16 v[102:105], v[158:161], v[182:185], v[102:105]
	v_mfma_f32_16x16x32_bf16 v[102:105], v[162:165], v[186:189], v[102:105]
	v_mfma_f32_16x16x32_bf16 v[98:101], v[166:169], v[182:185], v[98:101]
	v_mfma_f32_16x16x32_bf16 v[98:101], v[170:173], v[186:189], v[98:101]
	v_mfma_f32_16x16x32_bf16 v[86:89], v[158:161], v[190:193], v[86:89]
	v_mfma_f32_16x16x32_bf16 v[86:89], v[162:165], v[194:197], v[86:89]
	v_mfma_f32_16x16x32_bf16 v[82:85], v[166:169], v[190:193], v[82:85]
	v_mfma_f32_16x16x32_bf16 v[82:85], v[170:173], v[194:197], v[82:85]
	v_mfma_f32_16x16x32_bf16 v[70:73], v[158:161], v[198:201], v[70:73]
	v_mfma_f32_16x16x32_bf16 v[70:73], v[162:165], v[212:215], v[70:73]
	v_mfma_f32_16x16x32_bf16 v[66:69], v[166:169], v[198:201], v[66:69]
	v_mfma_f32_16x16x32_bf16 v[66:69], v[170:173], v[212:215], v[66:69]
	s_setprio 0
	s_barrier
	s_or_b32 s40, s43, 0x80
	s_mov_b32 m0, s30
	v_add_u32_e32 v141, s40, v131
	ds_read_b128 v[174:177], v140 offset:49152
	ds_read_b128 v[178:181], v140 offset:50176
	ds_read_b128 v[182:185], v140 offset:51200
	ds_read_b128 v[186:189], v140 offset:52224
	ds_read_b128 v[190:193], v140 offset:53248
	ds_read_b128 v[194:197], v140 offset:54272
	ds_read_b128 v[198:201], v140 offset:55296
	ds_read_b128 v[212:215], v140 offset:56320
	global_load_lds_dwordx4 v141, s[6:7]
	v_add_u32_e32 v141, s40, v133
	s_mov_b32 m0, s31
	s_add_i32 s43, s43, 0x80080
	global_load_lds_dwordx4 v141, s[6:7]
	v_add_u32_e32 v141, s43, v131
	s_mov_b32 m0, s37
	s_nop 0
	global_load_lds_dwordx4 v141, s[6:7]
	v_add_u32_e32 v141, s43, v133
	s_mov_b32 m0, s38
	s_nop 0
	global_load_lds_dwordx4 v141, s[6:7]
	v_add_u32_e32 v141, s42, v130
	s_mov_b32 m0, s34
	s_nop 0
	global_load_lds_dwordx4 v141, s[4:5]
	v_add_u32_e32 v141, s42, v132
	s_mov_b32 m0, s35
	s_nop 0
	global_load_lds_dwordx4 v141, s[4:5]
	s_waitcnt vmcnt(8)
	s_waitcnt lgkmcnt(0)
	s_setprio 1
	s_barrier
	v_mfma_f32_16x16x32_bf16 v[62:65], v[142:145], v[174:177], v[62:65]
	v_mfma_f32_16x16x32_bf16 v[62:65], v[146:149], v[178:181], v[62:65]
	v_mfma_f32_16x16x32_bf16 v[58:61], v[150:153], v[174:177], v[58:61]
	v_mfma_f32_16x16x32_bf16 v[58:61], v[154:157], v[178:181], v[58:61]
	v_mfma_f32_16x16x32_bf16 v[46:49], v[142:145], v[182:185], v[46:49]
	v_mfma_f32_16x16x32_bf16 v[46:49], v[146:149], v[186:189], v[46:49]
	v_mfma_f32_16x16x32_bf16 v[42:45], v[150:153], v[182:185], v[42:45]
	v_mfma_f32_16x16x32_bf16 v[42:45], v[154:157], v[186:189], v[42:45]
	v_mfma_f32_16x16x32_bf16 v[30:33], v[142:145], v[190:193], v[30:33]
	v_mfma_f32_16x16x32_bf16 v[30:33], v[146:149], v[194:197], v[30:33]
	v_mfma_f32_16x16x32_bf16 v[26:29], v[150:153], v[190:193], v[26:29]
	v_mfma_f32_16x16x32_bf16 v[26:29], v[154:157], v[194:197], v[26:29]
	v_mfma_f32_16x16x32_bf16 v[14:17], v[142:145], v[198:201], v[14:17]
	v_mfma_f32_16x16x32_bf16 v[14:17], v[146:149], v[212:215], v[14:17]
	v_mfma_f32_16x16x32_bf16 v[10:13], v[150:153], v[198:201], v[10:13]
	v_mfma_f32_16x16x32_bf16 v[10:13], v[154:157], v[212:215], v[10:13]
	s_setprio 0
	s_setprio 1
	v_mfma_f32_16x16x32_bf16 v[54:57], v[158:161], v[174:177], v[54:57]
	v_mfma_f32_16x16x32_bf16 v[54:57], v[162:165], v[178:181], v[54:57]
	v_mfma_f32_16x16x32_bf16 v[50:53], v[166:169], v[174:177], v[50:53]
	v_mfma_f32_16x16x32_bf16 v[50:53], v[170:173], v[178:181], v[50:53]
	v_mfma_f32_16x16x32_bf16 v[38:41], v[158:161], v[182:185], v[38:41]
	v_mfma_f32_16x16x32_bf16 v[38:41], v[162:165], v[186:189], v[38:41]
	v_mfma_f32_16x16x32_bf16 v[34:37], v[166:169], v[182:185], v[34:37]
	v_mfma_f32_16x16x32_bf16 v[34:37], v[170:173], v[186:189], v[34:37]
	v_mfma_f32_16x16x32_bf16 v[22:25], v[158:161], v[190:193], v[22:25]
	v_mfma_f32_16x16x32_bf16 v[22:25], v[162:165], v[194:197], v[22:25]
	v_mfma_f32_16x16x32_bf16 v[18:21], v[166:169], v[190:193], v[18:21]
	v_mfma_f32_16x16x32_bf16 v[18:21], v[170:173], v[194:197], v[18:21]
	v_mfma_f32_16x16x32_bf16 v[6:9], v[158:161], v[198:201], v[6:9]
	v_mfma_f32_16x16x32_bf16 v[6:9], v[162:165], v[212:215], v[6:9]
	v_mfma_f32_16x16x32_bf16 v[2:5], v[166:169], v[198:201], v[2:5]
	v_mfma_f32_16x16x32_bf16 v[2:5], v[170:173], v[212:215], v[2:5]
	s_setprio 0
	s_barrier
	s_add_i32 s39, s39, 2
	s_cmp_gt_u32 s39, 29
	s_mov_b32 s40, s41
	s_cbranch_scc0 .LBB0_136
	s_cmpk_lt_u32 s9, 0x100
	s_cbranch_scc0 .LBB0_139
	s_barrier

.LBB0_151:
	v_lshrrev_b32_e32 v9, 1, v5
	v_and_b32_e32 v135, 24, v9
	v_and_b32_e32 v136, 15, v5
	v_lshlrev_b32_e32 v9, 1, v135
	v_lshlrev_b32_e32 v5, 2, v5
	s_lshl_b32 s20, s20, 5
	s_lshl_b32 s19, s21, 6
	v_lshl_or_b32 v9, v136, 6, v9
	s_lshl_b32 s21, s21, 13
	v_and_b32_e32 v5, 32, v5
	s_and_b32 s20, s20, 0x60
	v_bitop3_b32 v10, v9, s21, v5 bitop3:0xde
	s_lshl_b32 s21, s20, 7
	v_bitop3_b32 v137, v9, s21, v5 bitop3:0xde
	s_add_i32 s21, s28, 0x18000
	s_or_b32 s23, s2, 0x80
	s_add_i32 s22, s21, s27
	v_add_u32_e32 v5, s23, v131
	s_mov_b32 m0, s22
	s_waitcnt vmcnt(2)
	s_barrier
	global_load_lds_dwordx4 v5, s[6:7]
	v_add_u32_e32 v5, s23, v133
	s_add_i32 s23, s22, 0x2000
	s_mov_b32 m0, s23
	s_or_b32 s25, s14, 0x80
	s_add_i32 s24, s15, 0x8000
	global_load_lds_dwordx4 v5, s[6:7]
	v_add_u32_e32 v5, s25, v130
	s_mov_b32 m0, s24
	s_add_i32 s26, s28, 0x1c000
	global_load_lds_dwordx4 v5, s[4:5]
	v_add_u32_e32 v5, s25, v132
	s_add_i32 s25, s15, 0xa000
	s_mov_b32 m0, s25
	s_or_b32 s29, s2, 0x80080
	s_add_i32 s27, s26, s27
	global_load_lds_dwordx4 v5, s[4:5]
	v_add_u32_e32 v5, s29, v131
	s_mov_b32 m0, s27
	s_add_i32 s30, s14, 0x80080
	global_load_lds_dwordx4 v5, s[6:7]
	v_add_u32_e32 v5, s29, v133
	s_add_i32 s29, s27, 0x2000
	s_mov_b32 m0, s29
	v_lshlrev_b32_e32 v7, 12, v7
	global_load_lds_dwordx4 v5, s[6:7]
	v_lshlrev_b32_e32 v5, 15, v6
	v_and_b32_e32 v5, 0xffff0000, v5
	v_and_b32_e32 v6, 1, v6
	v_add3_u32 v5, s30, v5, v7
	v_lshlrev_b32_e32 v6, 6, v6
	v_lshlrev_b32_e32 v7, 1, v8
	v_add3_u32 v138, v5, v6, v7
	v_lshlrev_b32_e32 v5, 15, v2
	v_and_b32_e32 v5, 0xffff0000, v5
	v_lshlrev_b32_e32 v3, 12, v3
	v_and_b32_e32 v2, 1, v2
	s_waitcnt vmcnt(6)
	v_add3_u32 v3, s30, v5, v3
	v_lshlrev_b32_e32 v2, 6, v2
	v_lshlrev_b32_e32 v4, 1, v4
	v_add3_u32 v139, v3, v2, v4
	v_or_b32_e32 v134, s19, v136
	s_mov_b32 s30, -2
	s_mov_b32 s31, 0
	v_add_u32_e32 v140, s28, v10
	s_barrier
	v_add_u32_e32 v141, s3, v137
	ds_read_b128 v[142:145], v141
	ds_read_b128 v[146:149], v141 offset:1024
	ds_read_b128 v[150:153], v141 offset:2048
	ds_read_b128 v[154:157], v141 offset:3072
	v_add_u32_e32 v141, s11, v137
	ds_read_b128 v[158:161], v141
	ds_read_b128 v[162:165], v141 offset:1024
	ds_read_b128 v[166:169], v141 offset:2048
	ds_read_b128 v[170:173], v141 offset:3072
	s_add_i32 s34, s31, 0x100
	s_cmp_lg_u32 s30, 28
	s_cselect_b32 s36, s34, 0
	s_add_i32 s37, s36, s14
	s_or_b32 s35, s37, 0x80
	s_add_i32 s36, s36, s2
	v_add_u32_e32 v141, s31, v139
	s_add_i32 m0, s15, 0xc000
	ds_read_b128 v[174:177], v140
	ds_read_b128 v[178:181], v140 offset:1024
	ds_read_b128 v[182:185], v140 offset:2048
	ds_read_b128 v[186:189], v140 offset:3072
	ds_read_b128 v[190:193], v140 offset:4096
	ds_read_b128 v[194:197], v140 offset:5120
	ds_read_b128 v[198:201], v140 offset:6144
	ds_read_b128 v[212:215], v140 offset:7168
	global_load_lds_dwordx4 v141, s[4:5]
	v_add_u32_e32 v141, s31, v138
	s_add_i32 m0, s15, 0xe000
	s_nop 0
	global_load_lds_dwordx4 v141, s[4:5]
	s_waitcnt vmcnt(8)
	s_waitcnt lgkmcnt(0)
	s_setprio 1
	s_barrier
	v_mfma_f32_16x16x32_bf16 v[126:129], v[142:145], v[174:177], 0
	v_mfma_f32_16x16x32_bf16 v[126:129], v[146:149], v[178:181], v[126:129]
	v_mfma_f32_16x16x32_bf16 v[122:125], v[150:153], v[174:177], 0
	v_mfma_f32_16x16x32_bf16 v[122:125], v[154:157], v[178:181], v[122:125]
	v_mfma_f32_16x16x32_bf16 v[110:113], v[142:145], v[182:185], 0
	v_mfma_f32_16x16x32_bf16 v[110:113], v[146:149], v[186:189], v[110:113]
	v_mfma_f32_16x16x32_bf16 v[106:109], v[150:153], v[182:185], 0
	v_mfma_f32_16x16x32_bf16 v[106:109], v[154:157], v[186:189], v[106:109]
	v_mfma_f32_16x16x32_bf16 v[94:97], v[142:145], v[190:193], 0
	v_mfma_f32_16x16x32_bf16 v[94:97], v[146:149], v[194:197], v[94:97]
	v_mfma_f32_16x16x32_bf16 v[90:93], v[150:153], v[190:193], 0
	v_mfma_f32_16x16x32_bf16 v[90:93], v[154:157], v[194:197], v[90:93]
	v_mfma_f32_16x16x32_bf16 v[78:81], v[142:145], v[198:201], 0
	v_mfma_f32_16x16x32_bf16 v[78:81], v[146:149], v[212:215], v[78:81]
	v_mfma_f32_16x16x32_bf16 v[74:77], v[150:153], v[198:201], 0
	v_mfma_f32_16x16x32_bf16 v[74:77], v[154:157], v[212:215], v[74:77]
	s_setprio 0
	s_setprio 1
	v_mfma_f32_16x16x32_bf16 v[118:121], v[158:161], v[174:177], 0
	v_mfma_f32_16x16x32_bf16 v[118:121], v[162:165], v[178:181], v[118:121]
	v_mfma_f32_16x16x32_bf16 v[114:117], v[166:169], v[174:177], 0
	v_mfma_f32_16x16x32_bf16 v[114:117], v[170:173], v[178:181], v[114:117]
	v_mfma_f32_16x16x32_bf16 v[102:105], v[158:161], v[182:185], 0
	v_mfma_f32_16x16x32_bf16 v[102:105], v[162:165], v[186:189], v[102:105]
	v_mfma_f32_16x16x32_bf16 v[98:101], v[166:169], v[182:185], 0
	v_mfma_f32_16x16x32_bf16 v[98:101], v[170:173], v[186:189], v[98:101]
	v_mfma_f32_16x16x32_bf16 v[86:89], v[158:161], v[190:193], 0
	v_mfma_f32_16x16x32_bf16 v[86:89], v[162:165], v[194:197], v[86:89]
	v_mfma_f32_16x16x32_bf16 v[82:85], v[166:169], v[190:193], 0
	v_mfma_f32_16x16x32_bf16 v[82:85], v[170:173], v[194:197], v[82:85]
	v_mfma_f32_16x16x32_bf16 v[70:73], v[158:161], v[198:201], 0
	v_mfma_f32_16x16x32_bf16 v[70:73], v[162:165], v[212:215], v[70:73]
	v_mfma_f32_16x16x32_bf16 v[66:69], v[166:169], v[198:201], 0
	v_mfma_f32_16x16x32_bf16 v[66:69], v[170:173], v[212:215], v[66:69]
	s_setprio 0
	s_barrier
	s_mov_b32 m0, s9
	v_add_u32_e32 v141, s36, v131
	ds_read_b128 v[174:177], v140 offset:16384
	ds_read_b128 v[178:181], v140 offset:17408
	ds_read_b128 v[182:185], v140 offset:18432
	ds_read_b128 v[186:189], v140 offset:19456
	ds_read_b128 v[190:193], v140 offset:20480
	ds_read_b128 v[194:197], v140 offset:21504
	ds_read_b128 v[198:201], v140 offset:22528
	ds_read_b128 v[212:215], v140 offset:23552
	global_load_lds_dwordx4 v141, s[6:7]
	v_add_u32_e32 v141, s36, v133
	s_mov_b32 m0, s10
	s_add_i32 s31, s36, 0x80000
	global_load_lds_dwordx4 v141, s[6:7]
	v_add_u32_e32 v141, s31, v131
	s_mov_b32 m0, s12
	s_nop 0
	global_load_lds_dwordx4 v141, s[6:7]
	v_add_u32_e32 v141, s31, v133
	s_mov_b32 m0, s13
	s_nop 0
	global_load_lds_dwordx4 v141, s[6:7]
	v_add_u32_e32 v141, s37, v130
	s_mov_b32 m0, s15
	s_nop 0
	global_load_lds_dwordx4 v141, s[4:5]
	v_add_u32_e32 v141, s37, v132
	s_mov_b32 m0, s16
	s_nop 0
	global_load_lds_dwordx4 v141, s[4:5]
	s_waitcnt vmcnt(8)
	s_waitcnt lgkmcnt(0)
	s_setprio 1
	s_barrier
	v_mfma_f32_16x16x32_bf16 v[62:65], v[142:145], v[174:177], 0
	v_mfma_f32_16x16x32_bf16 v[62:65], v[146:149], v[178:181], v[62:65]
	v_mfma_f32_16x16x32_bf16 v[58:61], v[150:153], v[174:177], 0
	v_mfma_f32_16x16x32_bf16 v[58:61], v[154:157], v[178:181], v[58:61]
	v_mfma_f32_16x16x32_bf16 v[46:49], v[142:145], v[182:185], 0
	v_mfma_f32_16x16x32_bf16 v[46:49], v[146:149], v[186:189], v[46:49]
	v_mfma_f32_16x16x32_bf16 v[42:45], v[150:153], v[182:185], 0
	v_mfma_f32_16x16x32_bf16 v[42:45], v[154:157], v[186:189], v[42:45]
	v_mfma_f32_16x16x32_bf16 v[30:33], v[142:145], v[190:193], 0
	v_mfma_f32_16x16x32_bf16 v[30:33], v[146:149], v[194:197], v[30:33]
	v_mfma_f32_16x16x32_bf16 v[26:29], v[150:153], v[190:193], 0
	v_mfma_f32_16x16x32_bf16 v[26:29], v[154:157], v[194:197], v[26:29]
	v_mfma_f32_16x16x32_bf16 v[14:17], v[142:145], v[198:201], 0
	v_mfma_f32_16x16x32_bf16 v[14:17], v[146:149], v[212:215], v[14:17]
	v_mfma_f32_16x16x32_bf16 v[10:13], v[150:153], v[198:201], 0
	v_mfma_f32_16x16x32_bf16 v[10:13], v[154:157], v[212:215], v[10:13]
	s_setprio 0
	s_setprio 1
	v_mfma_f32_16x16x32_bf16 v[54:57], v[158:161], v[174:177], 0
	v_mfma_f32_16x16x32_bf16 v[54:57], v[162:165], v[178:181], v[54:57]
	v_mfma_f32_16x16x32_bf16 v[50:53], v[166:169], v[174:177], 0
	v_mfma_f32_16x16x32_bf16 v[50:53], v[170:173], v[178:181], v[50:53]
	v_mfma_f32_16x16x32_bf16 v[38:41], v[158:161], v[182:185], 0
	v_mfma_f32_16x16x32_bf16 v[38:41], v[162:165], v[186:189], v[38:41]
	v_mfma_f32_16x16x32_bf16 v[34:37], v[166:169], v[182:185], 0
	v_mfma_f32_16x16x32_bf16 v[34:37], v[170:173], v[186:189], v[34:37]
	v_mfma_f32_16x16x32_bf16 v[22:25], v[158:161], v[190:193], 0
	v_mfma_f32_16x16x32_bf16 v[22:25], v[162:165], v[194:197], v[22:25]
	v_mfma_f32_16x16x32_bf16 v[18:21], v[166:169], v[190:193], 0
	v_mfma_f32_16x16x32_bf16 v[18:21], v[170:173], v[194:197], v[18:21]
	v_mfma_f32_16x16x32_bf16 v[6:9], v[158:161], v[198:201], 0
	v_mfma_f32_16x16x32_bf16 v[6:9], v[162:165], v[212:215], v[6:9]
	v_mfma_f32_16x16x32_bf16 v[2:5], v[166:169], v[198:201], 0
	v_mfma_f32_16x16x32_bf16 v[2:5], v[170:173], v[212:215], v[2:5]
	s_setprio 0
	s_barrier
	v_add_u32_e32 v141, s21, v137
	ds_read_b128 v[142:145], v141
	ds_read_b128 v[146:149], v141 offset:1024
	ds_read_b128 v[150:153], v141 offset:2048
	ds_read_b128 v[154:157], v141 offset:3072
	v_add_u32_e32 v141, s26, v137
	ds_read_b128 v[158:161], v141
	ds_read_b128 v[162:165], v141 offset:1024
	ds_read_b128 v[166:169], v141 offset:2048
	ds_read_b128 v[170:173], v141 offset:3072
	s_add_i32 s37, s37, 0x80000
	s_mov_b32 m0, s17
	v_add_u32_e32 v141, s37, v130
	ds_read_b128 v[174:177], v140 offset:32768
	ds_read_b128 v[178:181], v140 offset:33792
	ds_read_b128 v[182:185], v140 offset:34816
	ds_read_b128 v[186:189], v140 offset:35840
	ds_read_b128 v[190:193], v140 offset:36864
	ds_read_b128 v[194:197], v140 offset:37888
	ds_read_b128 v[198:201], v140 offset:38912
	ds_read_b128 v[212:215], v140 offset:39936
	global_load_lds_dwordx4 v141, s[4:5]
	v_add_u32_e32 v141, s37, v132
	s_mov_b32 m0, s18
	s_nop 0
	global_load_lds_dwordx4 v141, s[4:5]
	s_waitcnt vmcnt(8)
	s_waitcnt lgkmcnt(0)
	s_setprio 1
	s_barrier
	v_mfma_f32_16x16x32_bf16 v[126:129], v[142:145], v[174:177], v[126:129]
	v_mfma_f32_16x16x32_bf16 v[126:129], v[146:149], v[178:181], v[126:129]
	v_mfma_f32_16x16x32_bf16 v[122:125], v[150:153], v[174:177], v[122:125]
	v_mfma_f32_16x16x32_bf16 v[122:125], v[154:157], v[178:181], v[122:125]
	v_mfma_f32_16x16x32_bf16 v[110:113], v[142:145], v[182:185], v[110:113]
	v_mfma_f32_16x16x32_bf16 v[110:113], v[146:149], v[186:189], v[110:113]
	v_mfma_f32_16x16x32_bf16 v[106:109], v[150:153], v[182:185], v[106:109]
	v_mfma_f32_16x16x32_bf16 v[106:109], v[154:157], v[186:189], v[106:109]
	v_mfma_f32_16x16x32_bf16 v[94:97], v[142:145], v[190:193], v[94:97]
	v_mfma_f32_16x16x32_bf16 v[94:97], v[146:149], v[194:197], v[94:97]
	v_mfma_f32_16x16x32_bf16 v[90:93], v[150:153], v[190:193], v[90:93]
	v_mfma_f32_16x16x32_bf16 v[90:93], v[154:157], v[194:197], v[90:93]
	v_mfma_f32_16x16x32_bf16 v[78:81], v[142:145], v[198:201], v[78:81]
	v_mfma_f32_16x16x32_bf16 v[78:81], v[146:149], v[212:215], v[78:81]
	v_mfma_f32_16x16x32_bf16 v[74:77], v[150:153], v[198:201], v[74:77]
	v_mfma_f32_16x16x32_bf16 v[74:77], v[154:157], v[212:215], v[74:77]
	s_setprio 0
	s_setprio 1
	v_mfma_f32_16x16x32_bf16 v[118:121], v[158:161], v[174:177], v[118:121]
	v_mfma_f32_16x16x32_bf16 v[118:121], v[162:165], v[178:181], v[118:121]
	v_mfma_f32_16x16x32_bf16 v[114:117], v[166:169], v[174:177], v[114:117]
	v_mfma_f32_16x16x32_bf16 v[114:117], v[170:173], v[178:181], v[114:117]
	v_mfma_f32_16x16x32_bf16 v[102:105], v[158:161], v[182:185], v[102:105]
	v_mfma_f32_16x16x32_bf16 v[102:105], v[162:165], v[186:189], v[102:105]
	v_mfma_f32_16x16x32_bf16 v[98:101], v[166:169], v[182:185], v[98:101]
	v_mfma_f32_16x16x32_bf16 v[98:101], v[170:173], v[186:189], v[98:101]
	v_mfma_f32_16x16x32_bf16 v[86:89], v[158:161], v[190:193], v[86:89]
	v_mfma_f32_16x16x32_bf16 v[86:89], v[162:165], v[194:197], v[86:89]
	v_mfma_f32_16x16x32_bf16 v[82:85], v[166:169], v[190:193], v[82:85]
	v_mfma_f32_16x16x32_bf16 v[82:85], v[170:173], v[194:197], v[82:85]
	v_mfma_f32_16x16x32_bf16 v[70:73], v[158:161], v[198:201], v[70:73]
	v_mfma_f32_16x16x32_bf16 v[70:73], v[162:165], v[212:215], v[70:73]
	v_mfma_f32_16x16x32_bf16 v[66:69], v[166:169], v[198:201], v[66:69]
	v_mfma_f32_16x16x32_bf16 v[66:69], v[170:173], v[212:215], v[66:69]
	s_setprio 0
	s_barrier
	s_or_b32 s31, s36, 0x80
	s_mov_b32 m0, s22
	v_add_u32_e32 v141, s31, v131
	ds_read_b128 v[174:177], v140 offset:49152
	ds_read_b128 v[178:181], v140 offset:50176
	ds_read_b128 v[182:185], v140 offset:51200
	ds_read_b128 v[186:189], v140 offset:52224
	ds_read_b128 v[190:193], v140 offset:53248
	ds_read_b128 v[194:197], v140 offset:54272
	ds_read_b128 v[198:201], v140 offset:55296
	ds_read_b128 v[212:215], v140 offset:56320
	global_load_lds_dwordx4 v141, s[6:7]
	v_add_u32_e32 v141, s31, v133
	s_mov_b32 m0, s23
	s_add_i32 s36, s36, 0x80080
	global_load_lds_dwordx4 v141, s[6:7]
	v_add_u32_e32 v141, s36, v131
	s_mov_b32 m0, s27
	s_nop 0
	global_load_lds_dwordx4 v141, s[6:7]
	v_add_u32_e32 v141, s36, v133
	s_mov_b32 m0, s29
	s_nop 0
	global_load_lds_dwordx4 v141, s[6:7]
	v_add_u32_e32 v141, s35, v130
	s_mov_b32 m0, s24
	s_nop 0
	global_load_lds_dwordx4 v141, s[4:5]
	v_add_u32_e32 v141, s35, v132
	s_mov_b32 m0, s25
	s_nop 0
	global_load_lds_dwordx4 v141, s[4:5]
	s_waitcnt vmcnt(8)
	s_waitcnt lgkmcnt(0)
	s_setprio 1
	s_barrier
	v_mfma_f32_16x16x32_bf16 v[62:65], v[142:145], v[174:177], v[62:65]
	v_mfma_f32_16x16x32_bf16 v[62:65], v[146:149], v[178:181], v[62:65]
	v_mfma_f32_16x16x32_bf16 v[58:61], v[150:153], v[174:177], v[58:61]
	v_mfma_f32_16x16x32_bf16 v[58:61], v[154:157], v[178:181], v[58:61]
	v_mfma_f32_16x16x32_bf16 v[46:49], v[142:145], v[182:185], v[46:49]
	v_mfma_f32_16x16x32_bf16 v[46:49], v[146:149], v[186:189], v[46:49]
	v_mfma_f32_16x16x32_bf16 v[42:45], v[150:153], v[182:185], v[42:45]
	v_mfma_f32_16x16x32_bf16 v[42:45], v[154:157], v[186:189], v[42:45]
	v_mfma_f32_16x16x32_bf16 v[30:33], v[142:145], v[190:193], v[30:33]
	v_mfma_f32_16x16x32_bf16 v[30:33], v[146:149], v[194:197], v[30:33]
	v_mfma_f32_16x16x32_bf16 v[26:29], v[150:153], v[190:193], v[26:29]
	v_mfma_f32_16x16x32_bf16 v[26:29], v[154:157], v[194:197], v[26:29]
	v_mfma_f32_16x16x32_bf16 v[14:17], v[142:145], v[198:201], v[14:17]
	v_mfma_f32_16x16x32_bf16 v[14:17], v[146:149], v[212:215], v[14:17]
	v_mfma_f32_16x16x32_bf16 v[10:13], v[150:153], v[198:201], v[10:13]
	v_mfma_f32_16x16x32_bf16 v[10:13], v[154:157], v[212:215], v[10:13]
	s_setprio 0
	s_setprio 1
	v_mfma_f32_16x16x32_bf16 v[54:57], v[158:161], v[174:177], v[54:57]
	v_mfma_f32_16x16x32_bf16 v[54:57], v[162:165], v[178:181], v[54:57]
	v_mfma_f32_16x16x32_bf16 v[50:53], v[166:169], v[174:177], v[50:53]
	v_mfma_f32_16x16x32_bf16 v[50:53], v[170:173], v[178:181], v[50:53]
	v_mfma_f32_16x16x32_bf16 v[38:41], v[158:161], v[182:185], v[38:41]
	v_mfma_f32_16x16x32_bf16 v[38:41], v[162:165], v[186:189], v[38:41]
	v_mfma_f32_16x16x32_bf16 v[34:37], v[166:169], v[182:185], v[34:37]
	v_mfma_f32_16x16x32_bf16 v[34:37], v[170:173], v[186:189], v[34:37]
	v_mfma_f32_16x16x32_bf16 v[22:25], v[158:161], v[190:193], v[22:25]
	v_mfma_f32_16x16x32_bf16 v[22:25], v[162:165], v[194:197], v[22:25]
	v_mfma_f32_16x16x32_bf16 v[18:21], v[166:169], v[190:193], v[18:21]
	v_mfma_f32_16x16x32_bf16 v[18:21], v[170:173], v[194:197], v[18:21]
	v_mfma_f32_16x16x32_bf16 v[6:9], v[158:161], v[198:201], v[6:9]
	v_mfma_f32_16x16x32_bf16 v[6:9], v[162:165], v[212:215], v[6:9]
	v_mfma_f32_16x16x32_bf16 v[2:5], v[166:169], v[198:201], v[2:5]
	v_mfma_f32_16x16x32_bf16 v[2:5], v[170:173], v[212:215], v[2:5]
	s_setprio 0
	s_barrier
	s_add_i32 s30, s30, 2
	s_cmp_gt_u32 s30, 29
	s_mov_b32 s31, s34
.LBB0_152:
	v_add_u32_e32 v141, s3, v137
	ds_read_b128 v[142:145], v141
	ds_read_b128 v[146:149], v141 offset:1024
	ds_read_b128 v[150:153], v141 offset:2048
	ds_read_b128 v[154:157], v141 offset:3072
	v_add_u32_e32 v141, s11, v137
	ds_read_b128 v[158:161], v141
	ds_read_b128 v[162:165], v141 offset:1024
	ds_read_b128 v[166:169], v141 offset:2048
	ds_read_b128 v[170:173], v141 offset:3072
	s_add_i32 s34, s31, 0x100
	s_cmp_lg_u32 s30, 28
	s_cselect_b32 s36, s34, 0
	s_add_i32 s37, s36, s14
	s_or_b32 s35, s37, 0x80
	s_add_i32 s36, s36, s2
	v_add_u32_e32 v141, s31, v139
	s_add_i32 m0, s15, 0xc000
	ds_read_b128 v[174:177], v140
	ds_read_b128 v[178:181], v140 offset:1024
	ds_read_b128 v[182:185], v140 offset:2048
	ds_read_b128 v[186:189], v140 offset:3072
	ds_read_b128 v[190:193], v140 offset:4096
	ds_read_b128 v[194:197], v140 offset:5120
	ds_read_b128 v[198:201], v140 offset:6144
	ds_read_b128 v[212:215], v140 offset:7168
	global_load_lds_dwordx4 v141, s[4:5]
	v_add_u32_e32 v141, s31, v138
	s_add_i32 m0, s15, 0xe000
	s_nop 0
	global_load_lds_dwordx4 v141, s[4:5]
	s_waitcnt vmcnt(8)
	s_waitcnt lgkmcnt(0)
	s_setprio 1
	s_barrier
	v_mfma_f32_16x16x32_bf16 v[126:129], v[142:145], v[174:177], v[126:129]
	v_mfma_f32_16x16x32_bf16 v[126:129], v[146:149], v[178:181], v[126:129]
	v_mfma_f32_16x16x32_bf16 v[122:125], v[150:153], v[174:177], v[122:125]
	v_mfma_f32_16x16x32_bf16 v[122:125], v[154:157], v[178:181], v[122:125]
	v_mfma_f32_16x16x32_bf16 v[110:113], v[142:145], v[182:185], v[110:113]
	v_mfma_f32_16x16x32_bf16 v[110:113], v[146:149], v[186:189], v[110:113]
	v_mfma_f32_16x16x32_bf16 v[106:109], v[150:153], v[182:185], v[106:109]
	v_mfma_f32_16x16x32_bf16 v[106:109], v[154:157], v[186:189], v[106:109]
	v_mfma_f32_16x16x32_bf16 v[94:97], v[142:145], v[190:193], v[94:97]
	v_mfma_f32_16x16x32_bf16 v[94:97], v[146:149], v[194:197], v[94:97]
	v_mfma_f32_16x16x32_bf16 v[90:93], v[150:153], v[190:193], v[90:93]
	v_mfma_f32_16x16x32_bf16 v[90:93], v[154:157], v[194:197], v[90:93]
	v_mfma_f32_16x16x32_bf16 v[78:81], v[142:145], v[198:201], v[78:81]
	v_mfma_f32_16x16x32_bf16 v[78:81], v[146:149], v[212:215], v[78:81]
	v_mfma_f32_16x16x32_bf16 v[74:77], v[150:153], v[198:201], v[74:77]
	v_mfma_f32_16x16x32_bf16 v[74:77], v[154:157], v[212:215], v[74:77]
	s_setprio 0
	s_setprio 1
	v_mfma_f32_16x16x32_bf16 v[118:121], v[158:161], v[174:177], v[118:121]
	v_mfma_f32_16x16x32_bf16 v[118:121], v[162:165], v[178:181], v[118:121]
	v_mfma_f32_16x16x32_bf16 v[114:117], v[166:169], v[174:177], v[114:117]
	v_mfma_f32_16x16x32_bf16 v[114:117], v[170:173], v[178:181], v[114:117]
	v_mfma_f32_16x16x32_bf16 v[102:105], v[158:161], v[182:185], v[102:105]
	v_mfma_f32_16x16x32_bf16 v[102:105], v[162:165], v[186:189], v[102:105]
	v_mfma_f32_16x16x32_bf16 v[98:101], v[166:169], v[182:185], v[98:101]
	v_mfma_f32_16x16x32_bf16 v[98:101], v[170:173], v[186:189], v[98:101]
	v_mfma_f32_16x16x32_bf16 v[86:89], v[158:161], v[190:193], v[86:89]
	v_mfma_f32_16x16x32_bf16 v[86:89], v[162:165], v[194:197], v[86:89]
	v_mfma_f32_16x16x32_bf16 v[82:85], v[166:169], v[190:193], v[82:85]
	v_mfma_f32_16x16x32_bf16 v[82:85], v[170:173], v[194:197], v[82:85]
	v_mfma_f32_16x16x32_bf16 v[70:73], v[158:161], v[198:201], v[70:73]
	v_mfma_f32_16x16x32_bf16 v[70:73], v[162:165], v[212:215], v[70:73]
	v_mfma_f32_16x16x32_bf16 v[66:69], v[166:169], v[198:201], v[66:69]
	v_mfma_f32_16x16x32_bf16 v[66:69], v[170:173], v[212:215], v[66:69]
	s_setprio 0
	s_barrier
	s_mov_b32 m0, s9
	v_add_u32_e32 v141, s36, v131
	ds_read_b128 v[174:177], v140 offset:16384
	ds_read_b128 v[178:181], v140 offset:17408
	ds_read_b128 v[182:185], v140 offset:18432
	ds_read_b128 v[186:189], v140 offset:19456
	ds_read_b128 v[190:193], v140 offset:20480
	ds_read_b128 v[194:197], v140 offset:21504
	ds_read_b128 v[198:201], v140 offset:22528
	ds_read_b128 v[212:215], v140 offset:23552
	global_load_lds_dwordx4 v141, s[6:7]
	v_add_u32_e32 v141, s36, v133
	s_mov_b32 m0, s10
	s_add_i32 s31, s36, 0x80000
	global_load_lds_dwordx4 v141, s[6:7]
	v_add_u32_e32 v141, s31, v131
	s_mov_b32 m0, s12
	s_nop 0
	global_load_lds_dwordx4 v141, s[6:7]
	v_add_u32_e32 v141, s31, v133
	s_mov_b32 m0, s13
	s_nop 0
	global_load_lds_dwordx4 v141, s[6:7]
	v_add_u32_e32 v141, s37, v130
	s_mov_b32 m0, s15
	s_nop 0
	global_load_lds_dwordx4 v141, s[4:5]
	v_add_u32_e32 v141, s37, v132
	s_mov_b32 m0, s16
	s_nop 0
	global_load_lds_dwordx4 v141, s[4:5]
	s_waitcnt vmcnt(8)
	s_waitcnt lgkmcnt(0)
	s_setprio 1
	s_barrier
	v_mfma_f32_16x16x32_bf16 v[62:65], v[142:145], v[174:177], v[62:65]
	v_mfma_f32_16x16x32_bf16 v[62:65], v[146:149], v[178:181], v[62:65]
	v_mfma_f32_16x16x32_bf16 v[58:61], v[150:153], v[174:177], v[58:61]
	v_mfma_f32_16x16x32_bf16 v[58:61], v[154:157], v[178:181], v[58:61]
	v_mfma_f32_16x16x32_bf16 v[46:49], v[142:145], v[182:185], v[46:49]
	v_mfma_f32_16x16x32_bf16 v[46:49], v[146:149], v[186:189], v[46:49]
	v_mfma_f32_16x16x32_bf16 v[42:45], v[150:153], v[182:185], v[42:45]
	v_mfma_f32_16x16x32_bf16 v[42:45], v[154:157], v[186:189], v[42:45]
	v_mfma_f32_16x16x32_bf16 v[30:33], v[142:145], v[190:193], v[30:33]
	v_mfma_f32_16x16x32_bf16 v[30:33], v[146:149], v[194:197], v[30:33]
	v_mfma_f32_16x16x32_bf16 v[26:29], v[150:153], v[190:193], v[26:29]
	v_mfma_f32_16x16x32_bf16 v[26:29], v[154:157], v[194:197], v[26:29]
	v_mfma_f32_16x16x32_bf16 v[14:17], v[142:145], v[198:201], v[14:17]
	v_mfma_f32_16x16x32_bf16 v[14:17], v[146:149], v[212:215], v[14:17]
	v_mfma_f32_16x16x32_bf16 v[10:13], v[150:153], v[198:201], v[10:13]
	v_mfma_f32_16x16x32_bf16 v[10:13], v[154:157], v[212:215], v[10:13]
	s_setprio 0
	s_setprio 1
	v_mfma_f32_16x16x32_bf16 v[54:57], v[158:161], v[174:177], v[54:57]
	v_mfma_f32_16x16x32_bf16 v[54:57], v[162:165], v[178:181], v[54:57]
	v_mfma_f32_16x16x32_bf16 v[50:53], v[166:169], v[174:177], v[50:53]
	v_mfma_f32_16x16x32_bf16 v[50:53], v[170:173], v[178:181], v[50:53]
	v_mfma_f32_16x16x32_bf16 v[38:41], v[158:161], v[182:185], v[38:41]
	v_mfma_f32_16x16x32_bf16 v[38:41], v[162:165], v[186:189], v[38:41]
	v_mfma_f32_16x16x32_bf16 v[34:37], v[166:169], v[182:185], v[34:37]
	v_mfma_f32_16x16x32_bf16 v[34:37], v[170:173], v[186:189], v[34:37]
	v_mfma_f32_16x16x32_bf16 v[22:25], v[158:161], v[190:193], v[22:25]
	v_mfma_f32_16x16x32_bf16 v[22:25], v[162:165], v[194:197], v[22:25]
	v_mfma_f32_16x16x32_bf16 v[18:21], v[166:169], v[190:193], v[18:21]
	v_mfma_f32_16x16x32_bf16 v[18:21], v[170:173], v[194:197], v[18:21]
	v_mfma_f32_16x16x32_bf16 v[6:9], v[158:161], v[198:201], v[6:9]
	v_mfma_f32_16x16x32_bf16 v[6:9], v[162:165], v[212:215], v[6:9]
	v_mfma_f32_16x16x32_bf16 v[2:5], v[166:169], v[198:201], v[2:5]
	v_mfma_f32_16x16x32_bf16 v[2:5], v[170:173], v[212:215], v[2:5]
	s_setprio 0
	s_barrier
	v_add_u32_e32 v141, s21, v137
	ds_read_b128 v[142:145], v141
	ds_read_b128 v[146:149], v141 offset:1024
	ds_read_b128 v[150:153], v141 offset:2048
	ds_read_b128 v[154:157], v141 offset:3072
	v_add_u32_e32 v141, s26, v137
	ds_read_b128 v[158:161], v141
	ds_read_b128 v[162:165], v141 offset:1024
	ds_read_b128 v[166:169], v141 offset:2048
	ds_read_b128 v[170:173], v141 offset:3072
	s_add_i32 s37, s37, 0x80000
	s_mov_b32 m0, s17
	v_add_u32_e32 v141, s37, v130
	ds_read_b128 v[174:177], v140 offset:32768
	ds_read_b128 v[178:181], v140 offset:33792
	ds_read_b128 v[182:185], v140 offset:34816
	ds_read_b128 v[186:189], v140 offset:35840
	ds_read_b128 v[190:193], v140 offset:36864
	ds_read_b128 v[194:197], v140 offset:37888
	ds_read_b128 v[198:201], v140 offset:38912
	ds_read_b128 v[212:215], v140 offset:39936
	global_load_lds_dwordx4 v141, s[4:5]
	v_add_u32_e32 v141, s37, v132
	s_mov_b32 m0, s18
	s_nop 0
	global_load_lds_dwordx4 v141, s[4:5]
	s_waitcnt vmcnt(8)
	s_waitcnt lgkmcnt(0)
	s_setprio 1
	s_barrier
	v_mfma_f32_16x16x32_bf16 v[126:129], v[142:145], v[174:177], v[126:129]
	v_mfma_f32_16x16x32_bf16 v[126:129], v[146:149], v[178:181], v[126:129]
	v_mfma_f32_16x16x32_bf16 v[122:125], v[150:153], v[174:177], v[122:125]
	v_mfma_f32_16x16x32_bf16 v[122:125], v[154:157], v[178:181], v[122:125]
	v_mfma_f32_16x16x32_bf16 v[110:113], v[142:145], v[182:185], v[110:113]
	v_mfma_f32_16x16x32_bf16 v[110:113], v[146:149], v[186:189], v[110:113]
	v_mfma_f32_16x16x32_bf16 v[106:109], v[150:153], v[182:185], v[106:109]
	v_mfma_f32_16x16x32_bf16 v[106:109], v[154:157], v[186:189], v[106:109]
	v_mfma_f32_16x16x32_bf16 v[94:97], v[142:145], v[190:193], v[94:97]
	v_mfma_f32_16x16x32_bf16 v[94:97], v[146:149], v[194:197], v[94:97]
	v_mfma_f32_16x16x32_bf16 v[90:93], v[150:153], v[190:193], v[90:93]
	v_mfma_f32_16x16x32_bf16 v[90:93], v[154:157], v[194:197], v[90:93]
	v_mfma_f32_16x16x32_bf16 v[78:81], v[142:145], v[198:201], v[78:81]
	v_mfma_f32_16x16x32_bf16 v[78:81], v[146:149], v[212:215], v[78:81]
	v_mfma_f32_16x16x32_bf16 v[74:77], v[150:153], v[198:201], v[74:77]
	v_mfma_f32_16x16x32_bf16 v[74:77], v[154:157], v[212:215], v[74:77]
	s_setprio 0
	s_setprio 1
	v_mfma_f32_16x16x32_bf16 v[118:121], v[158:161], v[174:177], v[118:121]
	v_mfma_f32_16x16x32_bf16 v[118:121], v[162:165], v[178:181], v[118:121]
	v_mfma_f32_16x16x32_bf16 v[114:117], v[166:169], v[174:177], v[114:117]
	v_mfma_f32_16x16x32_bf16 v[114:117], v[170:173], v[178:181], v[114:117]
	v_mfma_f32_16x16x32_bf16 v[102:105], v[158:161], v[182:185], v[102:105]
	v_mfma_f32_16x16x32_bf16 v[102:105], v[162:165], v[186:189], v[102:105]
	v_mfma_f32_16x16x32_bf16 v[98:101], v[166:169], v[182:185], v[98:101]
	v_mfma_f32_16x16x32_bf16 v[98:101], v[170:173], v[186:189], v[98:101]
	v_mfma_f32_16x16x32_bf16 v[86:89], v[158:161], v[190:193], v[86:89]
	v_mfma_f32_16x16x32_bf16 v[86:89], v[162:165], v[194:197], v[86:89]
	v_mfma_f32_16x16x32_bf16 v[82:85], v[166:169], v[190:193], v[82:85]
	v_mfma_f32_16x16x32_bf16 v[82:85], v[170:173], v[194:197], v[82:85]
	v_mfma_f32_16x16x32_bf16 v[70:73], v[158:161], v[198:201], v[70:73]
	v_mfma_f32_16x16x32_bf16 v[70:73], v[162:165], v[212:215], v[70:73]
	v_mfma_f32_16x16x32_bf16 v[66:69], v[166:169], v[198:201], v[66:69]
	v_mfma_f32_16x16x32_bf16 v[66:69], v[170:173], v[212:215], v[66:69]
	s_setprio 0
	s_barrier
	s_or_b32 s31, s36, 0x80
	s_mov_b32 m0, s22
	v_add_u32_e32 v141, s31, v131
	ds_read_b128 v[174:177], v140 offset:49152
	ds_read_b128 v[178:181], v140 offset:50176
	ds_read_b128 v[182:185], v140 offset:51200
	ds_read_b128 v[186:189], v140 offset:52224
	ds_read_b128 v[190:193], v140 offset:53248
	ds_read_b128 v[194:197], v140 offset:54272
	ds_read_b128 v[198:201], v140 offset:55296
	ds_read_b128 v[212:215], v140 offset:56320
	global_load_lds_dwordx4 v141, s[6:7]
	v_add_u32_e32 v141, s31, v133
	s_mov_b32 m0, s23
	s_add_i32 s36, s36, 0x80080
	global_load_lds_dwordx4 v141, s[6:7]
	v_add_u32_e32 v141, s36, v131
	s_mov_b32 m0, s27
	s_nop 0
	global_load_lds_dwordx4 v141, s[6:7]
	v_add_u32_e32 v141, s36, v133
	s_mov_b32 m0, s29
	s_nop 0
	global_load_lds_dwordx4 v141, s[6:7]
	v_add_u32_e32 v141, s35, v130
	s_mov_b32 m0, s24
	s_nop 0
	global_load_lds_dwordx4 v141, s[4:5]
	v_add_u32_e32 v141, s35, v132
	s_mov_b32 m0, s25
	s_nop 0
	global_load_lds_dwordx4 v141, s[4:5]
	s_waitcnt vmcnt(8)
	s_waitcnt lgkmcnt(0)
	s_setprio 1
	s_barrier
	v_mfma_f32_16x16x32_bf16 v[62:65], v[142:145], v[174:177], v[62:65]
	v_mfma_f32_16x16x32_bf16 v[62:65], v[146:149], v[178:181], v[62:65]
	v_mfma_f32_16x16x32_bf16 v[58:61], v[150:153], v[174:177], v[58:61]
	v_mfma_f32_16x16x32_bf16 v[58:61], v[154:157], v[178:181], v[58:61]
	v_mfma_f32_16x16x32_bf16 v[46:49], v[142:145], v[182:185], v[46:49]
	v_mfma_f32_16x16x32_bf16 v[46:49], v[146:149], v[186:189], v[46:49]
	v_mfma_f32_16x16x32_bf16 v[42:45], v[150:153], v[182:185], v[42:45]
	v_mfma_f32_16x16x32_bf16 v[42:45], v[154:157], v[186:189], v[42:45]
	v_mfma_f32_16x16x32_bf16 v[30:33], v[142:145], v[190:193], v[30:33]
	v_mfma_f32_16x16x32_bf16 v[30:33], v[146:149], v[194:197], v[30:33]
	v_mfma_f32_16x16x32_bf16 v[26:29], v[150:153], v[190:193], v[26:29]
	v_mfma_f32_16x16x32_bf16 v[26:29], v[154:157], v[194:197], v[26:29]
	v_mfma_f32_16x16x32_bf16 v[14:17], v[142:145], v[198:201], v[14:17]
	v_mfma_f32_16x16x32_bf16 v[14:17], v[146:149], v[212:215], v[14:17]
	v_mfma_f32_16x16x32_bf16 v[10:13], v[150:153], v[198:201], v[10:13]
	v_mfma_f32_16x16x32_bf16 v[10:13], v[154:157], v[212:215], v[10:13]
	s_setprio 0
	s_setprio 1
	v_mfma_f32_16x16x32_bf16 v[54:57], v[158:161], v[174:177], v[54:57]
	v_mfma_f32_16x16x32_bf16 v[54:57], v[162:165], v[178:181], v[54:57]
	v_mfma_f32_16x16x32_bf16 v[50:53], v[166:169], v[174:177], v[50:53]
	v_mfma_f32_16x16x32_bf16 v[50:53], v[170:173], v[178:181], v[50:53]
	v_mfma_f32_16x16x32_bf16 v[38:41], v[158:161], v[182:185], v[38:41]
	v_mfma_f32_16x16x32_bf16 v[38:41], v[162:165], v[186:189], v[38:41]
	v_mfma_f32_16x16x32_bf16 v[34:37], v[166:169], v[182:185], v[34:37]
	v_mfma_f32_16x16x32_bf16 v[34:37], v[170:173], v[186:189], v[34:37]
	v_mfma_f32_16x16x32_bf16 v[22:25], v[158:161], v[190:193], v[22:25]
	v_mfma_f32_16x16x32_bf16 v[22:25], v[162:165], v[194:197], v[22:25]
	v_mfma_f32_16x16x32_bf16 v[18:21], v[166:169], v[190:193], v[18:21]
	v_mfma_f32_16x16x32_bf16 v[18:21], v[170:173], v[194:197], v[18:21]
	v_mfma_f32_16x16x32_bf16 v[6:9], v[158:161], v[198:201], v[6:9]
	v_mfma_f32_16x16x32_bf16 v[6:9], v[162:165], v[212:215], v[6:9]
	v_mfma_f32_16x16x32_bf16 v[2:5], v[166:169], v[198:201], v[2:5]
	v_mfma_f32_16x16x32_bf16 v[2:5], v[170:173], v[212:215], v[2:5]
	s_setprio 0
	s_barrier
	s_add_i32 s30, s30, 2
	s_cmp_gt_u32 s30, 29
	s_mov_b32 s31, s34
	s_cbranch_scc0 .LBB0_152
	s_cmpk_lt_u32 s8, 0x100
	s_cbranch_scc0 .LBB0_155
	s_barrier

.LBB0_194:
	s_mul_i32 s12, s40, 0x2c0000
	s_and_b64 s[48:49], s[4:5], exec
	s_mul_i32 s13, s39, 0x2c0000
	s_cselect_b32 s43, s12, s45
	s_cselect_b32 s44, s13, s46
	s_add_i32 s45, s45, 0x160080
	s_addk_i32 s46, 0x100
	s_mov_b32 s47, -2
	v_add_u32_e32 v130, s17, v137
	ds_read_b128 v[142:145], v130
	ds_read_b128 v[146:149], v130 offset:1024
	ds_read_b128 v[150:153], v130 offset:2048
	ds_read_b128 v[154:157], v130 offset:3072
	v_add_u32_e32 v130, s20, v137
	ds_read_b128 v[158:161], v130
	ds_read_b128 v[162:165], v130 offset:1024
	ds_read_b128 v[166:169], v130 offset:2048
	ds_read_b128 v[170:173], v130 offset:3072
	s_add_i32 s48, s45, 0xffea0080
	s_cmpk_eq_i32 s47, 0x54
	s_cselect_b32 s50, s43, s48
	s_cselect_b32 s49, s44, s46
	s_or_b32 s48, s50, 0x80
	v_add_u32_e32 v130, s45, v140
	s_add_i32 m0, s23, 0xc000
	ds_read_b128 v[174:177], v141
	ds_read_b128 v[178:181], v141 offset:1024
	ds_read_b128 v[182:185], v141 offset:2048
	ds_read_b128 v[186:189], v141 offset:3072
	ds_read_b128 v[190:193], v141 offset:4096
	ds_read_b128 v[194:197], v141 offset:5120
	ds_read_b128 v[198:201], v141 offset:6144
	ds_read_b128 v[212:215], v141 offset:7168
	global_load_lds_dwordx4 v130, s[0:1]
	v_add_u32_e32 v130, s45, v139
	s_add_i32 m0, s23, 0xe000
	s_nop 0
	global_load_lds_dwordx4 v130, s[0:1]
	s_waitcnt vmcnt(8)
	s_waitcnt lgkmcnt(0)
	s_setprio 1
	s_barrier
	v_mfma_f32_16x16x32_bf16 v[126:129], v[142:145], v[174:177], 0
	v_mfma_f32_16x16x32_bf16 v[126:129], v[146:149], v[178:181], v[126:129]
	v_mfma_f32_16x16x32_bf16 v[122:125], v[150:153], v[174:177], 0
	v_mfma_f32_16x16x32_bf16 v[122:125], v[154:157], v[178:181], v[122:125]
	v_mfma_f32_16x16x32_bf16 v[118:121], v[142:145], v[182:185], 0
	v_mfma_f32_16x16x32_bf16 v[118:121], v[146:149], v[186:189], v[118:121]
	v_mfma_f32_16x16x32_bf16 v[110:113], v[150:153], v[182:185], 0
	v_mfma_f32_16x16x32_bf16 v[110:113], v[154:157], v[186:189], v[110:113]
	v_mfma_f32_16x16x32_bf16 v[102:105], v[142:145], v[190:193], 0
	v_mfma_f32_16x16x32_bf16 v[102:105], v[146:149], v[194:197], v[102:105]
	v_mfma_f32_16x16x32_bf16 v[94:97], v[150:153], v[190:193], 0
	v_mfma_f32_16x16x32_bf16 v[94:97], v[154:157], v[194:197], v[94:97]
	v_mfma_f32_16x16x32_bf16 v[86:89], v[142:145], v[198:201], 0
	v_mfma_f32_16x16x32_bf16 v[86:89], v[146:149], v[212:215], v[86:89]
	v_mfma_f32_16x16x32_bf16 v[78:81], v[150:153], v[198:201], 0
	v_mfma_f32_16x16x32_bf16 v[78:81], v[154:157], v[212:215], v[78:81]
	s_setprio 0
	s_setprio 1
	v_mfma_f32_16x16x32_bf16 v[114:117], v[158:161], v[174:177], 0
	v_mfma_f32_16x16x32_bf16 v[114:117], v[162:165], v[178:181], v[114:117]
	v_mfma_f32_16x16x32_bf16 v[106:109], v[166:169], v[174:177], 0
	v_mfma_f32_16x16x32_bf16 v[106:109], v[170:173], v[178:181], v[106:109]
	v_mfma_f32_16x16x32_bf16 v[98:101], v[158:161], v[182:185], 0
	v_mfma_f32_16x16x32_bf16 v[98:101], v[162:165], v[186:189], v[98:101]
	v_mfma_f32_16x16x32_bf16 v[90:93], v[166:169], v[182:185], 0
	v_mfma_f32_16x16x32_bf16 v[90:93], v[170:173], v[186:189], v[90:93]
	v_mfma_f32_16x16x32_bf16 v[82:85], v[158:161], v[190:193], 0
	v_mfma_f32_16x16x32_bf16 v[82:85], v[162:165], v[194:197], v[82:85]
	v_mfma_f32_16x16x32_bf16 v[74:77], v[166:169], v[190:193], 0
	v_mfma_f32_16x16x32_bf16 v[74:77], v[170:173], v[194:197], v[74:77]
	v_mfma_f32_16x16x32_bf16 v[70:73], v[158:161], v[198:201], 0
	v_mfma_f32_16x16x32_bf16 v[70:73], v[162:165], v[212:215], v[70:73]
	v_mfma_f32_16x16x32_bf16 v[66:69], v[166:169], v[198:201], 0
	v_mfma_f32_16x16x32_bf16 v[66:69], v[170:173], v[212:215], v[66:69]
	s_setprio 0
	s_barrier
	s_mov_b32 m0, s18
	v_add_u32_e32 v130, s49, v133
	ds_read_b128 v[174:177], v141 offset:16384
	ds_read_b128 v[178:181], v141 offset:17408
	ds_read_b128 v[182:185], v141 offset:18432
	ds_read_b128 v[186:189], v141 offset:19456
	ds_read_b128 v[190:193], v141 offset:20480
	ds_read_b128 v[194:197], v141 offset:21504
	ds_read_b128 v[198:201], v141 offset:22528
	ds_read_b128 v[212:215], v141 offset:23552
	global_load_lds_dwordx4 v130, s[2:3]
	v_add_u32_e32 v130, s49, v135
	s_mov_b32 m0, s19
	s_add_i32 s51, s49, 0x160000
	global_load_lds_dwordx4 v130, s[2:3]
	v_add_u32_e32 v130, s51, v133
	s_mov_b32 m0, s21
	s_nop 0
	global_load_lds_dwordx4 v130, s[2:3]
	v_add_u32_e32 v130, s51, v135
	s_mov_b32 m0, s22
	s_nop 0
	global_load_lds_dwordx4 v130, s[2:3]
	v_add_u32_e32 v130, s50, v132
	s_mov_b32 m0, s23
	s_nop 0
	global_load_lds_dwordx4 v130, s[0:1]
	v_add_u32_e32 v130, s50, v134
	s_mov_b32 m0, s24
	s_nop 0
	global_load_lds_dwordx4 v130, s[0:1]
	s_waitcnt vmcnt(8)
	s_waitcnt lgkmcnt(0)
	s_setprio 1
	s_barrier
	v_mfma_f32_16x16x32_bf16 v[62:65], v[142:145], v[174:177], 0
	v_mfma_f32_16x16x32_bf16 v[62:65], v[146:149], v[178:181], v[62:65]
	v_mfma_f32_16x16x32_bf16 v[58:61], v[150:153], v[174:177], 0
	v_mfma_f32_16x16x32_bf16 v[58:61], v[154:157], v[178:181], v[58:61]
	v_mfma_f32_16x16x32_bf16 v[54:57], v[142:145], v[182:185], 0
	v_mfma_f32_16x16x32_bf16 v[54:57], v[146:149], v[186:189], v[54:57]
	v_mfma_f32_16x16x32_bf16 v[46:49], v[150:153], v[182:185], 0
	v_mfma_f32_16x16x32_bf16 v[46:49], v[154:157], v[186:189], v[46:49]
	v_mfma_f32_16x16x32_bf16 v[38:41], v[142:145], v[190:193], 0
	v_mfma_f32_16x16x32_bf16 v[38:41], v[146:149], v[194:197], v[38:41]
	v_mfma_f32_16x16x32_bf16 v[30:33], v[150:153], v[190:193], 0
	v_mfma_f32_16x16x32_bf16 v[30:33], v[154:157], v[194:197], v[30:33]
	v_mfma_f32_16x16x32_bf16 v[22:25], v[142:145], v[198:201], 0
	v_mfma_f32_16x16x32_bf16 v[22:25], v[146:149], v[212:215], v[22:25]
	v_mfma_f32_16x16x32_bf16 v[14:17], v[150:153], v[198:201], 0
	v_mfma_f32_16x16x32_bf16 v[14:17], v[154:157], v[212:215], v[14:17]
	s_setprio 0
	s_setprio 1
	v_mfma_f32_16x16x32_bf16 v[50:53], v[158:161], v[174:177], 0
	v_mfma_f32_16x16x32_bf16 v[50:53], v[162:165], v[178:181], v[50:53]
	v_mfma_f32_16x16x32_bf16 v[42:45], v[166:169], v[174:177], 0
	v_mfma_f32_16x16x32_bf16 v[42:45], v[170:173], v[178:181], v[42:45]
	v_mfma_f32_16x16x32_bf16 v[34:37], v[158:161], v[182:185], 0
	v_mfma_f32_16x16x32_bf16 v[34:37], v[162:165], v[186:189], v[34:37]
	v_mfma_f32_16x16x32_bf16 v[26:29], v[166:169], v[182:185], 0
	v_mfma_f32_16x16x32_bf16 v[26:29], v[170:173], v[186:189], v[26:29]
	v_mfma_f32_16x16x32_bf16 v[18:21], v[158:161], v[190:193], 0
	v_mfma_f32_16x16x32_bf16 v[18:21], v[162:165], v[194:197], v[18:21]
	v_mfma_f32_16x16x32_bf16 v[10:13], v[166:169], v[190:193], 0
	v_mfma_f32_16x16x32_bf16 v[10:13], v[170:173], v[194:197], v[10:13]
	v_mfma_f32_16x16x32_bf16 v[6:9], v[158:161], v[198:201], 0
	v_mfma_f32_16x16x32_bf16 v[6:9], v[162:165], v[212:215], v[6:9]
	v_mfma_f32_16x16x32_bf16 v[2:5], v[166:169], v[198:201], 0
	v_mfma_f32_16x16x32_bf16 v[2:5], v[170:173], v[212:215], v[2:5]
	s_setprio 0
	s_barrier
	v_add_u32_e32 v130, s27, v137
	ds_read_b128 v[142:145], v130
	ds_read_b128 v[146:149], v130 offset:1024
	ds_read_b128 v[150:153], v130 offset:2048
	ds_read_b128 v[154:157], v130 offset:3072
	v_add_u32_e32 v130, s34, v137
	ds_read_b128 v[158:161], v130
	ds_read_b128 v[162:165], v130 offset:1024
	ds_read_b128 v[166:169], v130 offset:2048
	ds_read_b128 v[170:173], v130 offset:3072
	s_add_i32 s50, s50, 0x160000
	s_mov_b32 m0, s25
	v_add_u32_e32 v130, s50, v132
	ds_read_b128 v[174:177], v141 offset:32768
	ds_read_b128 v[178:181], v141 offset:33792
	ds_read_b128 v[182:185], v141 offset:34816
	ds_read_b128 v[186:189], v141 offset:35840
	ds_read_b128 v[190:193], v141 offset:36864
	ds_read_b128 v[194:197], v141 offset:37888
	ds_read_b128 v[198:201], v141 offset:38912
	ds_read_b128 v[212:215], v141 offset:39936
	global_load_lds_dwordx4 v130, s[0:1]
	v_add_u32_e32 v130, s50, v134
	s_mov_b32 m0, s26
	s_nop 0
	global_load_lds_dwordx4 v130, s[0:1]
	s_waitcnt vmcnt(8)
	s_waitcnt lgkmcnt(0)
	s_setprio 1
	s_barrier
	v_mfma_f32_16x16x32_bf16 v[126:129], v[142:145], v[174:177], v[126:129]
	v_mfma_f32_16x16x32_bf16 v[126:129], v[146:149], v[178:181], v[126:129]
	v_mfma_f32_16x16x32_bf16 v[122:125], v[150:153], v[174:177], v[122:125]
	v_mfma_f32_16x16x32_bf16 v[122:125], v[154:157], v[178:181], v[122:125]
	v_mfma_f32_16x16x32_bf16 v[118:121], v[142:145], v[182:185], v[118:121]
	v_mfma_f32_16x16x32_bf16 v[118:121], v[146:149], v[186:189], v[118:121]
	v_mfma_f32_16x16x32_bf16 v[110:113], v[150:153], v[182:185], v[110:113]
	v_mfma_f32_16x16x32_bf16 v[110:113], v[154:157], v[186:189], v[110:113]
	v_mfma_f32_16x16x32_bf16 v[102:105], v[142:145], v[190:193], v[102:105]
	v_mfma_f32_16x16x32_bf16 v[102:105], v[146:149], v[194:197], v[102:105]
	v_mfma_f32_16x16x32_bf16 v[94:97], v[150:153], v[190:193], v[94:97]
	v_mfma_f32_16x16x32_bf16 v[94:97], v[154:157], v[194:197], v[94:97]
	v_mfma_f32_16x16x32_bf16 v[86:89], v[142:145], v[198:201], v[86:89]
	v_mfma_f32_16x16x32_bf16 v[86:89], v[146:149], v[212:215], v[86:89]
	v_mfma_f32_16x16x32_bf16 v[78:81], v[150:153], v[198:201], v[78:81]
	v_mfma_f32_16x16x32_bf16 v[78:81], v[154:157], v[212:215], v[78:81]
	s_setprio 0
	s_setprio 1
	v_mfma_f32_16x16x32_bf16 v[114:117], v[158:161], v[174:177], v[114:117]
	v_mfma_f32_16x16x32_bf16 v[114:117], v[162:165], v[178:181], v[114:117]
	v_mfma_f32_16x16x32_bf16 v[106:109], v[166:169], v[174:177], v[106:109]
	v_mfma_f32_16x16x32_bf16 v[106:109], v[170:173], v[178:181], v[106:109]
	v_mfma_f32_16x16x32_bf16 v[98:101], v[158:161], v[182:185], v[98:101]
	v_mfma_f32_16x16x32_bf16 v[98:101], v[162:165], v[186:189], v[98:101]
	v_mfma_f32_16x16x32_bf16 v[90:93], v[166:169], v[182:185], v[90:93]
	v_mfma_f32_16x16x32_bf16 v[90:93], v[170:173], v[186:189], v[90:93]
	v_mfma_f32_16x16x32_bf16 v[82:85], v[158:161], v[190:193], v[82:85]
	v_mfma_f32_16x16x32_bf16 v[82:85], v[162:165], v[194:197], v[82:85]
	v_mfma_f32_16x16x32_bf16 v[74:77], v[166:169], v[190:193], v[74:77]
	v_mfma_f32_16x16x32_bf16 v[74:77], v[170:173], v[194:197], v[74:77]
	v_mfma_f32_16x16x32_bf16 v[70:73], v[158:161], v[198:201], v[70:73]
	v_mfma_f32_16x16x32_bf16 v[70:73], v[162:165], v[212:215], v[70:73]
	v_mfma_f32_16x16x32_bf16 v[66:69], v[166:169], v[198:201], v[66:69]
	v_mfma_f32_16x16x32_bf16 v[66:69], v[170:173], v[212:215], v[66:69]
	s_setprio 0
	s_barrier
	s_or_b32 s50, s49, 0x80
	s_mov_b32 m0, s28
	v_add_u32_e32 v130, s50, v133
	ds_read_b128 v[174:177], v141 offset:49152
	ds_read_b128 v[178:181], v141 offset:50176
	ds_read_b128 v[182:185], v141 offset:51200
	ds_read_b128 v[186:189], v141 offset:52224
	ds_read_b128 v[190:193], v141 offset:53248
	ds_read_b128 v[194:197], v141 offset:54272
	ds_read_b128 v[198:201], v141 offset:55296
	ds_read_b128 v[212:215], v141 offset:56320
	global_load_lds_dwordx4 v130, s[2:3]
	v_add_u32_e32 v130, s50, v135
	s_mov_b32 m0, s29
	s_add_i32 s49, s49, 0x160080
	global_load_lds_dwordx4 v130, s[2:3]
	v_add_u32_e32 v130, s49, v133
	s_mov_b32 m0, s35
	s_nop 0
	global_load_lds_dwordx4 v130, s[2:3]
	v_add_u32_e32 v130, s49, v135
	s_mov_b32 m0, s36
	s_nop 0
	global_load_lds_dwordx4 v130, s[2:3]
	v_add_u32_e32 v130, s48, v132
	s_mov_b32 m0, s30
	s_nop 0
	global_load_lds_dwordx4 v130, s[0:1]
	v_add_u32_e32 v130, s48, v134
	s_mov_b32 m0, s31
	s_nop 0
	global_load_lds_dwordx4 v130, s[0:1]
	s_waitcnt vmcnt(8)
	s_waitcnt lgkmcnt(0)
	s_setprio 1
	s_barrier
	v_mfma_f32_16x16x32_bf16 v[62:65], v[142:145], v[174:177], v[62:65]
	v_mfma_f32_16x16x32_bf16 v[62:65], v[146:149], v[178:181], v[62:65]
	v_mfma_f32_16x16x32_bf16 v[58:61], v[150:153], v[174:177], v[58:61]
	v_mfma_f32_16x16x32_bf16 v[58:61], v[154:157], v[178:181], v[58:61]
	v_mfma_f32_16x16x32_bf16 v[54:57], v[142:145], v[182:185], v[54:57]
	v_mfma_f32_16x16x32_bf16 v[54:57], v[146:149], v[186:189], v[54:57]
	v_mfma_f32_16x16x32_bf16 v[46:49], v[150:153], v[182:185], v[46:49]
	v_mfma_f32_16x16x32_bf16 v[46:49], v[154:157], v[186:189], v[46:49]
	v_mfma_f32_16x16x32_bf16 v[38:41], v[142:145], v[190:193], v[38:41]
	v_mfma_f32_16x16x32_bf16 v[38:41], v[146:149], v[194:197], v[38:41]
	v_mfma_f32_16x16x32_bf16 v[30:33], v[150:153], v[190:193], v[30:33]
	v_mfma_f32_16x16x32_bf16 v[30:33], v[154:157], v[194:197], v[30:33]
	v_mfma_f32_16x16x32_bf16 v[22:25], v[142:145], v[198:201], v[22:25]
	v_mfma_f32_16x16x32_bf16 v[22:25], v[146:149], v[212:215], v[22:25]
	v_mfma_f32_16x16x32_bf16 v[14:17], v[150:153], v[198:201], v[14:17]
	v_mfma_f32_16x16x32_bf16 v[14:17], v[154:157], v[212:215], v[14:17]
	s_setprio 0
	s_setprio 1
	v_mfma_f32_16x16x32_bf16 v[50:53], v[158:161], v[174:177], v[50:53]
	v_mfma_f32_16x16x32_bf16 v[50:53], v[162:165], v[178:181], v[50:53]
	v_mfma_f32_16x16x32_bf16 v[42:45], v[166:169], v[174:177], v[42:45]
	v_mfma_f32_16x16x32_bf16 v[42:45], v[170:173], v[178:181], v[42:45]
	v_mfma_f32_16x16x32_bf16 v[34:37], v[158:161], v[182:185], v[34:37]
	v_mfma_f32_16x16x32_bf16 v[34:37], v[162:165], v[186:189], v[34:37]
	v_mfma_f32_16x16x32_bf16 v[26:29], v[166:169], v[182:185], v[26:29]
	v_mfma_f32_16x16x32_bf16 v[26:29], v[170:173], v[186:189], v[26:29]
	v_mfma_f32_16x16x32_bf16 v[18:21], v[158:161], v[190:193], v[18:21]
	v_mfma_f32_16x16x32_bf16 v[18:21], v[162:165], v[194:197], v[18:21]
	v_mfma_f32_16x16x32_bf16 v[10:13], v[166:169], v[190:193], v[10:13]
	v_mfma_f32_16x16x32_bf16 v[10:13], v[170:173], v[194:197], v[10:13]
	v_mfma_f32_16x16x32_bf16 v[6:9], v[158:161], v[198:201], v[6:9]
	v_mfma_f32_16x16x32_bf16 v[6:9], v[162:165], v[212:215], v[6:9]
	v_mfma_f32_16x16x32_bf16 v[2:5], v[166:169], v[198:201], v[2:5]
	v_mfma_f32_16x16x32_bf16 v[2:5], v[170:173], v[212:215], v[2:5]
	s_setprio 0
	s_barrier
	s_add_i32 s47, s47, 2
	s_addk_i32 s45, 0x100
	s_addk_i32 s46, 0x100
	s_cmpk_gt_u32 s47, 0x55
.LBB0_195:
	v_add_u32_e32 v130, s17, v137
	ds_read_b128 v[142:145], v130
	ds_read_b128 v[146:149], v130 offset:1024
	ds_read_b128 v[150:153], v130 offset:2048
	ds_read_b128 v[154:157], v130 offset:3072
	v_add_u32_e32 v130, s20, v137
	ds_read_b128 v[158:161], v130
	ds_read_b128 v[162:165], v130 offset:1024
	ds_read_b128 v[166:169], v130 offset:2048
	ds_read_b128 v[170:173], v130 offset:3072
	s_add_i32 s48, s45, 0xffea0080
	s_cmpk_eq_i32 s47, 0x54
	s_cselect_b32 s50, s43, s48
	s_cselect_b32 s49, s44, s46
	s_or_b32 s48, s50, 0x80
	v_add_u32_e32 v130, s45, v140
	s_add_i32 m0, s23, 0xc000
	ds_read_b128 v[174:177], v141
	ds_read_b128 v[178:181], v141 offset:1024
	ds_read_b128 v[182:185], v141 offset:2048
	ds_read_b128 v[186:189], v141 offset:3072
	ds_read_b128 v[190:193], v141 offset:4096
	ds_read_b128 v[194:197], v141 offset:5120
	ds_read_b128 v[198:201], v141 offset:6144
	ds_read_b128 v[212:215], v141 offset:7168
	global_load_lds_dwordx4 v130, s[0:1]
	v_add_u32_e32 v130, s45, v139
	s_add_i32 m0, s23, 0xe000
	s_nop 0
	global_load_lds_dwordx4 v130, s[0:1]
	s_waitcnt vmcnt(8)
	s_waitcnt lgkmcnt(0)
	s_setprio 1
	s_barrier
	v_mfma_f32_16x16x32_bf16 v[126:129], v[142:145], v[174:177], v[126:129]
	v_mfma_f32_16x16x32_bf16 v[126:129], v[146:149], v[178:181], v[126:129]
	v_mfma_f32_16x16x32_bf16 v[122:125], v[150:153], v[174:177], v[122:125]
	v_mfma_f32_16x16x32_bf16 v[122:125], v[154:157], v[178:181], v[122:125]
	v_mfma_f32_16x16x32_bf16 v[118:121], v[142:145], v[182:185], v[118:121]
	v_mfma_f32_16x16x32_bf16 v[118:121], v[146:149], v[186:189], v[118:121]
	v_mfma_f32_16x16x32_bf16 v[110:113], v[150:153], v[182:185], v[110:113]
	v_mfma_f32_16x16x32_bf16 v[110:113], v[154:157], v[186:189], v[110:113]
	v_mfma_f32_16x16x32_bf16 v[102:105], v[142:145], v[190:193], v[102:105]
	v_mfma_f32_16x16x32_bf16 v[102:105], v[146:149], v[194:197], v[102:105]
	v_mfma_f32_16x16x32_bf16 v[94:97], v[150:153], v[190:193], v[94:97]
	v_mfma_f32_16x16x32_bf16 v[94:97], v[154:157], v[194:197], v[94:97]
	v_mfma_f32_16x16x32_bf16 v[86:89], v[142:145], v[198:201], v[86:89]
	v_mfma_f32_16x16x32_bf16 v[86:89], v[146:149], v[212:215], v[86:89]
	v_mfma_f32_16x16x32_bf16 v[78:81], v[150:153], v[198:201], v[78:81]
	v_mfma_f32_16x16x32_bf16 v[78:81], v[154:157], v[212:215], v[78:81]
	s_setprio 0
	s_setprio 1
	v_mfma_f32_16x16x32_bf16 v[114:117], v[158:161], v[174:177], v[114:117]
	v_mfma_f32_16x16x32_bf16 v[114:117], v[162:165], v[178:181], v[114:117]
	v_mfma_f32_16x16x32_bf16 v[106:109], v[166:169], v[174:177], v[106:109]
	v_mfma_f32_16x16x32_bf16 v[106:109], v[170:173], v[178:181], v[106:109]
	v_mfma_f32_16x16x32_bf16 v[98:101], v[158:161], v[182:185], v[98:101]
	v_mfma_f32_16x16x32_bf16 v[98:101], v[162:165], v[186:189], v[98:101]
	v_mfma_f32_16x16x32_bf16 v[90:93], v[166:169], v[182:185], v[90:93]
	v_mfma_f32_16x16x32_bf16 v[90:93], v[170:173], v[186:189], v[90:93]
	v_mfma_f32_16x16x32_bf16 v[82:85], v[158:161], v[190:193], v[82:85]
	v_mfma_f32_16x16x32_bf16 v[82:85], v[162:165], v[194:197], v[82:85]
	v_mfma_f32_16x16x32_bf16 v[74:77], v[166:169], v[190:193], v[74:77]
	v_mfma_f32_16x16x32_bf16 v[74:77], v[170:173], v[194:197], v[74:77]
	v_mfma_f32_16x16x32_bf16 v[70:73], v[158:161], v[198:201], v[70:73]
	v_mfma_f32_16x16x32_bf16 v[70:73], v[162:165], v[212:215], v[70:73]
	v_mfma_f32_16x16x32_bf16 v[66:69], v[166:169], v[198:201], v[66:69]
	v_mfma_f32_16x16x32_bf16 v[66:69], v[170:173], v[212:215], v[66:69]
	s_setprio 0
	s_barrier
	s_mov_b32 m0, s18
	v_add_u32_e32 v130, s49, v133
	ds_read_b128 v[174:177], v141 offset:16384
	ds_read_b128 v[178:181], v141 offset:17408
	ds_read_b128 v[182:185], v141 offset:18432
	ds_read_b128 v[186:189], v141 offset:19456
	ds_read_b128 v[190:193], v141 offset:20480
	ds_read_b128 v[194:197], v141 offset:21504
	ds_read_b128 v[198:201], v141 offset:22528
	ds_read_b128 v[212:215], v141 offset:23552
	global_load_lds_dwordx4 v130, s[2:3]
	v_add_u32_e32 v130, s49, v135
	s_mov_b32 m0, s19
	s_add_i32 s51, s49, 0x160000
	global_load_lds_dwordx4 v130, s[2:3]
	v_add_u32_e32 v130, s51, v133
	s_mov_b32 m0, s21
	s_nop 0
	global_load_lds_dwordx4 v130, s[2:3]
	v_add_u32_e32 v130, s51, v135
	s_mov_b32 m0, s22
	s_nop 0
	global_load_lds_dwordx4 v130, s[2:3]
	v_add_u32_e32 v130, s50, v132
	s_mov_b32 m0, s23
	s_nop 0
	global_load_lds_dwordx4 v130, s[0:1]
	v_add_u32_e32 v130, s50, v134
	s_mov_b32 m0, s24
	s_nop 0
	global_load_lds_dwordx4 v130, s[0:1]
	s_waitcnt vmcnt(8)
	s_waitcnt lgkmcnt(0)
	s_setprio 1
	s_barrier
	v_mfma_f32_16x16x32_bf16 v[62:65], v[142:145], v[174:177], v[62:65]
	v_mfma_f32_16x16x32_bf16 v[62:65], v[146:149], v[178:181], v[62:65]
	v_mfma_f32_16x16x32_bf16 v[58:61], v[150:153], v[174:177], v[58:61]
	v_mfma_f32_16x16x32_bf16 v[58:61], v[154:157], v[178:181], v[58:61]
	v_mfma_f32_16x16x32_bf16 v[54:57], v[142:145], v[182:185], v[54:57]
	v_mfma_f32_16x16x32_bf16 v[54:57], v[146:149], v[186:189], v[54:57]
	v_mfma_f32_16x16x32_bf16 v[46:49], v[150:153], v[182:185], v[46:49]
	v_mfma_f32_16x16x32_bf16 v[46:49], v[154:157], v[186:189], v[46:49]
	v_mfma_f32_16x16x32_bf16 v[38:41], v[142:145], v[190:193], v[38:41]
	v_mfma_f32_16x16x32_bf16 v[38:41], v[146:149], v[194:197], v[38:41]
	v_mfma_f32_16x16x32_bf16 v[30:33], v[150:153], v[190:193], v[30:33]
	v_mfma_f32_16x16x32_bf16 v[30:33], v[154:157], v[194:197], v[30:33]
	v_mfma_f32_16x16x32_bf16 v[22:25], v[142:145], v[198:201], v[22:25]
	v_mfma_f32_16x16x32_bf16 v[22:25], v[146:149], v[212:215], v[22:25]
	v_mfma_f32_16x16x32_bf16 v[14:17], v[150:153], v[198:201], v[14:17]
	v_mfma_f32_16x16x32_bf16 v[14:17], v[154:157], v[212:215], v[14:17]
	s_setprio 0
	s_setprio 1
	v_mfma_f32_16x16x32_bf16 v[50:53], v[158:161], v[174:177], v[50:53]
	v_mfma_f32_16x16x32_bf16 v[50:53], v[162:165], v[178:181], v[50:53]
	v_mfma_f32_16x16x32_bf16 v[42:45], v[166:169], v[174:177], v[42:45]
	v_mfma_f32_16x16x32_bf16 v[42:45], v[170:173], v[178:181], v[42:45]
	v_mfma_f32_16x16x32_bf16 v[34:37], v[158:161], v[182:185], v[34:37]
	v_mfma_f32_16x16x32_bf16 v[34:37], v[162:165], v[186:189], v[34:37]
	v_mfma_f32_16x16x32_bf16 v[26:29], v[166:169], v[182:185], v[26:29]
	v_mfma_f32_16x16x32_bf16 v[26:29], v[170:173], v[186:189], v[26:29]
	v_mfma_f32_16x16x32_bf16 v[18:21], v[158:161], v[190:193], v[18:21]
	v_mfma_f32_16x16x32_bf16 v[18:21], v[162:165], v[194:197], v[18:21]
	v_mfma_f32_16x16x32_bf16 v[10:13], v[166:169], v[190:193], v[10:13]
	v_mfma_f32_16x16x32_bf16 v[10:13], v[170:173], v[194:197], v[10:13]
	v_mfma_f32_16x16x32_bf16 v[6:9], v[158:161], v[198:201], v[6:9]
	v_mfma_f32_16x16x32_bf16 v[6:9], v[162:165], v[212:215], v[6:9]
	v_mfma_f32_16x16x32_bf16 v[2:5], v[166:169], v[198:201], v[2:5]
	v_mfma_f32_16x16x32_bf16 v[2:5], v[170:173], v[212:215], v[2:5]
	s_setprio 0
	s_barrier
	v_add_u32_e32 v130, s27, v137
	ds_read_b128 v[142:145], v130
	ds_read_b128 v[146:149], v130 offset:1024
	ds_read_b128 v[150:153], v130 offset:2048
	ds_read_b128 v[154:157], v130 offset:3072
	v_add_u32_e32 v130, s34, v137
	ds_read_b128 v[158:161], v130
	ds_read_b128 v[162:165], v130 offset:1024
	ds_read_b128 v[166:169], v130 offset:2048
	ds_read_b128 v[170:173], v130 offset:3072
	s_add_i32 s50, s50, 0x160000
	s_mov_b32 m0, s25
	v_add_u32_e32 v130, s50, v132
	ds_read_b128 v[174:177], v141 offset:32768
	ds_read_b128 v[178:181], v141 offset:33792
	ds_read_b128 v[182:185], v141 offset:34816
	ds_read_b128 v[186:189], v141 offset:35840
	ds_read_b128 v[190:193], v141 offset:36864
	ds_read_b128 v[194:197], v141 offset:37888
	ds_read_b128 v[198:201], v141 offset:38912
	ds_read_b128 v[212:215], v141 offset:39936
	global_load_lds_dwordx4 v130, s[0:1]
	v_add_u32_e32 v130, s50, v134
	s_mov_b32 m0, s26
	s_nop 0
	global_load_lds_dwordx4 v130, s[0:1]
	s_waitcnt vmcnt(8)
	s_waitcnt lgkmcnt(0)
	s_setprio 1
	s_barrier
	v_mfma_f32_16x16x32_bf16 v[126:129], v[142:145], v[174:177], v[126:129]
	v_mfma_f32_16x16x32_bf16 v[126:129], v[146:149], v[178:181], v[126:129]
	v_mfma_f32_16x16x32_bf16 v[122:125], v[150:153], v[174:177], v[122:125]
	v_mfma_f32_16x16x32_bf16 v[122:125], v[154:157], v[178:181], v[122:125]
	v_mfma_f32_16x16x32_bf16 v[118:121], v[142:145], v[182:185], v[118:121]
	v_mfma_f32_16x16x32_bf16 v[118:121], v[146:149], v[186:189], v[118:121]
	v_mfma_f32_16x16x32_bf16 v[110:113], v[150:153], v[182:185], v[110:113]
	v_mfma_f32_16x16x32_bf16 v[110:113], v[154:157], v[186:189], v[110:113]
	v_mfma_f32_16x16x32_bf16 v[102:105], v[142:145], v[190:193], v[102:105]
	v_mfma_f32_16x16x32_bf16 v[102:105], v[146:149], v[194:197], v[102:105]
	v_mfma_f32_16x16x32_bf16 v[94:97], v[150:153], v[190:193], v[94:97]
	v_mfma_f32_16x16x32_bf16 v[94:97], v[154:157], v[194:197], v[94:97]
	v_mfma_f32_16x16x32_bf16 v[86:89], v[142:145], v[198:201], v[86:89]
	v_mfma_f32_16x16x32_bf16 v[86:89], v[146:149], v[212:215], v[86:89]
	v_mfma_f32_16x16x32_bf16 v[78:81], v[150:153], v[198:201], v[78:81]
	v_mfma_f32_16x16x32_bf16 v[78:81], v[154:157], v[212:215], v[78:81]
	s_setprio 0
	s_setprio 1
	v_mfma_f32_16x16x32_bf16 v[114:117], v[158:161], v[174:177], v[114:117]
	v_mfma_f32_16x16x32_bf16 v[114:117], v[162:165], v[178:181], v[114:117]
	v_mfma_f32_16x16x32_bf16 v[106:109], v[166:169], v[174:177], v[106:109]
	v_mfma_f32_16x16x32_bf16 v[106:109], v[170:173], v[178:181], v[106:109]
	v_mfma_f32_16x16x32_bf16 v[98:101], v[158:161], v[182:185], v[98:101]
	v_mfma_f32_16x16x32_bf16 v[98:101], v[162:165], v[186:189], v[98:101]
	v_mfma_f32_16x16x32_bf16 v[90:93], v[166:169], v[182:185], v[90:93]
	v_mfma_f32_16x16x32_bf16 v[90:93], v[170:173], v[186:189], v[90:93]
	v_mfma_f32_16x16x32_bf16 v[82:85], v[158:161], v[190:193], v[82:85]
	v_mfma_f32_16x16x32_bf16 v[82:85], v[162:165], v[194:197], v[82:85]
	v_mfma_f32_16x16x32_bf16 v[74:77], v[166:169], v[190:193], v[74:77]
	v_mfma_f32_16x16x32_bf16 v[74:77], v[170:173], v[194:197], v[74:77]
	v_mfma_f32_16x16x32_bf16 v[70:73], v[158:161], v[198:201], v[70:73]
	v_mfma_f32_16x16x32_bf16 v[70:73], v[162:165], v[212:215], v[70:73]
	v_mfma_f32_16x16x32_bf16 v[66:69], v[166:169], v[198:201], v[66:69]
	v_mfma_f32_16x16x32_bf16 v[66:69], v[170:173], v[212:215], v[66:69]
	s_setprio 0
	s_barrier
	s_or_b32 s50, s49, 0x80
	s_mov_b32 m0, s28
	v_add_u32_e32 v130, s50, v133
	ds_read_b128 v[174:177], v141 offset:49152
	ds_read_b128 v[178:181], v141 offset:50176
	ds_read_b128 v[182:185], v141 offset:51200
	ds_read_b128 v[186:189], v141 offset:52224
	ds_read_b128 v[190:193], v141 offset:53248
	ds_read_b128 v[194:197], v141 offset:54272
	ds_read_b128 v[198:201], v141 offset:55296
	ds_read_b128 v[212:215], v141 offset:56320
	global_load_lds_dwordx4 v130, s[2:3]
	v_add_u32_e32 v130, s50, v135
	s_mov_b32 m0, s29
	s_add_i32 s49, s49, 0x160080
	global_load_lds_dwordx4 v130, s[2:3]
	v_add_u32_e32 v130, s49, v133
	s_mov_b32 m0, s35
	s_nop 0
	global_load_lds_dwordx4 v130, s[2:3]
	v_add_u32_e32 v130, s49, v135
	s_mov_b32 m0, s36
	s_nop 0
	global_load_lds_dwordx4 v130, s[2:3]
	v_add_u32_e32 v130, s48, v132
	s_mov_b32 m0, s30
	s_nop 0
	global_load_lds_dwordx4 v130, s[0:1]
	v_add_u32_e32 v130, s48, v134
	s_mov_b32 m0, s31
	s_nop 0
	global_load_lds_dwordx4 v130, s[0:1]
	s_add_i32 s47, s47, 2
	s_addk_i32 s45, 0x100
	s_addk_i32 s46, 0x100
	s_cmpk_gt_u32 s47, 0x55
	s_waitcnt vmcnt(8)
	s_waitcnt lgkmcnt(0)
	s_setprio 1
	s_barrier
	v_mfma_f32_16x16x32_bf16 v[62:65], v[142:145], v[174:177], v[62:65]
	v_mfma_f32_16x16x32_bf16 v[62:65], v[146:149], v[178:181], v[62:65]
	v_mfma_f32_16x16x32_bf16 v[58:61], v[150:153], v[174:177], v[58:61]
	v_mfma_f32_16x16x32_bf16 v[58:61], v[154:157], v[178:181], v[58:61]
	v_mfma_f32_16x16x32_bf16 v[54:57], v[142:145], v[182:185], v[54:57]
	v_mfma_f32_16x16x32_bf16 v[54:57], v[146:149], v[186:189], v[54:57]
	v_mfma_f32_16x16x32_bf16 v[46:49], v[150:153], v[182:185], v[46:49]
	v_mfma_f32_16x16x32_bf16 v[46:49], v[154:157], v[186:189], v[46:49]
	v_mfma_f32_16x16x32_bf16 v[38:41], v[142:145], v[190:193], v[38:41]
	v_mfma_f32_16x16x32_bf16 v[38:41], v[146:149], v[194:197], v[38:41]
	v_mfma_f32_16x16x32_bf16 v[30:33], v[150:153], v[190:193], v[30:33]
	v_mfma_f32_16x16x32_bf16 v[30:33], v[154:157], v[194:197], v[30:33]
	v_mfma_f32_16x16x32_bf16 v[22:25], v[142:145], v[198:201], v[22:25]
	v_mfma_f32_16x16x32_bf16 v[22:25], v[146:149], v[212:215], v[22:25]
	v_mfma_f32_16x16x32_bf16 v[14:17], v[150:153], v[198:201], v[14:17]
	v_mfma_f32_16x16x32_bf16 v[14:17], v[154:157], v[212:215], v[14:17]
	s_setprio 0
	s_setprio 1
	v_mfma_f32_16x16x32_bf16 v[50:53], v[158:161], v[174:177], v[50:53]
	v_mfma_f32_16x16x32_bf16 v[50:53], v[162:165], v[178:181], v[50:53]
	v_mfma_f32_16x16x32_bf16 v[42:45], v[166:169], v[174:177], v[42:45]
	v_mfma_f32_16x16x32_bf16 v[42:45], v[170:173], v[178:181], v[42:45]
	v_mfma_f32_16x16x32_bf16 v[34:37], v[158:161], v[182:185], v[34:37]
	v_mfma_f32_16x16x32_bf16 v[34:37], v[162:165], v[186:189], v[34:37]
	v_mfma_f32_16x16x32_bf16 v[26:29], v[166:169], v[182:185], v[26:29]
	v_mfma_f32_16x16x32_bf16 v[26:29], v[170:173], v[186:189], v[26:29]
	v_mfma_f32_16x16x32_bf16 v[18:21], v[158:161], v[190:193], v[18:21]
	v_mfma_f32_16x16x32_bf16 v[18:21], v[162:165], v[194:197], v[18:21]
	v_mfma_f32_16x16x32_bf16 v[10:13], v[166:169], v[190:193], v[10:13]
	v_mfma_f32_16x16x32_bf16 v[10:13], v[170:173], v[194:197], v[10:13]
	v_mfma_f32_16x16x32_bf16 v[6:9], v[158:161], v[198:201], v[6:9]
	v_mfma_f32_16x16x32_bf16 v[6:9], v[162:165], v[212:215], v[6:9]
	v_mfma_f32_16x16x32_bf16 v[2:5], v[166:169], v[198:201], v[2:5]
	v_mfma_f32_16x16x32_bf16 v[2:5], v[170:173], v[212:215], v[2:5]
	s_setprio 0
	s_barrier
	s_cbranch_scc0 .LBB0_195
	s_and_b64 vcc, exec, s[10:11]
	s_cbranch_vccz .LBB0_198
	s_barrier

.LBB0_282:
	s_lshl_b32 s65, s28, 20
	s_and_b64 s[36:37], s[30:31], exec
	s_cselect_b32 s36, s65, s68
	s_lshl_b32 s66, s64, 20
	s_and_b64 s[70:71], s[30:31], exec
	s_cselect_b32 s37, s66, s67
	v_add_u32_e32 v135, s68, v150
	v_add_u32_e32 v136, s68, v151
	s_addk_i32 s67, 0x100
	s_addk_i32 s68, 0x100
	s_mov_b32 s69, -2
	s_waitcnt vmcnt(0)
	v_add_u32_e32 v137, s42, v148
	ds_read_b128 v[138:141], v137
	ds_read_b128 v[154:157], v137 offset:1024
	ds_read_b128 v[158:161], v137 offset:2048
	ds_read_b128 v[162:165], v137 offset:3072
	v_add_u32_e32 v137, s45, v148
	ds_read_b128 v[166:169], v137
	ds_read_b128 v[170:173], v137 offset:1024
	ds_read_b128 v[174:177], v137 offset:2048
	ds_read_b128 v[178:181], v137 offset:3072
	s_cmp_eq_u32 s69, 28
	s_cselect_b32 s72, s36, s68
	s_cselect_b32 s71, s37, s67
	s_or_b32 s70, s72, 0x80
	s_add_i32 m0, s48, 0xc000
	ds_read_b128 v[182:185], v152
	ds_read_b128 v[186:189], v152 offset:1024
	ds_read_b128 v[190:193], v152 offset:2048
	ds_read_b128 v[194:197], v152 offset:3072
	ds_read_b128 v[198:201], v152 offset:4096
	ds_read_b128 v[212:215], v152 offset:5120
	ds_read_b128 v[218:221], v152 offset:6144
	ds_read_b128 v[222:225], v152 offset:7168
	global_load_lds_dwordx4 v136, s[8:9]
	s_add_i32 m0, s48, 0xe000
	s_nop 0
	global_load_lds_dwordx4 v135, s[8:9]
	s_waitcnt vmcnt(8)
	s_waitcnt lgkmcnt(0)
	s_setprio 1
	s_barrier
	v_mfma_f32_16x16x32_bf16 v[126:129], v[138:141], v[182:185], 0
	v_mfma_f32_16x16x32_bf16 v[126:129], v[154:157], v[186:189], v[126:129]
	v_mfma_f32_16x16x32_bf16 v[122:125], v[158:161], v[182:185], 0
	v_mfma_f32_16x16x32_bf16 v[122:125], v[162:165], v[186:189], v[122:125]
	v_mfma_f32_16x16x32_bf16 v[110:113], v[138:141], v[190:193], 0
	v_mfma_f32_16x16x32_bf16 v[110:113], v[154:157], v[194:197], v[110:113]
	v_mfma_f32_16x16x32_bf16 v[106:109], v[158:161], v[190:193], 0
	v_mfma_f32_16x16x32_bf16 v[106:109], v[162:165], v[194:197], v[106:109]
	v_mfma_f32_16x16x32_bf16 v[94:97], v[138:141], v[198:201], 0
	v_mfma_f32_16x16x32_bf16 v[94:97], v[154:157], v[212:215], v[94:97]
	v_mfma_f32_16x16x32_bf16 v[90:93], v[158:161], v[198:201], 0
	v_mfma_f32_16x16x32_bf16 v[90:93], v[162:165], v[212:215], v[90:93]
	v_mfma_f32_16x16x32_bf16 v[78:81], v[138:141], v[218:221], 0
	v_mfma_f32_16x16x32_bf16 v[78:81], v[154:157], v[222:225], v[78:81]
	v_mfma_f32_16x16x32_bf16 v[74:77], v[158:161], v[218:221], 0
	v_mfma_f32_16x16x32_bf16 v[74:77], v[162:165], v[222:225], v[74:77]
	s_setprio 0
	s_setprio 1
	v_mfma_f32_16x16x32_bf16 v[118:121], v[166:169], v[182:185], 0
	v_mfma_f32_16x16x32_bf16 v[118:121], v[170:173], v[186:189], v[118:121]
	v_mfma_f32_16x16x32_bf16 v[114:117], v[174:177], v[182:185], 0
	v_mfma_f32_16x16x32_bf16 v[114:117], v[178:181], v[186:189], v[114:117]
	v_mfma_f32_16x16x32_bf16 v[102:105], v[166:169], v[190:193], 0
	v_mfma_f32_16x16x32_bf16 v[102:105], v[170:173], v[194:197], v[102:105]
	v_mfma_f32_16x16x32_bf16 v[98:101], v[174:177], v[190:193], 0
	v_mfma_f32_16x16x32_bf16 v[98:101], v[178:181], v[194:197], v[98:101]
	v_mfma_f32_16x16x32_bf16 v[86:89], v[166:169], v[198:201], 0
	v_mfma_f32_16x16x32_bf16 v[86:89], v[170:173], v[212:215], v[86:89]
	v_mfma_f32_16x16x32_bf16 v[82:85], v[174:177], v[198:201], 0
	v_mfma_f32_16x16x32_bf16 v[82:85], v[178:181], v[212:215], v[82:85]
	v_mfma_f32_16x16x32_bf16 v[70:73], v[166:169], v[218:221], 0
	v_mfma_f32_16x16x32_bf16 v[70:73], v[170:173], v[222:225], v[70:73]
	v_mfma_f32_16x16x32_bf16 v[66:69], v[174:177], v[218:221], 0
	v_mfma_f32_16x16x32_bf16 v[66:69], v[178:181], v[222:225], v[66:69]
	s_setprio 0
	s_barrier
	s_mov_b32 m0, s43
	v_add_u32_e32 v137, s71, v143
	ds_read_b128 v[182:185], v152 offset:16384
	ds_read_b128 v[186:189], v152 offset:17408
	ds_read_b128 v[190:193], v152 offset:18432
	ds_read_b128 v[194:197], v152 offset:19456
	ds_read_b128 v[198:201], v152 offset:20480
	ds_read_b128 v[212:215], v152 offset:21504
	ds_read_b128 v[218:221], v152 offset:22528
	ds_read_b128 v[222:225], v152 offset:23552
	global_load_lds_dwordx4 v137, s[10:11]
	v_add_u32_e32 v137, s71, v145
	s_mov_b32 m0, s44
	s_add_i32 s73, s71, 0x80000
	global_load_lds_dwordx4 v137, s[10:11]
	v_add_u32_e32 v137, s73, v143
	s_mov_b32 m0, s46
	s_nop 0
	global_load_lds_dwordx4 v137, s[10:11]
	v_add_u32_e32 v137, s73, v145
	s_mov_b32 m0, s47
	s_nop 0
	global_load_lds_dwordx4 v137, s[10:11]
	v_add_u32_e32 v137, s72, v142
	s_mov_b32 m0, s48
	s_nop 0
	global_load_lds_dwordx4 v137, s[8:9]
	v_add_u32_e32 v137, s72, v144
	s_mov_b32 m0, s49
	s_nop 0
	global_load_lds_dwordx4 v137, s[8:9]
	s_waitcnt vmcnt(8)
	s_waitcnt lgkmcnt(0)
	s_setprio 1
	s_barrier
	v_mfma_f32_16x16x32_bf16 v[62:65], v[138:141], v[182:185], 0
	v_mfma_f32_16x16x32_bf16 v[62:65], v[154:157], v[186:189], v[62:65]
	v_mfma_f32_16x16x32_bf16 v[58:61], v[158:161], v[182:185], 0
	v_mfma_f32_16x16x32_bf16 v[58:61], v[162:165], v[186:189], v[58:61]
	v_mfma_f32_16x16x32_bf16 v[46:49], v[138:141], v[190:193], 0
	v_mfma_f32_16x16x32_bf16 v[46:49], v[154:157], v[194:197], v[46:49]
	v_mfma_f32_16x16x32_bf16 v[42:45], v[158:161], v[190:193], 0
	v_mfma_f32_16x16x32_bf16 v[42:45], v[162:165], v[194:197], v[42:45]
	v_mfma_f32_16x16x32_bf16 v[30:33], v[138:141], v[198:201], 0
	v_mfma_f32_16x16x32_bf16 v[30:33], v[154:157], v[212:215], v[30:33]
	v_mfma_f32_16x16x32_bf16 v[26:29], v[158:161], v[198:201], 0
	v_mfma_f32_16x16x32_bf16 v[26:29], v[162:165], v[212:215], v[26:29]
	v_mfma_f32_16x16x32_bf16 v[14:17], v[138:141], v[218:221], 0
	v_mfma_f32_16x16x32_bf16 v[14:17], v[154:157], v[222:225], v[14:17]
	v_mfma_f32_16x16x32_bf16 v[10:13], v[158:161], v[218:221], 0
	v_mfma_f32_16x16x32_bf16 v[10:13], v[162:165], v[222:225], v[10:13]
	s_setprio 0
	s_setprio 1
	v_mfma_f32_16x16x32_bf16 v[54:57], v[166:169], v[182:185], 0
	v_mfma_f32_16x16x32_bf16 v[54:57], v[170:173], v[186:189], v[54:57]
	v_mfma_f32_16x16x32_bf16 v[50:53], v[174:177], v[182:185], 0
	v_mfma_f32_16x16x32_bf16 v[50:53], v[178:181], v[186:189], v[50:53]
	v_mfma_f32_16x16x32_bf16 v[38:41], v[166:169], v[190:193], 0
	v_mfma_f32_16x16x32_bf16 v[38:41], v[170:173], v[194:197], v[38:41]
	v_mfma_f32_16x16x32_bf16 v[34:37], v[174:177], v[190:193], 0
	v_mfma_f32_16x16x32_bf16 v[34:37], v[178:181], v[194:197], v[34:37]
	v_mfma_f32_16x16x32_bf16 v[22:25], v[166:169], v[198:201], 0
	v_mfma_f32_16x16x32_bf16 v[22:25], v[170:173], v[212:215], v[22:25]
	v_mfma_f32_16x16x32_bf16 v[18:21], v[174:177], v[198:201], 0
	v_mfma_f32_16x16x32_bf16 v[18:21], v[178:181], v[212:215], v[18:21]
	v_mfma_f32_16x16x32_bf16 v[6:9], v[166:169], v[218:221], 0
	v_mfma_f32_16x16x32_bf16 v[6:9], v[170:173], v[222:225], v[6:9]
	v_mfma_f32_16x16x32_bf16 v[2:5], v[174:177], v[218:221], 0
	v_mfma_f32_16x16x32_bf16 v[2:5], v[178:181], v[222:225], v[2:5]
	s_setprio 0
	s_barrier
	v_add_u32_e32 v137, s52, v148
	ds_read_b128 v[138:141], v137
	ds_read_b128 v[154:157], v137 offset:1024
	ds_read_b128 v[158:161], v137 offset:2048
	ds_read_b128 v[162:165], v137 offset:3072
	v_add_u32_e32 v137, s57, v148
	ds_read_b128 v[166:169], v137
	ds_read_b128 v[170:173], v137 offset:1024
	ds_read_b128 v[174:177], v137 offset:2048
	ds_read_b128 v[178:181], v137 offset:3072
	s_add_i32 s72, s72, 0x80000
	s_mov_b32 m0, s50
	v_add_u32_e32 v137, s72, v142
	ds_read_b128 v[182:185], v152 offset:32768
	ds_read_b128 v[186:189], v152 offset:33792
	ds_read_b128 v[190:193], v152 offset:34816
	ds_read_b128 v[194:197], v152 offset:35840
	ds_read_b128 v[198:201], v152 offset:36864
	ds_read_b128 v[212:215], v152 offset:37888
	ds_read_b128 v[218:221], v152 offset:38912
	ds_read_b128 v[222:225], v152 offset:39936
	global_load_lds_dwordx4 v137, s[8:9]
	v_add_u32_e32 v137, s72, v144
	s_mov_b32 m0, s51
	s_nop 0
	global_load_lds_dwordx4 v137, s[8:9]
	s_waitcnt vmcnt(8)
	s_waitcnt lgkmcnt(0)
	s_setprio 1
	s_barrier
	v_mfma_f32_16x16x32_bf16 v[126:129], v[138:141], v[182:185], v[126:129]
	v_mfma_f32_16x16x32_bf16 v[126:129], v[154:157], v[186:189], v[126:129]
	v_mfma_f32_16x16x32_bf16 v[122:125], v[158:161], v[182:185], v[122:125]
	v_mfma_f32_16x16x32_bf16 v[122:125], v[162:165], v[186:189], v[122:125]
	v_mfma_f32_16x16x32_bf16 v[110:113], v[138:141], v[190:193], v[110:113]
	v_mfma_f32_16x16x32_bf16 v[110:113], v[154:157], v[194:197], v[110:113]
	v_mfma_f32_16x16x32_bf16 v[106:109], v[158:161], v[190:193], v[106:109]
	v_mfma_f32_16x16x32_bf16 v[106:109], v[162:165], v[194:197], v[106:109]
	v_mfma_f32_16x16x32_bf16 v[94:97], v[138:141], v[198:201], v[94:97]
	v_mfma_f32_16x16x32_bf16 v[94:97], v[154:157], v[212:215], v[94:97]
	v_mfma_f32_16x16x32_bf16 v[90:93], v[158:161], v[198:201], v[90:93]
	v_mfma_f32_16x16x32_bf16 v[90:93], v[162:165], v[212:215], v[90:93]
	v_mfma_f32_16x16x32_bf16 v[78:81], v[138:141], v[218:221], v[78:81]
	v_mfma_f32_16x16x32_bf16 v[78:81], v[154:157], v[222:225], v[78:81]
	v_mfma_f32_16x16x32_bf16 v[74:77], v[158:161], v[218:221], v[74:77]
	v_mfma_f32_16x16x32_bf16 v[74:77], v[162:165], v[222:225], v[74:77]
	s_setprio 0
	s_setprio 1
	v_mfma_f32_16x16x32_bf16 v[118:121], v[166:169], v[182:185], v[118:121]
	v_mfma_f32_16x16x32_bf16 v[118:121], v[170:173], v[186:189], v[118:121]
	v_mfma_f32_16x16x32_bf16 v[114:117], v[174:177], v[182:185], v[114:117]
	v_mfma_f32_16x16x32_bf16 v[114:117], v[178:181], v[186:189], v[114:117]
	v_mfma_f32_16x16x32_bf16 v[102:105], v[166:169], v[190:193], v[102:105]
	v_mfma_f32_16x16x32_bf16 v[102:105], v[170:173], v[194:197], v[102:105]
	v_mfma_f32_16x16x32_bf16 v[98:101], v[174:177], v[190:193], v[98:101]
	v_mfma_f32_16x16x32_bf16 v[98:101], v[178:181], v[194:197], v[98:101]
	v_mfma_f32_16x16x32_bf16 v[86:89], v[166:169], v[198:201], v[86:89]
	v_mfma_f32_16x16x32_bf16 v[86:89], v[170:173], v[212:215], v[86:89]
	v_mfma_f32_16x16x32_bf16 v[82:85], v[174:177], v[198:201], v[82:85]
	v_mfma_f32_16x16x32_bf16 v[82:85], v[178:181], v[212:215], v[82:85]
	v_mfma_f32_16x16x32_bf16 v[70:73], v[166:169], v[218:221], v[70:73]
	v_mfma_f32_16x16x32_bf16 v[70:73], v[170:173], v[222:225], v[70:73]
	v_mfma_f32_16x16x32_bf16 v[66:69], v[174:177], v[218:221], v[66:69]
	v_mfma_f32_16x16x32_bf16 v[66:69], v[178:181], v[222:225], v[66:69]
	s_setprio 0
	s_barrier
	s_or_b32 s72, s71, 0x80
	s_mov_b32 m0, s53
	v_add_u32_e32 v137, s72, v143
	ds_read_b128 v[182:185], v152 offset:49152
	ds_read_b128 v[186:189], v152 offset:50176
	ds_read_b128 v[190:193], v152 offset:51200
	ds_read_b128 v[194:197], v152 offset:52224
	ds_read_b128 v[198:201], v152 offset:53248
	ds_read_b128 v[212:215], v152 offset:54272
	ds_read_b128 v[218:221], v152 offset:55296
	ds_read_b128 v[222:225], v152 offset:56320
	global_load_lds_dwordx4 v137, s[10:11]
	v_add_u32_e32 v137, s72, v145
	s_mov_b32 m0, s54
	s_add_i32 s71, s71, 0x80080
	global_load_lds_dwordx4 v137, s[10:11]
	v_add_u32_e32 v137, s71, v143
	s_mov_b32 m0, s58
	s_nop 0
	global_load_lds_dwordx4 v137, s[10:11]
	v_add_u32_e32 v137, s71, v145
	s_mov_b32 m0, s59
	s_nop 0
	global_load_lds_dwordx4 v137, s[10:11]
	v_add_u32_e32 v137, s70, v142
	s_mov_b32 m0, s55
	s_nop 0
	global_load_lds_dwordx4 v137, s[8:9]
	v_add_u32_e32 v137, s70, v144
	s_mov_b32 m0, s56
	s_nop 0
	global_load_lds_dwordx4 v137, s[8:9]
	s_waitcnt vmcnt(8)
	s_waitcnt lgkmcnt(0)
	s_setprio 1
	s_barrier
	v_mfma_f32_16x16x32_bf16 v[62:65], v[138:141], v[182:185], v[62:65]
	v_mfma_f32_16x16x32_bf16 v[62:65], v[154:157], v[186:189], v[62:65]
	v_mfma_f32_16x16x32_bf16 v[58:61], v[158:161], v[182:185], v[58:61]
	v_mfma_f32_16x16x32_bf16 v[58:61], v[162:165], v[186:189], v[58:61]
	v_mfma_f32_16x16x32_bf16 v[46:49], v[138:141], v[190:193], v[46:49]
	v_mfma_f32_16x16x32_bf16 v[46:49], v[154:157], v[194:197], v[46:49]
	v_mfma_f32_16x16x32_bf16 v[42:45], v[158:161], v[190:193], v[42:45]
	v_mfma_f32_16x16x32_bf16 v[42:45], v[162:165], v[194:197], v[42:45]
	v_mfma_f32_16x16x32_bf16 v[30:33], v[138:141], v[198:201], v[30:33]
	v_mfma_f32_16x16x32_bf16 v[30:33], v[154:157], v[212:215], v[30:33]
	v_mfma_f32_16x16x32_bf16 v[26:29], v[158:161], v[198:201], v[26:29]
	v_mfma_f32_16x16x32_bf16 v[26:29], v[162:165], v[212:215], v[26:29]
	v_mfma_f32_16x16x32_bf16 v[14:17], v[138:141], v[218:221], v[14:17]
	v_mfma_f32_16x16x32_bf16 v[14:17], v[154:157], v[222:225], v[14:17]
	v_mfma_f32_16x16x32_bf16 v[10:13], v[158:161], v[218:221], v[10:13]
	v_mfma_f32_16x16x32_bf16 v[10:13], v[162:165], v[222:225], v[10:13]
	s_setprio 0
	s_setprio 1
	v_mfma_f32_16x16x32_bf16 v[54:57], v[166:169], v[182:185], v[54:57]
	v_mfma_f32_16x16x32_bf16 v[54:57], v[170:173], v[186:189], v[54:57]
	v_mfma_f32_16x16x32_bf16 v[50:53], v[174:177], v[182:185], v[50:53]
	v_mfma_f32_16x16x32_bf16 v[50:53], v[178:181], v[186:189], v[50:53]
	v_mfma_f32_16x16x32_bf16 v[38:41], v[166:169], v[190:193], v[38:41]
	v_mfma_f32_16x16x32_bf16 v[38:41], v[170:173], v[194:197], v[38:41]
	v_mfma_f32_16x16x32_bf16 v[34:37], v[174:177], v[190:193], v[34:37]
	v_mfma_f32_16x16x32_bf16 v[34:37], v[178:181], v[194:197], v[34:37]
	v_mfma_f32_16x16x32_bf16 v[22:25], v[166:169], v[198:201], v[22:25]
	v_mfma_f32_16x16x32_bf16 v[22:25], v[170:173], v[212:215], v[22:25]
	v_mfma_f32_16x16x32_bf16 v[18:21], v[174:177], v[198:201], v[18:21]
	v_mfma_f32_16x16x32_bf16 v[18:21], v[178:181], v[212:215], v[18:21]
	v_mfma_f32_16x16x32_bf16 v[6:9], v[166:169], v[218:221], v[6:9]
	v_mfma_f32_16x16x32_bf16 v[6:9], v[170:173], v[222:225], v[6:9]
	v_mfma_f32_16x16x32_bf16 v[2:5], v[174:177], v[218:221], v[2:5]
	v_mfma_f32_16x16x32_bf16 v[2:5], v[178:181], v[222:225], v[2:5]
	s_setprio 0
	s_barrier
	s_add_i32 s69, s69, 2
	s_addk_i32 s67, 0x100
	s_addk_i32 s68, 0x100
	v_add_u32_e32 v135, 0x100, v135
	s_cmp_gt_u32 s69, 29
	v_add_u32_e32 v136, 0x100, v136
.LBB0_283:
	v_add_u32_e32 v137, s42, v148
	ds_read_b128 v[138:141], v137
	ds_read_b128 v[154:157], v137 offset:1024
	ds_read_b128 v[158:161], v137 offset:2048
	ds_read_b128 v[162:165], v137 offset:3072
	v_add_u32_e32 v137, s45, v148
	ds_read_b128 v[166:169], v137
	ds_read_b128 v[170:173], v137 offset:1024
	ds_read_b128 v[174:177], v137 offset:2048
	ds_read_b128 v[178:181], v137 offset:3072
	s_cmp_eq_u32 s69, 28
	s_cselect_b32 s72, s36, s68
	s_cselect_b32 s71, s37, s67
	s_or_b32 s70, s72, 0x80
	s_add_i32 m0, s48, 0xc000
	ds_read_b128 v[182:185], v152
	ds_read_b128 v[186:189], v152 offset:1024
	ds_read_b128 v[190:193], v152 offset:2048
	ds_read_b128 v[194:197], v152 offset:3072
	ds_read_b128 v[198:201], v152 offset:4096
	ds_read_b128 v[212:215], v152 offset:5120
	ds_read_b128 v[218:221], v152 offset:6144
	ds_read_b128 v[222:225], v152 offset:7168
	global_load_lds_dwordx4 v136, s[8:9]
	s_add_i32 m0, s48, 0xe000
	s_nop 0
	global_load_lds_dwordx4 v135, s[8:9]
	s_waitcnt vmcnt(8)
	s_waitcnt lgkmcnt(0)
	s_setprio 1
	s_barrier
	v_mfma_f32_16x16x32_bf16 v[126:129], v[138:141], v[182:185], v[126:129]
	v_mfma_f32_16x16x32_bf16 v[126:129], v[154:157], v[186:189], v[126:129]
	v_mfma_f32_16x16x32_bf16 v[122:125], v[158:161], v[182:185], v[122:125]
	v_mfma_f32_16x16x32_bf16 v[122:125], v[162:165], v[186:189], v[122:125]
	v_mfma_f32_16x16x32_bf16 v[110:113], v[138:141], v[190:193], v[110:113]
	v_mfma_f32_16x16x32_bf16 v[110:113], v[154:157], v[194:197], v[110:113]
	v_mfma_f32_16x16x32_bf16 v[106:109], v[158:161], v[190:193], v[106:109]
	v_mfma_f32_16x16x32_bf16 v[106:109], v[162:165], v[194:197], v[106:109]
	v_mfma_f32_16x16x32_bf16 v[94:97], v[138:141], v[198:201], v[94:97]
	v_mfma_f32_16x16x32_bf16 v[94:97], v[154:157], v[212:215], v[94:97]
	v_mfma_f32_16x16x32_bf16 v[90:93], v[158:161], v[198:201], v[90:93]
	v_mfma_f32_16x16x32_bf16 v[90:93], v[162:165], v[212:215], v[90:93]
	v_mfma_f32_16x16x32_bf16 v[78:81], v[138:141], v[218:221], v[78:81]
	v_mfma_f32_16x16x32_bf16 v[78:81], v[154:157], v[222:225], v[78:81]
	v_mfma_f32_16x16x32_bf16 v[74:77], v[158:161], v[218:221], v[74:77]
	v_mfma_f32_16x16x32_bf16 v[74:77], v[162:165], v[222:225], v[74:77]
	s_setprio 0
	s_setprio 1
	v_mfma_f32_16x16x32_bf16 v[118:121], v[166:169], v[182:185], v[118:121]
	v_mfma_f32_16x16x32_bf16 v[118:121], v[170:173], v[186:189], v[118:121]
	v_mfma_f32_16x16x32_bf16 v[114:117], v[174:177], v[182:185], v[114:117]
	v_mfma_f32_16x16x32_bf16 v[114:117], v[178:181], v[186:189], v[114:117]
	v_mfma_f32_16x16x32_bf16 v[102:105], v[166:169], v[190:193], v[102:105]
	v_mfma_f32_16x16x32_bf16 v[102:105], v[170:173], v[194:197], v[102:105]
	v_mfma_f32_16x16x32_bf16 v[98:101], v[174:177], v[190:193], v[98:101]
	v_mfma_f32_16x16x32_bf16 v[98:101], v[178:181], v[194:197], v[98:101]
	v_mfma_f32_16x16x32_bf16 v[86:89], v[166:169], v[198:201], v[86:89]
	v_mfma_f32_16x16x32_bf16 v[86:89], v[170:173], v[212:215], v[86:89]
	v_mfma_f32_16x16x32_bf16 v[82:85], v[174:177], v[198:201], v[82:85]
	v_mfma_f32_16x16x32_bf16 v[82:85], v[178:181], v[212:215], v[82:85]
	v_mfma_f32_16x16x32_bf16 v[70:73], v[166:169], v[218:221], v[70:73]
	v_mfma_f32_16x16x32_bf16 v[70:73], v[170:173], v[222:225], v[70:73]
	v_mfma_f32_16x16x32_bf16 v[66:69], v[174:177], v[218:221], v[66:69]
	v_mfma_f32_16x16x32_bf16 v[66:69], v[178:181], v[222:225], v[66:69]
	s_setprio 0
	s_barrier
	s_mov_b32 m0, s43
	v_add_u32_e32 v137, s71, v143
	ds_read_b128 v[182:185], v152 offset:16384
	ds_read_b128 v[186:189], v152 offset:17408
	ds_read_b128 v[190:193], v152 offset:18432
	ds_read_b128 v[194:197], v152 offset:19456
	ds_read_b128 v[198:201], v152 offset:20480
	ds_read_b128 v[212:215], v152 offset:21504
	ds_read_b128 v[218:221], v152 offset:22528
	ds_read_b128 v[222:225], v152 offset:23552
	global_load_lds_dwordx4 v137, s[10:11]
	v_add_u32_e32 v137, s71, v145
	s_mov_b32 m0, s44
	s_add_i32 s73, s71, 0x80000
	global_load_lds_dwordx4 v137, s[10:11]
	v_add_u32_e32 v137, s73, v143
	s_mov_b32 m0, s46
	s_nop 0
	global_load_lds_dwordx4 v137, s[10:11]
	v_add_u32_e32 v137, s73, v145
	s_mov_b32 m0, s47
	s_nop 0
	global_load_lds_dwordx4 v137, s[10:11]
	v_add_u32_e32 v137, s72, v142
	s_mov_b32 m0, s48
	s_nop 0
	global_load_lds_dwordx4 v137, s[8:9]
	v_add_u32_e32 v137, s72, v144
	s_mov_b32 m0, s49
	s_nop 0
	global_load_lds_dwordx4 v137, s[8:9]
	s_waitcnt vmcnt(8)
	s_waitcnt lgkmcnt(0)
	s_setprio 1
	s_barrier
	v_mfma_f32_16x16x32_bf16 v[62:65], v[138:141], v[182:185], v[62:65]
	v_mfma_f32_16x16x32_bf16 v[62:65], v[154:157], v[186:189], v[62:65]
	v_mfma_f32_16x16x32_bf16 v[58:61], v[158:161], v[182:185], v[58:61]
	v_mfma_f32_16x16x32_bf16 v[58:61], v[162:165], v[186:189], v[58:61]
	v_mfma_f32_16x16x32_bf16 v[46:49], v[138:141], v[190:193], v[46:49]
	v_mfma_f32_16x16x32_bf16 v[46:49], v[154:157], v[194:197], v[46:49]
	v_mfma_f32_16x16x32_bf16 v[42:45], v[158:161], v[190:193], v[42:45]
	v_mfma_f32_16x16x32_bf16 v[42:45], v[162:165], v[194:197], v[42:45]
	v_mfma_f32_16x16x32_bf16 v[30:33], v[138:141], v[198:201], v[30:33]
	v_mfma_f32_16x16x32_bf16 v[30:33], v[154:157], v[212:215], v[30:33]
	v_mfma_f32_16x16x32_bf16 v[26:29], v[158:161], v[198:201], v[26:29]
	v_mfma_f32_16x16x32_bf16 v[26:29], v[162:165], v[212:215], v[26:29]
	v_mfma_f32_16x16x32_bf16 v[14:17], v[138:141], v[218:221], v[14:17]
	v_mfma_f32_16x16x32_bf16 v[14:17], v[154:157], v[222:225], v[14:17]
	v_mfma_f32_16x16x32_bf16 v[10:13], v[158:161], v[218:221], v[10:13]
	v_mfma_f32_16x16x32_bf16 v[10:13], v[162:165], v[222:225], v[10:13]
	s_setprio 0
	s_setprio 1
	v_mfma_f32_16x16x32_bf16 v[54:57], v[166:169], v[182:185], v[54:57]
	v_mfma_f32_16x16x32_bf16 v[54:57], v[170:173], v[186:189], v[54:57]
	v_mfma_f32_16x16x32_bf16 v[50:53], v[174:177], v[182:185], v[50:53]
	v_mfma_f32_16x16x32_bf16 v[50:53], v[178:181], v[186:189], v[50:53]
	v_mfma_f32_16x16x32_bf16 v[38:41], v[166:169], v[190:193], v[38:41]
	v_mfma_f32_16x16x32_bf16 v[38:41], v[170:173], v[194:197], v[38:41]
	v_mfma_f32_16x16x32_bf16 v[34:37], v[174:177], v[190:193], v[34:37]
	v_mfma_f32_16x16x32_bf16 v[34:37], v[178:181], v[194:197], v[34:37]
	v_mfma_f32_16x16x32_bf16 v[22:25], v[166:169], v[198:201], v[22:25]
	v_mfma_f32_16x16x32_bf16 v[22:25], v[170:173], v[212:215], v[22:25]
	v_mfma_f32_16x16x32_bf16 v[18:21], v[174:177], v[198:201], v[18:21]
	v_mfma_f32_16x16x32_bf16 v[18:21], v[178:181], v[212:215], v[18:21]
	v_mfma_f32_16x16x32_bf16 v[6:9], v[166:169], v[218:221], v[6:9]
	v_mfma_f32_16x16x32_bf16 v[6:9], v[170:173], v[222:225], v[6:9]
	v_mfma_f32_16x16x32_bf16 v[2:5], v[174:177], v[218:221], v[2:5]
	v_mfma_f32_16x16x32_bf16 v[2:5], v[178:181], v[222:225], v[2:5]
	s_setprio 0
	s_barrier
	v_add_u32_e32 v137, s52, v148
	ds_read_b128 v[138:141], v137
	ds_read_b128 v[154:157], v137 offset:1024
	ds_read_b128 v[158:161], v137 offset:2048
	ds_read_b128 v[162:165], v137 offset:3072
	v_add_u32_e32 v137, s57, v148
	ds_read_b128 v[166:169], v137
	ds_read_b128 v[170:173], v137 offset:1024
	ds_read_b128 v[174:177], v137 offset:2048
	ds_read_b128 v[178:181], v137 offset:3072
	s_add_i32 s72, s72, 0x80000
	s_mov_b32 m0, s50
	v_add_u32_e32 v137, s72, v142
	ds_read_b128 v[182:185], v152 offset:32768
	ds_read_b128 v[186:189], v152 offset:33792
	ds_read_b128 v[190:193], v152 offset:34816
	ds_read_b128 v[194:197], v152 offset:35840
	ds_read_b128 v[198:201], v152 offset:36864
	ds_read_b128 v[212:215], v152 offset:37888
	ds_read_b128 v[218:221], v152 offset:38912
	ds_read_b128 v[222:225], v152 offset:39936
	global_load_lds_dwordx4 v137, s[8:9]
	v_add_u32_e32 v137, s72, v144
	s_mov_b32 m0, s51
	s_nop 0
	global_load_lds_dwordx4 v137, s[8:9]
	s_waitcnt vmcnt(8)
	s_waitcnt lgkmcnt(0)
	s_setprio 1
	s_barrier
	v_mfma_f32_16x16x32_bf16 v[126:129], v[138:141], v[182:185], v[126:129]
	v_mfma_f32_16x16x32_bf16 v[126:129], v[154:157], v[186:189], v[126:129]
	v_mfma_f32_16x16x32_bf16 v[122:125], v[158:161], v[182:185], v[122:125]
	v_mfma_f32_16x16x32_bf16 v[122:125], v[162:165], v[186:189], v[122:125]
	v_mfma_f32_16x16x32_bf16 v[110:113], v[138:141], v[190:193], v[110:113]
	v_mfma_f32_16x16x32_bf16 v[110:113], v[154:157], v[194:197], v[110:113]
	v_mfma_f32_16x16x32_bf16 v[106:109], v[158:161], v[190:193], v[106:109]
	v_mfma_f32_16x16x32_bf16 v[106:109], v[162:165], v[194:197], v[106:109]
	v_mfma_f32_16x16x32_bf16 v[94:97], v[138:141], v[198:201], v[94:97]
	v_mfma_f32_16x16x32_bf16 v[94:97], v[154:157], v[212:215], v[94:97]
	v_mfma_f32_16x16x32_bf16 v[90:93], v[158:161], v[198:201], v[90:93]
	v_mfma_f32_16x16x32_bf16 v[90:93], v[162:165], v[212:215], v[90:93]
	v_mfma_f32_16x16x32_bf16 v[78:81], v[138:141], v[218:221], v[78:81]
	v_mfma_f32_16x16x32_bf16 v[78:81], v[154:157], v[222:225], v[78:81]
	v_mfma_f32_16x16x32_bf16 v[74:77], v[158:161], v[218:221], v[74:77]
	v_mfma_f32_16x16x32_bf16 v[74:77], v[162:165], v[222:225], v[74:77]
	s_setprio 0
	s_setprio 1
	v_mfma_f32_16x16x32_bf16 v[118:121], v[166:169], v[182:185], v[118:121]
	v_mfma_f32_16x16x32_bf16 v[118:121], v[170:173], v[186:189], v[118:121]
	v_mfma_f32_16x16x32_bf16 v[114:117], v[174:177], v[182:185], v[114:117]
	v_mfma_f32_16x16x32_bf16 v[114:117], v[178:181], v[186:189], v[114:117]
	v_mfma_f32_16x16x32_bf16 v[102:105], v[166:169], v[190:193], v[102:105]
	v_mfma_f32_16x16x32_bf16 v[102:105], v[170:173], v[194:197], v[102:105]
	v_mfma_f32_16x16x32_bf16 v[98:101], v[174:177], v[190:193], v[98:101]
	v_mfma_f32_16x16x32_bf16 v[98:101], v[178:181], v[194:197], v[98:101]
	v_mfma_f32_16x16x32_bf16 v[86:89], v[166:169], v[198:201], v[86:89]
	v_mfma_f32_16x16x32_bf16 v[86:89], v[170:173], v[212:215], v[86:89]
	v_mfma_f32_16x16x32_bf16 v[82:85], v[174:177], v[198:201], v[82:85]
	v_mfma_f32_16x16x32_bf16 v[82:85], v[178:181], v[212:215], v[82:85]
	v_mfma_f32_16x16x32_bf16 v[70:73], v[166:169], v[218:221], v[70:73]
	v_mfma_f32_16x16x32_bf16 v[70:73], v[170:173], v[222:225], v[70:73]
	v_mfma_f32_16x16x32_bf16 v[66:69], v[174:177], v[218:221], v[66:69]
	v_mfma_f32_16x16x32_bf16 v[66:69], v[178:181], v[222:225], v[66:69]
	s_setprio 0
	s_barrier
	s_or_b32 s72, s71, 0x80
	s_mov_b32 m0, s53
	v_add_u32_e32 v137, s72, v143
	ds_read_b128 v[182:185], v152 offset:49152
	ds_read_b128 v[186:189], v152 offset:50176
	ds_read_b128 v[190:193], v152 offset:51200
	ds_read_b128 v[194:197], v152 offset:52224
	ds_read_b128 v[198:201], v152 offset:53248
	ds_read_b128 v[212:215], v152 offset:54272
	ds_read_b128 v[218:221], v152 offset:55296
	ds_read_b128 v[222:225], v152 offset:56320
	global_load_lds_dwordx4 v137, s[10:11]
	v_add_u32_e32 v137, s72, v145
	s_mov_b32 m0, s54
	s_add_i32 s71, s71, 0x80080
	global_load_lds_dwordx4 v137, s[10:11]
	v_add_u32_e32 v137, s71, v143
	s_mov_b32 m0, s58
	s_nop 0
	global_load_lds_dwordx4 v137, s[10:11]
	v_add_u32_e32 v137, s71, v145
	s_mov_b32 m0, s59
	s_nop 0
	global_load_lds_dwordx4 v137, s[10:11]
	v_add_u32_e32 v137, s70, v142
	s_mov_b32 m0, s55
	s_nop 0
	global_load_lds_dwordx4 v137, s[8:9]
	v_add_u32_e32 v137, s70, v144
	s_mov_b32 m0, s56
	s_nop 0
	global_load_lds_dwordx4 v137, s[8:9]
	s_add_i32 s69, s69, 2
	s_addk_i32 s67, 0x100
	s_addk_i32 s68, 0x100
	v_add_u32_e32 v135, 0x100, v135
	s_cmp_gt_u32 s69, 29
	v_add_u32_e32 v136, 0x100, v136
	s_waitcnt vmcnt(8)
	s_waitcnt lgkmcnt(0)
	s_setprio 1
	s_barrier
	v_mfma_f32_16x16x32_bf16 v[62:65], v[138:141], v[182:185], v[62:65]
	v_mfma_f32_16x16x32_bf16 v[62:65], v[154:157], v[186:189], v[62:65]
	v_mfma_f32_16x16x32_bf16 v[58:61], v[158:161], v[182:185], v[58:61]
	v_mfma_f32_16x16x32_bf16 v[58:61], v[162:165], v[186:189], v[58:61]
	v_mfma_f32_16x16x32_bf16 v[46:49], v[138:141], v[190:193], v[46:49]
	v_mfma_f32_16x16x32_bf16 v[46:49], v[154:157], v[194:197], v[46:49]
	v_mfma_f32_16x16x32_bf16 v[42:45], v[158:161], v[190:193], v[42:45]
	v_mfma_f32_16x16x32_bf16 v[42:45], v[162:165], v[194:197], v[42:45]
	v_mfma_f32_16x16x32_bf16 v[30:33], v[138:141], v[198:201], v[30:33]
	v_mfma_f32_16x16x32_bf16 v[30:33], v[154:157], v[212:215], v[30:33]
	v_mfma_f32_16x16x32_bf16 v[26:29], v[158:161], v[198:201], v[26:29]
	v_mfma_f32_16x16x32_bf16 v[26:29], v[162:165], v[212:215], v[26:29]
	v_mfma_f32_16x16x32_bf16 v[14:17], v[138:141], v[218:221], v[14:17]
	v_mfma_f32_16x16x32_bf16 v[14:17], v[154:157], v[222:225], v[14:17]
	v_mfma_f32_16x16x32_bf16 v[10:13], v[158:161], v[218:221], v[10:13]
	v_mfma_f32_16x16x32_bf16 v[10:13], v[162:165], v[222:225], v[10:13]
	s_setprio 0
	s_setprio 1
	v_mfma_f32_16x16x32_bf16 v[54:57], v[166:169], v[182:185], v[54:57]
	v_mfma_f32_16x16x32_bf16 v[54:57], v[170:173], v[186:189], v[54:57]
	v_mfma_f32_16x16x32_bf16 v[50:53], v[174:177], v[182:185], v[50:53]
	v_mfma_f32_16x16x32_bf16 v[50:53], v[178:181], v[186:189], v[50:53]
	v_mfma_f32_16x16x32_bf16 v[38:41], v[166:169], v[190:193], v[38:41]
	v_mfma_f32_16x16x32_bf16 v[38:41], v[170:173], v[194:197], v[38:41]
	v_mfma_f32_16x16x32_bf16 v[34:37], v[174:177], v[190:193], v[34:37]
	v_mfma_f32_16x16x32_bf16 v[34:37], v[178:181], v[194:197], v[34:37]
	v_mfma_f32_16x16x32_bf16 v[22:25], v[166:169], v[198:201], v[22:25]
	v_mfma_f32_16x16x32_bf16 v[22:25], v[170:173], v[212:215], v[22:25]
	v_mfma_f32_16x16x32_bf16 v[18:21], v[174:177], v[198:201], v[18:21]
	v_mfma_f32_16x16x32_bf16 v[18:21], v[178:181], v[212:215], v[18:21]
	v_mfma_f32_16x16x32_bf16 v[6:9], v[166:169], v[218:221], v[6:9]
	v_mfma_f32_16x16x32_bf16 v[6:9], v[170:173], v[222:225], v[6:9]
	v_mfma_f32_16x16x32_bf16 v[2:5], v[174:177], v[218:221], v[2:5]
	v_mfma_f32_16x16x32_bf16 v[2:5], v[178:181], v[222:225], v[2:5]
	s_setprio 0
	s_barrier
	s_cbranch_scc0 .LBB0_283
	s_and_b64 vcc, exec, s[20:21]
	s_cbranch_vccz .LBB0_286
	s_barrier

.LBB0_313:
	v_and_b32_e32 v134, 15, v130
	v_and_b32_e32 v8, 48, v130
	v_lshlrev_b32_e32 v9, 2, v130
	s_and_b32 s14, s12, 3
	s_lshl_b32 s26, s13, 13
	v_lshl_or_b32 v8, v134, 6, v8
	v_and_b32_e32 v9, 32, v9
	v_bitop3_b32 v10, v8, s26, v9 bitop3:0xde
	s_lshl_b32 s26, s14, 12
	v_bitop3_b32 v138, v8, s26, v9 bitop3:0xde
	s_add_i32 s26, s40, 0x18000
	s_or_b32 s28, s2, 0x80
	s_add_i32 s27, s26, s34
	v_add_u32_e32 v8, s28, v133
	s_mov_b32 m0, s27
	s_waitcnt vmcnt(2)
	s_barrier
	global_load_lds_dwordx4 v8, s[10:11]
	v_add_u32_e32 v8, s28, v136
	s_add_i32 s28, s27, 0x2000
	s_mov_b32 m0, s28
	s_or_b32 s30, s21, 0x80
	s_add_i32 s29, s22, 0x8000
	global_load_lds_dwordx4 v8, s[10:11]
	v_add_u32_e32 v8, s30, v131
	s_mov_b32 m0, s29
	s_add_i32 s31, s40, 0x1c000
	global_load_lds_dwordx4 v8, s[8:9]
	v_add_u32_e32 v8, s30, v135
	s_add_i32 s30, s22, 0xa000
	s_mov_b32 m0, s30
	s_or_b32 s35, s2, 0x80080
	s_add_i32 s34, s31, s34
	global_load_lds_dwordx4 v8, s[8:9]
	v_add_u32_e32 v8, s35, v133
	s_mov_b32 m0, s34
	s_add_i32 s36, s21, 0x80080
	global_load_lds_dwordx4 v8, s[10:11]
	v_add_u32_e32 v8, s35, v136
	s_add_i32 s35, s34, 0x2000
	s_mov_b32 m0, s35
	v_lshlrev_b32_e32 v6, 12, v6
	global_load_lds_dwordx4 v8, s[10:11]
	v_lshlrev_b32_e32 v8, 15, v5
	v_and_b32_e32 v8, 0xffff0000, v8
	v_and_b32_e32 v5, 1, v5
	v_add3_u32 v6, s36, v8, v6
	v_lshlrev_b32_e32 v5, 6, v5
	v_lshlrev_b32_e32 v7, 1, v7
	v_add3_u32 v139, v6, v5, v7
	v_lshlrev_b32_e32 v5, 15, v2
	v_and_b32_e32 v5, 0xffff0000, v5
	v_lshlrev_b32_e32 v3, 12, v3
	v_and_b32_e32 v2, 1, v2
	s_waitcnt vmcnt(6)
	v_add3_u32 v3, s36, v5, v3
	v_lshlrev_b32_e32 v2, 6, v2
	v_lshlrev_b32_e32 v4, 1, v4
	s_lshl_b32 s12, s13, 6
	v_add3_u32 v140, v3, v2, v4
	v_or_b32_e32 v137, s12, v134
	s_mov_b32 s36, -2
	s_mov_b32 s37, 0
	v_add_u32_e32 v141, s40, v10
	s_barrier
	v_add_u32_e32 v154, s3, v138
	v_add_u32_e32 v170, s18, v138
	ds_read_b128 v[142:145], v154
	ds_read_b128 v[146:149], v154 offset:1024
	ds_read_b128 v[150:153], v154 offset:2048
	ds_read_b128 v[154:157], v154 offset:3072
	ds_read_b128 v[158:161], v170
	ds_read_b128 v[162:165], v170 offset:1024
	ds_read_b128 v[166:169], v170 offset:2048
	ds_read_b128 v[170:173], v170 offset:3072
	s_add_i32 s41, s37, 0x100
	s_cmp_lg_u32 s36, 28
	s_cselect_b32 s43, s41, 0
	s_add_i32 s44, s43, s21
	s_or_b32 s42, s44, 0x80
	s_add_i32 s43, s43, s2
	v_add_u32_e32 v202, s37, v140
	s_add_i32 m0, s22, 0xc000
	ds_read_b128 v[174:177], v141
	ds_read_b128 v[178:181], v141 offset:1024
	ds_read_b128 v[182:185], v141 offset:2048
	ds_read_b128 v[186:189], v141 offset:3072
	ds_read_b128 v[190:193], v141 offset:4096
	ds_read_b128 v[194:197], v141 offset:5120
	ds_read_b128 v[198:201], v141 offset:6144
	ds_read_b128 v[212:215], v141 offset:7168
	global_load_lds_dwordx4 v202, s[8:9]
	v_add_u32_e32 v202, s37, v139
	s_add_i32 m0, s22, 0xe000
	s_nop 0
	global_load_lds_dwordx4 v202, s[8:9]
	s_waitcnt vmcnt(8)
	s_waitcnt lgkmcnt(0)
	s_setprio 1
	s_barrier
	v_mfma_f32_16x16x32_bf16 v[126:129], v[142:145], v[174:177], 0
	v_mfma_f32_16x16x32_bf16 v[126:129], v[146:149], v[178:181], v[126:129]
	v_mfma_f32_16x16x32_bf16 v[122:125], v[150:153], v[174:177], 0
	v_mfma_f32_16x16x32_bf16 v[122:125], v[154:157], v[178:181], v[122:125]
	v_mfma_f32_16x16x32_bf16 v[110:113], v[142:145], v[182:185], 0
	v_mfma_f32_16x16x32_bf16 v[110:113], v[146:149], v[186:189], v[110:113]
	v_mfma_f32_16x16x32_bf16 v[106:109], v[150:153], v[182:185], 0
	v_mfma_f32_16x16x32_bf16 v[106:109], v[154:157], v[186:189], v[106:109]
	v_mfma_f32_16x16x32_bf16 v[94:97], v[142:145], v[190:193], 0
	v_mfma_f32_16x16x32_bf16 v[94:97], v[146:149], v[194:197], v[94:97]
	v_mfma_f32_16x16x32_bf16 v[90:93], v[150:153], v[190:193], 0
	v_mfma_f32_16x16x32_bf16 v[90:93], v[154:157], v[194:197], v[90:93]
	v_mfma_f32_16x16x32_bf16 v[78:81], v[142:145], v[198:201], 0
	v_mfma_f32_16x16x32_bf16 v[78:81], v[146:149], v[212:215], v[78:81]
	v_mfma_f32_16x16x32_bf16 v[74:77], v[150:153], v[198:201], 0
	v_mfma_f32_16x16x32_bf16 v[74:77], v[154:157], v[212:215], v[74:77]
	s_setprio 0
	s_setprio 1
	v_mfma_f32_16x16x32_bf16 v[118:121], v[158:161], v[174:177], 0
	v_mfma_f32_16x16x32_bf16 v[118:121], v[162:165], v[178:181], v[118:121]
	v_mfma_f32_16x16x32_bf16 v[114:117], v[166:169], v[174:177], 0
	v_mfma_f32_16x16x32_bf16 v[114:117], v[170:173], v[178:181], v[114:117]
	v_mfma_f32_16x16x32_bf16 v[102:105], v[158:161], v[182:185], 0
	v_mfma_f32_16x16x32_bf16 v[102:105], v[162:165], v[186:189], v[102:105]
	v_mfma_f32_16x16x32_bf16 v[98:101], v[166:169], v[182:185], 0
	v_mfma_f32_16x16x32_bf16 v[98:101], v[170:173], v[186:189], v[98:101]
	v_mfma_f32_16x16x32_bf16 v[86:89], v[158:161], v[190:193], 0
	v_mfma_f32_16x16x32_bf16 v[86:89], v[162:165], v[194:197], v[86:89]
	v_mfma_f32_16x16x32_bf16 v[82:85], v[166:169], v[190:193], 0
	v_mfma_f32_16x16x32_bf16 v[82:85], v[170:173], v[194:197], v[82:85]
	v_mfma_f32_16x16x32_bf16 v[70:73], v[158:161], v[198:201], 0
	v_mfma_f32_16x16x32_bf16 v[70:73], v[162:165], v[212:215], v[70:73]
	v_mfma_f32_16x16x32_bf16 v[66:69], v[166:169], v[198:201], 0
	v_mfma_f32_16x16x32_bf16 v[66:69], v[170:173], v[212:215], v[66:69]
	s_setprio 0
	s_barrier
	s_mov_b32 m0, s16
	v_add_u32_e32 v202, s43, v133
	ds_read_b128 v[174:177], v141 offset:16384
	ds_read_b128 v[178:181], v141 offset:17408
	ds_read_b128 v[182:185], v141 offset:18432
	ds_read_b128 v[186:189], v141 offset:19456
	ds_read_b128 v[190:193], v141 offset:20480
	ds_read_b128 v[194:197], v141 offset:21504
	ds_read_b128 v[198:201], v141 offset:22528
	ds_read_b128 v[212:215], v141 offset:23552
	global_load_lds_dwordx4 v202, s[10:11]
	v_add_u32_e32 v202, s43, v136
	s_mov_b32 m0, s17
	s_add_i32 s37, s43, 0x80000
	global_load_lds_dwordx4 v202, s[10:11]
	v_add_u32_e32 v202, s37, v133
	s_mov_b32 m0, s19
	s_nop 0
	global_load_lds_dwordx4 v202, s[10:11]
	v_add_u32_e32 v202, s37, v136
	s_mov_b32 m0, s20
	s_nop 0
	global_load_lds_dwordx4 v202, s[10:11]
	v_add_u32_e32 v202, s44, v131
	s_mov_b32 m0, s22
	s_nop 0
	global_load_lds_dwordx4 v202, s[8:9]
	v_add_u32_e32 v202, s44, v135
	s_mov_b32 m0, s23
	s_nop 0
	global_load_lds_dwordx4 v202, s[8:9]
	s_waitcnt vmcnt(8)
	s_waitcnt lgkmcnt(0)
	s_setprio 1
	s_barrier
	v_mfma_f32_16x16x32_bf16 v[62:65], v[142:145], v[174:177], 0
	v_mfma_f32_16x16x32_bf16 v[62:65], v[146:149], v[178:181], v[62:65]
	v_mfma_f32_16x16x32_bf16 v[58:61], v[150:153], v[174:177], 0
	v_mfma_f32_16x16x32_bf16 v[58:61], v[154:157], v[178:181], v[58:61]
	v_mfma_f32_16x16x32_bf16 v[46:49], v[142:145], v[182:185], 0
	v_mfma_f32_16x16x32_bf16 v[46:49], v[146:149], v[186:189], v[46:49]
	v_mfma_f32_16x16x32_bf16 v[42:45], v[150:153], v[182:185], 0
	v_mfma_f32_16x16x32_bf16 v[42:45], v[154:157], v[186:189], v[42:45]
	v_mfma_f32_16x16x32_bf16 v[30:33], v[142:145], v[190:193], 0
	v_mfma_f32_16x16x32_bf16 v[30:33], v[146:149], v[194:197], v[30:33]
	v_mfma_f32_16x16x32_bf16 v[26:29], v[150:153], v[190:193], 0
	v_mfma_f32_16x16x32_bf16 v[26:29], v[154:157], v[194:197], v[26:29]
	v_mfma_f32_16x16x32_bf16 v[14:17], v[142:145], v[198:201], 0
	v_mfma_f32_16x16x32_bf16 v[14:17], v[146:149], v[212:215], v[14:17]
	v_mfma_f32_16x16x32_bf16 v[10:13], v[150:153], v[198:201], 0
	v_mfma_f32_16x16x32_bf16 v[10:13], v[154:157], v[212:215], v[10:13]
	s_setprio 0
	s_setprio 1
	v_mfma_f32_16x16x32_bf16 v[54:57], v[158:161], v[174:177], 0
	v_mfma_f32_16x16x32_bf16 v[54:57], v[162:165], v[178:181], v[54:57]
	v_mfma_f32_16x16x32_bf16 v[50:53], v[166:169], v[174:177], 0
	v_mfma_f32_16x16x32_bf16 v[50:53], v[170:173], v[178:181], v[50:53]
	v_mfma_f32_16x16x32_bf16 v[38:41], v[158:161], v[182:185], 0
	v_mfma_f32_16x16x32_bf16 v[38:41], v[162:165], v[186:189], v[38:41]
	v_mfma_f32_16x16x32_bf16 v[34:37], v[166:169], v[182:185], 0
	v_mfma_f32_16x16x32_bf16 v[34:37], v[170:173], v[186:189], v[34:37]
	v_mfma_f32_16x16x32_bf16 v[22:25], v[158:161], v[190:193], 0
	v_mfma_f32_16x16x32_bf16 v[22:25], v[162:165], v[194:197], v[22:25]
	v_mfma_f32_16x16x32_bf16 v[18:21], v[166:169], v[190:193], 0
	v_mfma_f32_16x16x32_bf16 v[18:21], v[170:173], v[194:197], v[18:21]
	v_mfma_f32_16x16x32_bf16 v[6:9], v[158:161], v[198:201], 0
	v_mfma_f32_16x16x32_bf16 v[6:9], v[162:165], v[212:215], v[6:9]
	v_mfma_f32_16x16x32_bf16 v[2:5], v[166:169], v[198:201], 0
	v_mfma_f32_16x16x32_bf16 v[2:5], v[170:173], v[212:215], v[2:5]
	s_setprio 0
	s_barrier
	v_add_u32_e32 v154, s26, v138
	v_add_u32_e32 v170, s31, v138
	ds_read_b128 v[142:145], v154
	ds_read_b128 v[146:149], v154 offset:1024
	ds_read_b128 v[150:153], v154 offset:2048
	ds_read_b128 v[154:157], v154 offset:3072
	ds_read_b128 v[158:161], v170
	ds_read_b128 v[162:165], v170 offset:1024
	ds_read_b128 v[166:169], v170 offset:2048
	ds_read_b128 v[170:173], v170 offset:3072
	s_add_i32 s44, s44, 0x80000
	s_mov_b32 m0, s24
	v_add_u32_e32 v202, s44, v131
	ds_read_b128 v[174:177], v141 offset:32768
	ds_read_b128 v[178:181], v141 offset:33792
	ds_read_b128 v[182:185], v141 offset:34816
	ds_read_b128 v[186:189], v141 offset:35840
	ds_read_b128 v[190:193], v141 offset:36864
	ds_read_b128 v[194:197], v141 offset:37888
	ds_read_b128 v[198:201], v141 offset:38912
	ds_read_b128 v[212:215], v141 offset:39936
	global_load_lds_dwordx4 v202, s[8:9]
	v_add_u32_e32 v202, s44, v135
	s_mov_b32 m0, s25
	s_nop 0
	global_load_lds_dwordx4 v202, s[8:9]
	s_waitcnt vmcnt(8)
	s_waitcnt lgkmcnt(0)
	s_setprio 1
	s_barrier
	v_mfma_f32_16x16x32_bf16 v[126:129], v[142:145], v[174:177], v[126:129]
	v_mfma_f32_16x16x32_bf16 v[126:129], v[146:149], v[178:181], v[126:129]
	v_mfma_f32_16x16x32_bf16 v[122:125], v[150:153], v[174:177], v[122:125]
	v_mfma_f32_16x16x32_bf16 v[122:125], v[154:157], v[178:181], v[122:125]
	v_mfma_f32_16x16x32_bf16 v[110:113], v[142:145], v[182:185], v[110:113]
	v_mfma_f32_16x16x32_bf16 v[110:113], v[146:149], v[186:189], v[110:113]
	v_mfma_f32_16x16x32_bf16 v[106:109], v[150:153], v[182:185], v[106:109]
	v_mfma_f32_16x16x32_bf16 v[106:109], v[154:157], v[186:189], v[106:109]
	v_mfma_f32_16x16x32_bf16 v[94:97], v[142:145], v[190:193], v[94:97]
	v_mfma_f32_16x16x32_bf16 v[94:97], v[146:149], v[194:197], v[94:97]
	v_mfma_f32_16x16x32_bf16 v[90:93], v[150:153], v[190:193], v[90:93]
	v_mfma_f32_16x16x32_bf16 v[90:93], v[154:157], v[194:197], v[90:93]
	v_mfma_f32_16x16x32_bf16 v[78:81], v[142:145], v[198:201], v[78:81]
	v_mfma_f32_16x16x32_bf16 v[78:81], v[146:149], v[212:215], v[78:81]
	v_mfma_f32_16x16x32_bf16 v[74:77], v[150:153], v[198:201], v[74:77]
	v_mfma_f32_16x16x32_bf16 v[74:77], v[154:157], v[212:215], v[74:77]
	s_setprio 0
	s_setprio 1
	v_mfma_f32_16x16x32_bf16 v[118:121], v[158:161], v[174:177], v[118:121]
	v_mfma_f32_16x16x32_bf16 v[118:121], v[162:165], v[178:181], v[118:121]
	v_mfma_f32_16x16x32_bf16 v[114:117], v[166:169], v[174:177], v[114:117]
	v_mfma_f32_16x16x32_bf16 v[114:117], v[170:173], v[178:181], v[114:117]
	v_mfma_f32_16x16x32_bf16 v[102:105], v[158:161], v[182:185], v[102:105]
	v_mfma_f32_16x16x32_bf16 v[102:105], v[162:165], v[186:189], v[102:105]
	v_mfma_f32_16x16x32_bf16 v[98:101], v[166:169], v[182:185], v[98:101]
	v_mfma_f32_16x16x32_bf16 v[98:101], v[170:173], v[186:189], v[98:101]
	v_mfma_f32_16x16x32_bf16 v[86:89], v[158:161], v[190:193], v[86:89]
	v_mfma_f32_16x16x32_bf16 v[86:89], v[162:165], v[194:197], v[86:89]
	v_mfma_f32_16x16x32_bf16 v[82:85], v[166:169], v[190:193], v[82:85]
	v_mfma_f32_16x16x32_bf16 v[82:85], v[170:173], v[194:197], v[82:85]
	v_mfma_f32_16x16x32_bf16 v[70:73], v[158:161], v[198:201], v[70:73]
	v_mfma_f32_16x16x32_bf16 v[70:73], v[162:165], v[212:215], v[70:73]
	v_mfma_f32_16x16x32_bf16 v[66:69], v[166:169], v[198:201], v[66:69]
	v_mfma_f32_16x16x32_bf16 v[66:69], v[170:173], v[212:215], v[66:69]
	s_setprio 0
	s_barrier
	s_or_b32 s37, s43, 0x80
	s_mov_b32 m0, s27
	v_add_u32_e32 v202, s37, v133
	ds_read_b128 v[174:177], v141 offset:49152
	ds_read_b128 v[178:181], v141 offset:50176
	ds_read_b128 v[182:185], v141 offset:51200
	ds_read_b128 v[186:189], v141 offset:52224
	ds_read_b128 v[190:193], v141 offset:53248
	ds_read_b128 v[194:197], v141 offset:54272
	ds_read_b128 v[198:201], v141 offset:55296
	ds_read_b128 v[212:215], v141 offset:56320
	global_load_lds_dwordx4 v202, s[10:11]
	v_add_u32_e32 v202, s37, v136
	s_mov_b32 m0, s28
	s_add_i32 s43, s43, 0x80080
	global_load_lds_dwordx4 v202, s[10:11]
	v_add_u32_e32 v202, s43, v133
	s_mov_b32 m0, s34
	s_nop 0
	global_load_lds_dwordx4 v202, s[10:11]
	v_add_u32_e32 v202, s43, v136
	s_mov_b32 m0, s35
	s_nop 0
	global_load_lds_dwordx4 v202, s[10:11]
	v_add_u32_e32 v202, s42, v131
	s_mov_b32 m0, s29
	s_nop 0
	global_load_lds_dwordx4 v202, s[8:9]
	v_add_u32_e32 v202, s42, v135
	s_mov_b32 m0, s30
	s_nop 0
	global_load_lds_dwordx4 v202, s[8:9]
	s_waitcnt vmcnt(8)
	s_waitcnt lgkmcnt(0)
	s_setprio 1
	s_barrier
	v_mfma_f32_16x16x32_bf16 v[62:65], v[142:145], v[174:177], v[62:65]
	v_mfma_f32_16x16x32_bf16 v[62:65], v[146:149], v[178:181], v[62:65]
	v_mfma_f32_16x16x32_bf16 v[58:61], v[150:153], v[174:177], v[58:61]
	v_mfma_f32_16x16x32_bf16 v[58:61], v[154:157], v[178:181], v[58:61]
	v_mfma_f32_16x16x32_bf16 v[46:49], v[142:145], v[182:185], v[46:49]
	v_mfma_f32_16x16x32_bf16 v[46:49], v[146:149], v[186:189], v[46:49]
	v_mfma_f32_16x16x32_bf16 v[42:45], v[150:153], v[182:185], v[42:45]
	v_mfma_f32_16x16x32_bf16 v[42:45], v[154:157], v[186:189], v[42:45]
	v_mfma_f32_16x16x32_bf16 v[30:33], v[142:145], v[190:193], v[30:33]
	v_mfma_f32_16x16x32_bf16 v[30:33], v[146:149], v[194:197], v[30:33]
	v_mfma_f32_16x16x32_bf16 v[26:29], v[150:153], v[190:193], v[26:29]
	v_mfma_f32_16x16x32_bf16 v[26:29], v[154:157], v[194:197], v[26:29]
	v_mfma_f32_16x16x32_bf16 v[14:17], v[142:145], v[198:201], v[14:17]
	v_mfma_f32_16x16x32_bf16 v[14:17], v[146:149], v[212:215], v[14:17]
	v_mfma_f32_16x16x32_bf16 v[10:13], v[150:153], v[198:201], v[10:13]
	v_mfma_f32_16x16x32_bf16 v[10:13], v[154:157], v[212:215], v[10:13]
	s_setprio 0
	s_setprio 1
	v_mfma_f32_16x16x32_bf16 v[54:57], v[158:161], v[174:177], v[54:57]
	v_mfma_f32_16x16x32_bf16 v[54:57], v[162:165], v[178:181], v[54:57]
	v_mfma_f32_16x16x32_bf16 v[50:53], v[166:169], v[174:177], v[50:53]
	v_mfma_f32_16x16x32_bf16 v[50:53], v[170:173], v[178:181], v[50:53]
	v_mfma_f32_16x16x32_bf16 v[38:41], v[158:161], v[182:185], v[38:41]
	v_mfma_f32_16x16x32_bf16 v[38:41], v[162:165], v[186:189], v[38:41]
	v_mfma_f32_16x16x32_bf16 v[34:37], v[166:169], v[182:185], v[34:37]
	v_mfma_f32_16x16x32_bf16 v[34:37], v[170:173], v[186:189], v[34:37]
	v_mfma_f32_16x16x32_bf16 v[22:25], v[158:161], v[190:193], v[22:25]
	v_mfma_f32_16x16x32_bf16 v[22:25], v[162:165], v[194:197], v[22:25]
	v_mfma_f32_16x16x32_bf16 v[18:21], v[166:169], v[190:193], v[18:21]
	v_mfma_f32_16x16x32_bf16 v[18:21], v[170:173], v[194:197], v[18:21]
	v_mfma_f32_16x16x32_bf16 v[6:9], v[158:161], v[198:201], v[6:9]
	v_mfma_f32_16x16x32_bf16 v[6:9], v[162:165], v[212:215], v[6:9]
	v_mfma_f32_16x16x32_bf16 v[2:5], v[166:169], v[198:201], v[2:5]
	v_mfma_f32_16x16x32_bf16 v[2:5], v[170:173], v[212:215], v[2:5]
	s_setprio 0
	s_barrier
	s_add_i32 s36, s36, 2
	s_cmp_gt_u32 s36, 29
	s_mov_b32 s37, s41
.LBB0_314:
	v_add_u32_e32 v154, s3, v138
	v_add_u32_e32 v170, s18, v138
	ds_read_b128 v[142:145], v154
	ds_read_b128 v[146:149], v154 offset:1024
	ds_read_b128 v[150:153], v154 offset:2048
	ds_read_b128 v[154:157], v154 offset:3072
	ds_read_b128 v[158:161], v170
	ds_read_b128 v[162:165], v170 offset:1024
	ds_read_b128 v[166:169], v170 offset:2048
	ds_read_b128 v[170:173], v170 offset:3072
	s_add_i32 s41, s37, 0x100
	s_cmp_lg_u32 s36, 28
	s_cselect_b32 s43, s41, 0
	s_add_i32 s44, s43, s21
	s_or_b32 s42, s44, 0x80
	s_add_i32 s43, s43, s2
	v_add_u32_e32 v202, s37, v140
	s_add_i32 m0, s22, 0xc000
	ds_read_b128 v[174:177], v141
	ds_read_b128 v[178:181], v141 offset:1024
	ds_read_b128 v[182:185], v141 offset:2048
	ds_read_b128 v[186:189], v141 offset:3072
	ds_read_b128 v[190:193], v141 offset:4096
	ds_read_b128 v[194:197], v141 offset:5120
	ds_read_b128 v[198:201], v141 offset:6144
	ds_read_b128 v[212:215], v141 offset:7168
	global_load_lds_dwordx4 v202, s[8:9]
	v_add_u32_e32 v202, s37, v139
	s_add_i32 m0, s22, 0xe000
	s_nop 0
	global_load_lds_dwordx4 v202, s[8:9]
	s_waitcnt vmcnt(8)
	s_waitcnt lgkmcnt(0)
	s_setprio 1
	s_barrier
	v_mfma_f32_16x16x32_bf16 v[126:129], v[142:145], v[174:177], v[126:129]
	v_mfma_f32_16x16x32_bf16 v[126:129], v[146:149], v[178:181], v[126:129]
	v_mfma_f32_16x16x32_bf16 v[122:125], v[150:153], v[174:177], v[122:125]
	v_mfma_f32_16x16x32_bf16 v[122:125], v[154:157], v[178:181], v[122:125]
	v_mfma_f32_16x16x32_bf16 v[110:113], v[142:145], v[182:185], v[110:113]
	v_mfma_f32_16x16x32_bf16 v[110:113], v[146:149], v[186:189], v[110:113]
	v_mfma_f32_16x16x32_bf16 v[106:109], v[150:153], v[182:185], v[106:109]
	v_mfma_f32_16x16x32_bf16 v[106:109], v[154:157], v[186:189], v[106:109]
	v_mfma_f32_16x16x32_bf16 v[94:97], v[142:145], v[190:193], v[94:97]
	v_mfma_f32_16x16x32_bf16 v[94:97], v[146:149], v[194:197], v[94:97]
	v_mfma_f32_16x16x32_bf16 v[90:93], v[150:153], v[190:193], v[90:93]
	v_mfma_f32_16x16x32_bf16 v[90:93], v[154:157], v[194:197], v[90:93]
	v_mfma_f32_16x16x32_bf16 v[78:81], v[142:145], v[198:201], v[78:81]
	v_mfma_f32_16x16x32_bf16 v[78:81], v[146:149], v[212:215], v[78:81]
	v_mfma_f32_16x16x32_bf16 v[74:77], v[150:153], v[198:201], v[74:77]
	v_mfma_f32_16x16x32_bf16 v[74:77], v[154:157], v[212:215], v[74:77]
	s_setprio 0
	s_setprio 1
	v_mfma_f32_16x16x32_bf16 v[118:121], v[158:161], v[174:177], v[118:121]
	v_mfma_f32_16x16x32_bf16 v[118:121], v[162:165], v[178:181], v[118:121]
	v_mfma_f32_16x16x32_bf16 v[114:117], v[166:169], v[174:177], v[114:117]
	v_mfma_f32_16x16x32_bf16 v[114:117], v[170:173], v[178:181], v[114:117]
	v_mfma_f32_16x16x32_bf16 v[102:105], v[158:161], v[182:185], v[102:105]
	v_mfma_f32_16x16x32_bf16 v[102:105], v[162:165], v[186:189], v[102:105]
	v_mfma_f32_16x16x32_bf16 v[98:101], v[166:169], v[182:185], v[98:101]
	v_mfma_f32_16x16x32_bf16 v[98:101], v[170:173], v[186:189], v[98:101]
	v_mfma_f32_16x16x32_bf16 v[86:89], v[158:161], v[190:193], v[86:89]
	v_mfma_f32_16x16x32_bf16 v[86:89], v[162:165], v[194:197], v[86:89]
	v_mfma_f32_16x16x32_bf16 v[82:85], v[166:169], v[190:193], v[82:85]
	v_mfma_f32_16x16x32_bf16 v[82:85], v[170:173], v[194:197], v[82:85]
	v_mfma_f32_16x16x32_bf16 v[70:73], v[158:161], v[198:201], v[70:73]
	v_mfma_f32_16x16x32_bf16 v[70:73], v[162:165], v[212:215], v[70:73]
	v_mfma_f32_16x16x32_bf16 v[66:69], v[166:169], v[198:201], v[66:69]
	v_mfma_f32_16x16x32_bf16 v[66:69], v[170:173], v[212:215], v[66:69]
	s_setprio 0
	s_barrier
	s_mov_b32 m0, s16
	v_add_u32_e32 v202, s43, v133
	ds_read_b128 v[174:177], v141 offset:16384
	ds_read_b128 v[178:181], v141 offset:17408
	ds_read_b128 v[182:185], v141 offset:18432
	ds_read_b128 v[186:189], v141 offset:19456
	ds_read_b128 v[190:193], v141 offset:20480
	ds_read_b128 v[194:197], v141 offset:21504
	ds_read_b128 v[198:201], v141 offset:22528
	ds_read_b128 v[212:215], v141 offset:23552
	global_load_lds_dwordx4 v202, s[10:11]
	v_add_u32_e32 v202, s43, v136
	s_mov_b32 m0, s17
	s_add_i32 s37, s43, 0x80000
	global_load_lds_dwordx4 v202, s[10:11]
	v_add_u32_e32 v202, s37, v133
	s_mov_b32 m0, s19
	s_nop 0
	global_load_lds_dwordx4 v202, s[10:11]
	v_add_u32_e32 v202, s37, v136
	s_mov_b32 m0, s20
	s_nop 0
	global_load_lds_dwordx4 v202, s[10:11]
	v_add_u32_e32 v202, s44, v131
	s_mov_b32 m0, s22
	s_nop 0
	global_load_lds_dwordx4 v202, s[8:9]
	v_add_u32_e32 v202, s44, v135
	s_mov_b32 m0, s23
	s_nop 0
	global_load_lds_dwordx4 v202, s[8:9]
	s_waitcnt vmcnt(8)
	s_waitcnt lgkmcnt(0)
	s_setprio 1
	s_barrier
	v_mfma_f32_16x16x32_bf16 v[62:65], v[142:145], v[174:177], v[62:65]
	v_mfma_f32_16x16x32_bf16 v[62:65], v[146:149], v[178:181], v[62:65]
	v_mfma_f32_16x16x32_bf16 v[58:61], v[150:153], v[174:177], v[58:61]
	v_mfma_f32_16x16x32_bf16 v[58:61], v[154:157], v[178:181], v[58:61]
	v_mfma_f32_16x16x32_bf16 v[46:49], v[142:145], v[182:185], v[46:49]
	v_mfma_f32_16x16x32_bf16 v[46:49], v[146:149], v[186:189], v[46:49]
	v_mfma_f32_16x16x32_bf16 v[42:45], v[150:153], v[182:185], v[42:45]
	v_mfma_f32_16x16x32_bf16 v[42:45], v[154:157], v[186:189], v[42:45]
	v_mfma_f32_16x16x32_bf16 v[30:33], v[142:145], v[190:193], v[30:33]
	v_mfma_f32_16x16x32_bf16 v[30:33], v[146:149], v[194:197], v[30:33]
	v_mfma_f32_16x16x32_bf16 v[26:29], v[150:153], v[190:193], v[26:29]
	v_mfma_f32_16x16x32_bf16 v[26:29], v[154:157], v[194:197], v[26:29]
	v_mfma_f32_16x16x32_bf16 v[14:17], v[142:145], v[198:201], v[14:17]
	v_mfma_f32_16x16x32_bf16 v[14:17], v[146:149], v[212:215], v[14:17]
	v_mfma_f32_16x16x32_bf16 v[10:13], v[150:153], v[198:201], v[10:13]
	v_mfma_f32_16x16x32_bf16 v[10:13], v[154:157], v[212:215], v[10:13]
	s_setprio 0
	s_setprio 1
	v_mfma_f32_16x16x32_bf16 v[54:57], v[158:161], v[174:177], v[54:57]
	v_mfma_f32_16x16x32_bf16 v[54:57], v[162:165], v[178:181], v[54:57]
	v_mfma_f32_16x16x32_bf16 v[50:53], v[166:169], v[174:177], v[50:53]
	v_mfma_f32_16x16x32_bf16 v[50:53], v[170:173], v[178:181], v[50:53]
	v_mfma_f32_16x16x32_bf16 v[38:41], v[158:161], v[182:185], v[38:41]
	v_mfma_f32_16x16x32_bf16 v[38:41], v[162:165], v[186:189], v[38:41]
	v_mfma_f32_16x16x32_bf16 v[34:37], v[166:169], v[182:185], v[34:37]
	v_mfma_f32_16x16x32_bf16 v[34:37], v[170:173], v[186:189], v[34:37]
	v_mfma_f32_16x16x32_bf16 v[22:25], v[158:161], v[190:193], v[22:25]
	v_mfma_f32_16x16x32_bf16 v[22:25], v[162:165], v[194:197], v[22:25]
	v_mfma_f32_16x16x32_bf16 v[18:21], v[166:169], v[190:193], v[18:21]
	v_mfma_f32_16x16x32_bf16 v[18:21], v[170:173], v[194:197], v[18:21]
	v_mfma_f32_16x16x32_bf16 v[6:9], v[158:161], v[198:201], v[6:9]
	v_mfma_f32_16x16x32_bf16 v[6:9], v[162:165], v[212:215], v[6:9]
	v_mfma_f32_16x16x32_bf16 v[2:5], v[166:169], v[198:201], v[2:5]
	v_mfma_f32_16x16x32_bf16 v[2:5], v[170:173], v[212:215], v[2:5]
	s_setprio 0
	s_barrier
	v_add_u32_e32 v154, s26, v138
	v_add_u32_e32 v170, s31, v138
	ds_read_b128 v[142:145], v154
	ds_read_b128 v[146:149], v154 offset:1024
	ds_read_b128 v[150:153], v154 offset:2048
	ds_read_b128 v[154:157], v154 offset:3072
	ds_read_b128 v[158:161], v170
	ds_read_b128 v[162:165], v170 offset:1024
	ds_read_b128 v[166:169], v170 offset:2048
	ds_read_b128 v[170:173], v170 offset:3072
	s_add_i32 s44, s44, 0x80000
	s_mov_b32 m0, s24
	v_add_u32_e32 v202, s44, v131
	ds_read_b128 v[174:177], v141 offset:32768
	ds_read_b128 v[178:181], v141 offset:33792
	ds_read_b128 v[182:185], v141 offset:34816
	ds_read_b128 v[186:189], v141 offset:35840
	ds_read_b128 v[190:193], v141 offset:36864
	ds_read_b128 v[194:197], v141 offset:37888
	ds_read_b128 v[198:201], v141 offset:38912
	ds_read_b128 v[212:215], v141 offset:39936
	global_load_lds_dwordx4 v202, s[8:9]
	v_add_u32_e32 v202, s44, v135
	s_mov_b32 m0, s25
	s_nop 0
	global_load_lds_dwordx4 v202, s[8:9]
	s_waitcnt vmcnt(8)
	s_waitcnt lgkmcnt(0)
	s_setprio 1
	s_barrier
	v_mfma_f32_16x16x32_bf16 v[126:129], v[142:145], v[174:177], v[126:129]
	v_mfma_f32_16x16x32_bf16 v[126:129], v[146:149], v[178:181], v[126:129]
	v_mfma_f32_16x16x32_bf16 v[122:125], v[150:153], v[174:177], v[122:125]
	v_mfma_f32_16x16x32_bf16 v[122:125], v[154:157], v[178:181], v[122:125]
	v_mfma_f32_16x16x32_bf16 v[110:113], v[142:145], v[182:185], v[110:113]
	v_mfma_f32_16x16x32_bf16 v[110:113], v[146:149], v[186:189], v[110:113]
	v_mfma_f32_16x16x32_bf16 v[106:109], v[150:153], v[182:185], v[106:109]
	v_mfma_f32_16x16x32_bf16 v[106:109], v[154:157], v[186:189], v[106:109]
	v_mfma_f32_16x16x32_bf16 v[94:97], v[142:145], v[190:193], v[94:97]
	v_mfma_f32_16x16x32_bf16 v[94:97], v[146:149], v[194:197], v[94:97]
	v_mfma_f32_16x16x32_bf16 v[90:93], v[150:153], v[190:193], v[90:93]
	v_mfma_f32_16x16x32_bf16 v[90:93], v[154:157], v[194:197], v[90:93]
	v_mfma_f32_16x16x32_bf16 v[78:81], v[142:145], v[198:201], v[78:81]
	v_mfma_f32_16x16x32_bf16 v[78:81], v[146:149], v[212:215], v[78:81]
	v_mfma_f32_16x16x32_bf16 v[74:77], v[150:153], v[198:201], v[74:77]
	v_mfma_f32_16x16x32_bf16 v[74:77], v[154:157], v[212:215], v[74:77]
	s_setprio 0
	s_setprio 1
	v_mfma_f32_16x16x32_bf16 v[118:121], v[158:161], v[174:177], v[118:121]
	v_mfma_f32_16x16x32_bf16 v[118:121], v[162:165], v[178:181], v[118:121]
	v_mfma_f32_16x16x32_bf16 v[114:117], v[166:169], v[174:177], v[114:117]
	v_mfma_f32_16x16x32_bf16 v[114:117], v[170:173], v[178:181], v[114:117]
	v_mfma_f32_16x16x32_bf16 v[102:105], v[158:161], v[182:185], v[102:105]
	v_mfma_f32_16x16x32_bf16 v[102:105], v[162:165], v[186:189], v[102:105]
	v_mfma_f32_16x16x32_bf16 v[98:101], v[166:169], v[182:185], v[98:101]
	v_mfma_f32_16x16x32_bf16 v[98:101], v[170:173], v[186:189], v[98:101]
	v_mfma_f32_16x16x32_bf16 v[86:89], v[158:161], v[190:193], v[86:89]
	v_mfma_f32_16x16x32_bf16 v[86:89], v[162:165], v[194:197], v[86:89]
	v_mfma_f32_16x16x32_bf16 v[82:85], v[166:169], v[190:193], v[82:85]
	v_mfma_f32_16x16x32_bf16 v[82:85], v[170:173], v[194:197], v[82:85]
	v_mfma_f32_16x16x32_bf16 v[70:73], v[158:161], v[198:201], v[70:73]
	v_mfma_f32_16x16x32_bf16 v[70:73], v[162:165], v[212:215], v[70:73]
	v_mfma_f32_16x16x32_bf16 v[66:69], v[166:169], v[198:201], v[66:69]
	v_mfma_f32_16x16x32_bf16 v[66:69], v[170:173], v[212:215], v[66:69]
	s_setprio 0
	s_barrier
	s_or_b32 s37, s43, 0x80
	s_mov_b32 m0, s27
	v_add_u32_e32 v202, s37, v133
	ds_read_b128 v[174:177], v141 offset:49152
	ds_read_b128 v[178:181], v141 offset:50176
	ds_read_b128 v[182:185], v141 offset:51200
	ds_read_b128 v[186:189], v141 offset:52224
	ds_read_b128 v[190:193], v141 offset:53248
	ds_read_b128 v[194:197], v141 offset:54272
	ds_read_b128 v[198:201], v141 offset:55296
	ds_read_b128 v[212:215], v141 offset:56320
	global_load_lds_dwordx4 v202, s[10:11]
	v_add_u32_e32 v202, s37, v136
	s_mov_b32 m0, s28
	s_add_i32 s43, s43, 0x80080
	global_load_lds_dwordx4 v202, s[10:11]
	v_add_u32_e32 v202, s43, v133
	s_mov_b32 m0, s34
	s_nop 0
	global_load_lds_dwordx4 v202, s[10:11]
	v_add_u32_e32 v202, s43, v136
	s_mov_b32 m0, s35
	s_nop 0
	global_load_lds_dwordx4 v202, s[10:11]
	v_add_u32_e32 v202, s42, v131
	s_mov_b32 m0, s29
	s_nop 0
	global_load_lds_dwordx4 v202, s[8:9]
	v_add_u32_e32 v202, s42, v135
	s_mov_b32 m0, s30
	s_nop 0
	global_load_lds_dwordx4 v202, s[8:9]
	s_waitcnt vmcnt(8)
	s_waitcnt lgkmcnt(0)
	s_setprio 1
	s_barrier
	v_mfma_f32_16x16x32_bf16 v[62:65], v[142:145], v[174:177], v[62:65]
	v_mfma_f32_16x16x32_bf16 v[62:65], v[146:149], v[178:181], v[62:65]
	v_mfma_f32_16x16x32_bf16 v[58:61], v[150:153], v[174:177], v[58:61]
	v_mfma_f32_16x16x32_bf16 v[58:61], v[154:157], v[178:181], v[58:61]
	v_mfma_f32_16x16x32_bf16 v[46:49], v[142:145], v[182:185], v[46:49]
	v_mfma_f32_16x16x32_bf16 v[46:49], v[146:149], v[186:189], v[46:49]
	v_mfma_f32_16x16x32_bf16 v[42:45], v[150:153], v[182:185], v[42:45]
	v_mfma_f32_16x16x32_bf16 v[42:45], v[154:157], v[186:189], v[42:45]
	v_mfma_f32_16x16x32_bf16 v[30:33], v[142:145], v[190:193], v[30:33]
	v_mfma_f32_16x16x32_bf16 v[30:33], v[146:149], v[194:197], v[30:33]
	v_mfma_f32_16x16x32_bf16 v[26:29], v[150:153], v[190:193], v[26:29]
	v_mfma_f32_16x16x32_bf16 v[26:29], v[154:157], v[194:197], v[26:29]
	v_mfma_f32_16x16x32_bf16 v[14:17], v[142:145], v[198:201], v[14:17]
	v_mfma_f32_16x16x32_bf16 v[14:17], v[146:149], v[212:215], v[14:17]
	v_mfma_f32_16x16x32_bf16 v[10:13], v[150:153], v[198:201], v[10:13]
	v_mfma_f32_16x16x32_bf16 v[10:13], v[154:157], v[212:215], v[10:13]
	s_setprio 0
	s_setprio 1
	v_mfma_f32_16x16x32_bf16 v[54:57], v[158:161], v[174:177], v[54:57]
	v_mfma_f32_16x16x32_bf16 v[54:57], v[162:165], v[178:181], v[54:57]
	v_mfma_f32_16x16x32_bf16 v[50:53], v[166:169], v[174:177], v[50:53]
	v_mfma_f32_16x16x32_bf16 v[50:53], v[170:173], v[178:181], v[50:53]
	v_mfma_f32_16x16x32_bf16 v[38:41], v[158:161], v[182:185], v[38:41]
	v_mfma_f32_16x16x32_bf16 v[38:41], v[162:165], v[186:189], v[38:41]
	v_mfma_f32_16x16x32_bf16 v[34:37], v[166:169], v[182:185], v[34:37]
	v_mfma_f32_16x16x32_bf16 v[34:37], v[170:173], v[186:189], v[34:37]
	v_mfma_f32_16x16x32_bf16 v[22:25], v[158:161], v[190:193], v[22:25]
	v_mfma_f32_16x16x32_bf16 v[22:25], v[162:165], v[194:197], v[22:25]
	v_mfma_f32_16x16x32_bf16 v[18:21], v[166:169], v[190:193], v[18:21]
	v_mfma_f32_16x16x32_bf16 v[18:21], v[170:173], v[194:197], v[18:21]
	v_mfma_f32_16x16x32_bf16 v[6:9], v[158:161], v[198:201], v[6:9]
	v_mfma_f32_16x16x32_bf16 v[6:9], v[162:165], v[212:215], v[6:9]
	v_mfma_f32_16x16x32_bf16 v[2:5], v[166:169], v[198:201], v[2:5]
	v_mfma_f32_16x16x32_bf16 v[2:5], v[170:173], v[212:215], v[2:5]
	s_setprio 0
	s_barrier
	s_add_i32 s36, s36, 2
	s_cmp_gt_u32 s36, 29
	s_mov_b32 s37, s41
	s_cbranch_scc0 .LBB0_314
	s_cmpk_lt_u32 s15, 0x100
	s_cbranch_scc0 .LBB0_317
	s_barrier

.LBB0_568:
	v_add_u32_e32 v142, s29, v201
	v_add_u32_e32 v158, s34, v201
	ds_read_b128 v[130:133], v142
	ds_read_b128 v[134:137], v142 offset:1024
	ds_read_b128 v[138:141], v142 offset:2048
	ds_read_b128 v[142:145], v142 offset:3072
	ds_read_b128 v[146:149], v158
	ds_read_b128 v[150:153], v158 offset:1024
	ds_read_b128 v[154:157], v158 offset:2048
	ds_read_b128 v[158:161], v158 offset:3072
	s_add_i32 s22, s62, 0x100
	s_add_i32 s23, s22, s59
	s_add_i32 s24, s15, s62
	s_cmpk_eq_i32 s62, 0xf00
	s_cselect_b32 s25, s60, s23
	s_cselect_b32 s24, s61, s24
	s_or_b32 s23, s25, 0x80
	v_add_u32_e32 v204, s62, v218
	s_add_i32 m0, s37, 0xc000
	ds_read_b128 v[162:165], v215
	ds_read_b128 v[166:169], v215 offset:1024
	ds_read_b128 v[170:173], v215 offset:2048
	ds_read_b128 v[174:177], v215 offset:3072
	ds_read_b128 v[178:181], v215 offset:4096
	ds_read_b128 v[182:185], v215 offset:5120
	ds_read_b128 v[186:189], v215 offset:6144
	ds_read_b128 v[190:193], v215 offset:7168
	global_load_lds_dwordx4 v204, s[0:1]
	v_add_u32_e32 v204, s62, v216
	s_add_i32 m0, s37, 0xe000
	s_nop 0
	global_load_lds_dwordx4 v204, s[0:1]
	s_waitcnt vmcnt(8)
	s_waitcnt lgkmcnt(0)
	s_setprio 1
	s_barrier
	v_mfma_f32_16x16x32_bf16 v[126:129], v[130:133], v[162:165], v[126:129]
	v_mfma_f32_16x16x32_bf16 v[126:129], v[134:137], v[166:169], v[126:129]
	v_mfma_f32_16x16x32_bf16 v[122:125], v[138:141], v[162:165], v[122:125]
	v_mfma_f32_16x16x32_bf16 v[122:125], v[142:145], v[166:169], v[122:125]
	v_mfma_f32_16x16x32_bf16 v[110:113], v[130:133], v[170:173], v[110:113]
	v_mfma_f32_16x16x32_bf16 v[110:113], v[134:137], v[174:177], v[110:113]
	v_mfma_f32_16x16x32_bf16 v[106:109], v[138:141], v[170:173], v[106:109]
	v_mfma_f32_16x16x32_bf16 v[106:109], v[142:145], v[174:177], v[106:109]
	v_mfma_f32_16x16x32_bf16 v[94:97], v[130:133], v[178:181], v[94:97]
	v_mfma_f32_16x16x32_bf16 v[94:97], v[134:137], v[182:185], v[94:97]
	v_mfma_f32_16x16x32_bf16 v[90:93], v[138:141], v[178:181], v[90:93]
	v_mfma_f32_16x16x32_bf16 v[90:93], v[142:145], v[182:185], v[90:93]
	v_mfma_f32_16x16x32_bf16 v[78:81], v[130:133], v[186:189], v[78:81]
	v_mfma_f32_16x16x32_bf16 v[78:81], v[134:137], v[190:193], v[78:81]
	v_mfma_f32_16x16x32_bf16 v[74:77], v[138:141], v[186:189], v[74:77]
	v_mfma_f32_16x16x32_bf16 v[74:77], v[142:145], v[190:193], v[74:77]
	s_setprio 0
	s_setprio 1
	v_mfma_f32_16x16x32_bf16 v[118:121], v[146:149], v[162:165], v[118:121]
	v_mfma_f32_16x16x32_bf16 v[118:121], v[150:153], v[166:169], v[118:121]
	v_mfma_f32_16x16x32_bf16 v[114:117], v[154:157], v[162:165], v[114:117]
	v_mfma_f32_16x16x32_bf16 v[114:117], v[158:161], v[166:169], v[114:117]
	v_mfma_f32_16x16x32_bf16 v[102:105], v[146:149], v[170:173], v[102:105]
	v_mfma_f32_16x16x32_bf16 v[102:105], v[150:153], v[174:177], v[102:105]
	v_mfma_f32_16x16x32_bf16 v[98:101], v[154:157], v[170:173], v[98:101]
	v_mfma_f32_16x16x32_bf16 v[98:101], v[158:161], v[174:177], v[98:101]
	v_mfma_f32_16x16x32_bf16 v[86:89], v[146:149], v[178:181], v[86:89]
	v_mfma_f32_16x16x32_bf16 v[86:89], v[150:153], v[182:185], v[86:89]
	v_mfma_f32_16x16x32_bf16 v[82:85], v[154:157], v[178:181], v[82:85]
	v_mfma_f32_16x16x32_bf16 v[82:85], v[158:161], v[182:185], v[82:85]
	v_mfma_f32_16x16x32_bf16 v[70:73], v[146:149], v[186:189], v[70:73]
	v_mfma_f32_16x16x32_bf16 v[70:73], v[150:153], v[190:193], v[70:73]
	v_mfma_f32_16x16x32_bf16 v[66:69], v[154:157], v[186:189], v[66:69]
	v_mfma_f32_16x16x32_bf16 v[66:69], v[158:161], v[190:193], v[66:69]
	s_setprio 0
	s_barrier
	s_mov_b32 m0, s30
	v_add_u32_e32 v204, s24, v197
	ds_read_b128 v[162:165], v215 offset:16384
	ds_read_b128 v[166:169], v215 offset:17408
	ds_read_b128 v[170:173], v215 offset:18432
	ds_read_b128 v[174:177], v215 offset:19456
	ds_read_b128 v[178:181], v215 offset:20480
	ds_read_b128 v[182:185], v215 offset:21504
	ds_read_b128 v[186:189], v215 offset:22528
	ds_read_b128 v[190:193], v215 offset:23552
	global_load_lds_dwordx4 v204, s[2:3]
	v_add_u32_e32 v204, s24, v199
	s_mov_b32 m0, s31
	s_add_i32 s62, s24, 0x80000
	global_load_lds_dwordx4 v204, s[2:3]
	v_add_u32_e32 v204, s62, v197
	s_mov_b32 m0, s35
	s_nop 0
	global_load_lds_dwordx4 v204, s[2:3]
	v_add_u32_e32 v204, s62, v199
	s_mov_b32 m0, s36
	s_nop 0
	global_load_lds_dwordx4 v204, s[2:3]
	v_add_u32_e32 v204, s25, v196
	s_mov_b32 m0, s37
	s_nop 0
	global_load_lds_dwordx4 v204, s[0:1]
	v_add_u32_e32 v204, s25, v198
	s_mov_b32 m0, s38
	s_nop 0
	global_load_lds_dwordx4 v204, s[0:1]
	s_waitcnt vmcnt(8)
	s_waitcnt lgkmcnt(0)
	s_setprio 1
	s_barrier
	v_mfma_f32_16x16x32_bf16 v[62:65], v[130:133], v[162:165], v[62:65]
	v_mfma_f32_16x16x32_bf16 v[62:65], v[134:137], v[166:169], v[62:65]
	v_mfma_f32_16x16x32_bf16 v[58:61], v[138:141], v[162:165], v[58:61]
	v_mfma_f32_16x16x32_bf16 v[58:61], v[142:145], v[166:169], v[58:61]
	v_mfma_f32_16x16x32_bf16 v[46:49], v[130:133], v[170:173], v[46:49]
	v_mfma_f32_16x16x32_bf16 v[46:49], v[134:137], v[174:177], v[46:49]
	v_mfma_f32_16x16x32_bf16 v[42:45], v[138:141], v[170:173], v[42:45]
	v_mfma_f32_16x16x32_bf16 v[42:45], v[142:145], v[174:177], v[42:45]
	v_mfma_f32_16x16x32_bf16 v[30:33], v[130:133], v[178:181], v[30:33]
	v_mfma_f32_16x16x32_bf16 v[30:33], v[134:137], v[182:185], v[30:33]
	v_mfma_f32_16x16x32_bf16 v[26:29], v[138:141], v[178:181], v[26:29]
	v_mfma_f32_16x16x32_bf16 v[26:29], v[142:145], v[182:185], v[26:29]
	v_mfma_f32_16x16x32_bf16 v[14:17], v[130:133], v[186:189], v[14:17]
	v_mfma_f32_16x16x32_bf16 v[14:17], v[134:137], v[190:193], v[14:17]
	v_mfma_f32_16x16x32_bf16 v[10:13], v[138:141], v[186:189], v[10:13]
	v_mfma_f32_16x16x32_bf16 v[10:13], v[142:145], v[190:193], v[10:13]
	s_setprio 0
	s_setprio 1
	v_mfma_f32_16x16x32_bf16 v[54:57], v[146:149], v[162:165], v[54:57]
	v_mfma_f32_16x16x32_bf16 v[54:57], v[150:153], v[166:169], v[54:57]
	v_mfma_f32_16x16x32_bf16 v[50:53], v[154:157], v[162:165], v[50:53]
	v_mfma_f32_16x16x32_bf16 v[50:53], v[158:161], v[166:169], v[50:53]
	v_mfma_f32_16x16x32_bf16 v[38:41], v[146:149], v[170:173], v[38:41]
	v_mfma_f32_16x16x32_bf16 v[38:41], v[150:153], v[174:177], v[38:41]
	v_mfma_f32_16x16x32_bf16 v[34:37], v[154:157], v[170:173], v[34:37]
	v_mfma_f32_16x16x32_bf16 v[34:37], v[158:161], v[174:177], v[34:37]
	v_mfma_f32_16x16x32_bf16 v[22:25], v[146:149], v[178:181], v[22:25]
	v_mfma_f32_16x16x32_bf16 v[22:25], v[150:153], v[182:185], v[22:25]
	v_mfma_f32_16x16x32_bf16 v[18:21], v[154:157], v[178:181], v[18:21]
	v_mfma_f32_16x16x32_bf16 v[18:21], v[158:161], v[182:185], v[18:21]
	v_mfma_f32_16x16x32_bf16 v[6:9], v[146:149], v[186:189], v[6:9]
	v_mfma_f32_16x16x32_bf16 v[6:9], v[150:153], v[190:193], v[6:9]
	v_mfma_f32_16x16x32_bf16 v[2:5], v[154:157], v[186:189], v[2:5]
	v_mfma_f32_16x16x32_bf16 v[2:5], v[158:161], v[190:193], v[2:5]
	s_setprio 0
	s_barrier
	v_add_u32_e32 v142, s43, v201
	v_add_u32_e32 v158, s48, v201
	ds_read_b128 v[130:133], v142
	ds_read_b128 v[134:137], v142 offset:1024
	ds_read_b128 v[138:141], v142 offset:2048
	ds_read_b128 v[142:145], v142 offset:3072
	ds_read_b128 v[146:149], v158
	ds_read_b128 v[150:153], v158 offset:1024
	ds_read_b128 v[154:157], v158 offset:2048
	ds_read_b128 v[158:161], v158 offset:3072
	s_add_i32 s25, s25, 0x80000
	s_mov_b32 m0, s39
	v_add_u32_e32 v204, s25, v196
	ds_read_b128 v[162:165], v215 offset:32768
	ds_read_b128 v[166:169], v215 offset:33792
	ds_read_b128 v[170:173], v215 offset:34816
	ds_read_b128 v[174:177], v215 offset:35840
	ds_read_b128 v[178:181], v215 offset:36864
	ds_read_b128 v[182:185], v215 offset:37888
	ds_read_b128 v[186:189], v215 offset:38912
	ds_read_b128 v[190:193], v215 offset:39936
	global_load_lds_dwordx4 v204, s[0:1]
	v_add_u32_e32 v204, s25, v198
	s_mov_b32 m0, s40
	s_nop 0
	global_load_lds_dwordx4 v204, s[0:1]
	s_waitcnt vmcnt(8)
	s_waitcnt lgkmcnt(0)
	s_setprio 1
	s_barrier
	v_mfma_f32_16x16x32_bf16 v[126:129], v[130:133], v[162:165], v[126:129]
	v_mfma_f32_16x16x32_bf16 v[126:129], v[134:137], v[166:169], v[126:129]
	v_mfma_f32_16x16x32_bf16 v[122:125], v[138:141], v[162:165], v[122:125]
	v_mfma_f32_16x16x32_bf16 v[122:125], v[142:145], v[166:169], v[122:125]
	v_mfma_f32_16x16x32_bf16 v[110:113], v[130:133], v[170:173], v[110:113]
	v_mfma_f32_16x16x32_bf16 v[110:113], v[134:137], v[174:177], v[110:113]
	v_mfma_f32_16x16x32_bf16 v[106:109], v[138:141], v[170:173], v[106:109]
	v_mfma_f32_16x16x32_bf16 v[106:109], v[142:145], v[174:177], v[106:109]
	v_mfma_f32_16x16x32_bf16 v[94:97], v[130:133], v[178:181], v[94:97]
	v_mfma_f32_16x16x32_bf16 v[94:97], v[134:137], v[182:185], v[94:97]
	v_mfma_f32_16x16x32_bf16 v[90:93], v[138:141], v[178:181], v[90:93]
	v_mfma_f32_16x16x32_bf16 v[90:93], v[142:145], v[182:185], v[90:93]
	v_mfma_f32_16x16x32_bf16 v[78:81], v[130:133], v[186:189], v[78:81]
	v_mfma_f32_16x16x32_bf16 v[78:81], v[134:137], v[190:193], v[78:81]
	v_mfma_f32_16x16x32_bf16 v[74:77], v[138:141], v[186:189], v[74:77]
	v_mfma_f32_16x16x32_bf16 v[74:77], v[142:145], v[190:193], v[74:77]
	s_setprio 0
	s_setprio 1
	v_mfma_f32_16x16x32_bf16 v[118:121], v[146:149], v[162:165], v[118:121]
	v_mfma_f32_16x16x32_bf16 v[118:121], v[150:153], v[166:169], v[118:121]
	v_mfma_f32_16x16x32_bf16 v[114:117], v[154:157], v[162:165], v[114:117]
	v_mfma_f32_16x16x32_bf16 v[114:117], v[158:161], v[166:169], v[114:117]
	v_mfma_f32_16x16x32_bf16 v[102:105], v[146:149], v[170:173], v[102:105]
	v_mfma_f32_16x16x32_bf16 v[102:105], v[150:153], v[174:177], v[102:105]
	v_mfma_f32_16x16x32_bf16 v[98:101], v[154:157], v[170:173], v[98:101]
	v_mfma_f32_16x16x32_bf16 v[98:101], v[158:161], v[174:177], v[98:101]
	v_mfma_f32_16x16x32_bf16 v[86:89], v[146:149], v[178:181], v[86:89]
	v_mfma_f32_16x16x32_bf16 v[86:89], v[150:153], v[182:185], v[86:89]
	v_mfma_f32_16x16x32_bf16 v[82:85], v[154:157], v[178:181], v[82:85]
	v_mfma_f32_16x16x32_bf16 v[82:85], v[158:161], v[182:185], v[82:85]
	v_mfma_f32_16x16x32_bf16 v[70:73], v[146:149], v[186:189], v[70:73]
	v_mfma_f32_16x16x32_bf16 v[70:73], v[150:153], v[190:193], v[70:73]
	v_mfma_f32_16x16x32_bf16 v[66:69], v[154:157], v[186:189], v[66:69]
	v_mfma_f32_16x16x32_bf16 v[66:69], v[158:161], v[190:193], v[66:69]
	s_setprio 0
	s_barrier
	s_or_b32 s25, s24, 0x80
	s_mov_b32 m0, s44
	v_add_u32_e32 v204, s25, v197
	ds_read_b128 v[162:165], v215 offset:49152
	ds_read_b128 v[166:169], v215 offset:50176
	ds_read_b128 v[170:173], v215 offset:51200
	ds_read_b128 v[174:177], v215 offset:52224
	ds_read_b128 v[178:181], v215 offset:53248
	ds_read_b128 v[182:185], v215 offset:54272
	ds_read_b128 v[186:189], v215 offset:55296
	ds_read_b128 v[190:193], v215 offset:56320
	global_load_lds_dwordx4 v204, s[2:3]
	v_add_u32_e32 v204, s25, v199
	s_mov_b32 m0, s45
	s_add_i32 s24, s24, 0x80080
	global_load_lds_dwordx4 v204, s[2:3]
	v_add_u32_e32 v204, s24, v197
	s_mov_b32 m0, s49
	s_nop 0
	global_load_lds_dwordx4 v204, s[2:3]
	v_add_u32_e32 v204, s24, v199
	s_mov_b32 m0, s50
	s_nop 0
	global_load_lds_dwordx4 v204, s[2:3]
	v_add_u32_e32 v204, s23, v196
	s_mov_b32 m0, s46
	s_nop 0
	global_load_lds_dwordx4 v204, s[0:1]
	v_add_u32_e32 v204, s23, v198
	s_mov_b32 m0, s47
	s_nop 0
	global_load_lds_dwordx4 v204, s[0:1]
	s_waitcnt vmcnt(8)
	s_waitcnt lgkmcnt(0)
	s_setprio 1
	s_barrier
	v_mfma_f32_16x16x32_bf16 v[62:65], v[130:133], v[162:165], v[62:65]
	v_mfma_f32_16x16x32_bf16 v[62:65], v[134:137], v[166:169], v[62:65]
	v_mfma_f32_16x16x32_bf16 v[58:61], v[138:141], v[162:165], v[58:61]
	v_mfma_f32_16x16x32_bf16 v[58:61], v[142:145], v[166:169], v[58:61]
	v_mfma_f32_16x16x32_bf16 v[46:49], v[130:133], v[170:173], v[46:49]
	v_mfma_f32_16x16x32_bf16 v[46:49], v[134:137], v[174:177], v[46:49]
	v_mfma_f32_16x16x32_bf16 v[42:45], v[138:141], v[170:173], v[42:45]
	v_mfma_f32_16x16x32_bf16 v[42:45], v[142:145], v[174:177], v[42:45]
	v_mfma_f32_16x16x32_bf16 v[30:33], v[130:133], v[178:181], v[30:33]
	v_mfma_f32_16x16x32_bf16 v[30:33], v[134:137], v[182:185], v[30:33]
	v_mfma_f32_16x16x32_bf16 v[26:29], v[138:141], v[178:181], v[26:29]
	v_mfma_f32_16x16x32_bf16 v[26:29], v[142:145], v[182:185], v[26:29]
	v_mfma_f32_16x16x32_bf16 v[14:17], v[130:133], v[186:189], v[14:17]
	v_mfma_f32_16x16x32_bf16 v[14:17], v[134:137], v[190:193], v[14:17]
	v_mfma_f32_16x16x32_bf16 v[10:13], v[138:141], v[186:189], v[10:13]
	v_mfma_f32_16x16x32_bf16 v[10:13], v[142:145], v[190:193], v[10:13]
	s_setprio 0
	s_setprio 1
	v_mfma_f32_16x16x32_bf16 v[54:57], v[146:149], v[162:165], v[54:57]
	v_mfma_f32_16x16x32_bf16 v[54:57], v[150:153], v[166:169], v[54:57]
	v_mfma_f32_16x16x32_bf16 v[50:53], v[154:157], v[162:165], v[50:53]
	v_mfma_f32_16x16x32_bf16 v[50:53], v[158:161], v[166:169], v[50:53]
	v_mfma_f32_16x16x32_bf16 v[38:41], v[146:149], v[170:173], v[38:41]
	v_mfma_f32_16x16x32_bf16 v[38:41], v[150:153], v[174:177], v[38:41]
	v_mfma_f32_16x16x32_bf16 v[34:37], v[154:157], v[170:173], v[34:37]
	v_mfma_f32_16x16x32_bf16 v[34:37], v[158:161], v[174:177], v[34:37]
	v_mfma_f32_16x16x32_bf16 v[22:25], v[146:149], v[178:181], v[22:25]
	v_mfma_f32_16x16x32_bf16 v[22:25], v[150:153], v[182:185], v[22:25]
	v_mfma_f32_16x16x32_bf16 v[18:21], v[154:157], v[178:181], v[18:21]
	v_mfma_f32_16x16x32_bf16 v[18:21], v[158:161], v[182:185], v[18:21]
	v_mfma_f32_16x16x32_bf16 v[6:9], v[146:149], v[186:189], v[6:9]
	v_mfma_f32_16x16x32_bf16 v[6:9], v[150:153], v[190:193], v[6:9]
	v_mfma_f32_16x16x32_bf16 v[2:5], v[154:157], v[186:189], v[2:5]
	v_mfma_f32_16x16x32_bf16 v[2:5], v[158:161], v[190:193], v[2:5]
	s_setprio 0
	s_barrier
	s_add_i32 s23, s17, 2
	s_cmp_gt_u32 s17, 29
	s_cbranch_scc1 .LBB0_571
	s_mov_b32 s62, s22
	s_mov_b32 s17, s23
	s_cmp_lt_i32 s17, 24
	s_cbranch_scc1 .LBB0_564

.LBB0_615:
	s_lshl_b32 s12, s40, 20
	s_and_b64 s[48:49], s[4:5], exec
	s_cselect_b32 s43, s12, s46
	s_lshl_b32 s13, s39, 20
	s_and_b64 s[48:49], s[4:5], exec
	s_cselect_b32 s44, s13, s45
	v_add_u32_e32 v130, s46, v139
	v_add_u32_e32 v131, s46, v140
	s_addk_i32 s45, 0x100
	s_addk_i32 s46, 0x100
	s_mov_b32 s47, -2
	v_add_u32_e32 v154, s17, v137
	v_add_u32_e32 v170, s20, v137
	ds_read_b128 v[142:145], v154
	ds_read_b128 v[146:149], v154 offset:1024
	ds_read_b128 v[150:153], v154 offset:2048
	ds_read_b128 v[154:157], v154 offset:3072
	ds_read_b128 v[158:161], v170
	ds_read_b128 v[162:165], v170 offset:1024
	ds_read_b128 v[166:169], v170 offset:2048
	ds_read_b128 v[170:173], v170 offset:3072
	s_cmp_eq_u32 s47, 28
	s_cselect_b32 s50, s43, s46
	s_cselect_b32 s49, s44, s45
	s_or_b32 s48, s50, 0x80
	s_add_i32 m0, s23, 0xc000
	ds_read_b128 v[174:177], v141
	ds_read_b128 v[178:181], v141 offset:1024
	ds_read_b128 v[182:185], v141 offset:2048
	ds_read_b128 v[186:189], v141 offset:3072
	ds_read_b128 v[190:193], v141 offset:4096
	ds_read_b128 v[194:197], v141 offset:5120
	ds_read_b128 v[198:201], v141 offset:6144
	ds_read_b128 v[204:207], v141 offset:7168
	global_load_lds_dwordx4 v131, s[0:1]
	s_add_i32 m0, s23, 0xe000
	s_nop 0
	global_load_lds_dwordx4 v130, s[0:1]
	s_waitcnt vmcnt(8)
	s_waitcnt lgkmcnt(0)
	s_setprio 1
	s_barrier
	v_mfma_f32_16x16x32_bf16 v[126:129], v[142:145], v[174:177], 0
	v_mfma_f32_16x16x32_bf16 v[126:129], v[146:149], v[178:181], v[126:129]
	v_mfma_f32_16x16x32_bf16 v[122:125], v[150:153], v[174:177], 0
	v_mfma_f32_16x16x32_bf16 v[122:125], v[154:157], v[178:181], v[122:125]
	v_mfma_f32_16x16x32_bf16 v[118:121], v[142:145], v[182:185], 0
	v_mfma_f32_16x16x32_bf16 v[118:121], v[146:149], v[186:189], v[118:121]
	v_mfma_f32_16x16x32_bf16 v[110:113], v[150:153], v[182:185], 0
	v_mfma_f32_16x16x32_bf16 v[110:113], v[154:157], v[186:189], v[110:113]
	v_mfma_f32_16x16x32_bf16 v[102:105], v[142:145], v[190:193], 0
	v_mfma_f32_16x16x32_bf16 v[102:105], v[146:149], v[194:197], v[102:105]
	v_mfma_f32_16x16x32_bf16 v[94:97], v[150:153], v[190:193], 0
	v_mfma_f32_16x16x32_bf16 v[94:97], v[154:157], v[194:197], v[94:97]
	v_mfma_f32_16x16x32_bf16 v[86:89], v[142:145], v[198:201], 0
	v_mfma_f32_16x16x32_bf16 v[86:89], v[146:149], v[204:207], v[86:89]
	v_mfma_f32_16x16x32_bf16 v[78:81], v[150:153], v[198:201], 0
	v_mfma_f32_16x16x32_bf16 v[78:81], v[154:157], v[204:207], v[78:81]
	s_setprio 0
	s_setprio 1
	v_mfma_f32_16x16x32_bf16 v[114:117], v[158:161], v[174:177], 0
	v_mfma_f32_16x16x32_bf16 v[114:117], v[162:165], v[178:181], v[114:117]
	v_mfma_f32_16x16x32_bf16 v[106:109], v[166:169], v[174:177], 0
	v_mfma_f32_16x16x32_bf16 v[106:109], v[170:173], v[178:181], v[106:109]
	v_mfma_f32_16x16x32_bf16 v[98:101], v[158:161], v[182:185], 0
	v_mfma_f32_16x16x32_bf16 v[98:101], v[162:165], v[186:189], v[98:101]
	v_mfma_f32_16x16x32_bf16 v[90:93], v[166:169], v[182:185], 0
	v_mfma_f32_16x16x32_bf16 v[90:93], v[170:173], v[186:189], v[90:93]
	v_mfma_f32_16x16x32_bf16 v[82:85], v[158:161], v[190:193], 0
	v_mfma_f32_16x16x32_bf16 v[82:85], v[162:165], v[194:197], v[82:85]
	v_mfma_f32_16x16x32_bf16 v[74:77], v[166:169], v[190:193], 0
	v_mfma_f32_16x16x32_bf16 v[74:77], v[170:173], v[194:197], v[74:77]
	v_mfma_f32_16x16x32_bf16 v[70:73], v[158:161], v[198:201], 0
	v_mfma_f32_16x16x32_bf16 v[70:73], v[162:165], v[204:207], v[70:73]
	v_mfma_f32_16x16x32_bf16 v[66:69], v[166:169], v[198:201], 0
	v_mfma_f32_16x16x32_bf16 v[66:69], v[170:173], v[204:207], v[66:69]
	s_setprio 0
	s_barrier
	s_mov_b32 m0, s18
	v_add_u32_e32 v202, s49, v133
	ds_read_b128 v[174:177], v141 offset:16384
	ds_read_b128 v[178:181], v141 offset:17408
	ds_read_b128 v[182:185], v141 offset:18432
	ds_read_b128 v[186:189], v141 offset:19456
	ds_read_b128 v[190:193], v141 offset:20480
	ds_read_b128 v[194:197], v141 offset:21504
	ds_read_b128 v[198:201], v141 offset:22528
	ds_read_b128 v[204:207], v141 offset:23552
	global_load_lds_dwordx4 v202, s[2:3]
	v_add_u32_e32 v202, s49, v135
	s_mov_b32 m0, s19
	s_add_i32 s51, s49, 0x80000
	global_load_lds_dwordx4 v202, s[2:3]
	v_add_u32_e32 v202, s51, v133
	s_mov_b32 m0, s21
	s_nop 0
	global_load_lds_dwordx4 v202, s[2:3]
	v_add_u32_e32 v202, s51, v135
	s_mov_b32 m0, s22
	s_nop 0
	global_load_lds_dwordx4 v202, s[2:3]
	v_add_u32_e32 v202, s50, v132
	s_mov_b32 m0, s23
	s_nop 0
	global_load_lds_dwordx4 v202, s[0:1]
	v_add_u32_e32 v202, s50, v134
	s_mov_b32 m0, s24
	s_nop 0
	global_load_lds_dwordx4 v202, s[0:1]
	s_waitcnt vmcnt(8)
	s_waitcnt lgkmcnt(0)
	s_setprio 1
	s_barrier
	v_mfma_f32_16x16x32_bf16 v[62:65], v[142:145], v[174:177], 0
	v_mfma_f32_16x16x32_bf16 v[62:65], v[146:149], v[178:181], v[62:65]
	v_mfma_f32_16x16x32_bf16 v[58:61], v[150:153], v[174:177], 0
	v_mfma_f32_16x16x32_bf16 v[58:61], v[154:157], v[178:181], v[58:61]
	v_mfma_f32_16x16x32_bf16 v[54:57], v[142:145], v[182:185], 0
	v_mfma_f32_16x16x32_bf16 v[54:57], v[146:149], v[186:189], v[54:57]
	v_mfma_f32_16x16x32_bf16 v[46:49], v[150:153], v[182:185], 0
	v_mfma_f32_16x16x32_bf16 v[46:49], v[154:157], v[186:189], v[46:49]
	v_mfma_f32_16x16x32_bf16 v[38:41], v[142:145], v[190:193], 0
	v_mfma_f32_16x16x32_bf16 v[38:41], v[146:149], v[194:197], v[38:41]
	v_mfma_f32_16x16x32_bf16 v[30:33], v[150:153], v[190:193], 0
	v_mfma_f32_16x16x32_bf16 v[30:33], v[154:157], v[194:197], v[30:33]
	v_mfma_f32_16x16x32_bf16 v[22:25], v[142:145], v[198:201], 0
	v_mfma_f32_16x16x32_bf16 v[22:25], v[146:149], v[204:207], v[22:25]
	v_mfma_f32_16x16x32_bf16 v[14:17], v[150:153], v[198:201], 0
	v_mfma_f32_16x16x32_bf16 v[14:17], v[154:157], v[204:207], v[14:17]
	s_setprio 0
	s_setprio 1
	v_mfma_f32_16x16x32_bf16 v[50:53], v[158:161], v[174:177], 0
	v_mfma_f32_16x16x32_bf16 v[50:53], v[162:165], v[178:181], v[50:53]
	v_mfma_f32_16x16x32_bf16 v[42:45], v[166:169], v[174:177], 0
	v_mfma_f32_16x16x32_bf16 v[42:45], v[170:173], v[178:181], v[42:45]
	v_mfma_f32_16x16x32_bf16 v[34:37], v[158:161], v[182:185], 0
	v_mfma_f32_16x16x32_bf16 v[34:37], v[162:165], v[186:189], v[34:37]
	v_mfma_f32_16x16x32_bf16 v[26:29], v[166:169], v[182:185], 0
	v_mfma_f32_16x16x32_bf16 v[26:29], v[170:173], v[186:189], v[26:29]
	v_mfma_f32_16x16x32_bf16 v[18:21], v[158:161], v[190:193], 0
	v_mfma_f32_16x16x32_bf16 v[18:21], v[162:165], v[194:197], v[18:21]
	v_mfma_f32_16x16x32_bf16 v[10:13], v[166:169], v[190:193], 0
	v_mfma_f32_16x16x32_bf16 v[10:13], v[170:173], v[194:197], v[10:13]
	v_mfma_f32_16x16x32_bf16 v[6:9], v[158:161], v[198:201], 0
	v_mfma_f32_16x16x32_bf16 v[6:9], v[162:165], v[204:207], v[6:9]
	v_mfma_f32_16x16x32_bf16 v[2:5], v[166:169], v[198:201], 0
	v_mfma_f32_16x16x32_bf16 v[2:5], v[170:173], v[204:207], v[2:5]
	s_setprio 0
	s_barrier
	v_add_u32_e32 v154, s27, v137
	v_add_u32_e32 v170, s34, v137
	ds_read_b128 v[142:145], v154
	ds_read_b128 v[146:149], v154 offset:1024
	ds_read_b128 v[150:153], v154 offset:2048
	ds_read_b128 v[154:157], v154 offset:3072
	ds_read_b128 v[158:161], v170
	ds_read_b128 v[162:165], v170 offset:1024
	ds_read_b128 v[166:169], v170 offset:2048
	ds_read_b128 v[170:173], v170 offset:3072
	s_add_i32 s50, s50, 0x80000
	s_mov_b32 m0, s25
	v_add_u32_e32 v202, s50, v132
	ds_read_b128 v[174:177], v141 offset:32768
	ds_read_b128 v[178:181], v141 offset:33792
	ds_read_b128 v[182:185], v141 offset:34816
	ds_read_b128 v[186:189], v141 offset:35840
	ds_read_b128 v[190:193], v141 offset:36864
	ds_read_b128 v[194:197], v141 offset:37888
	ds_read_b128 v[198:201], v141 offset:38912
	ds_read_b128 v[204:207], v141 offset:39936
	global_load_lds_dwordx4 v202, s[0:1]
	v_add_u32_e32 v202, s50, v134
	s_mov_b32 m0, s26
	s_nop 0
	global_load_lds_dwordx4 v202, s[0:1]
	s_waitcnt vmcnt(8)
	s_waitcnt lgkmcnt(0)
	s_setprio 1
	s_barrier
	v_mfma_f32_16x16x32_bf16 v[126:129], v[142:145], v[174:177], v[126:129]
	v_mfma_f32_16x16x32_bf16 v[126:129], v[146:149], v[178:181], v[126:129]
	v_mfma_f32_16x16x32_bf16 v[122:125], v[150:153], v[174:177], v[122:125]
	v_mfma_f32_16x16x32_bf16 v[122:125], v[154:157], v[178:181], v[122:125]
	v_mfma_f32_16x16x32_bf16 v[118:121], v[142:145], v[182:185], v[118:121]
	v_mfma_f32_16x16x32_bf16 v[118:121], v[146:149], v[186:189], v[118:121]
	v_mfma_f32_16x16x32_bf16 v[110:113], v[150:153], v[182:185], v[110:113]
	v_mfma_f32_16x16x32_bf16 v[110:113], v[154:157], v[186:189], v[110:113]
	v_mfma_f32_16x16x32_bf16 v[102:105], v[142:145], v[190:193], v[102:105]
	v_mfma_f32_16x16x32_bf16 v[102:105], v[146:149], v[194:197], v[102:105]
	v_mfma_f32_16x16x32_bf16 v[94:97], v[150:153], v[190:193], v[94:97]
	v_mfma_f32_16x16x32_bf16 v[94:97], v[154:157], v[194:197], v[94:97]
	v_mfma_f32_16x16x32_bf16 v[86:89], v[142:145], v[198:201], v[86:89]
	v_mfma_f32_16x16x32_bf16 v[86:89], v[146:149], v[204:207], v[86:89]
	v_mfma_f32_16x16x32_bf16 v[78:81], v[150:153], v[198:201], v[78:81]
	v_mfma_f32_16x16x32_bf16 v[78:81], v[154:157], v[204:207], v[78:81]
	s_setprio 0
	s_setprio 1
	v_mfma_f32_16x16x32_bf16 v[114:117], v[158:161], v[174:177], v[114:117]
	v_mfma_f32_16x16x32_bf16 v[114:117], v[162:165], v[178:181], v[114:117]
	v_mfma_f32_16x16x32_bf16 v[106:109], v[166:169], v[174:177], v[106:109]
	v_mfma_f32_16x16x32_bf16 v[106:109], v[170:173], v[178:181], v[106:109]
	v_mfma_f32_16x16x32_bf16 v[98:101], v[158:161], v[182:185], v[98:101]
	v_mfma_f32_16x16x32_bf16 v[98:101], v[162:165], v[186:189], v[98:101]
	v_mfma_f32_16x16x32_bf16 v[90:93], v[166:169], v[182:185], v[90:93]
	v_mfma_f32_16x16x32_bf16 v[90:93], v[170:173], v[186:189], v[90:93]
	v_mfma_f32_16x16x32_bf16 v[82:85], v[158:161], v[190:193], v[82:85]
	v_mfma_f32_16x16x32_bf16 v[82:85], v[162:165], v[194:197], v[82:85]
	v_mfma_f32_16x16x32_bf16 v[74:77], v[166:169], v[190:193], v[74:77]
	v_mfma_f32_16x16x32_bf16 v[74:77], v[170:173], v[194:197], v[74:77]
	v_mfma_f32_16x16x32_bf16 v[70:73], v[158:161], v[198:201], v[70:73]
	v_mfma_f32_16x16x32_bf16 v[70:73], v[162:165], v[204:207], v[70:73]
	v_mfma_f32_16x16x32_bf16 v[66:69], v[166:169], v[198:201], v[66:69]
	v_mfma_f32_16x16x32_bf16 v[66:69], v[170:173], v[204:207], v[66:69]
	s_setprio 0
	s_barrier
	s_or_b32 s50, s49, 0x80
	s_mov_b32 m0, s28
	v_add_u32_e32 v202, s50, v133
	ds_read_b128 v[174:177], v141 offset:49152
	ds_read_b128 v[178:181], v141 offset:50176
	ds_read_b128 v[182:185], v141 offset:51200
	ds_read_b128 v[186:189], v141 offset:52224
	ds_read_b128 v[190:193], v141 offset:53248
	ds_read_b128 v[194:197], v141 offset:54272
	ds_read_b128 v[198:201], v141 offset:55296
	ds_read_b128 v[204:207], v141 offset:56320
	global_load_lds_dwordx4 v202, s[2:3]
	v_add_u32_e32 v202, s50, v135
	s_mov_b32 m0, s29
	s_add_i32 s49, s49, 0x80080
	global_load_lds_dwordx4 v202, s[2:3]
	v_add_u32_e32 v202, s49, v133
	s_mov_b32 m0, s35
	s_nop 0
	global_load_lds_dwordx4 v202, s[2:3]
	v_add_u32_e32 v202, s49, v135
	s_mov_b32 m0, s36
	s_nop 0
	global_load_lds_dwordx4 v202, s[2:3]
	v_add_u32_e32 v202, s48, v132
	s_mov_b32 m0, s30
	s_nop 0
	global_load_lds_dwordx4 v202, s[0:1]
	v_add_u32_e32 v202, s48, v134
	s_mov_b32 m0, s31
	s_nop 0
	global_load_lds_dwordx4 v202, s[0:1]
	s_waitcnt vmcnt(8)
	s_waitcnt lgkmcnt(0)
	s_setprio 1
	s_barrier
	v_mfma_f32_16x16x32_bf16 v[62:65], v[142:145], v[174:177], v[62:65]
	v_mfma_f32_16x16x32_bf16 v[62:65], v[146:149], v[178:181], v[62:65]
	v_mfma_f32_16x16x32_bf16 v[58:61], v[150:153], v[174:177], v[58:61]
	v_mfma_f32_16x16x32_bf16 v[58:61], v[154:157], v[178:181], v[58:61]
	v_mfma_f32_16x16x32_bf16 v[54:57], v[142:145], v[182:185], v[54:57]
	v_mfma_f32_16x16x32_bf16 v[54:57], v[146:149], v[186:189], v[54:57]
	v_mfma_f32_16x16x32_bf16 v[46:49], v[150:153], v[182:185], v[46:49]
	v_mfma_f32_16x16x32_bf16 v[46:49], v[154:157], v[186:189], v[46:49]
	v_mfma_f32_16x16x32_bf16 v[38:41], v[142:145], v[190:193], v[38:41]
	v_mfma_f32_16x16x32_bf16 v[38:41], v[146:149], v[194:197], v[38:41]
	v_mfma_f32_16x16x32_bf16 v[30:33], v[150:153], v[190:193], v[30:33]
	v_mfma_f32_16x16x32_bf16 v[30:33], v[154:157], v[194:197], v[30:33]
	v_mfma_f32_16x16x32_bf16 v[22:25], v[142:145], v[198:201], v[22:25]
	v_mfma_f32_16x16x32_bf16 v[22:25], v[146:149], v[204:207], v[22:25]
	v_mfma_f32_16x16x32_bf16 v[14:17], v[150:153], v[198:201], v[14:17]
	v_mfma_f32_16x16x32_bf16 v[14:17], v[154:157], v[204:207], v[14:17]
	s_setprio 0
	s_setprio 1
	v_mfma_f32_16x16x32_bf16 v[50:53], v[158:161], v[174:177], v[50:53]
	v_mfma_f32_16x16x32_bf16 v[50:53], v[162:165], v[178:181], v[50:53]
	v_mfma_f32_16x16x32_bf16 v[42:45], v[166:169], v[174:177], v[42:45]
	v_mfma_f32_16x16x32_bf16 v[42:45], v[170:173], v[178:181], v[42:45]
	v_mfma_f32_16x16x32_bf16 v[34:37], v[158:161], v[182:185], v[34:37]
	v_mfma_f32_16x16x32_bf16 v[34:37], v[162:165], v[186:189], v[34:37]
	v_mfma_f32_16x16x32_bf16 v[26:29], v[166:169], v[182:185], v[26:29]
	v_mfma_f32_16x16x32_bf16 v[26:29], v[170:173], v[186:189], v[26:29]
	v_mfma_f32_16x16x32_bf16 v[18:21], v[158:161], v[190:193], v[18:21]
	v_mfma_f32_16x16x32_bf16 v[18:21], v[162:165], v[194:197], v[18:21]
	v_mfma_f32_16x16x32_bf16 v[10:13], v[166:169], v[190:193], v[10:13]
	v_mfma_f32_16x16x32_bf16 v[10:13], v[170:173], v[194:197], v[10:13]
	v_mfma_f32_16x16x32_bf16 v[6:9], v[158:161], v[198:201], v[6:9]
	v_mfma_f32_16x16x32_bf16 v[6:9], v[162:165], v[204:207], v[6:9]
	v_mfma_f32_16x16x32_bf16 v[2:5], v[166:169], v[198:201], v[2:5]
	v_mfma_f32_16x16x32_bf16 v[2:5], v[170:173], v[204:207], v[2:5]
	s_setprio 0
	s_barrier
	s_add_i32 s47, s47, 2
	s_addk_i32 s45, 0x100
	s_addk_i32 s46, 0x100
	v_add_u32_e32 v130, 0x100, v130
	s_cmp_gt_u32 s47, 29
	v_add_u32_e32 v131, 0x100, v131
.LBB0_616:
	v_add_u32_e32 v154, s17, v137
	v_add_u32_e32 v170, s20, v137
	ds_read_b128 v[142:145], v154
	ds_read_b128 v[146:149], v154 offset:1024
	ds_read_b128 v[150:153], v154 offset:2048
	ds_read_b128 v[154:157], v154 offset:3072
	ds_read_b128 v[158:161], v170
	ds_read_b128 v[162:165], v170 offset:1024
	ds_read_b128 v[166:169], v170 offset:2048
	ds_read_b128 v[170:173], v170 offset:3072
	s_cmp_eq_u32 s47, 28
	s_cselect_b32 s50, s43, s46
	s_cselect_b32 s49, s44, s45
	s_or_b32 s48, s50, 0x80
	s_add_i32 m0, s23, 0xc000
	ds_read_b128 v[174:177], v141
	ds_read_b128 v[178:181], v141 offset:1024
	ds_read_b128 v[182:185], v141 offset:2048
	ds_read_b128 v[186:189], v141 offset:3072
	ds_read_b128 v[190:193], v141 offset:4096
	ds_read_b128 v[194:197], v141 offset:5120
	ds_read_b128 v[198:201], v141 offset:6144
	ds_read_b128 v[204:207], v141 offset:7168
	global_load_lds_dwordx4 v131, s[0:1]
	s_add_i32 m0, s23, 0xe000
	s_nop 0
	global_load_lds_dwordx4 v130, s[0:1]
	s_waitcnt vmcnt(8)
	s_waitcnt lgkmcnt(0)
	s_setprio 1
	s_barrier
	v_mfma_f32_16x16x32_bf16 v[126:129], v[142:145], v[174:177], v[126:129]
	v_mfma_f32_16x16x32_bf16 v[126:129], v[146:149], v[178:181], v[126:129]
	v_mfma_f32_16x16x32_bf16 v[122:125], v[150:153], v[174:177], v[122:125]
	v_mfma_f32_16x16x32_bf16 v[122:125], v[154:157], v[178:181], v[122:125]
	v_mfma_f32_16x16x32_bf16 v[118:121], v[142:145], v[182:185], v[118:121]
	v_mfma_f32_16x16x32_bf16 v[118:121], v[146:149], v[186:189], v[118:121]
	v_mfma_f32_16x16x32_bf16 v[110:113], v[150:153], v[182:185], v[110:113]
	v_mfma_f32_16x16x32_bf16 v[110:113], v[154:157], v[186:189], v[110:113]
	v_mfma_f32_16x16x32_bf16 v[102:105], v[142:145], v[190:193], v[102:105]
	v_mfma_f32_16x16x32_bf16 v[102:105], v[146:149], v[194:197], v[102:105]
	v_mfma_f32_16x16x32_bf16 v[94:97], v[150:153], v[190:193], v[94:97]
	v_mfma_f32_16x16x32_bf16 v[94:97], v[154:157], v[194:197], v[94:97]
	v_mfma_f32_16x16x32_bf16 v[86:89], v[142:145], v[198:201], v[86:89]
	v_mfma_f32_16x16x32_bf16 v[86:89], v[146:149], v[204:207], v[86:89]
	v_mfma_f32_16x16x32_bf16 v[78:81], v[150:153], v[198:201], v[78:81]
	v_mfma_f32_16x16x32_bf16 v[78:81], v[154:157], v[204:207], v[78:81]
	s_setprio 0
	s_setprio 1
	v_mfma_f32_16x16x32_bf16 v[114:117], v[158:161], v[174:177], v[114:117]
	v_mfma_f32_16x16x32_bf16 v[114:117], v[162:165], v[178:181], v[114:117]
	v_mfma_f32_16x16x32_bf16 v[106:109], v[166:169], v[174:177], v[106:109]
	v_mfma_f32_16x16x32_bf16 v[106:109], v[170:173], v[178:181], v[106:109]
	v_mfma_f32_16x16x32_bf16 v[98:101], v[158:161], v[182:185], v[98:101]
	v_mfma_f32_16x16x32_bf16 v[98:101], v[162:165], v[186:189], v[98:101]
	v_mfma_f32_16x16x32_bf16 v[90:93], v[166:169], v[182:185], v[90:93]
	v_mfma_f32_16x16x32_bf16 v[90:93], v[170:173], v[186:189], v[90:93]
	v_mfma_f32_16x16x32_bf16 v[82:85], v[158:161], v[190:193], v[82:85]
	v_mfma_f32_16x16x32_bf16 v[82:85], v[162:165], v[194:197], v[82:85]
	v_mfma_f32_16x16x32_bf16 v[74:77], v[166:169], v[190:193], v[74:77]
	v_mfma_f32_16x16x32_bf16 v[74:77], v[170:173], v[194:197], v[74:77]
	v_mfma_f32_16x16x32_bf16 v[70:73], v[158:161], v[198:201], v[70:73]
	v_mfma_f32_16x16x32_bf16 v[70:73], v[162:165], v[204:207], v[70:73]
	v_mfma_f32_16x16x32_bf16 v[66:69], v[166:169], v[198:201], v[66:69]
	v_mfma_f32_16x16x32_bf16 v[66:69], v[170:173], v[204:207], v[66:69]
	s_setprio 0
	s_barrier
	s_mov_b32 m0, s18
	v_add_u32_e32 v202, s49, v133
	ds_read_b128 v[174:177], v141 offset:16384
	ds_read_b128 v[178:181], v141 offset:17408
	ds_read_b128 v[182:185], v141 offset:18432
	ds_read_b128 v[186:189], v141 offset:19456
	ds_read_b128 v[190:193], v141 offset:20480
	ds_read_b128 v[194:197], v141 offset:21504
	ds_read_b128 v[198:201], v141 offset:22528
	ds_read_b128 v[204:207], v141 offset:23552
	global_load_lds_dwordx4 v202, s[2:3]
	v_add_u32_e32 v202, s49, v135
	s_mov_b32 m0, s19
	s_add_i32 s51, s49, 0x80000
	global_load_lds_dwordx4 v202, s[2:3]
	v_add_u32_e32 v202, s51, v133
	s_mov_b32 m0, s21
	s_nop 0
	global_load_lds_dwordx4 v202, s[2:3]
	v_add_u32_e32 v202, s51, v135
	s_mov_b32 m0, s22
	s_nop 0
	global_load_lds_dwordx4 v202, s[2:3]
	v_add_u32_e32 v202, s50, v132
	s_mov_b32 m0, s23
	s_nop 0
	global_load_lds_dwordx4 v202, s[0:1]
	v_add_u32_e32 v202, s50, v134
	s_mov_b32 m0, s24
	s_nop 0
	global_load_lds_dwordx4 v202, s[0:1]
	s_waitcnt vmcnt(8)
	s_waitcnt lgkmcnt(0)
	s_setprio 1
	s_barrier
	v_mfma_f32_16x16x32_bf16 v[62:65], v[142:145], v[174:177], v[62:65]
	v_mfma_f32_16x16x32_bf16 v[62:65], v[146:149], v[178:181], v[62:65]
	v_mfma_f32_16x16x32_bf16 v[58:61], v[150:153], v[174:177], v[58:61]
	v_mfma_f32_16x16x32_bf16 v[58:61], v[154:157], v[178:181], v[58:61]
	v_mfma_f32_16x16x32_bf16 v[54:57], v[142:145], v[182:185], v[54:57]
	v_mfma_f32_16x16x32_bf16 v[54:57], v[146:149], v[186:189], v[54:57]
	v_mfma_f32_16x16x32_bf16 v[46:49], v[150:153], v[182:185], v[46:49]
	v_mfma_f32_16x16x32_bf16 v[46:49], v[154:157], v[186:189], v[46:49]
	v_mfma_f32_16x16x32_bf16 v[38:41], v[142:145], v[190:193], v[38:41]
	v_mfma_f32_16x16x32_bf16 v[38:41], v[146:149], v[194:197], v[38:41]
	v_mfma_f32_16x16x32_bf16 v[30:33], v[150:153], v[190:193], v[30:33]
	v_mfma_f32_16x16x32_bf16 v[30:33], v[154:157], v[194:197], v[30:33]
	v_mfma_f32_16x16x32_bf16 v[22:25], v[142:145], v[198:201], v[22:25]
	v_mfma_f32_16x16x32_bf16 v[22:25], v[146:149], v[204:207], v[22:25]
	v_mfma_f32_16x16x32_bf16 v[14:17], v[150:153], v[198:201], v[14:17]
	v_mfma_f32_16x16x32_bf16 v[14:17], v[154:157], v[204:207], v[14:17]
	s_setprio 0
	s_setprio 1
	v_mfma_f32_16x16x32_bf16 v[50:53], v[158:161], v[174:177], v[50:53]
	v_mfma_f32_16x16x32_bf16 v[50:53], v[162:165], v[178:181], v[50:53]
	v_mfma_f32_16x16x32_bf16 v[42:45], v[166:169], v[174:177], v[42:45]
	v_mfma_f32_16x16x32_bf16 v[42:45], v[170:173], v[178:181], v[42:45]
	v_mfma_f32_16x16x32_bf16 v[34:37], v[158:161], v[182:185], v[34:37]
	v_mfma_f32_16x16x32_bf16 v[34:37], v[162:165], v[186:189], v[34:37]
	v_mfma_f32_16x16x32_bf16 v[26:29], v[166:169], v[182:185], v[26:29]
	v_mfma_f32_16x16x32_bf16 v[26:29], v[170:173], v[186:189], v[26:29]
	v_mfma_f32_16x16x32_bf16 v[18:21], v[158:161], v[190:193], v[18:21]
	v_mfma_f32_16x16x32_bf16 v[18:21], v[162:165], v[194:197], v[18:21]
	v_mfma_f32_16x16x32_bf16 v[10:13], v[166:169], v[190:193], v[10:13]
	v_mfma_f32_16x16x32_bf16 v[10:13], v[170:173], v[194:197], v[10:13]
	v_mfma_f32_16x16x32_bf16 v[6:9], v[158:161], v[198:201], v[6:9]
	v_mfma_f32_16x16x32_bf16 v[6:9], v[162:165], v[204:207], v[6:9]
	v_mfma_f32_16x16x32_bf16 v[2:5], v[166:169], v[198:201], v[2:5]
	v_mfma_f32_16x16x32_bf16 v[2:5], v[170:173], v[204:207], v[2:5]
	s_setprio 0
	s_barrier
	v_add_u32_e32 v154, s27, v137
	v_add_u32_e32 v170, s34, v137
	ds_read_b128 v[142:145], v154
	ds_read_b128 v[146:149], v154 offset:1024
	ds_read_b128 v[150:153], v154 offset:2048
	ds_read_b128 v[154:157], v154 offset:3072
	ds_read_b128 v[158:161], v170
	ds_read_b128 v[162:165], v170 offset:1024
	ds_read_b128 v[166:169], v170 offset:2048
	ds_read_b128 v[170:173], v170 offset:3072
	s_add_i32 s50, s50, 0x80000
	s_mov_b32 m0, s25
	v_add_u32_e32 v202, s50, v132
	ds_read_b128 v[174:177], v141 offset:32768
	ds_read_b128 v[178:181], v141 offset:33792
	ds_read_b128 v[182:185], v141 offset:34816
	ds_read_b128 v[186:189], v141 offset:35840
	ds_read_b128 v[190:193], v141 offset:36864
	ds_read_b128 v[194:197], v141 offset:37888
	ds_read_b128 v[198:201], v141 offset:38912
	ds_read_b128 v[204:207], v141 offset:39936
	global_load_lds_dwordx4 v202, s[0:1]
	v_add_u32_e32 v202, s50, v134
	s_mov_b32 m0, s26
	s_nop 0
	global_load_lds_dwordx4 v202, s[0:1]
	s_waitcnt vmcnt(8)
	s_waitcnt lgkmcnt(0)
	s_setprio 1
	s_barrier
	v_mfma_f32_16x16x32_bf16 v[126:129], v[142:145], v[174:177], v[126:129]
	v_mfma_f32_16x16x32_bf16 v[126:129], v[146:149], v[178:181], v[126:129]
	v_mfma_f32_16x16x32_bf16 v[122:125], v[150:153], v[174:177], v[122:125]
	v_mfma_f32_16x16x32_bf16 v[122:125], v[154:157], v[178:181], v[122:125]
	v_mfma_f32_16x16x32_bf16 v[118:121], v[142:145], v[182:185], v[118:121]
	v_mfma_f32_16x16x32_bf16 v[118:121], v[146:149], v[186:189], v[118:121]
	v_mfma_f32_16x16x32_bf16 v[110:113], v[150:153], v[182:185], v[110:113]
	v_mfma_f32_16x16x32_bf16 v[110:113], v[154:157], v[186:189], v[110:113]
	v_mfma_f32_16x16x32_bf16 v[102:105], v[142:145], v[190:193], v[102:105]
	v_mfma_f32_16x16x32_bf16 v[102:105], v[146:149], v[194:197], v[102:105]
	v_mfma_f32_16x16x32_bf16 v[94:97], v[150:153], v[190:193], v[94:97]
	v_mfma_f32_16x16x32_bf16 v[94:97], v[154:157], v[194:197], v[94:97]
	v_mfma_f32_16x16x32_bf16 v[86:89], v[142:145], v[198:201], v[86:89]
	v_mfma_f32_16x16x32_bf16 v[86:89], v[146:149], v[204:207], v[86:89]
	v_mfma_f32_16x16x32_bf16 v[78:81], v[150:153], v[198:201], v[78:81]
	v_mfma_f32_16x16x32_bf16 v[78:81], v[154:157], v[204:207], v[78:81]
	s_setprio 0
	s_setprio 1
	v_mfma_f32_16x16x32_bf16 v[114:117], v[158:161], v[174:177], v[114:117]
	v_mfma_f32_16x16x32_bf16 v[114:117], v[162:165], v[178:181], v[114:117]
	v_mfma_f32_16x16x32_bf16 v[106:109], v[166:169], v[174:177], v[106:109]
	v_mfma_f32_16x16x32_bf16 v[106:109], v[170:173], v[178:181], v[106:109]
	v_mfma_f32_16x16x32_bf16 v[98:101], v[158:161], v[182:185], v[98:101]
	v_mfma_f32_16x16x32_bf16 v[98:101], v[162:165], v[186:189], v[98:101]
	v_mfma_f32_16x16x32_bf16 v[90:93], v[166:169], v[182:185], v[90:93]
	v_mfma_f32_16x16x32_bf16 v[90:93], v[170:173], v[186:189], v[90:93]
	v_mfma_f32_16x16x32_bf16 v[82:85], v[158:161], v[190:193], v[82:85]
	v_mfma_f32_16x16x32_bf16 v[82:85], v[162:165], v[194:197], v[82:85]
	v_mfma_f32_16x16x32_bf16 v[74:77], v[166:169], v[190:193], v[74:77]
	v_mfma_f32_16x16x32_bf16 v[74:77], v[170:173], v[194:197], v[74:77]
	v_mfma_f32_16x16x32_bf16 v[70:73], v[158:161], v[198:201], v[70:73]
	v_mfma_f32_16x16x32_bf16 v[70:73], v[162:165], v[204:207], v[70:73]
	v_mfma_f32_16x16x32_bf16 v[66:69], v[166:169], v[198:201], v[66:69]
	v_mfma_f32_16x16x32_bf16 v[66:69], v[170:173], v[204:207], v[66:69]
	s_setprio 0
	s_barrier
	s_or_b32 s50, s49, 0x80
	s_mov_b32 m0, s28
	v_add_u32_e32 v202, s50, v133
	ds_read_b128 v[174:177], v141 offset:49152
	ds_read_b128 v[178:181], v141 offset:50176
	ds_read_b128 v[182:185], v141 offset:51200
	ds_read_b128 v[186:189], v141 offset:52224
	ds_read_b128 v[190:193], v141 offset:53248
	ds_read_b128 v[194:197], v141 offset:54272
	ds_read_b128 v[198:201], v141 offset:55296
	ds_read_b128 v[204:207], v141 offset:56320
	global_load_lds_dwordx4 v202, s[2:3]
	v_add_u32_e32 v202, s50, v135
	s_mov_b32 m0, s29
	s_add_i32 s49, s49, 0x80080
	global_load_lds_dwordx4 v202, s[2:3]
	v_add_u32_e32 v202, s49, v133
	s_mov_b32 m0, s35
	s_nop 0
	global_load_lds_dwordx4 v202, s[2:3]
	v_add_u32_e32 v202, s49, v135
	s_mov_b32 m0, s36
	s_nop 0
	global_load_lds_dwordx4 v202, s[2:3]
	v_add_u32_e32 v202, s48, v132
	s_mov_b32 m0, s30
	s_nop 0
	global_load_lds_dwordx4 v202, s[0:1]
	v_add_u32_e32 v202, s48, v134
	s_mov_b32 m0, s31
	s_nop 0
	global_load_lds_dwordx4 v202, s[0:1]
	s_add_i32 s47, s47, 2
	s_addk_i32 s45, 0x100
	s_addk_i32 s46, 0x100
	v_add_u32_e32 v130, 0x100, v130
	s_cmp_gt_u32 s47, 29
	v_add_u32_e32 v131, 0x100, v131
	s_waitcnt vmcnt(8)
	s_waitcnt lgkmcnt(0)
	s_setprio 1
	s_barrier
	v_mfma_f32_16x16x32_bf16 v[62:65], v[142:145], v[174:177], v[62:65]
	v_mfma_f32_16x16x32_bf16 v[62:65], v[146:149], v[178:181], v[62:65]
	v_mfma_f32_16x16x32_bf16 v[58:61], v[150:153], v[174:177], v[58:61]
	v_mfma_f32_16x16x32_bf16 v[58:61], v[154:157], v[178:181], v[58:61]
	v_mfma_f32_16x16x32_bf16 v[54:57], v[142:145], v[182:185], v[54:57]
	v_mfma_f32_16x16x32_bf16 v[54:57], v[146:149], v[186:189], v[54:57]
	v_mfma_f32_16x16x32_bf16 v[46:49], v[150:153], v[182:185], v[46:49]
	v_mfma_f32_16x16x32_bf16 v[46:49], v[154:157], v[186:189], v[46:49]
	v_mfma_f32_16x16x32_bf16 v[38:41], v[142:145], v[190:193], v[38:41]
	v_mfma_f32_16x16x32_bf16 v[38:41], v[146:149], v[194:197], v[38:41]
	v_mfma_f32_16x16x32_bf16 v[30:33], v[150:153], v[190:193], v[30:33]
	v_mfma_f32_16x16x32_bf16 v[30:33], v[154:157], v[194:197], v[30:33]
	v_mfma_f32_16x16x32_bf16 v[22:25], v[142:145], v[198:201], v[22:25]
	v_mfma_f32_16x16x32_bf16 v[22:25], v[146:149], v[204:207], v[22:25]
	v_mfma_f32_16x16x32_bf16 v[14:17], v[150:153], v[198:201], v[14:17]
	v_mfma_f32_16x16x32_bf16 v[14:17], v[154:157], v[204:207], v[14:17]
	s_setprio 0
	s_setprio 1
	v_mfma_f32_16x16x32_bf16 v[50:53], v[158:161], v[174:177], v[50:53]
	v_mfma_f32_16x16x32_bf16 v[50:53], v[162:165], v[178:181], v[50:53]
	v_mfma_f32_16x16x32_bf16 v[42:45], v[166:169], v[174:177], v[42:45]
	v_mfma_f32_16x16x32_bf16 v[42:45], v[170:173], v[178:181], v[42:45]
	v_mfma_f32_16x16x32_bf16 v[34:37], v[158:161], v[182:185], v[34:37]
	v_mfma_f32_16x16x32_bf16 v[34:37], v[162:165], v[186:189], v[34:37]
	v_mfma_f32_16x16x32_bf16 v[26:29], v[166:169], v[182:185], v[26:29]
	v_mfma_f32_16x16x32_bf16 v[26:29], v[170:173], v[186:189], v[26:29]
	v_mfma_f32_16x16x32_bf16 v[18:21], v[158:161], v[190:193], v[18:21]
	v_mfma_f32_16x16x32_bf16 v[18:21], v[162:165], v[194:197], v[18:21]
	v_mfma_f32_16x16x32_bf16 v[10:13], v[166:169], v[190:193], v[10:13]
	v_mfma_f32_16x16x32_bf16 v[10:13], v[170:173], v[194:197], v[10:13]
	v_mfma_f32_16x16x32_bf16 v[6:9], v[158:161], v[198:201], v[6:9]
	v_mfma_f32_16x16x32_bf16 v[6:9], v[162:165], v[204:207], v[6:9]
	v_mfma_f32_16x16x32_bf16 v[2:5], v[166:169], v[198:201], v[2:5]
	v_mfma_f32_16x16x32_bf16 v[2:5], v[170:173], v[204:207], v[2:5]
	s_setprio 0
	s_barrier
	s_cbranch_scc0 .LBB0_616
	s_and_b64 vcc, exec, s[10:11]
	s_cbranch_vccz .LBB0_619
	s_barrier

.LBB0_703:
	s_lshl_b32 s26, s20, 20
	s_and_b64 s[54:55], s[22:23], exec
	s_cselect_b32 s54, s26, s57
	s_lshl_b32 s27, s52, 20
	s_and_b64 s[58:59], s[22:23], exec
	s_cselect_b32 s55, s27, s56
	v_add_u32_e32 v132, s57, v144
	v_add_u32_e32 v133, s57, v145
	s_addk_i32 s56, 0x100
	s_addk_i32 s57, 0x100
	s_mov_b32 s58, -2
	v_add_u32_e32 v134, s25, v141
	ds_read_b128 v[148:151], v134
	ds_read_b128 v[152:155], v134 offset:1024
	ds_read_b128 v[156:159], v134 offset:2048
	ds_read_b128 v[160:163], v134 offset:3072
	v_add_u32_e32 v134, s34, v141
	ds_read_b128 v[164:167], v134
	ds_read_b128 v[168:171], v134 offset:1024
	ds_read_b128 v[172:175], v134 offset:2048
	ds_read_b128 v[176:179], v134 offset:3072
	s_cmp_eq_u32 s58, 28
	s_cselect_b32 s61, s54, s57
	s_cselect_b32 s60, s55, s56
	s_or_b32 s59, s61, 0x80
	s_add_i32 m0, s37, 0xc000
	ds_read_b128 v[180:183], v146
	ds_read_b128 v[184:187], v146 offset:1024
	ds_read_b128 v[188:191], v146 offset:2048
	ds_read_b128 v[192:195], v146 offset:3072
	ds_read_b128 v[196:199], v146 offset:4096
	ds_read_b128 v[204:207], v146 offset:5120
	ds_read_b128 v[212:215], v146 offset:6144
	ds_read_b128 v[218:221], v146 offset:7168
	global_load_lds_dwordx4 v133, s[4:5]
	s_add_i32 m0, s37, 0xe000
	s_nop 0
	global_load_lds_dwordx4 v132, s[4:5]
	s_waitcnt vmcnt(8)
	s_waitcnt lgkmcnt(0)
	s_setprio 1
	s_barrier
	v_mfma_f32_16x16x32_bf16 v[126:129], v[148:151], v[180:183], 0
	v_mfma_f32_16x16x32_bf16 v[126:129], v[152:155], v[184:187], v[126:129]
	v_mfma_f32_16x16x32_bf16 v[122:125], v[156:159], v[180:183], 0
	v_mfma_f32_16x16x32_bf16 v[122:125], v[160:163], v[184:187], v[122:125]
	v_mfma_f32_16x16x32_bf16 v[110:113], v[148:151], v[188:191], 0
	v_mfma_f32_16x16x32_bf16 v[110:113], v[152:155], v[192:195], v[110:113]
	v_mfma_f32_16x16x32_bf16 v[106:109], v[156:159], v[188:191], 0
	v_mfma_f32_16x16x32_bf16 v[106:109], v[160:163], v[192:195], v[106:109]
	v_mfma_f32_16x16x32_bf16 v[94:97], v[148:151], v[196:199], 0
	v_mfma_f32_16x16x32_bf16 v[94:97], v[152:155], v[204:207], v[94:97]
	v_mfma_f32_16x16x32_bf16 v[90:93], v[156:159], v[196:199], 0
	v_mfma_f32_16x16x32_bf16 v[90:93], v[160:163], v[204:207], v[90:93]
	v_mfma_f32_16x16x32_bf16 v[78:81], v[148:151], v[212:215], 0
	v_mfma_f32_16x16x32_bf16 v[78:81], v[152:155], v[218:221], v[78:81]
	v_mfma_f32_16x16x32_bf16 v[74:77], v[156:159], v[212:215], 0
	v_mfma_f32_16x16x32_bf16 v[74:77], v[160:163], v[218:221], v[74:77]
	s_setprio 0
	s_setprio 1
	v_mfma_f32_16x16x32_bf16 v[118:121], v[164:167], v[180:183], 0
	v_mfma_f32_16x16x32_bf16 v[118:121], v[168:171], v[184:187], v[118:121]
	v_mfma_f32_16x16x32_bf16 v[114:117], v[172:175], v[180:183], 0
	v_mfma_f32_16x16x32_bf16 v[114:117], v[176:179], v[184:187], v[114:117]
	v_mfma_f32_16x16x32_bf16 v[102:105], v[164:167], v[188:191], 0
	v_mfma_f32_16x16x32_bf16 v[102:105], v[168:171], v[192:195], v[102:105]
	v_mfma_f32_16x16x32_bf16 v[98:101], v[172:175], v[188:191], 0
	v_mfma_f32_16x16x32_bf16 v[98:101], v[176:179], v[192:195], v[98:101]
	v_mfma_f32_16x16x32_bf16 v[86:89], v[164:167], v[196:199], 0
	v_mfma_f32_16x16x32_bf16 v[86:89], v[168:171], v[204:207], v[86:89]
	v_mfma_f32_16x16x32_bf16 v[82:85], v[172:175], v[196:199], 0
	v_mfma_f32_16x16x32_bf16 v[82:85], v[176:179], v[204:207], v[82:85]
	v_mfma_f32_16x16x32_bf16 v[70:73], v[164:167], v[212:215], 0
	v_mfma_f32_16x16x32_bf16 v[70:73], v[168:171], v[218:221], v[70:73]
	v_mfma_f32_16x16x32_bf16 v[66:69], v[172:175], v[212:215], 0
	v_mfma_f32_16x16x32_bf16 v[66:69], v[176:179], v[218:221], v[66:69]
	s_setprio 0
	s_barrier
	s_mov_b32 m0, s30
	v_add_u32_e32 v134, s60, v137
	ds_read_b128 v[180:183], v146 offset:16384
	ds_read_b128 v[184:187], v146 offset:17408
	ds_read_b128 v[188:191], v146 offset:18432
	ds_read_b128 v[192:195], v146 offset:19456
	ds_read_b128 v[196:199], v146 offset:20480
	ds_read_b128 v[204:207], v146 offset:21504
	ds_read_b128 v[212:215], v146 offset:22528
	ds_read_b128 v[218:221], v146 offset:23552
	global_load_lds_dwordx4 v134, s[6:7]
	v_add_u32_e32 v134, s60, v139
	s_mov_b32 m0, s31
	s_add_i32 s62, s60, 0x80000
	global_load_lds_dwordx4 v134, s[6:7]
	v_add_u32_e32 v134, s62, v137
	s_mov_b32 m0, s35
	s_nop 0
	global_load_lds_dwordx4 v134, s[6:7]
	v_add_u32_e32 v134, s62, v139
	s_mov_b32 m0, s36
	s_nop 0
	global_load_lds_dwordx4 v134, s[6:7]
	v_add_u32_e32 v134, s61, v136
	s_mov_b32 m0, s37
	s_nop 0
	global_load_lds_dwordx4 v134, s[4:5]
	v_add_u32_e32 v134, s61, v138
	s_mov_b32 m0, s38
	s_nop 0
	global_load_lds_dwordx4 v134, s[4:5]
	s_waitcnt vmcnt(8)
	s_waitcnt lgkmcnt(0)
	s_setprio 1
	s_barrier
	v_mfma_f32_16x16x32_bf16 v[62:65], v[148:151], v[180:183], 0
	v_mfma_f32_16x16x32_bf16 v[62:65], v[152:155], v[184:187], v[62:65]
	v_mfma_f32_16x16x32_bf16 v[58:61], v[156:159], v[180:183], 0
	v_mfma_f32_16x16x32_bf16 v[58:61], v[160:163], v[184:187], v[58:61]
	v_mfma_f32_16x16x32_bf16 v[46:49], v[148:151], v[188:191], 0
	v_mfma_f32_16x16x32_bf16 v[46:49], v[152:155], v[192:195], v[46:49]
	v_mfma_f32_16x16x32_bf16 v[42:45], v[156:159], v[188:191], 0
	v_mfma_f32_16x16x32_bf16 v[42:45], v[160:163], v[192:195], v[42:45]
	v_mfma_f32_16x16x32_bf16 v[30:33], v[148:151], v[196:199], 0
	v_mfma_f32_16x16x32_bf16 v[30:33], v[152:155], v[204:207], v[30:33]
	v_mfma_f32_16x16x32_bf16 v[26:29], v[156:159], v[196:199], 0
	v_mfma_f32_16x16x32_bf16 v[26:29], v[160:163], v[204:207], v[26:29]
	v_mfma_f32_16x16x32_bf16 v[14:17], v[148:151], v[212:215], 0
	v_mfma_f32_16x16x32_bf16 v[14:17], v[152:155], v[218:221], v[14:17]
	v_mfma_f32_16x16x32_bf16 v[10:13], v[156:159], v[212:215], 0
	v_mfma_f32_16x16x32_bf16 v[10:13], v[160:163], v[218:221], v[10:13]
	s_setprio 0
	s_setprio 1
	v_mfma_f32_16x16x32_bf16 v[54:57], v[164:167], v[180:183], 0
	v_mfma_f32_16x16x32_bf16 v[54:57], v[168:171], v[184:187], v[54:57]
	v_mfma_f32_16x16x32_bf16 v[50:53], v[172:175], v[180:183], 0
	v_mfma_f32_16x16x32_bf16 v[50:53], v[176:179], v[184:187], v[50:53]
	v_mfma_f32_16x16x32_bf16 v[38:41], v[164:167], v[188:191], 0
	v_mfma_f32_16x16x32_bf16 v[38:41], v[168:171], v[192:195], v[38:41]
	v_mfma_f32_16x16x32_bf16 v[34:37], v[172:175], v[188:191], 0
	v_mfma_f32_16x16x32_bf16 v[34:37], v[176:179], v[192:195], v[34:37]
	v_mfma_f32_16x16x32_bf16 v[22:25], v[164:167], v[196:199], 0
	v_mfma_f32_16x16x32_bf16 v[22:25], v[168:171], v[204:207], v[22:25]
	v_mfma_f32_16x16x32_bf16 v[18:21], v[172:175], v[196:199], 0
	v_mfma_f32_16x16x32_bf16 v[18:21], v[176:179], v[204:207], v[18:21]
	v_mfma_f32_16x16x32_bf16 v[6:9], v[164:167], v[212:215], 0
	v_mfma_f32_16x16x32_bf16 v[6:9], v[168:171], v[218:221], v[6:9]
	v_mfma_f32_16x16x32_bf16 v[2:5], v[172:175], v[212:215], 0
	v_mfma_f32_16x16x32_bf16 v[2:5], v[176:179], v[218:221], v[2:5]
	s_setprio 0
	s_barrier
	v_add_u32_e32 v134, s41, v141
	ds_read_b128 v[148:151], v134
	ds_read_b128 v[152:155], v134 offset:1024
	ds_read_b128 v[156:159], v134 offset:2048
	ds_read_b128 v[160:163], v134 offset:3072
	v_add_u32_e32 v134, s46, v141
	ds_read_b128 v[164:167], v134
	ds_read_b128 v[168:171], v134 offset:1024
	ds_read_b128 v[172:175], v134 offset:2048
	ds_read_b128 v[176:179], v134 offset:3072
	s_add_i32 s61, s61, 0x80000
	s_mov_b32 m0, s39
	v_add_u32_e32 v134, s61, v136
	ds_read_b128 v[180:183], v146 offset:32768
	ds_read_b128 v[184:187], v146 offset:33792
	ds_read_b128 v[188:191], v146 offset:34816
	ds_read_b128 v[192:195], v146 offset:35840
	ds_read_b128 v[196:199], v146 offset:36864
	ds_read_b128 v[204:207], v146 offset:37888
	ds_read_b128 v[212:215], v146 offset:38912
	ds_read_b128 v[218:221], v146 offset:39936
	global_load_lds_dwordx4 v134, s[4:5]
	v_add_u32_e32 v134, s61, v138
	s_mov_b32 m0, s40
	s_nop 0
	global_load_lds_dwordx4 v134, s[4:5]
	s_waitcnt vmcnt(8)
	s_waitcnt lgkmcnt(0)
	s_setprio 1
	s_barrier
	v_mfma_f32_16x16x32_bf16 v[126:129], v[148:151], v[180:183], v[126:129]
	v_mfma_f32_16x16x32_bf16 v[126:129], v[152:155], v[184:187], v[126:129]
	v_mfma_f32_16x16x32_bf16 v[122:125], v[156:159], v[180:183], v[122:125]
	v_mfma_f32_16x16x32_bf16 v[122:125], v[160:163], v[184:187], v[122:125]
	v_mfma_f32_16x16x32_bf16 v[110:113], v[148:151], v[188:191], v[110:113]
	v_mfma_f32_16x16x32_bf16 v[110:113], v[152:155], v[192:195], v[110:113]
	v_mfma_f32_16x16x32_bf16 v[106:109], v[156:159], v[188:191], v[106:109]
	v_mfma_f32_16x16x32_bf16 v[106:109], v[160:163], v[192:195], v[106:109]
	v_mfma_f32_16x16x32_bf16 v[94:97], v[148:151], v[196:199], v[94:97]
	v_mfma_f32_16x16x32_bf16 v[94:97], v[152:155], v[204:207], v[94:97]
	v_mfma_f32_16x16x32_bf16 v[90:93], v[156:159], v[196:199], v[90:93]
	v_mfma_f32_16x16x32_bf16 v[90:93], v[160:163], v[204:207], v[90:93]
	v_mfma_f32_16x16x32_bf16 v[78:81], v[148:151], v[212:215], v[78:81]
	v_mfma_f32_16x16x32_bf16 v[78:81], v[152:155], v[218:221], v[78:81]
	v_mfma_f32_16x16x32_bf16 v[74:77], v[156:159], v[212:215], v[74:77]
	v_mfma_f32_16x16x32_bf16 v[74:77], v[160:163], v[218:221], v[74:77]
	s_setprio 0
	s_setprio 1
	v_mfma_f32_16x16x32_bf16 v[118:121], v[164:167], v[180:183], v[118:121]
	v_mfma_f32_16x16x32_bf16 v[118:121], v[168:171], v[184:187], v[118:121]
	v_mfma_f32_16x16x32_bf16 v[114:117], v[172:175], v[180:183], v[114:117]
	v_mfma_f32_16x16x32_bf16 v[114:117], v[176:179], v[184:187], v[114:117]
	v_mfma_f32_16x16x32_bf16 v[102:105], v[164:167], v[188:191], v[102:105]
	v_mfma_f32_16x16x32_bf16 v[102:105], v[168:171], v[192:195], v[102:105]
	v_mfma_f32_16x16x32_bf16 v[98:101], v[172:175], v[188:191], v[98:101]
	v_mfma_f32_16x16x32_bf16 v[98:101], v[176:179], v[192:195], v[98:101]
	v_mfma_f32_16x16x32_bf16 v[86:89], v[164:167], v[196:199], v[86:89]
	v_mfma_f32_16x16x32_bf16 v[86:89], v[168:171], v[204:207], v[86:89]
	v_mfma_f32_16x16x32_bf16 v[82:85], v[172:175], v[196:199], v[82:85]
	v_mfma_f32_16x16x32_bf16 v[82:85], v[176:179], v[204:207], v[82:85]
	v_mfma_f32_16x16x32_bf16 v[70:73], v[164:167], v[212:215], v[70:73]
	v_mfma_f32_16x16x32_bf16 v[70:73], v[168:171], v[218:221], v[70:73]
	v_mfma_f32_16x16x32_bf16 v[66:69], v[172:175], v[212:215], v[66:69]
	v_mfma_f32_16x16x32_bf16 v[66:69], v[176:179], v[218:221], v[66:69]
	s_setprio 0
	s_barrier
	s_or_b32 s61, s60, 0x80
	s_mov_b32 m0, s42
	v_add_u32_e32 v134, s61, v137
	ds_read_b128 v[180:183], v146 offset:49152
	ds_read_b128 v[184:187], v146 offset:50176
	ds_read_b128 v[188:191], v146 offset:51200
	ds_read_b128 v[192:195], v146 offset:52224
	ds_read_b128 v[196:199], v146 offset:53248
	ds_read_b128 v[204:207], v146 offset:54272
	ds_read_b128 v[212:215], v146 offset:55296
	ds_read_b128 v[218:221], v146 offset:56320
	global_load_lds_dwordx4 v134, s[6:7]
	v_add_u32_e32 v134, s61, v139
	s_mov_b32 m0, s43
	s_add_i32 s60, s60, 0x80080
	global_load_lds_dwordx4 v134, s[6:7]
	v_add_u32_e32 v134, s60, v137
	s_mov_b32 m0, s47
	s_nop 0
	global_load_lds_dwordx4 v134, s[6:7]
	v_add_u32_e32 v134, s60, v139
	s_mov_b32 m0, s48
	s_nop 0
	global_load_lds_dwordx4 v134, s[6:7]
	v_add_u32_e32 v134, s59, v136
	s_mov_b32 m0, s44
	s_nop 0
	global_load_lds_dwordx4 v134, s[4:5]
	v_add_u32_e32 v134, s59, v138
	s_mov_b32 m0, s45
	s_nop 0
	global_load_lds_dwordx4 v134, s[4:5]
	s_waitcnt vmcnt(8)
	s_waitcnt lgkmcnt(0)
	s_setprio 1
	s_barrier
	v_mfma_f32_16x16x32_bf16 v[62:65], v[148:151], v[180:183], v[62:65]
	v_mfma_f32_16x16x32_bf16 v[62:65], v[152:155], v[184:187], v[62:65]
	v_mfma_f32_16x16x32_bf16 v[58:61], v[156:159], v[180:183], v[58:61]
	v_mfma_f32_16x16x32_bf16 v[58:61], v[160:163], v[184:187], v[58:61]
	v_mfma_f32_16x16x32_bf16 v[46:49], v[148:151], v[188:191], v[46:49]
	v_mfma_f32_16x16x32_bf16 v[46:49], v[152:155], v[192:195], v[46:49]
	v_mfma_f32_16x16x32_bf16 v[42:45], v[156:159], v[188:191], v[42:45]
	v_mfma_f32_16x16x32_bf16 v[42:45], v[160:163], v[192:195], v[42:45]
	v_mfma_f32_16x16x32_bf16 v[30:33], v[148:151], v[196:199], v[30:33]
	v_mfma_f32_16x16x32_bf16 v[30:33], v[152:155], v[204:207], v[30:33]
	v_mfma_f32_16x16x32_bf16 v[26:29], v[156:159], v[196:199], v[26:29]
	v_mfma_f32_16x16x32_bf16 v[26:29], v[160:163], v[204:207], v[26:29]
	v_mfma_f32_16x16x32_bf16 v[14:17], v[148:151], v[212:215], v[14:17]
	v_mfma_f32_16x16x32_bf16 v[14:17], v[152:155], v[218:221], v[14:17]
	v_mfma_f32_16x16x32_bf16 v[10:13], v[156:159], v[212:215], v[10:13]
	v_mfma_f32_16x16x32_bf16 v[10:13], v[160:163], v[218:221], v[10:13]
	s_setprio 0
	s_setprio 1
	v_mfma_f32_16x16x32_bf16 v[54:57], v[164:167], v[180:183], v[54:57]
	v_mfma_f32_16x16x32_bf16 v[54:57], v[168:171], v[184:187], v[54:57]
	v_mfma_f32_16x16x32_bf16 v[50:53], v[172:175], v[180:183], v[50:53]
	v_mfma_f32_16x16x32_bf16 v[50:53], v[176:179], v[184:187], v[50:53]
	v_mfma_f32_16x16x32_bf16 v[38:41], v[164:167], v[188:191], v[38:41]
	v_mfma_f32_16x16x32_bf16 v[38:41], v[168:171], v[192:195], v[38:41]
	v_mfma_f32_16x16x32_bf16 v[34:37], v[172:175], v[188:191], v[34:37]
	v_mfma_f32_16x16x32_bf16 v[34:37], v[176:179], v[192:195], v[34:37]
	v_mfma_f32_16x16x32_bf16 v[22:25], v[164:167], v[196:199], v[22:25]
	v_mfma_f32_16x16x32_bf16 v[22:25], v[168:171], v[204:207], v[22:25]
	v_mfma_f32_16x16x32_bf16 v[18:21], v[172:175], v[196:199], v[18:21]
	v_mfma_f32_16x16x32_bf16 v[18:21], v[176:179], v[204:207], v[18:21]
	v_mfma_f32_16x16x32_bf16 v[6:9], v[164:167], v[212:215], v[6:9]
	v_mfma_f32_16x16x32_bf16 v[6:9], v[168:171], v[218:221], v[6:9]
	v_mfma_f32_16x16x32_bf16 v[2:5], v[172:175], v[212:215], v[2:5]
	v_mfma_f32_16x16x32_bf16 v[2:5], v[176:179], v[218:221], v[2:5]
	s_setprio 0
	s_barrier
	s_add_i32 s58, s58, 2
	s_addk_i32 s56, 0x100
	s_addk_i32 s57, 0x100
	v_add_u32_e32 v132, 0x100, v132
	s_cmp_gt_u32 s58, 29
	v_add_u32_e32 v133, 0x100, v133
.LBB0_704:
	v_add_u32_e32 v134, s25, v141
	ds_read_b128 v[148:151], v134
	ds_read_b128 v[152:155], v134 offset:1024
	ds_read_b128 v[156:159], v134 offset:2048
	ds_read_b128 v[160:163], v134 offset:3072
	v_add_u32_e32 v134, s34, v141
	ds_read_b128 v[164:167], v134
	ds_read_b128 v[168:171], v134 offset:1024
	ds_read_b128 v[172:175], v134 offset:2048
	ds_read_b128 v[176:179], v134 offset:3072
	s_cmp_eq_u32 s58, 28
	s_cselect_b32 s61, s54, s57
	s_cselect_b32 s60, s55, s56
	s_or_b32 s59, s61, 0x80
	s_add_i32 m0, s37, 0xc000
	ds_read_b128 v[180:183], v146
	ds_read_b128 v[184:187], v146 offset:1024
	ds_read_b128 v[188:191], v146 offset:2048
	ds_read_b128 v[192:195], v146 offset:3072
	ds_read_b128 v[196:199], v146 offset:4096
	ds_read_b128 v[204:207], v146 offset:5120
	ds_read_b128 v[212:215], v146 offset:6144
	ds_read_b128 v[218:221], v146 offset:7168
	global_load_lds_dwordx4 v133, s[4:5]
	s_add_i32 m0, s37, 0xe000
	s_nop 0
	global_load_lds_dwordx4 v132, s[4:5]
	s_waitcnt vmcnt(8)
	s_waitcnt lgkmcnt(0)
	s_setprio 1
	s_barrier
	v_mfma_f32_16x16x32_bf16 v[126:129], v[148:151], v[180:183], v[126:129]
	v_mfma_f32_16x16x32_bf16 v[126:129], v[152:155], v[184:187], v[126:129]
	v_mfma_f32_16x16x32_bf16 v[122:125], v[156:159], v[180:183], v[122:125]
	v_mfma_f32_16x16x32_bf16 v[122:125], v[160:163], v[184:187], v[122:125]
	v_mfma_f32_16x16x32_bf16 v[110:113], v[148:151], v[188:191], v[110:113]
	v_mfma_f32_16x16x32_bf16 v[110:113], v[152:155], v[192:195], v[110:113]
	v_mfma_f32_16x16x32_bf16 v[106:109], v[156:159], v[188:191], v[106:109]
	v_mfma_f32_16x16x32_bf16 v[106:109], v[160:163], v[192:195], v[106:109]
	v_mfma_f32_16x16x32_bf16 v[94:97], v[148:151], v[196:199], v[94:97]
	v_mfma_f32_16x16x32_bf16 v[94:97], v[152:155], v[204:207], v[94:97]
	v_mfma_f32_16x16x32_bf16 v[90:93], v[156:159], v[196:199], v[90:93]
	v_mfma_f32_16x16x32_bf16 v[90:93], v[160:163], v[204:207], v[90:93]
	v_mfma_f32_16x16x32_bf16 v[78:81], v[148:151], v[212:215], v[78:81]
	v_mfma_f32_16x16x32_bf16 v[78:81], v[152:155], v[218:221], v[78:81]
	v_mfma_f32_16x16x32_bf16 v[74:77], v[156:159], v[212:215], v[74:77]
	v_mfma_f32_16x16x32_bf16 v[74:77], v[160:163], v[218:221], v[74:77]
	s_setprio 0
	s_setprio 1
	v_mfma_f32_16x16x32_bf16 v[118:121], v[164:167], v[180:183], v[118:121]
	v_mfma_f32_16x16x32_bf16 v[118:121], v[168:171], v[184:187], v[118:121]
	v_mfma_f32_16x16x32_bf16 v[114:117], v[172:175], v[180:183], v[114:117]
	v_mfma_f32_16x16x32_bf16 v[114:117], v[176:179], v[184:187], v[114:117]
	v_mfma_f32_16x16x32_bf16 v[102:105], v[164:167], v[188:191], v[102:105]
	v_mfma_f32_16x16x32_bf16 v[102:105], v[168:171], v[192:195], v[102:105]
	v_mfma_f32_16x16x32_bf16 v[98:101], v[172:175], v[188:191], v[98:101]
	v_mfma_f32_16x16x32_bf16 v[98:101], v[176:179], v[192:195], v[98:101]
	v_mfma_f32_16x16x32_bf16 v[86:89], v[164:167], v[196:199], v[86:89]
	v_mfma_f32_16x16x32_bf16 v[86:89], v[168:171], v[204:207], v[86:89]
	v_mfma_f32_16x16x32_bf16 v[82:85], v[172:175], v[196:199], v[82:85]
	v_mfma_f32_16x16x32_bf16 v[82:85], v[176:179], v[204:207], v[82:85]
	v_mfma_f32_16x16x32_bf16 v[70:73], v[164:167], v[212:215], v[70:73]
	v_mfma_f32_16x16x32_bf16 v[70:73], v[168:171], v[218:221], v[70:73]
	v_mfma_f32_16x16x32_bf16 v[66:69], v[172:175], v[212:215], v[66:69]
	v_mfma_f32_16x16x32_bf16 v[66:69], v[176:179], v[218:221], v[66:69]
	s_setprio 0
	s_barrier
	s_mov_b32 m0, s30
	v_add_u32_e32 v134, s60, v137
	ds_read_b128 v[180:183], v146 offset:16384
	ds_read_b128 v[184:187], v146 offset:17408
	ds_read_b128 v[188:191], v146 offset:18432
	ds_read_b128 v[192:195], v146 offset:19456
	ds_read_b128 v[196:199], v146 offset:20480
	ds_read_b128 v[204:207], v146 offset:21504
	ds_read_b128 v[212:215], v146 offset:22528
	ds_read_b128 v[218:221], v146 offset:23552
	global_load_lds_dwordx4 v134, s[6:7]
	v_add_u32_e32 v134, s60, v139
	s_mov_b32 m0, s31
	s_add_i32 s62, s60, 0x80000
	global_load_lds_dwordx4 v134, s[6:7]
	v_add_u32_e32 v134, s62, v137
	s_mov_b32 m0, s35
	s_nop 0
	global_load_lds_dwordx4 v134, s[6:7]
	v_add_u32_e32 v134, s62, v139
	s_mov_b32 m0, s36
	s_nop 0
	global_load_lds_dwordx4 v134, s[6:7]
	v_add_u32_e32 v134, s61, v136
	s_mov_b32 m0, s37
	s_nop 0
	global_load_lds_dwordx4 v134, s[4:5]
	v_add_u32_e32 v134, s61, v138
	s_mov_b32 m0, s38
	s_nop 0
	global_load_lds_dwordx4 v134, s[4:5]
	s_waitcnt vmcnt(8)
	s_waitcnt lgkmcnt(0)
	s_setprio 1
	s_barrier
	v_mfma_f32_16x16x32_bf16 v[62:65], v[148:151], v[180:183], v[62:65]
	v_mfma_f32_16x16x32_bf16 v[62:65], v[152:155], v[184:187], v[62:65]
	v_mfma_f32_16x16x32_bf16 v[58:61], v[156:159], v[180:183], v[58:61]
	v_mfma_f32_16x16x32_bf16 v[58:61], v[160:163], v[184:187], v[58:61]
	v_mfma_f32_16x16x32_bf16 v[46:49], v[148:151], v[188:191], v[46:49]
	v_mfma_f32_16x16x32_bf16 v[46:49], v[152:155], v[192:195], v[46:49]
	v_mfma_f32_16x16x32_bf16 v[42:45], v[156:159], v[188:191], v[42:45]
	v_mfma_f32_16x16x32_bf16 v[42:45], v[160:163], v[192:195], v[42:45]
	v_mfma_f32_16x16x32_bf16 v[30:33], v[148:151], v[196:199], v[30:33]
	v_mfma_f32_16x16x32_bf16 v[30:33], v[152:155], v[204:207], v[30:33]
	v_mfma_f32_16x16x32_bf16 v[26:29], v[156:159], v[196:199], v[26:29]
	v_mfma_f32_16x16x32_bf16 v[26:29], v[160:163], v[204:207], v[26:29]
	v_mfma_f32_16x16x32_bf16 v[14:17], v[148:151], v[212:215], v[14:17]
	v_mfma_f32_16x16x32_bf16 v[14:17], v[152:155], v[218:221], v[14:17]
	v_mfma_f32_16x16x32_bf16 v[10:13], v[156:159], v[212:215], v[10:13]
	v_mfma_f32_16x16x32_bf16 v[10:13], v[160:163], v[218:221], v[10:13]
	s_setprio 0
	s_setprio 1
	v_mfma_f32_16x16x32_bf16 v[54:57], v[164:167], v[180:183], v[54:57]
	v_mfma_f32_16x16x32_bf16 v[54:57], v[168:171], v[184:187], v[54:57]
	v_mfma_f32_16x16x32_bf16 v[50:53], v[172:175], v[180:183], v[50:53]
	v_mfma_f32_16x16x32_bf16 v[50:53], v[176:179], v[184:187], v[50:53]
	v_mfma_f32_16x16x32_bf16 v[38:41], v[164:167], v[188:191], v[38:41]
	v_mfma_f32_16x16x32_bf16 v[38:41], v[168:171], v[192:195], v[38:41]
	v_mfma_f32_16x16x32_bf16 v[34:37], v[172:175], v[188:191], v[34:37]
	v_mfma_f32_16x16x32_bf16 v[34:37], v[176:179], v[192:195], v[34:37]
	v_mfma_f32_16x16x32_bf16 v[22:25], v[164:167], v[196:199], v[22:25]
	v_mfma_f32_16x16x32_bf16 v[22:25], v[168:171], v[204:207], v[22:25]
	v_mfma_f32_16x16x32_bf16 v[18:21], v[172:175], v[196:199], v[18:21]
	v_mfma_f32_16x16x32_bf16 v[18:21], v[176:179], v[204:207], v[18:21]
	v_mfma_f32_16x16x32_bf16 v[6:9], v[164:167], v[212:215], v[6:9]
	v_mfma_f32_16x16x32_bf16 v[6:9], v[168:171], v[218:221], v[6:9]
	v_mfma_f32_16x16x32_bf16 v[2:5], v[172:175], v[212:215], v[2:5]
	v_mfma_f32_16x16x32_bf16 v[2:5], v[176:179], v[218:221], v[2:5]
	s_setprio 0
	s_barrier
	v_add_u32_e32 v134, s41, v141
	ds_read_b128 v[148:151], v134
	ds_read_b128 v[152:155], v134 offset:1024
	ds_read_b128 v[156:159], v134 offset:2048
	ds_read_b128 v[160:163], v134 offset:3072
	v_add_u32_e32 v134, s46, v141
	ds_read_b128 v[164:167], v134
	ds_read_b128 v[168:171], v134 offset:1024
	ds_read_b128 v[172:175], v134 offset:2048
	ds_read_b128 v[176:179], v134 offset:3072
	s_add_i32 s61, s61, 0x80000
	s_mov_b32 m0, s39
	v_add_u32_e32 v134, s61, v136
	ds_read_b128 v[180:183], v146 offset:32768
	ds_read_b128 v[184:187], v146 offset:33792
	ds_read_b128 v[188:191], v146 offset:34816
	ds_read_b128 v[192:195], v146 offset:35840
	ds_read_b128 v[196:199], v146 offset:36864
	ds_read_b128 v[204:207], v146 offset:37888
	ds_read_b128 v[212:215], v146 offset:38912
	ds_read_b128 v[218:221], v146 offset:39936
	global_load_lds_dwordx4 v134, s[4:5]
	v_add_u32_e32 v134, s61, v138
	s_mov_b32 m0, s40
	s_nop 0
	global_load_lds_dwordx4 v134, s[4:5]
	s_waitcnt vmcnt(8)
	s_waitcnt lgkmcnt(0)
	s_setprio 1
	s_barrier
	v_mfma_f32_16x16x32_bf16 v[126:129], v[148:151], v[180:183], v[126:129]
	v_mfma_f32_16x16x32_bf16 v[126:129], v[152:155], v[184:187], v[126:129]
	v_mfma_f32_16x16x32_bf16 v[122:125], v[156:159], v[180:183], v[122:125]
	v_mfma_f32_16x16x32_bf16 v[122:125], v[160:163], v[184:187], v[122:125]
	v_mfma_f32_16x16x32_bf16 v[110:113], v[148:151], v[188:191], v[110:113]
	v_mfma_f32_16x16x32_bf16 v[110:113], v[152:155], v[192:195], v[110:113]
	v_mfma_f32_16x16x32_bf16 v[106:109], v[156:159], v[188:191], v[106:109]
	v_mfma_f32_16x16x32_bf16 v[106:109], v[160:163], v[192:195], v[106:109]
	v_mfma_f32_16x16x32_bf16 v[94:97], v[148:151], v[196:199], v[94:97]
	v_mfma_f32_16x16x32_bf16 v[94:97], v[152:155], v[204:207], v[94:97]
	v_mfma_f32_16x16x32_bf16 v[90:93], v[156:159], v[196:199], v[90:93]
	v_mfma_f32_16x16x32_bf16 v[90:93], v[160:163], v[204:207], v[90:93]
	v_mfma_f32_16x16x32_bf16 v[78:81], v[148:151], v[212:215], v[78:81]
	v_mfma_f32_16x16x32_bf16 v[78:81], v[152:155], v[218:221], v[78:81]
	v_mfma_f32_16x16x32_bf16 v[74:77], v[156:159], v[212:215], v[74:77]
	v_mfma_f32_16x16x32_bf16 v[74:77], v[160:163], v[218:221], v[74:77]
	s_setprio 0
	s_setprio 1
	v_mfma_f32_16x16x32_bf16 v[118:121], v[164:167], v[180:183], v[118:121]
	v_mfma_f32_16x16x32_bf16 v[118:121], v[168:171], v[184:187], v[118:121]
	v_mfma_f32_16x16x32_bf16 v[114:117], v[172:175], v[180:183], v[114:117]
	v_mfma_f32_16x16x32_bf16 v[114:117], v[176:179], v[184:187], v[114:117]
	v_mfma_f32_16x16x32_bf16 v[102:105], v[164:167], v[188:191], v[102:105]
	v_mfma_f32_16x16x32_bf16 v[102:105], v[168:171], v[192:195], v[102:105]
	v_mfma_f32_16x16x32_bf16 v[98:101], v[172:175], v[188:191], v[98:101]
	v_mfma_f32_16x16x32_bf16 v[98:101], v[176:179], v[192:195], v[98:101]
	v_mfma_f32_16x16x32_bf16 v[86:89], v[164:167], v[196:199], v[86:89]
	v_mfma_f32_16x16x32_bf16 v[86:89], v[168:171], v[204:207], v[86:89]
	v_mfma_f32_16x16x32_bf16 v[82:85], v[172:175], v[196:199], v[82:85]
	v_mfma_f32_16x16x32_bf16 v[82:85], v[176:179], v[204:207], v[82:85]
	v_mfma_f32_16x16x32_bf16 v[70:73], v[164:167], v[212:215], v[70:73]
	v_mfma_f32_16x16x32_bf16 v[70:73], v[168:171], v[218:221], v[70:73]
	v_mfma_f32_16x16x32_bf16 v[66:69], v[172:175], v[212:215], v[66:69]
	v_mfma_f32_16x16x32_bf16 v[66:69], v[176:179], v[218:221], v[66:69]
	s_setprio 0
	s_barrier
	s_or_b32 s61, s60, 0x80
	s_mov_b32 m0, s42
	v_add_u32_e32 v134, s61, v137
	ds_read_b128 v[180:183], v146 offset:49152
	ds_read_b128 v[184:187], v146 offset:50176
	ds_read_b128 v[188:191], v146 offset:51200
	ds_read_b128 v[192:195], v146 offset:52224
	ds_read_b128 v[196:199], v146 offset:53248
	ds_read_b128 v[204:207], v146 offset:54272
	ds_read_b128 v[212:215], v146 offset:55296
	ds_read_b128 v[218:221], v146 offset:56320
	global_load_lds_dwordx4 v134, s[6:7]
	v_add_u32_e32 v134, s61, v139
	s_mov_b32 m0, s43
	s_add_i32 s60, s60, 0x80080
	global_load_lds_dwordx4 v134, s[6:7]
	v_add_u32_e32 v134, s60, v137
	s_mov_b32 m0, s47
	s_nop 0
	global_load_lds_dwordx4 v134, s[6:7]
	v_add_u32_e32 v134, s60, v139
	s_mov_b32 m0, s48
	s_nop 0
	global_load_lds_dwordx4 v134, s[6:7]
	v_add_u32_e32 v134, s59, v136
	s_mov_b32 m0, s44
	s_nop 0
	global_load_lds_dwordx4 v134, s[4:5]
	v_add_u32_e32 v134, s59, v138
	s_mov_b32 m0, s45
	s_nop 0
	global_load_lds_dwordx4 v134, s[4:5]
	s_add_i32 s58, s58, 2
	s_addk_i32 s56, 0x100
	s_addk_i32 s57, 0x100
	v_add_u32_e32 v132, 0x100, v132
	s_cmp_gt_u32 s58, 29
	v_add_u32_e32 v133, 0x100, v133
	s_waitcnt vmcnt(8)
	s_waitcnt lgkmcnt(0)
	s_setprio 1
	s_barrier
	v_mfma_f32_16x16x32_bf16 v[62:65], v[148:151], v[180:183], v[62:65]
	v_mfma_f32_16x16x32_bf16 v[62:65], v[152:155], v[184:187], v[62:65]
	v_mfma_f32_16x16x32_bf16 v[58:61], v[156:159], v[180:183], v[58:61]
	v_mfma_f32_16x16x32_bf16 v[58:61], v[160:163], v[184:187], v[58:61]
	v_mfma_f32_16x16x32_bf16 v[46:49], v[148:151], v[188:191], v[46:49]
	v_mfma_f32_16x16x32_bf16 v[46:49], v[152:155], v[192:195], v[46:49]
	v_mfma_f32_16x16x32_bf16 v[42:45], v[156:159], v[188:191], v[42:45]
	v_mfma_f32_16x16x32_bf16 v[42:45], v[160:163], v[192:195], v[42:45]
	v_mfma_f32_16x16x32_bf16 v[30:33], v[148:151], v[196:199], v[30:33]
	v_mfma_f32_16x16x32_bf16 v[30:33], v[152:155], v[204:207], v[30:33]
	v_mfma_f32_16x16x32_bf16 v[26:29], v[156:159], v[196:199], v[26:29]
	v_mfma_f32_16x16x32_bf16 v[26:29], v[160:163], v[204:207], v[26:29]
	v_mfma_f32_16x16x32_bf16 v[14:17], v[148:151], v[212:215], v[14:17]
	v_mfma_f32_16x16x32_bf16 v[14:17], v[152:155], v[218:221], v[14:17]
	v_mfma_f32_16x16x32_bf16 v[10:13], v[156:159], v[212:215], v[10:13]
	v_mfma_f32_16x16x32_bf16 v[10:13], v[160:163], v[218:221], v[10:13]
	s_setprio 0
	s_setprio 1
	v_mfma_f32_16x16x32_bf16 v[54:57], v[164:167], v[180:183], v[54:57]
	v_mfma_f32_16x16x32_bf16 v[54:57], v[168:171], v[184:187], v[54:57]
	v_mfma_f32_16x16x32_bf16 v[50:53], v[172:175], v[180:183], v[50:53]
	v_mfma_f32_16x16x32_bf16 v[50:53], v[176:179], v[184:187], v[50:53]
	v_mfma_f32_16x16x32_bf16 v[38:41], v[164:167], v[188:191], v[38:41]
	v_mfma_f32_16x16x32_bf16 v[38:41], v[168:171], v[192:195], v[38:41]
	v_mfma_f32_16x16x32_bf16 v[34:37], v[172:175], v[188:191], v[34:37]
	v_mfma_f32_16x16x32_bf16 v[34:37], v[176:179], v[192:195], v[34:37]
	v_mfma_f32_16x16x32_bf16 v[22:25], v[164:167], v[196:199], v[22:25]
	v_mfma_f32_16x16x32_bf16 v[22:25], v[168:171], v[204:207], v[22:25]
	v_mfma_f32_16x16x32_bf16 v[18:21], v[172:175], v[196:199], v[18:21]
	v_mfma_f32_16x16x32_bf16 v[18:21], v[176:179], v[204:207], v[18:21]
	v_mfma_f32_16x16x32_bf16 v[6:9], v[164:167], v[212:215], v[6:9]
	v_mfma_f32_16x16x32_bf16 v[6:9], v[168:171], v[218:221], v[6:9]
	v_mfma_f32_16x16x32_bf16 v[2:5], v[172:175], v[212:215], v[2:5]
	v_mfma_f32_16x16x32_bf16 v[2:5], v[176:179], v[218:221], v[2:5]
	s_setprio 0
	s_barrier
	s_cbranch_scc0 .LBB0_704
	s_and_b64 vcc, exec, s[16:17]
	s_cbranch_vccz .LBB0_707
	s_barrier

.LBB0_724:
	v_lshrrev_b32_e32 v9, 1, v5
	v_and_b32_e32 v135, 24, v9
	v_and_b32_e32 v136, 15, v5
	v_lshlrev_b32_e32 v9, 1, v135
	v_lshlrev_b32_e32 v5, 2, v5
	s_lshl_b32 s27, s27, 5
	s_lshl_b32 s26, s29, 6
	v_lshl_or_b32 v9, v136, 6, v9
	s_lshl_b32 s29, s29, 13
	v_and_b32_e32 v5, 32, v5
	s_and_b32 s27, s27, 0x60
	v_bitop3_b32 v10, v9, s29, v5 bitop3:0xde
	s_lshl_b32 s29, s27, 7
	v_bitop3_b32 v137, v9, s29, v5 bitop3:0xde
	s_add_i32 s29, s28, 0x18000
	s_or_b32 s31, s12, 0x80
	s_add_i32 s30, s29, s37
	v_add_u32_e32 v5, s31, v131
	s_mov_b32 m0, s30
	s_waitcnt vmcnt(2)
	s_barrier
	global_load_lds_dwordx4 v5, s[6:7]
	v_add_u32_e32 v5, s31, v133
	s_add_i32 s31, s30, 0x2000
	s_mov_b32 m0, s31
	s_or_b32 s35, s21, 0x80
	s_add_i32 s34, s22, 0x8000
	global_load_lds_dwordx4 v5, s[6:7]
	v_add_u32_e32 v5, s35, v130
	s_mov_b32 m0, s34
	s_add_i32 s36, s28, 0x1c000
	global_load_lds_dwordx4 v5, s[4:5]
	v_add_u32_e32 v5, s35, v132
	s_add_i32 s35, s22, 0xa000
	s_mov_b32 m0, s35
	s_or_b32 s38, s12, 0x80080
	s_add_i32 s37, s36, s37
	global_load_lds_dwordx4 v5, s[4:5]
	v_add_u32_e32 v5, s38, v131
	s_mov_b32 m0, s37
	s_add_i32 s39, s21, 0x80080
	global_load_lds_dwordx4 v5, s[6:7]
	v_add_u32_e32 v5, s38, v133
	s_add_i32 s38, s37, 0x2000
	s_mov_b32 m0, s38
	v_lshlrev_b32_e32 v7, 12, v7
	global_load_lds_dwordx4 v5, s[6:7]
	v_lshlrev_b32_e32 v5, 15, v6
	v_and_b32_e32 v5, 0xffff0000, v5
	v_and_b32_e32 v6, 1, v6
	v_add3_u32 v5, s39, v5, v7
	v_lshlrev_b32_e32 v6, 6, v6
	v_lshlrev_b32_e32 v7, 1, v8
	v_add3_u32 v138, v5, v6, v7
	v_lshlrev_b32_e32 v5, 15, v2
	v_and_b32_e32 v5, 0xffff0000, v5
	v_lshlrev_b32_e32 v3, 12, v3
	v_and_b32_e32 v2, 1, v2
	s_waitcnt vmcnt(6)
	v_add3_u32 v3, s39, v5, v3
	v_lshlrev_b32_e32 v2, 6, v2
	v_lshlrev_b32_e32 v4, 1, v4
	v_add3_u32 v139, v3, v2, v4
	v_or_b32_e32 v134, s26, v136
	s_mov_b32 s39, -2
	s_mov_b32 s40, 0
	v_add_u32_e32 v140, s28, v10
	s_barrier
	v_add_u32_e32 v141, s13, v137
	ds_read_b128 v[142:145], v141
	ds_read_b128 v[146:149], v141 offset:1024
	ds_read_b128 v[150:153], v141 offset:2048
	ds_read_b128 v[154:157], v141 offset:3072
	v_add_u32_e32 v141, s16, v137
	ds_read_b128 v[158:161], v141
	ds_read_b128 v[162:165], v141 offset:1024
	ds_read_b128 v[166:169], v141 offset:2048
	ds_read_b128 v[170:173], v141 offset:3072
	s_add_i32 s41, s40, 0x100
	s_cmp_lg_u32 s39, 28
	s_cselect_b32 s43, s41, 0
	s_add_i32 s44, s43, s21
	s_or_b32 s42, s44, 0x80
	s_add_i32 s43, s43, s12
	v_add_u32_e32 v141, s40, v139
	s_add_i32 m0, s22, 0xc000
	ds_read_b128 v[174:177], v140
	ds_read_b128 v[178:181], v140 offset:1024
	ds_read_b128 v[182:185], v140 offset:2048
	ds_read_b128 v[186:189], v140 offset:3072
	ds_read_b128 v[190:193], v140 offset:4096
	ds_read_b128 v[194:197], v140 offset:5120
	ds_read_b128 v[198:201], v140 offset:6144
	ds_read_b128 v[204:207], v140 offset:7168
	global_load_lds_dwordx4 v141, s[4:5]
	v_add_u32_e32 v141, s40, v138
	s_add_i32 m0, s22, 0xe000
	s_nop 0
	global_load_lds_dwordx4 v141, s[4:5]
	s_waitcnt vmcnt(8)
	s_waitcnt lgkmcnt(0)
	s_setprio 1
	s_barrier
	v_mfma_f32_16x16x32_bf16 v[126:129], v[142:145], v[174:177], 0
	v_mfma_f32_16x16x32_bf16 v[126:129], v[146:149], v[178:181], v[126:129]
	v_mfma_f32_16x16x32_bf16 v[122:125], v[150:153], v[174:177], 0
	v_mfma_f32_16x16x32_bf16 v[122:125], v[154:157], v[178:181], v[122:125]
	v_mfma_f32_16x16x32_bf16 v[110:113], v[142:145], v[182:185], 0
	v_mfma_f32_16x16x32_bf16 v[110:113], v[146:149], v[186:189], v[110:113]
	v_mfma_f32_16x16x32_bf16 v[106:109], v[150:153], v[182:185], 0
	v_mfma_f32_16x16x32_bf16 v[106:109], v[154:157], v[186:189], v[106:109]
	v_mfma_f32_16x16x32_bf16 v[94:97], v[142:145], v[190:193], 0
	v_mfma_f32_16x16x32_bf16 v[94:97], v[146:149], v[194:197], v[94:97]
	v_mfma_f32_16x16x32_bf16 v[90:93], v[150:153], v[190:193], 0
	v_mfma_f32_16x16x32_bf16 v[90:93], v[154:157], v[194:197], v[90:93]
	v_mfma_f32_16x16x32_bf16 v[78:81], v[142:145], v[198:201], 0
	v_mfma_f32_16x16x32_bf16 v[78:81], v[146:149], v[204:207], v[78:81]
	v_mfma_f32_16x16x32_bf16 v[74:77], v[150:153], v[198:201], 0
	v_mfma_f32_16x16x32_bf16 v[74:77], v[154:157], v[204:207], v[74:77]
	s_setprio 0
	s_setprio 1
	v_mfma_f32_16x16x32_bf16 v[118:121], v[158:161], v[174:177], 0
	v_mfma_f32_16x16x32_bf16 v[118:121], v[162:165], v[178:181], v[118:121]
	v_mfma_f32_16x16x32_bf16 v[114:117], v[166:169], v[174:177], 0
	v_mfma_f32_16x16x32_bf16 v[114:117], v[170:173], v[178:181], v[114:117]
	v_mfma_f32_16x16x32_bf16 v[102:105], v[158:161], v[182:185], 0
	v_mfma_f32_16x16x32_bf16 v[102:105], v[162:165], v[186:189], v[102:105]
	v_mfma_f32_16x16x32_bf16 v[98:101], v[166:169], v[182:185], 0
	v_mfma_f32_16x16x32_bf16 v[98:101], v[170:173], v[186:189], v[98:101]
	v_mfma_f32_16x16x32_bf16 v[86:89], v[158:161], v[190:193], 0
	v_mfma_f32_16x16x32_bf16 v[86:89], v[162:165], v[194:197], v[86:89]
	v_mfma_f32_16x16x32_bf16 v[82:85], v[166:169], v[190:193], 0
	v_mfma_f32_16x16x32_bf16 v[82:85], v[170:173], v[194:197], v[82:85]
	v_mfma_f32_16x16x32_bf16 v[70:73], v[158:161], v[198:201], 0
	v_mfma_f32_16x16x32_bf16 v[70:73], v[162:165], v[204:207], v[70:73]
	v_mfma_f32_16x16x32_bf16 v[66:69], v[166:169], v[198:201], 0
	v_mfma_f32_16x16x32_bf16 v[66:69], v[170:173], v[204:207], v[66:69]
	s_setprio 0
	s_barrier
	s_mov_b32 m0, s14
	v_add_u32_e32 v141, s43, v131
	ds_read_b128 v[174:177], v140 offset:16384
	ds_read_b128 v[178:181], v140 offset:17408
	ds_read_b128 v[182:185], v140 offset:18432
	ds_read_b128 v[186:189], v140 offset:19456
	ds_read_b128 v[190:193], v140 offset:20480
	ds_read_b128 v[194:197], v140 offset:21504
	ds_read_b128 v[198:201], v140 offset:22528
	ds_read_b128 v[204:207], v140 offset:23552
	global_load_lds_dwordx4 v141, s[6:7]
	v_add_u32_e32 v141, s43, v133
	s_mov_b32 m0, s15
	s_add_i32 s40, s43, 0x80000
	global_load_lds_dwordx4 v141, s[6:7]
	v_add_u32_e32 v141, s40, v131
	s_mov_b32 m0, s17
	s_nop 0
	global_load_lds_dwordx4 v141, s[6:7]
	v_add_u32_e32 v141, s40, v133
	s_mov_b32 m0, s20
	s_nop 0
	global_load_lds_dwordx4 v141, s[6:7]
	v_add_u32_e32 v141, s44, v130
	s_mov_b32 m0, s22
	s_nop 0
	global_load_lds_dwordx4 v141, s[4:5]
	v_add_u32_e32 v141, s44, v132
	s_mov_b32 m0, s23
	s_nop 0
	global_load_lds_dwordx4 v141, s[4:5]
	s_waitcnt vmcnt(8)
	s_waitcnt lgkmcnt(0)
	s_setprio 1
	s_barrier
	v_mfma_f32_16x16x32_bf16 v[62:65], v[142:145], v[174:177], 0
	v_mfma_f32_16x16x32_bf16 v[62:65], v[146:149], v[178:181], v[62:65]
	v_mfma_f32_16x16x32_bf16 v[58:61], v[150:153], v[174:177], 0
	v_mfma_f32_16x16x32_bf16 v[58:61], v[154:157], v[178:181], v[58:61]
	v_mfma_f32_16x16x32_bf16 v[46:49], v[142:145], v[182:185], 0
	v_mfma_f32_16x16x32_bf16 v[46:49], v[146:149], v[186:189], v[46:49]
	v_mfma_f32_16x16x32_bf16 v[42:45], v[150:153], v[182:185], 0
	v_mfma_f32_16x16x32_bf16 v[42:45], v[154:157], v[186:189], v[42:45]
	v_mfma_f32_16x16x32_bf16 v[30:33], v[142:145], v[190:193], 0
	v_mfma_f32_16x16x32_bf16 v[30:33], v[146:149], v[194:197], v[30:33]
	v_mfma_f32_16x16x32_bf16 v[26:29], v[150:153], v[190:193], 0
	v_mfma_f32_16x16x32_bf16 v[26:29], v[154:157], v[194:197], v[26:29]
	v_mfma_f32_16x16x32_bf16 v[14:17], v[142:145], v[198:201], 0
	v_mfma_f32_16x16x32_bf16 v[14:17], v[146:149], v[204:207], v[14:17]
	v_mfma_f32_16x16x32_bf16 v[10:13], v[150:153], v[198:201], 0
	v_mfma_f32_16x16x32_bf16 v[10:13], v[154:157], v[204:207], v[10:13]
	s_setprio 0
	s_setprio 1
	v_mfma_f32_16x16x32_bf16 v[54:57], v[158:161], v[174:177], 0
	v_mfma_f32_16x16x32_bf16 v[54:57], v[162:165], v[178:181], v[54:57]
	v_mfma_f32_16x16x32_bf16 v[50:53], v[166:169], v[174:177], 0
	v_mfma_f32_16x16x32_bf16 v[50:53], v[170:173], v[178:181], v[50:53]
	v_mfma_f32_16x16x32_bf16 v[38:41], v[158:161], v[182:185], 0
	v_mfma_f32_16x16x32_bf16 v[38:41], v[162:165], v[186:189], v[38:41]
	v_mfma_f32_16x16x32_bf16 v[34:37], v[166:169], v[182:185], 0
	v_mfma_f32_16x16x32_bf16 v[34:37], v[170:173], v[186:189], v[34:37]
	v_mfma_f32_16x16x32_bf16 v[22:25], v[158:161], v[190:193], 0
	v_mfma_f32_16x16x32_bf16 v[22:25], v[162:165], v[194:197], v[22:25]
	v_mfma_f32_16x16x32_bf16 v[18:21], v[166:169], v[190:193], 0
	v_mfma_f32_16x16x32_bf16 v[18:21], v[170:173], v[194:197], v[18:21]
	v_mfma_f32_16x16x32_bf16 v[6:9], v[158:161], v[198:201], 0
	v_mfma_f32_16x16x32_bf16 v[6:9], v[162:165], v[204:207], v[6:9]
	v_mfma_f32_16x16x32_bf16 v[2:5], v[166:169], v[198:201], 0
	v_mfma_f32_16x16x32_bf16 v[2:5], v[170:173], v[204:207], v[2:5]
	s_setprio 0
	s_barrier
	v_add_u32_e32 v141, s29, v137
	ds_read_b128 v[142:145], v141
	ds_read_b128 v[146:149], v141 offset:1024
	ds_read_b128 v[150:153], v141 offset:2048
	ds_read_b128 v[154:157], v141 offset:3072
	v_add_u32_e32 v141, s36, v137
	ds_read_b128 v[158:161], v141
	ds_read_b128 v[162:165], v141 offset:1024
	ds_read_b128 v[166:169], v141 offset:2048
	ds_read_b128 v[170:173], v141 offset:3072
	s_add_i32 s44, s44, 0x80000
	s_mov_b32 m0, s24
	v_add_u32_e32 v141, s44, v130
	ds_read_b128 v[174:177], v140 offset:32768
	ds_read_b128 v[178:181], v140 offset:33792
	ds_read_b128 v[182:185], v140 offset:34816
	ds_read_b128 v[186:189], v140 offset:35840
	ds_read_b128 v[190:193], v140 offset:36864
	ds_read_b128 v[194:197], v140 offset:37888
	ds_read_b128 v[198:201], v140 offset:38912
	ds_read_b128 v[204:207], v140 offset:39936
	global_load_lds_dwordx4 v141, s[4:5]
	v_add_u32_e32 v141, s44, v132
	s_mov_b32 m0, s25
	s_nop 0
	global_load_lds_dwordx4 v141, s[4:5]
	s_waitcnt vmcnt(8)
	s_waitcnt lgkmcnt(0)
	s_setprio 1
	s_barrier
	v_mfma_f32_16x16x32_bf16 v[126:129], v[142:145], v[174:177], v[126:129]
	v_mfma_f32_16x16x32_bf16 v[126:129], v[146:149], v[178:181], v[126:129]
	v_mfma_f32_16x16x32_bf16 v[122:125], v[150:153], v[174:177], v[122:125]
	v_mfma_f32_16x16x32_bf16 v[122:125], v[154:157], v[178:181], v[122:125]
	v_mfma_f32_16x16x32_bf16 v[110:113], v[142:145], v[182:185], v[110:113]
	v_mfma_f32_16x16x32_bf16 v[110:113], v[146:149], v[186:189], v[110:113]
	v_mfma_f32_16x16x32_bf16 v[106:109], v[150:153], v[182:185], v[106:109]
	v_mfma_f32_16x16x32_bf16 v[106:109], v[154:157], v[186:189], v[106:109]
	v_mfma_f32_16x16x32_bf16 v[94:97], v[142:145], v[190:193], v[94:97]
	v_mfma_f32_16x16x32_bf16 v[94:97], v[146:149], v[194:197], v[94:97]
	v_mfma_f32_16x16x32_bf16 v[90:93], v[150:153], v[190:193], v[90:93]
	v_mfma_f32_16x16x32_bf16 v[90:93], v[154:157], v[194:197], v[90:93]
	v_mfma_f32_16x16x32_bf16 v[78:81], v[142:145], v[198:201], v[78:81]
	v_mfma_f32_16x16x32_bf16 v[78:81], v[146:149], v[204:207], v[78:81]
	v_mfma_f32_16x16x32_bf16 v[74:77], v[150:153], v[198:201], v[74:77]
	v_mfma_f32_16x16x32_bf16 v[74:77], v[154:157], v[204:207], v[74:77]
	s_setprio 0
	s_setprio 1
	v_mfma_f32_16x16x32_bf16 v[118:121], v[158:161], v[174:177], v[118:121]
	v_mfma_f32_16x16x32_bf16 v[118:121], v[162:165], v[178:181], v[118:121]
	v_mfma_f32_16x16x32_bf16 v[114:117], v[166:169], v[174:177], v[114:117]
	v_mfma_f32_16x16x32_bf16 v[114:117], v[170:173], v[178:181], v[114:117]
	v_mfma_f32_16x16x32_bf16 v[102:105], v[158:161], v[182:185], v[102:105]
	v_mfma_f32_16x16x32_bf16 v[102:105], v[162:165], v[186:189], v[102:105]
	v_mfma_f32_16x16x32_bf16 v[98:101], v[166:169], v[182:185], v[98:101]
	v_mfma_f32_16x16x32_bf16 v[98:101], v[170:173], v[186:189], v[98:101]
	v_mfma_f32_16x16x32_bf16 v[86:89], v[158:161], v[190:193], v[86:89]
	v_mfma_f32_16x16x32_bf16 v[86:89], v[162:165], v[194:197], v[86:89]
	v_mfma_f32_16x16x32_bf16 v[82:85], v[166:169], v[190:193], v[82:85]
	v_mfma_f32_16x16x32_bf16 v[82:85], v[170:173], v[194:197], v[82:85]
	v_mfma_f32_16x16x32_bf16 v[70:73], v[158:161], v[198:201], v[70:73]
	v_mfma_f32_16x16x32_bf16 v[70:73], v[162:165], v[204:207], v[70:73]
	v_mfma_f32_16x16x32_bf16 v[66:69], v[166:169], v[198:201], v[66:69]
	v_mfma_f32_16x16x32_bf16 v[66:69], v[170:173], v[204:207], v[66:69]
	s_setprio 0
	s_barrier
	s_or_b32 s40, s43, 0x80
	s_mov_b32 m0, s30
	v_add_u32_e32 v141, s40, v131
	ds_read_b128 v[174:177], v140 offset:49152
	ds_read_b128 v[178:181], v140 offset:50176
	ds_read_b128 v[182:185], v140 offset:51200
	ds_read_b128 v[186:189], v140 offset:52224
	ds_read_b128 v[190:193], v140 offset:53248
	ds_read_b128 v[194:197], v140 offset:54272
	ds_read_b128 v[198:201], v140 offset:55296
	ds_read_b128 v[204:207], v140 offset:56320
	global_load_lds_dwordx4 v141, s[6:7]
	v_add_u32_e32 v141, s40, v133
	s_mov_b32 m0, s31
	s_add_i32 s43, s43, 0x80080
	global_load_lds_dwordx4 v141, s[6:7]
	v_add_u32_e32 v141, s43, v131
	s_mov_b32 m0, s37
	s_nop 0
	global_load_lds_dwordx4 v141, s[6:7]
	v_add_u32_e32 v141, s43, v133
	s_mov_b32 m0, s38
	s_nop 0
	global_load_lds_dwordx4 v141, s[6:7]
	v_add_u32_e32 v141, s42, v130
	s_mov_b32 m0, s34
	s_nop 0
	global_load_lds_dwordx4 v141, s[4:5]
	v_add_u32_e32 v141, s42, v132
	s_mov_b32 m0, s35
	s_nop 0
	global_load_lds_dwordx4 v141, s[4:5]
	s_waitcnt vmcnt(8)
	s_waitcnt lgkmcnt(0)
	s_setprio 1
	s_barrier
	v_mfma_f32_16x16x32_bf16 v[62:65], v[142:145], v[174:177], v[62:65]
	v_mfma_f32_16x16x32_bf16 v[62:65], v[146:149], v[178:181], v[62:65]
	v_mfma_f32_16x16x32_bf16 v[58:61], v[150:153], v[174:177], v[58:61]
	v_mfma_f32_16x16x32_bf16 v[58:61], v[154:157], v[178:181], v[58:61]
	v_mfma_f32_16x16x32_bf16 v[46:49], v[142:145], v[182:185], v[46:49]
	v_mfma_f32_16x16x32_bf16 v[46:49], v[146:149], v[186:189], v[46:49]
	v_mfma_f32_16x16x32_bf16 v[42:45], v[150:153], v[182:185], v[42:45]
	v_mfma_f32_16x16x32_bf16 v[42:45], v[154:157], v[186:189], v[42:45]
	v_mfma_f32_16x16x32_bf16 v[30:33], v[142:145], v[190:193], v[30:33]
	v_mfma_f32_16x16x32_bf16 v[30:33], v[146:149], v[194:197], v[30:33]
	v_mfma_f32_16x16x32_bf16 v[26:29], v[150:153], v[190:193], v[26:29]
	v_mfma_f32_16x16x32_bf16 v[26:29], v[154:157], v[194:197], v[26:29]
	v_mfma_f32_16x16x32_bf16 v[14:17], v[142:145], v[198:201], v[14:17]
	v_mfma_f32_16x16x32_bf16 v[14:17], v[146:149], v[204:207], v[14:17]
	v_mfma_f32_16x16x32_bf16 v[10:13], v[150:153], v[198:201], v[10:13]
	v_mfma_f32_16x16x32_bf16 v[10:13], v[154:157], v[204:207], v[10:13]
	s_setprio 0
	s_setprio 1
	v_mfma_f32_16x16x32_bf16 v[54:57], v[158:161], v[174:177], v[54:57]
	v_mfma_f32_16x16x32_bf16 v[54:57], v[162:165], v[178:181], v[54:57]
	v_mfma_f32_16x16x32_bf16 v[50:53], v[166:169], v[174:177], v[50:53]
	v_mfma_f32_16x16x32_bf16 v[50:53], v[170:173], v[178:181], v[50:53]
	v_mfma_f32_16x16x32_bf16 v[38:41], v[158:161], v[182:185], v[38:41]
	v_mfma_f32_16x16x32_bf16 v[38:41], v[162:165], v[186:189], v[38:41]
	v_mfma_f32_16x16x32_bf16 v[34:37], v[166:169], v[182:185], v[34:37]
	v_mfma_f32_16x16x32_bf16 v[34:37], v[170:173], v[186:189], v[34:37]
	v_mfma_f32_16x16x32_bf16 v[22:25], v[158:161], v[190:193], v[22:25]
	v_mfma_f32_16x16x32_bf16 v[22:25], v[162:165], v[194:197], v[22:25]
	v_mfma_f32_16x16x32_bf16 v[18:21], v[166:169], v[190:193], v[18:21]
	v_mfma_f32_16x16x32_bf16 v[18:21], v[170:173], v[194:197], v[18:21]
	v_mfma_f32_16x16x32_bf16 v[6:9], v[158:161], v[198:201], v[6:9]
	v_mfma_f32_16x16x32_bf16 v[6:9], v[162:165], v[204:207], v[6:9]
	v_mfma_f32_16x16x32_bf16 v[2:5], v[166:169], v[198:201], v[2:5]
	v_mfma_f32_16x16x32_bf16 v[2:5], v[170:173], v[204:207], v[2:5]
	s_setprio 0
	s_barrier
	s_add_i32 s39, s39, 2
	s_cmp_gt_u32 s39, 29
	s_mov_b32 s40, s41
.LBB0_725:
	v_add_u32_e32 v141, s13, v137
	ds_read_b128 v[142:145], v141
	ds_read_b128 v[146:149], v141 offset:1024
	ds_read_b128 v[150:153], v141 offset:2048
	ds_read_b128 v[154:157], v141 offset:3072
	v_add_u32_e32 v141, s16, v137
	ds_read_b128 v[158:161], v141
	ds_read_b128 v[162:165], v141 offset:1024
	ds_read_b128 v[166:169], v141 offset:2048
	ds_read_b128 v[170:173], v141 offset:3072
	s_add_i32 s41, s40, 0x100
	s_cmp_lg_u32 s39, 28
	s_cselect_b32 s43, s41, 0
	s_add_i32 s44, s43, s21
	s_or_b32 s42, s44, 0x80
	s_add_i32 s43, s43, s12
	v_add_u32_e32 v141, s40, v139
	s_add_i32 m0, s22, 0xc000
	ds_read_b128 v[174:177], v140
	ds_read_b128 v[178:181], v140 offset:1024
	ds_read_b128 v[182:185], v140 offset:2048
	ds_read_b128 v[186:189], v140 offset:3072
	ds_read_b128 v[190:193], v140 offset:4096
	ds_read_b128 v[194:197], v140 offset:5120
	ds_read_b128 v[198:201], v140 offset:6144
	ds_read_b128 v[204:207], v140 offset:7168
	global_load_lds_dwordx4 v141, s[4:5]
	v_add_u32_e32 v141, s40, v138
	s_add_i32 m0, s22, 0xe000
	s_nop 0
	global_load_lds_dwordx4 v141, s[4:5]
	s_waitcnt vmcnt(8)
	s_waitcnt lgkmcnt(0)
	s_setprio 1
	s_barrier
	v_mfma_f32_16x16x32_bf16 v[126:129], v[142:145], v[174:177], v[126:129]
	v_mfma_f32_16x16x32_bf16 v[126:129], v[146:149], v[178:181], v[126:129]
	v_mfma_f32_16x16x32_bf16 v[122:125], v[150:153], v[174:177], v[122:125]
	v_mfma_f32_16x16x32_bf16 v[122:125], v[154:157], v[178:181], v[122:125]
	v_mfma_f32_16x16x32_bf16 v[110:113], v[142:145], v[182:185], v[110:113]
	v_mfma_f32_16x16x32_bf16 v[110:113], v[146:149], v[186:189], v[110:113]
	v_mfma_f32_16x16x32_bf16 v[106:109], v[150:153], v[182:185], v[106:109]
	v_mfma_f32_16x16x32_bf16 v[106:109], v[154:157], v[186:189], v[106:109]
	v_mfma_f32_16x16x32_bf16 v[94:97], v[142:145], v[190:193], v[94:97]
	v_mfma_f32_16x16x32_bf16 v[94:97], v[146:149], v[194:197], v[94:97]
	v_mfma_f32_16x16x32_bf16 v[90:93], v[150:153], v[190:193], v[90:93]
	v_mfma_f32_16x16x32_bf16 v[90:93], v[154:157], v[194:197], v[90:93]
	v_mfma_f32_16x16x32_bf16 v[78:81], v[142:145], v[198:201], v[78:81]
	v_mfma_f32_16x16x32_bf16 v[78:81], v[146:149], v[204:207], v[78:81]
	v_mfma_f32_16x16x32_bf16 v[74:77], v[150:153], v[198:201], v[74:77]
	v_mfma_f32_16x16x32_bf16 v[74:77], v[154:157], v[204:207], v[74:77]
	s_setprio 0
	s_setprio 1
	v_mfma_f32_16x16x32_bf16 v[118:121], v[158:161], v[174:177], v[118:121]
	v_mfma_f32_16x16x32_bf16 v[118:121], v[162:165], v[178:181], v[118:121]
	v_mfma_f32_16x16x32_bf16 v[114:117], v[166:169], v[174:177], v[114:117]
	v_mfma_f32_16x16x32_bf16 v[114:117], v[170:173], v[178:181], v[114:117]
	v_mfma_f32_16x16x32_bf16 v[102:105], v[158:161], v[182:185], v[102:105]
	v_mfma_f32_16x16x32_bf16 v[102:105], v[162:165], v[186:189], v[102:105]
	v_mfma_f32_16x16x32_bf16 v[98:101], v[166:169], v[182:185], v[98:101]
	v_mfma_f32_16x16x32_bf16 v[98:101], v[170:173], v[186:189], v[98:101]
	v_mfma_f32_16x16x32_bf16 v[86:89], v[158:161], v[190:193], v[86:89]
	v_mfma_f32_16x16x32_bf16 v[86:89], v[162:165], v[194:197], v[86:89]
	v_mfma_f32_16x16x32_bf16 v[82:85], v[166:169], v[190:193], v[82:85]
	v_mfma_f32_16x16x32_bf16 v[82:85], v[170:173], v[194:197], v[82:85]
	v_mfma_f32_16x16x32_bf16 v[70:73], v[158:161], v[198:201], v[70:73]
	v_mfma_f32_16x16x32_bf16 v[70:73], v[162:165], v[204:207], v[70:73]
	v_mfma_f32_16x16x32_bf16 v[66:69], v[166:169], v[198:201], v[66:69]
	v_mfma_f32_16x16x32_bf16 v[66:69], v[170:173], v[204:207], v[66:69]
	s_setprio 0
	s_barrier
	s_mov_b32 m0, s14
	v_add_u32_e32 v141, s43, v131
	ds_read_b128 v[174:177], v140 offset:16384
	ds_read_b128 v[178:181], v140 offset:17408
	ds_read_b128 v[182:185], v140 offset:18432
	ds_read_b128 v[186:189], v140 offset:19456
	ds_read_b128 v[190:193], v140 offset:20480
	ds_read_b128 v[194:197], v140 offset:21504
	ds_read_b128 v[198:201], v140 offset:22528
	ds_read_b128 v[204:207], v140 offset:23552
	global_load_lds_dwordx4 v141, s[6:7]
	v_add_u32_e32 v141, s43, v133
	s_mov_b32 m0, s15
	s_add_i32 s40, s43, 0x80000
	global_load_lds_dwordx4 v141, s[6:7]
	v_add_u32_e32 v141, s40, v131
	s_mov_b32 m0, s17
	s_nop 0
	global_load_lds_dwordx4 v141, s[6:7]
	v_add_u32_e32 v141, s40, v133
	s_mov_b32 m0, s20
	s_nop 0
	global_load_lds_dwordx4 v141, s[6:7]
	v_add_u32_e32 v141, s44, v130
	s_mov_b32 m0, s22
	s_nop 0
	global_load_lds_dwordx4 v141, s[4:5]
	v_add_u32_e32 v141, s44, v132
	s_mov_b32 m0, s23
	s_nop 0
	global_load_lds_dwordx4 v141, s[4:5]
	s_waitcnt vmcnt(8)
	s_waitcnt lgkmcnt(0)
	s_setprio 1
	s_barrier
	v_mfma_f32_16x16x32_bf16 v[62:65], v[142:145], v[174:177], v[62:65]
	v_mfma_f32_16x16x32_bf16 v[62:65], v[146:149], v[178:181], v[62:65]
	v_mfma_f32_16x16x32_bf16 v[58:61], v[150:153], v[174:177], v[58:61]
	v_mfma_f32_16x16x32_bf16 v[58:61], v[154:157], v[178:181], v[58:61]
	v_mfma_f32_16x16x32_bf16 v[46:49], v[142:145], v[182:185], v[46:49]
	v_mfma_f32_16x16x32_bf16 v[46:49], v[146:149], v[186:189], v[46:49]
	v_mfma_f32_16x16x32_bf16 v[42:45], v[150:153], v[182:185], v[42:45]
	v_mfma_f32_16x16x32_bf16 v[42:45], v[154:157], v[186:189], v[42:45]
	v_mfma_f32_16x16x32_bf16 v[30:33], v[142:145], v[190:193], v[30:33]
	v_mfma_f32_16x16x32_bf16 v[30:33], v[146:149], v[194:197], v[30:33]
	v_mfma_f32_16x16x32_bf16 v[26:29], v[150:153], v[190:193], v[26:29]
	v_mfma_f32_16x16x32_bf16 v[26:29], v[154:157], v[194:197], v[26:29]
	v_mfma_f32_16x16x32_bf16 v[14:17], v[142:145], v[198:201], v[14:17]
	v_mfma_f32_16x16x32_bf16 v[14:17], v[146:149], v[204:207], v[14:17]
	v_mfma_f32_16x16x32_bf16 v[10:13], v[150:153], v[198:201], v[10:13]
	v_mfma_f32_16x16x32_bf16 v[10:13], v[154:157], v[204:207], v[10:13]
	s_setprio 0
	s_setprio 1
	v_mfma_f32_16x16x32_bf16 v[54:57], v[158:161], v[174:177], v[54:57]
	v_mfma_f32_16x16x32_bf16 v[54:57], v[162:165], v[178:181], v[54:57]
	v_mfma_f32_16x16x32_bf16 v[50:53], v[166:169], v[174:177], v[50:53]
	v_mfma_f32_16x16x32_bf16 v[50:53], v[170:173], v[178:181], v[50:53]
	v_mfma_f32_16x16x32_bf16 v[38:41], v[158:161], v[182:185], v[38:41]
	v_mfma_f32_16x16x32_bf16 v[38:41], v[162:165], v[186:189], v[38:41]
	v_mfma_f32_16x16x32_bf16 v[34:37], v[166:169], v[182:185], v[34:37]
	v_mfma_f32_16x16x32_bf16 v[34:37], v[170:173], v[186:189], v[34:37]
	v_mfma_f32_16x16x32_bf16 v[22:25], v[158:161], v[190:193], v[22:25]
	v_mfma_f32_16x16x32_bf16 v[22:25], v[162:165], v[194:197], v[22:25]
	v_mfma_f32_16x16x32_bf16 v[18:21], v[166:169], v[190:193], v[18:21]
	v_mfma_f32_16x16x32_bf16 v[18:21], v[170:173], v[194:197], v[18:21]
	v_mfma_f32_16x16x32_bf16 v[6:9], v[158:161], v[198:201], v[6:9]
	v_mfma_f32_16x16x32_bf16 v[6:9], v[162:165], v[204:207], v[6:9]
	v_mfma_f32_16x16x32_bf16 v[2:5], v[166:169], v[198:201], v[2:5]
	v_mfma_f32_16x16x32_bf16 v[2:5], v[170:173], v[204:207], v[2:5]
	s_setprio 0
	s_barrier
	v_add_u32_e32 v141, s29, v137
	ds_read_b128 v[142:145], v141
	ds_read_b128 v[146:149], v141 offset:1024
	ds_read_b128 v[150:153], v141 offset:2048
	ds_read_b128 v[154:157], v141 offset:3072
	v_add_u32_e32 v141, s36, v137
	ds_read_b128 v[158:161], v141
	ds_read_b128 v[162:165], v141 offset:1024
	ds_read_b128 v[166:169], v141 offset:2048
	ds_read_b128 v[170:173], v141 offset:3072
	s_add_i32 s44, s44, 0x80000
	s_mov_b32 m0, s24
	v_add_u32_e32 v141, s44, v130
	ds_read_b128 v[174:177], v140 offset:32768
	ds_read_b128 v[178:181], v140 offset:33792
	ds_read_b128 v[182:185], v140 offset:34816
	ds_read_b128 v[186:189], v140 offset:35840
	ds_read_b128 v[190:193], v140 offset:36864
	ds_read_b128 v[194:197], v140 offset:37888
	ds_read_b128 v[198:201], v140 offset:38912
	ds_read_b128 v[204:207], v140 offset:39936
	global_load_lds_dwordx4 v141, s[4:5]
	v_add_u32_e32 v141, s44, v132
	s_mov_b32 m0, s25
	s_nop 0
	global_load_lds_dwordx4 v141, s[4:5]
	s_waitcnt vmcnt(8)
	s_waitcnt lgkmcnt(0)
	s_setprio 1
	s_barrier
	v_mfma_f32_16x16x32_bf16 v[126:129], v[142:145], v[174:177], v[126:129]
	v_mfma_f32_16x16x32_bf16 v[126:129], v[146:149], v[178:181], v[126:129]
	v_mfma_f32_16x16x32_bf16 v[122:125], v[150:153], v[174:177], v[122:125]
	v_mfma_f32_16x16x32_bf16 v[122:125], v[154:157], v[178:181], v[122:125]
	v_mfma_f32_16x16x32_bf16 v[110:113], v[142:145], v[182:185], v[110:113]
	v_mfma_f32_16x16x32_bf16 v[110:113], v[146:149], v[186:189], v[110:113]
	v_mfma_f32_16x16x32_bf16 v[106:109], v[150:153], v[182:185], v[106:109]
	v_mfma_f32_16x16x32_bf16 v[106:109], v[154:157], v[186:189], v[106:109]
	v_mfma_f32_16x16x32_bf16 v[94:97], v[142:145], v[190:193], v[94:97]
	v_mfma_f32_16x16x32_bf16 v[94:97], v[146:149], v[194:197], v[94:97]
	v_mfma_f32_16x16x32_bf16 v[90:93], v[150:153], v[190:193], v[90:93]
	v_mfma_f32_16x16x32_bf16 v[90:93], v[154:157], v[194:197], v[90:93]
	v_mfma_f32_16x16x32_bf16 v[78:81], v[142:145], v[198:201], v[78:81]
	v_mfma_f32_16x16x32_bf16 v[78:81], v[146:149], v[204:207], v[78:81]
	v_mfma_f32_16x16x32_bf16 v[74:77], v[150:153], v[198:201], v[74:77]
	v_mfma_f32_16x16x32_bf16 v[74:77], v[154:157], v[204:207], v[74:77]
	s_setprio 0
	s_setprio 1
	v_mfma_f32_16x16x32_bf16 v[118:121], v[158:161], v[174:177], v[118:121]
	v_mfma_f32_16x16x32_bf16 v[118:121], v[162:165], v[178:181], v[118:121]
	v_mfma_f32_16x16x32_bf16 v[114:117], v[166:169], v[174:177], v[114:117]
	v_mfma_f32_16x16x32_bf16 v[114:117], v[170:173], v[178:181], v[114:117]
	v_mfma_f32_16x16x32_bf16 v[102:105], v[158:161], v[182:185], v[102:105]
	v_mfma_f32_16x16x32_bf16 v[102:105], v[162:165], v[186:189], v[102:105]
	v_mfma_f32_16x16x32_bf16 v[98:101], v[166:169], v[182:185], v[98:101]
	v_mfma_f32_16x16x32_bf16 v[98:101], v[170:173], v[186:189], v[98:101]
	v_mfma_f32_16x16x32_bf16 v[86:89], v[158:161], v[190:193], v[86:89]
	v_mfma_f32_16x16x32_bf16 v[86:89], v[162:165], v[194:197], v[86:89]
	v_mfma_f32_16x16x32_bf16 v[82:85], v[166:169], v[190:193], v[82:85]
	v_mfma_f32_16x16x32_bf16 v[82:85], v[170:173], v[194:197], v[82:85]
	v_mfma_f32_16x16x32_bf16 v[70:73], v[158:161], v[198:201], v[70:73]
	v_mfma_f32_16x16x32_bf16 v[70:73], v[162:165], v[204:207], v[70:73]
	v_mfma_f32_16x16x32_bf16 v[66:69], v[166:169], v[198:201], v[66:69]
	v_mfma_f32_16x16x32_bf16 v[66:69], v[170:173], v[204:207], v[66:69]
	s_setprio 0
	s_barrier
	s_or_b32 s40, s43, 0x80
	s_mov_b32 m0, s30
	v_add_u32_e32 v141, s40, v131
	ds_read_b128 v[174:177], v140 offset:49152
	ds_read_b128 v[178:181], v140 offset:50176
	ds_read_b128 v[182:185], v140 offset:51200
	ds_read_b128 v[186:189], v140 offset:52224
	ds_read_b128 v[190:193], v140 offset:53248
	ds_read_b128 v[194:197], v140 offset:54272
	ds_read_b128 v[198:201], v140 offset:55296
	ds_read_b128 v[204:207], v140 offset:56320
	global_load_lds_dwordx4 v141, s[6:7]
	v_add_u32_e32 v141, s40, v133
	s_mov_b32 m0, s31
	s_add_i32 s43, s43, 0x80080
	global_load_lds_dwordx4 v141, s[6:7]
	v_add_u32_e32 v141, s43, v131
	s_mov_b32 m0, s37
	s_nop 0
	global_load_lds_dwordx4 v141, s[6:7]
	v_add_u32_e32 v141, s43, v133
	s_mov_b32 m0, s38
	s_nop 0
	global_load_lds_dwordx4 v141, s[6:7]
	v_add_u32_e32 v141, s42, v130
	s_mov_b32 m0, s34
	s_nop 0
	global_load_lds_dwordx4 v141, s[4:5]
	v_add_u32_e32 v141, s42, v132
	s_mov_b32 m0, s35
	s_nop 0
	global_load_lds_dwordx4 v141, s[4:5]
	s_waitcnt vmcnt(8)
	s_waitcnt lgkmcnt(0)
	s_setprio 1
	s_barrier
	v_mfma_f32_16x16x32_bf16 v[62:65], v[142:145], v[174:177], v[62:65]
	v_mfma_f32_16x16x32_bf16 v[62:65], v[146:149], v[178:181], v[62:65]
	v_mfma_f32_16x16x32_bf16 v[58:61], v[150:153], v[174:177], v[58:61]
	v_mfma_f32_16x16x32_bf16 v[58:61], v[154:157], v[178:181], v[58:61]
	v_mfma_f32_16x16x32_bf16 v[46:49], v[142:145], v[182:185], v[46:49]
	v_mfma_f32_16x16x32_bf16 v[46:49], v[146:149], v[186:189], v[46:49]
	v_mfma_f32_16x16x32_bf16 v[42:45], v[150:153], v[182:185], v[42:45]
	v_mfma_f32_16x16x32_bf16 v[42:45], v[154:157], v[186:189], v[42:45]
	v_mfma_f32_16x16x32_bf16 v[30:33], v[142:145], v[190:193], v[30:33]
	v_mfma_f32_16x16x32_bf16 v[30:33], v[146:149], v[194:197], v[30:33]
	v_mfma_f32_16x16x32_bf16 v[26:29], v[150:153], v[190:193], v[26:29]
	v_mfma_f32_16x16x32_bf16 v[26:29], v[154:157], v[194:197], v[26:29]
	v_mfma_f32_16x16x32_bf16 v[14:17], v[142:145], v[198:201], v[14:17]
	v_mfma_f32_16x16x32_bf16 v[14:17], v[146:149], v[204:207], v[14:17]
	v_mfma_f32_16x16x32_bf16 v[10:13], v[150:153], v[198:201], v[10:13]
	v_mfma_f32_16x16x32_bf16 v[10:13], v[154:157], v[204:207], v[10:13]
	s_setprio 0
	s_setprio 1
	v_mfma_f32_16x16x32_bf16 v[54:57], v[158:161], v[174:177], v[54:57]
	v_mfma_f32_16x16x32_bf16 v[54:57], v[162:165], v[178:181], v[54:57]
	v_mfma_f32_16x16x32_bf16 v[50:53], v[166:169], v[174:177], v[50:53]
	v_mfma_f32_16x16x32_bf16 v[50:53], v[170:173], v[178:181], v[50:53]
	v_mfma_f32_16x16x32_bf16 v[38:41], v[158:161], v[182:185], v[38:41]
	v_mfma_f32_16x16x32_bf16 v[38:41], v[162:165], v[186:189], v[38:41]
	v_mfma_f32_16x16x32_bf16 v[34:37], v[166:169], v[182:185], v[34:37]
	v_mfma_f32_16x16x32_bf16 v[34:37], v[170:173], v[186:189], v[34:37]
	v_mfma_f32_16x16x32_bf16 v[22:25], v[158:161], v[190:193], v[22:25]
	v_mfma_f32_16x16x32_bf16 v[22:25], v[162:165], v[194:197], v[22:25]
	v_mfma_f32_16x16x32_bf16 v[18:21], v[166:169], v[190:193], v[18:21]
	v_mfma_f32_16x16x32_bf16 v[18:21], v[170:173], v[194:197], v[18:21]
	v_mfma_f32_16x16x32_bf16 v[6:9], v[158:161], v[198:201], v[6:9]
	v_mfma_f32_16x16x32_bf16 v[6:9], v[162:165], v[204:207], v[6:9]
	v_mfma_f32_16x16x32_bf16 v[2:5], v[166:169], v[198:201], v[2:5]
	v_mfma_f32_16x16x32_bf16 v[2:5], v[170:173], v[204:207], v[2:5]
	s_setprio 0
	s_barrier
	s_add_i32 s39, s39, 2
	s_cmp_gt_u32 s39, 29
	s_mov_b32 s40, s41
	s_cbranch_scc0 .LBB0_725
	s_cmpk_lt_u32 s9, 0x100
	s_cbranch_scc0 .LBB0_728
	s_barrier

.LBB0_740:
	v_lshrrev_b32_e32 v9, 1, v5
	v_and_b32_e32 v135, 24, v9
	v_and_b32_e32 v136, 15, v5
	v_lshlrev_b32_e32 v9, 1, v135
	v_lshlrev_b32_e32 v5, 2, v5
	s_lshl_b32 s20, s20, 5
	s_lshl_b32 s19, s21, 6
	v_lshl_or_b32 v9, v136, 6, v9
	s_lshl_b32 s21, s21, 13
	v_and_b32_e32 v5, 32, v5
	s_and_b32 s20, s20, 0x60
	v_bitop3_b32 v10, v9, s21, v5 bitop3:0xde
	s_lshl_b32 s21, s20, 7
	v_bitop3_b32 v137, v9, s21, v5 bitop3:0xde
	s_add_i32 s21, s28, 0x18000
	s_or_b32 s23, s2, 0x80
	s_add_i32 s22, s21, s27
	v_add_u32_e32 v5, s23, v131
	s_mov_b32 m0, s22
	s_waitcnt vmcnt(2)
	s_barrier
	global_load_lds_dwordx4 v5, s[6:7]
	v_add_u32_e32 v5, s23, v133
	s_add_i32 s23, s22, 0x2000
	s_mov_b32 m0, s23
	s_or_b32 s25, s14, 0x80
	s_add_i32 s24, s15, 0x8000
	global_load_lds_dwordx4 v5, s[6:7]
	v_add_u32_e32 v5, s25, v130
	s_mov_b32 m0, s24
	s_add_i32 s26, s28, 0x1c000
	global_load_lds_dwordx4 v5, s[4:5]
	v_add_u32_e32 v5, s25, v132
	s_add_i32 s25, s15, 0xa000
	s_mov_b32 m0, s25
	s_or_b32 s29, s2, 0x80080
	s_add_i32 s27, s26, s27
	global_load_lds_dwordx4 v5, s[4:5]
	v_add_u32_e32 v5, s29, v131
	s_mov_b32 m0, s27
	s_add_i32 s30, s14, 0x80080
	global_load_lds_dwordx4 v5, s[6:7]
	v_add_u32_e32 v5, s29, v133
	s_add_i32 s29, s27, 0x2000
	s_mov_b32 m0, s29
	v_lshlrev_b32_e32 v7, 12, v7
	global_load_lds_dwordx4 v5, s[6:7]
	v_lshlrev_b32_e32 v5, 15, v6
	v_and_b32_e32 v5, 0xffff0000, v5
	v_and_b32_e32 v6, 1, v6
	v_add3_u32 v5, s30, v5, v7
	v_lshlrev_b32_e32 v6, 6, v6
	v_lshlrev_b32_e32 v7, 1, v8
	v_add3_u32 v138, v5, v6, v7
	v_lshlrev_b32_e32 v5, 15, v2
	v_and_b32_e32 v5, 0xffff0000, v5
	v_lshlrev_b32_e32 v3, 12, v3
	v_and_b32_e32 v2, 1, v2
	s_waitcnt vmcnt(6)
	v_add3_u32 v3, s30, v5, v3
	v_lshlrev_b32_e32 v2, 6, v2
	v_lshlrev_b32_e32 v4, 1, v4
	v_add3_u32 v139, v3, v2, v4
	v_or_b32_e32 v134, s19, v136
	s_mov_b32 s30, -2
	s_mov_b32 s31, 0
	v_add_u32_e32 v140, s28, v10
	s_barrier
	v_add_u32_e32 v141, s3, v137
	ds_read_b128 v[142:145], v141
	ds_read_b128 v[146:149], v141 offset:1024
	ds_read_b128 v[150:153], v141 offset:2048
	ds_read_b128 v[154:157], v141 offset:3072
	v_add_u32_e32 v141, s11, v137
	ds_read_b128 v[158:161], v141
	ds_read_b128 v[162:165], v141 offset:1024
	ds_read_b128 v[166:169], v141 offset:2048
	ds_read_b128 v[170:173], v141 offset:3072
	s_add_i32 s34, s31, 0x100
	s_cmp_lg_u32 s30, 28
	s_cselect_b32 s36, s34, 0
	s_add_i32 s37, s36, s14
	s_or_b32 s35, s37, 0x80
	s_add_i32 s36, s36, s2
	v_add_u32_e32 v141, s31, v139
	s_add_i32 m0, s15, 0xc000
	ds_read_b128 v[174:177], v140
	ds_read_b128 v[178:181], v140 offset:1024
	ds_read_b128 v[182:185], v140 offset:2048
	ds_read_b128 v[186:189], v140 offset:3072
	ds_read_b128 v[190:193], v140 offset:4096
	ds_read_b128 v[194:197], v140 offset:5120
	ds_read_b128 v[198:201], v140 offset:6144
	ds_read_b128 v[204:207], v140 offset:7168
	global_load_lds_dwordx4 v141, s[4:5]
	v_add_u32_e32 v141, s31, v138
	s_add_i32 m0, s15, 0xe000
	s_nop 0
	global_load_lds_dwordx4 v141, s[4:5]
	s_waitcnt vmcnt(8)
	s_waitcnt lgkmcnt(0)
	s_setprio 1
	s_barrier
	v_mfma_f32_16x16x32_bf16 v[126:129], v[142:145], v[174:177], 0
	v_mfma_f32_16x16x32_bf16 v[126:129], v[146:149], v[178:181], v[126:129]
	v_mfma_f32_16x16x32_bf16 v[122:125], v[150:153], v[174:177], 0
	v_mfma_f32_16x16x32_bf16 v[122:125], v[154:157], v[178:181], v[122:125]
	v_mfma_f32_16x16x32_bf16 v[110:113], v[142:145], v[182:185], 0
	v_mfma_f32_16x16x32_bf16 v[110:113], v[146:149], v[186:189], v[110:113]
	v_mfma_f32_16x16x32_bf16 v[106:109], v[150:153], v[182:185], 0
	v_mfma_f32_16x16x32_bf16 v[106:109], v[154:157], v[186:189], v[106:109]
	v_mfma_f32_16x16x32_bf16 v[94:97], v[142:145], v[190:193], 0
	v_mfma_f32_16x16x32_bf16 v[94:97], v[146:149], v[194:197], v[94:97]
	v_mfma_f32_16x16x32_bf16 v[90:93], v[150:153], v[190:193], 0
	v_mfma_f32_16x16x32_bf16 v[90:93], v[154:157], v[194:197], v[90:93]
	v_mfma_f32_16x16x32_bf16 v[78:81], v[142:145], v[198:201], 0
	v_mfma_f32_16x16x32_bf16 v[78:81], v[146:149], v[204:207], v[78:81]
	v_mfma_f32_16x16x32_bf16 v[74:77], v[150:153], v[198:201], 0
	v_mfma_f32_16x16x32_bf16 v[74:77], v[154:157], v[204:207], v[74:77]
	s_setprio 0
	s_setprio 1
	v_mfma_f32_16x16x32_bf16 v[118:121], v[158:161], v[174:177], 0
	v_mfma_f32_16x16x32_bf16 v[118:121], v[162:165], v[178:181], v[118:121]
	v_mfma_f32_16x16x32_bf16 v[114:117], v[166:169], v[174:177], 0
	v_mfma_f32_16x16x32_bf16 v[114:117], v[170:173], v[178:181], v[114:117]
	v_mfma_f32_16x16x32_bf16 v[102:105], v[158:161], v[182:185], 0
	v_mfma_f32_16x16x32_bf16 v[102:105], v[162:165], v[186:189], v[102:105]
	v_mfma_f32_16x16x32_bf16 v[98:101], v[166:169], v[182:185], 0
	v_mfma_f32_16x16x32_bf16 v[98:101], v[170:173], v[186:189], v[98:101]
	v_mfma_f32_16x16x32_bf16 v[86:89], v[158:161], v[190:193], 0
	v_mfma_f32_16x16x32_bf16 v[86:89], v[162:165], v[194:197], v[86:89]
	v_mfma_f32_16x16x32_bf16 v[82:85], v[166:169], v[190:193], 0
	v_mfma_f32_16x16x32_bf16 v[82:85], v[170:173], v[194:197], v[82:85]
	v_mfma_f32_16x16x32_bf16 v[70:73], v[158:161], v[198:201], 0
	v_mfma_f32_16x16x32_bf16 v[70:73], v[162:165], v[204:207], v[70:73]
	v_mfma_f32_16x16x32_bf16 v[66:69], v[166:169], v[198:201], 0
	v_mfma_f32_16x16x32_bf16 v[66:69], v[170:173], v[204:207], v[66:69]
	s_setprio 0
	s_barrier
	s_mov_b32 m0, s9
	v_add_u32_e32 v141, s36, v131
	ds_read_b128 v[174:177], v140 offset:16384
	ds_read_b128 v[178:181], v140 offset:17408
	ds_read_b128 v[182:185], v140 offset:18432
	ds_read_b128 v[186:189], v140 offset:19456
	ds_read_b128 v[190:193], v140 offset:20480
	ds_read_b128 v[194:197], v140 offset:21504
	ds_read_b128 v[198:201], v140 offset:22528
	ds_read_b128 v[204:207], v140 offset:23552
	global_load_lds_dwordx4 v141, s[6:7]
	v_add_u32_e32 v141, s36, v133
	s_mov_b32 m0, s10
	s_add_i32 s31, s36, 0x80000
	global_load_lds_dwordx4 v141, s[6:7]
	v_add_u32_e32 v141, s31, v131
	s_mov_b32 m0, s12
	s_nop 0
	global_load_lds_dwordx4 v141, s[6:7]
	v_add_u32_e32 v141, s31, v133
	s_mov_b32 m0, s13
	s_nop 0
	global_load_lds_dwordx4 v141, s[6:7]
	v_add_u32_e32 v141, s37, v130
	s_mov_b32 m0, s15
	s_nop 0
	global_load_lds_dwordx4 v141, s[4:5]
	v_add_u32_e32 v141, s37, v132
	s_mov_b32 m0, s16
	s_nop 0
	global_load_lds_dwordx4 v141, s[4:5]
	s_waitcnt vmcnt(8)
	s_waitcnt lgkmcnt(0)
	s_setprio 1
	s_barrier
	v_mfma_f32_16x16x32_bf16 v[62:65], v[142:145], v[174:177], 0
	v_mfma_f32_16x16x32_bf16 v[62:65], v[146:149], v[178:181], v[62:65]
	v_mfma_f32_16x16x32_bf16 v[58:61], v[150:153], v[174:177], 0
	v_mfma_f32_16x16x32_bf16 v[58:61], v[154:157], v[178:181], v[58:61]
	v_mfma_f32_16x16x32_bf16 v[46:49], v[142:145], v[182:185], 0
	v_mfma_f32_16x16x32_bf16 v[46:49], v[146:149], v[186:189], v[46:49]
	v_mfma_f32_16x16x32_bf16 v[42:45], v[150:153], v[182:185], 0
	v_mfma_f32_16x16x32_bf16 v[42:45], v[154:157], v[186:189], v[42:45]
	v_mfma_f32_16x16x32_bf16 v[30:33], v[142:145], v[190:193], 0
	v_mfma_f32_16x16x32_bf16 v[30:33], v[146:149], v[194:197], v[30:33]
	v_mfma_f32_16x16x32_bf16 v[26:29], v[150:153], v[190:193], 0
	v_mfma_f32_16x16x32_bf16 v[26:29], v[154:157], v[194:197], v[26:29]
	v_mfma_f32_16x16x32_bf16 v[14:17], v[142:145], v[198:201], 0
	v_mfma_f32_16x16x32_bf16 v[14:17], v[146:149], v[204:207], v[14:17]
	v_mfma_f32_16x16x32_bf16 v[10:13], v[150:153], v[198:201], 0
	v_mfma_f32_16x16x32_bf16 v[10:13], v[154:157], v[204:207], v[10:13]
	s_setprio 0
	s_setprio 1
	v_mfma_f32_16x16x32_bf16 v[54:57], v[158:161], v[174:177], 0
	v_mfma_f32_16x16x32_bf16 v[54:57], v[162:165], v[178:181], v[54:57]
	v_mfma_f32_16x16x32_bf16 v[50:53], v[166:169], v[174:177], 0
	v_mfma_f32_16x16x32_bf16 v[50:53], v[170:173], v[178:181], v[50:53]
	v_mfma_f32_16x16x32_bf16 v[38:41], v[158:161], v[182:185], 0
	v_mfma_f32_16x16x32_bf16 v[38:41], v[162:165], v[186:189], v[38:41]
	v_mfma_f32_16x16x32_bf16 v[34:37], v[166:169], v[182:185], 0
	v_mfma_f32_16x16x32_bf16 v[34:37], v[170:173], v[186:189], v[34:37]
	v_mfma_f32_16x16x32_bf16 v[22:25], v[158:161], v[190:193], 0
	v_mfma_f32_16x16x32_bf16 v[22:25], v[162:165], v[194:197], v[22:25]
	v_mfma_f32_16x16x32_bf16 v[18:21], v[166:169], v[190:193], 0
	v_mfma_f32_16x16x32_bf16 v[18:21], v[170:173], v[194:197], v[18:21]
	v_mfma_f32_16x16x32_bf16 v[6:9], v[158:161], v[198:201], 0
	v_mfma_f32_16x16x32_bf16 v[6:9], v[162:165], v[204:207], v[6:9]
	v_mfma_f32_16x16x32_bf16 v[2:5], v[166:169], v[198:201], 0
	v_mfma_f32_16x16x32_bf16 v[2:5], v[170:173], v[204:207], v[2:5]
	s_setprio 0
	s_barrier
	v_add_u32_e32 v141, s21, v137
	ds_read_b128 v[142:145], v141
	ds_read_b128 v[146:149], v141 offset:1024
	ds_read_b128 v[150:153], v141 offset:2048
	ds_read_b128 v[154:157], v141 offset:3072
	v_add_u32_e32 v141, s26, v137
	ds_read_b128 v[158:161], v141
	ds_read_b128 v[162:165], v141 offset:1024
	ds_read_b128 v[166:169], v141 offset:2048
	ds_read_b128 v[170:173], v141 offset:3072
	s_add_i32 s37, s37, 0x80000
	s_mov_b32 m0, s17
	v_add_u32_e32 v141, s37, v130
	ds_read_b128 v[174:177], v140 offset:32768
	ds_read_b128 v[178:181], v140 offset:33792
	ds_read_b128 v[182:185], v140 offset:34816
	ds_read_b128 v[186:189], v140 offset:35840
	ds_read_b128 v[190:193], v140 offset:36864
	ds_read_b128 v[194:197], v140 offset:37888
	ds_read_b128 v[198:201], v140 offset:38912
	ds_read_b128 v[204:207], v140 offset:39936
	global_load_lds_dwordx4 v141, s[4:5]
	v_add_u32_e32 v141, s37, v132
	s_mov_b32 m0, s18
	s_nop 0
	global_load_lds_dwordx4 v141, s[4:5]
	s_waitcnt vmcnt(8)
	s_waitcnt lgkmcnt(0)
	s_setprio 1
	s_barrier
	v_mfma_f32_16x16x32_bf16 v[126:129], v[142:145], v[174:177], v[126:129]
	v_mfma_f32_16x16x32_bf16 v[126:129], v[146:149], v[178:181], v[126:129]
	v_mfma_f32_16x16x32_bf16 v[122:125], v[150:153], v[174:177], v[122:125]
	v_mfma_f32_16x16x32_bf16 v[122:125], v[154:157], v[178:181], v[122:125]
	v_mfma_f32_16x16x32_bf16 v[110:113], v[142:145], v[182:185], v[110:113]
	v_mfma_f32_16x16x32_bf16 v[110:113], v[146:149], v[186:189], v[110:113]
	v_mfma_f32_16x16x32_bf16 v[106:109], v[150:153], v[182:185], v[106:109]
	v_mfma_f32_16x16x32_bf16 v[106:109], v[154:157], v[186:189], v[106:109]
	v_mfma_f32_16x16x32_bf16 v[94:97], v[142:145], v[190:193], v[94:97]
	v_mfma_f32_16x16x32_bf16 v[94:97], v[146:149], v[194:197], v[94:97]
	v_mfma_f32_16x16x32_bf16 v[90:93], v[150:153], v[190:193], v[90:93]
	v_mfma_f32_16x16x32_bf16 v[90:93], v[154:157], v[194:197], v[90:93]
	v_mfma_f32_16x16x32_bf16 v[78:81], v[142:145], v[198:201], v[78:81]
	v_mfma_f32_16x16x32_bf16 v[78:81], v[146:149], v[204:207], v[78:81]
	v_mfma_f32_16x16x32_bf16 v[74:77], v[150:153], v[198:201], v[74:77]
	v_mfma_f32_16x16x32_bf16 v[74:77], v[154:157], v[204:207], v[74:77]
	s_setprio 0
	s_setprio 1
	v_mfma_f32_16x16x32_bf16 v[118:121], v[158:161], v[174:177], v[118:121]
	v_mfma_f32_16x16x32_bf16 v[118:121], v[162:165], v[178:181], v[118:121]
	v_mfma_f32_16x16x32_bf16 v[114:117], v[166:169], v[174:177], v[114:117]
	v_mfma_f32_16x16x32_bf16 v[114:117], v[170:173], v[178:181], v[114:117]
	v_mfma_f32_16x16x32_bf16 v[102:105], v[158:161], v[182:185], v[102:105]
	v_mfma_f32_16x16x32_bf16 v[102:105], v[162:165], v[186:189], v[102:105]
	v_mfma_f32_16x16x32_bf16 v[98:101], v[166:169], v[182:185], v[98:101]
	v_mfma_f32_16x16x32_bf16 v[98:101], v[170:173], v[186:189], v[98:101]
	v_mfma_f32_16x16x32_bf16 v[86:89], v[158:161], v[190:193], v[86:89]
	v_mfma_f32_16x16x32_bf16 v[86:89], v[162:165], v[194:197], v[86:89]
	v_mfma_f32_16x16x32_bf16 v[82:85], v[166:169], v[190:193], v[82:85]
	v_mfma_f32_16x16x32_bf16 v[82:85], v[170:173], v[194:197], v[82:85]
	v_mfma_f32_16x16x32_bf16 v[70:73], v[158:161], v[198:201], v[70:73]
	v_mfma_f32_16x16x32_bf16 v[70:73], v[162:165], v[204:207], v[70:73]
	v_mfma_f32_16x16x32_bf16 v[66:69], v[166:169], v[198:201], v[66:69]
	v_mfma_f32_16x16x32_bf16 v[66:69], v[170:173], v[204:207], v[66:69]
	s_setprio 0
	s_barrier
	s_or_b32 s31, s36, 0x80
	s_mov_b32 m0, s22
	v_add_u32_e32 v141, s31, v131
	ds_read_b128 v[174:177], v140 offset:49152
	ds_read_b128 v[178:181], v140 offset:50176
	ds_read_b128 v[182:185], v140 offset:51200
	ds_read_b128 v[186:189], v140 offset:52224
	ds_read_b128 v[190:193], v140 offset:53248
	ds_read_b128 v[194:197], v140 offset:54272
	ds_read_b128 v[198:201], v140 offset:55296
	ds_read_b128 v[204:207], v140 offset:56320
	global_load_lds_dwordx4 v141, s[6:7]
	v_add_u32_e32 v141, s31, v133
	s_mov_b32 m0, s23
	s_add_i32 s36, s36, 0x80080
	global_load_lds_dwordx4 v141, s[6:7]
	v_add_u32_e32 v141, s36, v131
	s_mov_b32 m0, s27
	s_nop 0
	global_load_lds_dwordx4 v141, s[6:7]
	v_add_u32_e32 v141, s36, v133
	s_mov_b32 m0, s29
	s_nop 0
	global_load_lds_dwordx4 v141, s[6:7]
	v_add_u32_e32 v141, s35, v130
	s_mov_b32 m0, s24
	s_nop 0
	global_load_lds_dwordx4 v141, s[4:5]
	v_add_u32_e32 v141, s35, v132
	s_mov_b32 m0, s25
	s_nop 0
	global_load_lds_dwordx4 v141, s[4:5]
	s_waitcnt vmcnt(8)
	s_waitcnt lgkmcnt(0)
	s_setprio 1
	s_barrier
	v_mfma_f32_16x16x32_bf16 v[62:65], v[142:145], v[174:177], v[62:65]
	v_mfma_f32_16x16x32_bf16 v[62:65], v[146:149], v[178:181], v[62:65]
	v_mfma_f32_16x16x32_bf16 v[58:61], v[150:153], v[174:177], v[58:61]
	v_mfma_f32_16x16x32_bf16 v[58:61], v[154:157], v[178:181], v[58:61]
	v_mfma_f32_16x16x32_bf16 v[46:49], v[142:145], v[182:185], v[46:49]
	v_mfma_f32_16x16x32_bf16 v[46:49], v[146:149], v[186:189], v[46:49]
	v_mfma_f32_16x16x32_bf16 v[42:45], v[150:153], v[182:185], v[42:45]
	v_mfma_f32_16x16x32_bf16 v[42:45], v[154:157], v[186:189], v[42:45]
	v_mfma_f32_16x16x32_bf16 v[30:33], v[142:145], v[190:193], v[30:33]
	v_mfma_f32_16x16x32_bf16 v[30:33], v[146:149], v[194:197], v[30:33]
	v_mfma_f32_16x16x32_bf16 v[26:29], v[150:153], v[190:193], v[26:29]
	v_mfma_f32_16x16x32_bf16 v[26:29], v[154:157], v[194:197], v[26:29]
	v_mfma_f32_16x16x32_bf16 v[14:17], v[142:145], v[198:201], v[14:17]
	v_mfma_f32_16x16x32_bf16 v[14:17], v[146:149], v[204:207], v[14:17]
	v_mfma_f32_16x16x32_bf16 v[10:13], v[150:153], v[198:201], v[10:13]
	v_mfma_f32_16x16x32_bf16 v[10:13], v[154:157], v[204:207], v[10:13]
	s_setprio 0
	s_setprio 1
	v_mfma_f32_16x16x32_bf16 v[54:57], v[158:161], v[174:177], v[54:57]
	v_mfma_f32_16x16x32_bf16 v[54:57], v[162:165], v[178:181], v[54:57]
	v_mfma_f32_16x16x32_bf16 v[50:53], v[166:169], v[174:177], v[50:53]
	v_mfma_f32_16x16x32_bf16 v[50:53], v[170:173], v[178:181], v[50:53]
	v_mfma_f32_16x16x32_bf16 v[38:41], v[158:161], v[182:185], v[38:41]
	v_mfma_f32_16x16x32_bf16 v[38:41], v[162:165], v[186:189], v[38:41]
	v_mfma_f32_16x16x32_bf16 v[34:37], v[166:169], v[182:185], v[34:37]
	v_mfma_f32_16x16x32_bf16 v[34:37], v[170:173], v[186:189], v[34:37]
	v_mfma_f32_16x16x32_bf16 v[22:25], v[158:161], v[190:193], v[22:25]
	v_mfma_f32_16x16x32_bf16 v[22:25], v[162:165], v[194:197], v[22:25]
	v_mfma_f32_16x16x32_bf16 v[18:21], v[166:169], v[190:193], v[18:21]
	v_mfma_f32_16x16x32_bf16 v[18:21], v[170:173], v[194:197], v[18:21]
	v_mfma_f32_16x16x32_bf16 v[6:9], v[158:161], v[198:201], v[6:9]
	v_mfma_f32_16x16x32_bf16 v[6:9], v[162:165], v[204:207], v[6:9]
	v_mfma_f32_16x16x32_bf16 v[2:5], v[166:169], v[198:201], v[2:5]
	v_mfma_f32_16x16x32_bf16 v[2:5], v[170:173], v[204:207], v[2:5]
	s_setprio 0
	s_barrier
	s_add_i32 s30, s30, 2
	s_cmp_gt_u32 s30, 29
	s_mov_b32 s31, s34
.LBB0_741:
	v_add_u32_e32 v141, s3, v137
	ds_read_b128 v[142:145], v141
	ds_read_b128 v[146:149], v141 offset:1024
	ds_read_b128 v[150:153], v141 offset:2048
	ds_read_b128 v[154:157], v141 offset:3072
	v_add_u32_e32 v141, s11, v137
	ds_read_b128 v[158:161], v141
	ds_read_b128 v[162:165], v141 offset:1024
	ds_read_b128 v[166:169], v141 offset:2048
	ds_read_b128 v[170:173], v141 offset:3072
	s_add_i32 s34, s31, 0x100
	s_cmp_lg_u32 s30, 28
	s_cselect_b32 s36, s34, 0
	s_add_i32 s37, s36, s14
	s_or_b32 s35, s37, 0x80
	s_add_i32 s36, s36, s2
	v_add_u32_e32 v141, s31, v139
	s_add_i32 m0, s15, 0xc000
	ds_read_b128 v[174:177], v140
	ds_read_b128 v[178:181], v140 offset:1024
	ds_read_b128 v[182:185], v140 offset:2048
	ds_read_b128 v[186:189], v140 offset:3072
	ds_read_b128 v[190:193], v140 offset:4096
	ds_read_b128 v[194:197], v140 offset:5120
	ds_read_b128 v[198:201], v140 offset:6144
	ds_read_b128 v[204:207], v140 offset:7168
	global_load_lds_dwordx4 v141, s[4:5]
	v_add_u32_e32 v141, s31, v138
	s_add_i32 m0, s15, 0xe000
	s_nop 0
	global_load_lds_dwordx4 v141, s[4:5]
	s_waitcnt vmcnt(8)
	s_waitcnt lgkmcnt(0)
	s_setprio 1
	s_barrier
	v_mfma_f32_16x16x32_bf16 v[126:129], v[142:145], v[174:177], v[126:129]
	v_mfma_f32_16x16x32_bf16 v[126:129], v[146:149], v[178:181], v[126:129]
	v_mfma_f32_16x16x32_bf16 v[122:125], v[150:153], v[174:177], v[122:125]
	v_mfma_f32_16x16x32_bf16 v[122:125], v[154:157], v[178:181], v[122:125]
	v_mfma_f32_16x16x32_bf16 v[110:113], v[142:145], v[182:185], v[110:113]
	v_mfma_f32_16x16x32_bf16 v[110:113], v[146:149], v[186:189], v[110:113]
	v_mfma_f32_16x16x32_bf16 v[106:109], v[150:153], v[182:185], v[106:109]
	v_mfma_f32_16x16x32_bf16 v[106:109], v[154:157], v[186:189], v[106:109]
	v_mfma_f32_16x16x32_bf16 v[94:97], v[142:145], v[190:193], v[94:97]
	v_mfma_f32_16x16x32_bf16 v[94:97], v[146:149], v[194:197], v[94:97]
	v_mfma_f32_16x16x32_bf16 v[90:93], v[150:153], v[190:193], v[90:93]
	v_mfma_f32_16x16x32_bf16 v[90:93], v[154:157], v[194:197], v[90:93]
	v_mfma_f32_16x16x32_bf16 v[78:81], v[142:145], v[198:201], v[78:81]
	v_mfma_f32_16x16x32_bf16 v[78:81], v[146:149], v[204:207], v[78:81]
	v_mfma_f32_16x16x32_bf16 v[74:77], v[150:153], v[198:201], v[74:77]
	v_mfma_f32_16x16x32_bf16 v[74:77], v[154:157], v[204:207], v[74:77]
	s_setprio 0
	s_setprio 1
	v_mfma_f32_16x16x32_bf16 v[118:121], v[158:161], v[174:177], v[118:121]
	v_mfma_f32_16x16x32_bf16 v[118:121], v[162:165], v[178:181], v[118:121]
	v_mfma_f32_16x16x32_bf16 v[114:117], v[166:169], v[174:177], v[114:117]
	v_mfma_f32_16x16x32_bf16 v[114:117], v[170:173], v[178:181], v[114:117]
	v_mfma_f32_16x16x32_bf16 v[102:105], v[158:161], v[182:185], v[102:105]
	v_mfma_f32_16x16x32_bf16 v[102:105], v[162:165], v[186:189], v[102:105]
	v_mfma_f32_16x16x32_bf16 v[98:101], v[166:169], v[182:185], v[98:101]
	v_mfma_f32_16x16x32_bf16 v[98:101], v[170:173], v[186:189], v[98:101]
	v_mfma_f32_16x16x32_bf16 v[86:89], v[158:161], v[190:193], v[86:89]
	v_mfma_f32_16x16x32_bf16 v[86:89], v[162:165], v[194:197], v[86:89]
	v_mfma_f32_16x16x32_bf16 v[82:85], v[166:169], v[190:193], v[82:85]
	v_mfma_f32_16x16x32_bf16 v[82:85], v[170:173], v[194:197], v[82:85]
	v_mfma_f32_16x16x32_bf16 v[70:73], v[158:161], v[198:201], v[70:73]
	v_mfma_f32_16x16x32_bf16 v[70:73], v[162:165], v[204:207], v[70:73]
	v_mfma_f32_16x16x32_bf16 v[66:69], v[166:169], v[198:201], v[66:69]
	v_mfma_f32_16x16x32_bf16 v[66:69], v[170:173], v[204:207], v[66:69]
	s_setprio 0
	s_barrier
	s_mov_b32 m0, s9
	v_add_u32_e32 v141, s36, v131
	ds_read_b128 v[174:177], v140 offset:16384
	ds_read_b128 v[178:181], v140 offset:17408
	ds_read_b128 v[182:185], v140 offset:18432
	ds_read_b128 v[186:189], v140 offset:19456
	ds_read_b128 v[190:193], v140 offset:20480
	ds_read_b128 v[194:197], v140 offset:21504
	ds_read_b128 v[198:201], v140 offset:22528
	ds_read_b128 v[204:207], v140 offset:23552
	global_load_lds_dwordx4 v141, s[6:7]
	v_add_u32_e32 v141, s36, v133
	s_mov_b32 m0, s10
	s_add_i32 s31, s36, 0x80000
	global_load_lds_dwordx4 v141, s[6:7]
	v_add_u32_e32 v141, s31, v131
	s_mov_b32 m0, s12
	s_nop 0
	global_load_lds_dwordx4 v141, s[6:7]
	v_add_u32_e32 v141, s31, v133
	s_mov_b32 m0, s13
	s_nop 0
	global_load_lds_dwordx4 v141, s[6:7]
	v_add_u32_e32 v141, s37, v130
	s_mov_b32 m0, s15
	s_nop 0
	global_load_lds_dwordx4 v141, s[4:5]
	v_add_u32_e32 v141, s37, v132
	s_mov_b32 m0, s16
	s_nop 0
	global_load_lds_dwordx4 v141, s[4:5]
	s_waitcnt vmcnt(8)
	s_waitcnt lgkmcnt(0)
	s_setprio 1
	s_barrier
	v_mfma_f32_16x16x32_bf16 v[62:65], v[142:145], v[174:177], v[62:65]
	v_mfma_f32_16x16x32_bf16 v[62:65], v[146:149], v[178:181], v[62:65]
	v_mfma_f32_16x16x32_bf16 v[58:61], v[150:153], v[174:177], v[58:61]
	v_mfma_f32_16x16x32_bf16 v[58:61], v[154:157], v[178:181], v[58:61]
	v_mfma_f32_16x16x32_bf16 v[46:49], v[142:145], v[182:185], v[46:49]
	v_mfma_f32_16x16x32_bf16 v[46:49], v[146:149], v[186:189], v[46:49]
	v_mfma_f32_16x16x32_bf16 v[42:45], v[150:153], v[182:185], v[42:45]
	v_mfma_f32_16x16x32_bf16 v[42:45], v[154:157], v[186:189], v[42:45]
	v_mfma_f32_16x16x32_bf16 v[30:33], v[142:145], v[190:193], v[30:33]
	v_mfma_f32_16x16x32_bf16 v[30:33], v[146:149], v[194:197], v[30:33]
	v_mfma_f32_16x16x32_bf16 v[26:29], v[150:153], v[190:193], v[26:29]
	v_mfma_f32_16x16x32_bf16 v[26:29], v[154:157], v[194:197], v[26:29]
	v_mfma_f32_16x16x32_bf16 v[14:17], v[142:145], v[198:201], v[14:17]
	v_mfma_f32_16x16x32_bf16 v[14:17], v[146:149], v[204:207], v[14:17]
	v_mfma_f32_16x16x32_bf16 v[10:13], v[150:153], v[198:201], v[10:13]
	v_mfma_f32_16x16x32_bf16 v[10:13], v[154:157], v[204:207], v[10:13]
	s_setprio 0
	s_setprio 1
	v_mfma_f32_16x16x32_bf16 v[54:57], v[158:161], v[174:177], v[54:57]
	v_mfma_f32_16x16x32_bf16 v[54:57], v[162:165], v[178:181], v[54:57]
	v_mfma_f32_16x16x32_bf16 v[50:53], v[166:169], v[174:177], v[50:53]
	v_mfma_f32_16x16x32_bf16 v[50:53], v[170:173], v[178:181], v[50:53]
	v_mfma_f32_16x16x32_bf16 v[38:41], v[158:161], v[182:185], v[38:41]
	v_mfma_f32_16x16x32_bf16 v[38:41], v[162:165], v[186:189], v[38:41]
	v_mfma_f32_16x16x32_bf16 v[34:37], v[166:169], v[182:185], v[34:37]
	v_mfma_f32_16x16x32_bf16 v[34:37], v[170:173], v[186:189], v[34:37]
	v_mfma_f32_16x16x32_bf16 v[22:25], v[158:161], v[190:193], v[22:25]
	v_mfma_f32_16x16x32_bf16 v[22:25], v[162:165], v[194:197], v[22:25]
	v_mfma_f32_16x16x32_bf16 v[18:21], v[166:169], v[190:193], v[18:21]
	v_mfma_f32_16x16x32_bf16 v[18:21], v[170:173], v[194:197], v[18:21]
	v_mfma_f32_16x16x32_bf16 v[6:9], v[158:161], v[198:201], v[6:9]
	v_mfma_f32_16x16x32_bf16 v[6:9], v[162:165], v[204:207], v[6:9]
	v_mfma_f32_16x16x32_bf16 v[2:5], v[166:169], v[198:201], v[2:5]
	v_mfma_f32_16x16x32_bf16 v[2:5], v[170:173], v[204:207], v[2:5]
	s_setprio 0
	s_barrier
	v_add_u32_e32 v141, s21, v137
	ds_read_b128 v[142:145], v141
	ds_read_b128 v[146:149], v141 offset:1024
	ds_read_b128 v[150:153], v141 offset:2048
	ds_read_b128 v[154:157], v141 offset:3072
	v_add_u32_e32 v141, s26, v137
	ds_read_b128 v[158:161], v141
	ds_read_b128 v[162:165], v141 offset:1024
	ds_read_b128 v[166:169], v141 offset:2048
	ds_read_b128 v[170:173], v141 offset:3072
	s_add_i32 s37, s37, 0x80000
	s_mov_b32 m0, s17
	v_add_u32_e32 v141, s37, v130
	ds_read_b128 v[174:177], v140 offset:32768
	ds_read_b128 v[178:181], v140 offset:33792
	ds_read_b128 v[182:185], v140 offset:34816
	ds_read_b128 v[186:189], v140 offset:35840
	ds_read_b128 v[190:193], v140 offset:36864
	ds_read_b128 v[194:197], v140 offset:37888
	ds_read_b128 v[198:201], v140 offset:38912
	ds_read_b128 v[204:207], v140 offset:39936
	global_load_lds_dwordx4 v141, s[4:5]
	v_add_u32_e32 v141, s37, v132
	s_mov_b32 m0, s18
	s_nop 0
	global_load_lds_dwordx4 v141, s[4:5]
	s_waitcnt vmcnt(8)
	s_waitcnt lgkmcnt(0)
	s_setprio 1
	s_barrier
	v_mfma_f32_16x16x32_bf16 v[126:129], v[142:145], v[174:177], v[126:129]
	v_mfma_f32_16x16x32_bf16 v[126:129], v[146:149], v[178:181], v[126:129]
	v_mfma_f32_16x16x32_bf16 v[122:125], v[150:153], v[174:177], v[122:125]
	v_mfma_f32_16x16x32_bf16 v[122:125], v[154:157], v[178:181], v[122:125]
	v_mfma_f32_16x16x32_bf16 v[110:113], v[142:145], v[182:185], v[110:113]
	v_mfma_f32_16x16x32_bf16 v[110:113], v[146:149], v[186:189], v[110:113]
	v_mfma_f32_16x16x32_bf16 v[106:109], v[150:153], v[182:185], v[106:109]
	v_mfma_f32_16x16x32_bf16 v[106:109], v[154:157], v[186:189], v[106:109]
	v_mfma_f32_16x16x32_bf16 v[94:97], v[142:145], v[190:193], v[94:97]
	v_mfma_f32_16x16x32_bf16 v[94:97], v[146:149], v[194:197], v[94:97]
	v_mfma_f32_16x16x32_bf16 v[90:93], v[150:153], v[190:193], v[90:93]
	v_mfma_f32_16x16x32_bf16 v[90:93], v[154:157], v[194:197], v[90:93]
	v_mfma_f32_16x16x32_bf16 v[78:81], v[142:145], v[198:201], v[78:81]
	v_mfma_f32_16x16x32_bf16 v[78:81], v[146:149], v[204:207], v[78:81]
	v_mfma_f32_16x16x32_bf16 v[74:77], v[150:153], v[198:201], v[74:77]
	v_mfma_f32_16x16x32_bf16 v[74:77], v[154:157], v[204:207], v[74:77]
	s_setprio 0
	s_setprio 1
	v_mfma_f32_16x16x32_bf16 v[118:121], v[158:161], v[174:177], v[118:121]
	v_mfma_f32_16x16x32_bf16 v[118:121], v[162:165], v[178:181], v[118:121]
	v_mfma_f32_16x16x32_bf16 v[114:117], v[166:169], v[174:177], v[114:117]
	v_mfma_f32_16x16x32_bf16 v[114:117], v[170:173], v[178:181], v[114:117]
	v_mfma_f32_16x16x32_bf16 v[102:105], v[158:161], v[182:185], v[102:105]
	v_mfma_f32_16x16x32_bf16 v[102:105], v[162:165], v[186:189], v[102:105]
	v_mfma_f32_16x16x32_bf16 v[98:101], v[166:169], v[182:185], v[98:101]
	v_mfma_f32_16x16x32_bf16 v[98:101], v[170:173], v[186:189], v[98:101]
	v_mfma_f32_16x16x32_bf16 v[86:89], v[158:161], v[190:193], v[86:89]
	v_mfma_f32_16x16x32_bf16 v[86:89], v[162:165], v[194:197], v[86:89]
	v_mfma_f32_16x16x32_bf16 v[82:85], v[166:169], v[190:193], v[82:85]
	v_mfma_f32_16x16x32_bf16 v[82:85], v[170:173], v[194:197], v[82:85]
	v_mfma_f32_16x16x32_bf16 v[70:73], v[158:161], v[198:201], v[70:73]
	v_mfma_f32_16x16x32_bf16 v[70:73], v[162:165], v[204:207], v[70:73]
	v_mfma_f32_16x16x32_bf16 v[66:69], v[166:169], v[198:201], v[66:69]
	v_mfma_f32_16x16x32_bf16 v[66:69], v[170:173], v[204:207], v[66:69]
	s_setprio 0
	s_barrier
	s_or_b32 s31, s36, 0x80
	s_mov_b32 m0, s22
	v_add_u32_e32 v141, s31, v131
	ds_read_b128 v[174:177], v140 offset:49152
	ds_read_b128 v[178:181], v140 offset:50176
	ds_read_b128 v[182:185], v140 offset:51200
	ds_read_b128 v[186:189], v140 offset:52224
	ds_read_b128 v[190:193], v140 offset:53248
	ds_read_b128 v[194:197], v140 offset:54272
	ds_read_b128 v[198:201], v140 offset:55296
	ds_read_b128 v[204:207], v140 offset:56320
	global_load_lds_dwordx4 v141, s[6:7]
	v_add_u32_e32 v141, s31, v133
	s_mov_b32 m0, s23
	s_add_i32 s36, s36, 0x80080
	global_load_lds_dwordx4 v141, s[6:7]
	v_add_u32_e32 v141, s36, v131
	s_mov_b32 m0, s27
	s_nop 0
	global_load_lds_dwordx4 v141, s[6:7]
	v_add_u32_e32 v141, s36, v133
	s_mov_b32 m0, s29
	s_nop 0
	global_load_lds_dwordx4 v141, s[6:7]
	v_add_u32_e32 v141, s35, v130
	s_mov_b32 m0, s24
	s_nop 0
	global_load_lds_dwordx4 v141, s[4:5]
	v_add_u32_e32 v141, s35, v132
	s_mov_b32 m0, s25
	s_nop 0
	global_load_lds_dwordx4 v141, s[4:5]
	s_waitcnt vmcnt(8)
	s_waitcnt lgkmcnt(0)
	s_setprio 1
	s_barrier
	v_mfma_f32_16x16x32_bf16 v[62:65], v[142:145], v[174:177], v[62:65]
	v_mfma_f32_16x16x32_bf16 v[62:65], v[146:149], v[178:181], v[62:65]
	v_mfma_f32_16x16x32_bf16 v[58:61], v[150:153], v[174:177], v[58:61]
	v_mfma_f32_16x16x32_bf16 v[58:61], v[154:157], v[178:181], v[58:61]
	v_mfma_f32_16x16x32_bf16 v[46:49], v[142:145], v[182:185], v[46:49]
	v_mfma_f32_16x16x32_bf16 v[46:49], v[146:149], v[186:189], v[46:49]
	v_mfma_f32_16x16x32_bf16 v[42:45], v[150:153], v[182:185], v[42:45]
	v_mfma_f32_16x16x32_bf16 v[42:45], v[154:157], v[186:189], v[42:45]
	v_mfma_f32_16x16x32_bf16 v[30:33], v[142:145], v[190:193], v[30:33]
	v_mfma_f32_16x16x32_bf16 v[30:33], v[146:149], v[194:197], v[30:33]
	v_mfma_f32_16x16x32_bf16 v[26:29], v[150:153], v[190:193], v[26:29]
	v_mfma_f32_16x16x32_bf16 v[26:29], v[154:157], v[194:197], v[26:29]
	v_mfma_f32_16x16x32_bf16 v[14:17], v[142:145], v[198:201], v[14:17]
	v_mfma_f32_16x16x32_bf16 v[14:17], v[146:149], v[204:207], v[14:17]
	v_mfma_f32_16x16x32_bf16 v[10:13], v[150:153], v[198:201], v[10:13]
	v_mfma_f32_16x16x32_bf16 v[10:13], v[154:157], v[204:207], v[10:13]
	s_setprio 0
	s_setprio 1
	v_mfma_f32_16x16x32_bf16 v[54:57], v[158:161], v[174:177], v[54:57]
	v_mfma_f32_16x16x32_bf16 v[54:57], v[162:165], v[178:181], v[54:57]
	v_mfma_f32_16x16x32_bf16 v[50:53], v[166:169], v[174:177], v[50:53]
	v_mfma_f32_16x16x32_bf16 v[50:53], v[170:173], v[178:181], v[50:53]
	v_mfma_f32_16x16x32_bf16 v[38:41], v[158:161], v[182:185], v[38:41]
	v_mfma_f32_16x16x32_bf16 v[38:41], v[162:165], v[186:189], v[38:41]
	v_mfma_f32_16x16x32_bf16 v[34:37], v[166:169], v[182:185], v[34:37]
	v_mfma_f32_16x16x32_bf16 v[34:37], v[170:173], v[186:189], v[34:37]
	v_mfma_f32_16x16x32_bf16 v[22:25], v[158:161], v[190:193], v[22:25]
	v_mfma_f32_16x16x32_bf16 v[22:25], v[162:165], v[194:197], v[22:25]
	v_mfma_f32_16x16x32_bf16 v[18:21], v[166:169], v[190:193], v[18:21]
	v_mfma_f32_16x16x32_bf16 v[18:21], v[170:173], v[194:197], v[18:21]
	v_mfma_f32_16x16x32_bf16 v[6:9], v[158:161], v[198:201], v[6:9]
	v_mfma_f32_16x16x32_bf16 v[6:9], v[162:165], v[204:207], v[6:9]
	v_mfma_f32_16x16x32_bf16 v[2:5], v[166:169], v[198:201], v[2:5]
	v_mfma_f32_16x16x32_bf16 v[2:5], v[170:173], v[204:207], v[2:5]
	s_setprio 0
	s_barrier
	s_add_i32 s30, s30, 2
	s_cmp_gt_u32 s30, 29
	s_mov_b32 s31, s34
	s_cbranch_scc0 .LBB0_741
	s_cmpk_lt_u32 s8, 0x100
	s_cbranch_scc0 .LBB0_744
	s_barrier

.LBB0_783:
	s_mul_i32 s12, s40, 0x2c0000
	s_and_b64 s[48:49], s[4:5], exec
	s_mul_i32 s13, s39, 0x2c0000
	s_cselect_b32 s43, s12, s45
	s_cselect_b32 s44, s13, s46
	s_add_i32 s45, s45, 0x160080
	s_addk_i32 s46, 0x100
	s_mov_b32 s47, -2
	v_add_u32_e32 v130, s17, v137
	ds_read_b128 v[142:145], v130
	ds_read_b128 v[146:149], v130 offset:1024
	ds_read_b128 v[150:153], v130 offset:2048
	ds_read_b128 v[154:157], v130 offset:3072
	v_add_u32_e32 v130, s20, v137
	ds_read_b128 v[158:161], v130
	ds_read_b128 v[162:165], v130 offset:1024
	ds_read_b128 v[166:169], v130 offset:2048
	ds_read_b128 v[170:173], v130 offset:3072
	s_add_i32 s48, s45, 0xffea0080
	s_cmpk_eq_i32 s47, 0x54
	s_cselect_b32 s50, s43, s48
	s_cselect_b32 s49, s44, s46
	s_or_b32 s48, s50, 0x80
	v_add_u32_e32 v130, s45, v140
	s_add_i32 m0, s23, 0xc000
	ds_read_b128 v[174:177], v141
	ds_read_b128 v[178:181], v141 offset:1024
	ds_read_b128 v[182:185], v141 offset:2048
	ds_read_b128 v[186:189], v141 offset:3072
	ds_read_b128 v[190:193], v141 offset:4096
	ds_read_b128 v[194:197], v141 offset:5120
	ds_read_b128 v[198:201], v141 offset:6144
	ds_read_b128 v[204:207], v141 offset:7168
	global_load_lds_dwordx4 v130, s[0:1]
	v_add_u32_e32 v130, s45, v139
	s_add_i32 m0, s23, 0xe000
	s_nop 0
	global_load_lds_dwordx4 v130, s[0:1]
	s_waitcnt vmcnt(8)
	s_waitcnt lgkmcnt(0)
	s_setprio 1
	s_barrier
	v_mfma_f32_16x16x32_bf16 v[126:129], v[142:145], v[174:177], 0
	v_mfma_f32_16x16x32_bf16 v[126:129], v[146:149], v[178:181], v[126:129]
	v_mfma_f32_16x16x32_bf16 v[122:125], v[150:153], v[174:177], 0
	v_mfma_f32_16x16x32_bf16 v[122:125], v[154:157], v[178:181], v[122:125]
	v_mfma_f32_16x16x32_bf16 v[118:121], v[142:145], v[182:185], 0
	v_mfma_f32_16x16x32_bf16 v[118:121], v[146:149], v[186:189], v[118:121]
	v_mfma_f32_16x16x32_bf16 v[110:113], v[150:153], v[182:185], 0
	v_mfma_f32_16x16x32_bf16 v[110:113], v[154:157], v[186:189], v[110:113]
	v_mfma_f32_16x16x32_bf16 v[102:105], v[142:145], v[190:193], 0
	v_mfma_f32_16x16x32_bf16 v[102:105], v[146:149], v[194:197], v[102:105]
	v_mfma_f32_16x16x32_bf16 v[94:97], v[150:153], v[190:193], 0
	v_mfma_f32_16x16x32_bf16 v[94:97], v[154:157], v[194:197], v[94:97]
	v_mfma_f32_16x16x32_bf16 v[86:89], v[142:145], v[198:201], 0
	v_mfma_f32_16x16x32_bf16 v[86:89], v[146:149], v[204:207], v[86:89]
	v_mfma_f32_16x16x32_bf16 v[78:81], v[150:153], v[198:201], 0
	v_mfma_f32_16x16x32_bf16 v[78:81], v[154:157], v[204:207], v[78:81]
	s_setprio 0
	s_setprio 1
	v_mfma_f32_16x16x32_bf16 v[114:117], v[158:161], v[174:177], 0
	v_mfma_f32_16x16x32_bf16 v[114:117], v[162:165], v[178:181], v[114:117]
	v_mfma_f32_16x16x32_bf16 v[106:109], v[166:169], v[174:177], 0
	v_mfma_f32_16x16x32_bf16 v[106:109], v[170:173], v[178:181], v[106:109]
	v_mfma_f32_16x16x32_bf16 v[98:101], v[158:161], v[182:185], 0
	v_mfma_f32_16x16x32_bf16 v[98:101], v[162:165], v[186:189], v[98:101]
	v_mfma_f32_16x16x32_bf16 v[90:93], v[166:169], v[182:185], 0
	v_mfma_f32_16x16x32_bf16 v[90:93], v[170:173], v[186:189], v[90:93]
	v_mfma_f32_16x16x32_bf16 v[82:85], v[158:161], v[190:193], 0
	v_mfma_f32_16x16x32_bf16 v[82:85], v[162:165], v[194:197], v[82:85]
	v_mfma_f32_16x16x32_bf16 v[74:77], v[166:169], v[190:193], 0
	v_mfma_f32_16x16x32_bf16 v[74:77], v[170:173], v[194:197], v[74:77]
	v_mfma_f32_16x16x32_bf16 v[70:73], v[158:161], v[198:201], 0
	v_mfma_f32_16x16x32_bf16 v[70:73], v[162:165], v[204:207], v[70:73]
	v_mfma_f32_16x16x32_bf16 v[66:69], v[166:169], v[198:201], 0
	v_mfma_f32_16x16x32_bf16 v[66:69], v[170:173], v[204:207], v[66:69]
	s_setprio 0
	s_barrier
	s_mov_b32 m0, s18
	v_add_u32_e32 v130, s49, v133
	ds_read_b128 v[174:177], v141 offset:16384
	ds_read_b128 v[178:181], v141 offset:17408
	ds_read_b128 v[182:185], v141 offset:18432
	ds_read_b128 v[186:189], v141 offset:19456
	ds_read_b128 v[190:193], v141 offset:20480
	ds_read_b128 v[194:197], v141 offset:21504
	ds_read_b128 v[198:201], v141 offset:22528
	ds_read_b128 v[204:207], v141 offset:23552
	global_load_lds_dwordx4 v130, s[2:3]
	v_add_u32_e32 v130, s49, v135
	s_mov_b32 m0, s19
	s_add_i32 s51, s49, 0x160000
	global_load_lds_dwordx4 v130, s[2:3]
	v_add_u32_e32 v130, s51, v133
	s_mov_b32 m0, s21
	s_nop 0
	global_load_lds_dwordx4 v130, s[2:3]
	v_add_u32_e32 v130, s51, v135
	s_mov_b32 m0, s22
	s_nop 0
	global_load_lds_dwordx4 v130, s[2:3]
	v_add_u32_e32 v130, s50, v132
	s_mov_b32 m0, s23
	s_nop 0
	global_load_lds_dwordx4 v130, s[0:1]
	v_add_u32_e32 v130, s50, v134
	s_mov_b32 m0, s24
	s_nop 0
	global_load_lds_dwordx4 v130, s[0:1]
	s_waitcnt vmcnt(8)
	s_waitcnt lgkmcnt(0)
	s_setprio 1
	s_barrier
	v_mfma_f32_16x16x32_bf16 v[62:65], v[142:145], v[174:177], 0
	v_mfma_f32_16x16x32_bf16 v[62:65], v[146:149], v[178:181], v[62:65]
	v_mfma_f32_16x16x32_bf16 v[58:61], v[150:153], v[174:177], 0
	v_mfma_f32_16x16x32_bf16 v[58:61], v[154:157], v[178:181], v[58:61]
	v_mfma_f32_16x16x32_bf16 v[54:57], v[142:145], v[182:185], 0
	v_mfma_f32_16x16x32_bf16 v[54:57], v[146:149], v[186:189], v[54:57]
	v_mfma_f32_16x16x32_bf16 v[46:49], v[150:153], v[182:185], 0
	v_mfma_f32_16x16x32_bf16 v[46:49], v[154:157], v[186:189], v[46:49]
	v_mfma_f32_16x16x32_bf16 v[38:41], v[142:145], v[190:193], 0
	v_mfma_f32_16x16x32_bf16 v[38:41], v[146:149], v[194:197], v[38:41]
	v_mfma_f32_16x16x32_bf16 v[30:33], v[150:153], v[190:193], 0
	v_mfma_f32_16x16x32_bf16 v[30:33], v[154:157], v[194:197], v[30:33]
	v_mfma_f32_16x16x32_bf16 v[22:25], v[142:145], v[198:201], 0
	v_mfma_f32_16x16x32_bf16 v[22:25], v[146:149], v[204:207], v[22:25]
	v_mfma_f32_16x16x32_bf16 v[14:17], v[150:153], v[198:201], 0
	v_mfma_f32_16x16x32_bf16 v[14:17], v[154:157], v[204:207], v[14:17]
	s_setprio 0
	s_setprio 1
	v_mfma_f32_16x16x32_bf16 v[50:53], v[158:161], v[174:177], 0
	v_mfma_f32_16x16x32_bf16 v[50:53], v[162:165], v[178:181], v[50:53]
	v_mfma_f32_16x16x32_bf16 v[42:45], v[166:169], v[174:177], 0
	v_mfma_f32_16x16x32_bf16 v[42:45], v[170:173], v[178:181], v[42:45]
	v_mfma_f32_16x16x32_bf16 v[34:37], v[158:161], v[182:185], 0
	v_mfma_f32_16x16x32_bf16 v[34:37], v[162:165], v[186:189], v[34:37]
	v_mfma_f32_16x16x32_bf16 v[26:29], v[166:169], v[182:185], 0
	v_mfma_f32_16x16x32_bf16 v[26:29], v[170:173], v[186:189], v[26:29]
	v_mfma_f32_16x16x32_bf16 v[18:21], v[158:161], v[190:193], 0
	v_mfma_f32_16x16x32_bf16 v[18:21], v[162:165], v[194:197], v[18:21]
	v_mfma_f32_16x16x32_bf16 v[10:13], v[166:169], v[190:193], 0
	v_mfma_f32_16x16x32_bf16 v[10:13], v[170:173], v[194:197], v[10:13]
	v_mfma_f32_16x16x32_bf16 v[6:9], v[158:161], v[198:201], 0
	v_mfma_f32_16x16x32_bf16 v[6:9], v[162:165], v[204:207], v[6:9]
	v_mfma_f32_16x16x32_bf16 v[2:5], v[166:169], v[198:201], 0
	v_mfma_f32_16x16x32_bf16 v[2:5], v[170:173], v[204:207], v[2:5]
	s_setprio 0
	s_barrier
	v_add_u32_e32 v130, s27, v137
	ds_read_b128 v[142:145], v130
	ds_read_b128 v[146:149], v130 offset:1024
	ds_read_b128 v[150:153], v130 offset:2048
	ds_read_b128 v[154:157], v130 offset:3072
	v_add_u32_e32 v130, s34, v137
	ds_read_b128 v[158:161], v130
	ds_read_b128 v[162:165], v130 offset:1024
	ds_read_b128 v[166:169], v130 offset:2048
	ds_read_b128 v[170:173], v130 offset:3072
	s_add_i32 s50, s50, 0x160000
	s_mov_b32 m0, s25
	v_add_u32_e32 v130, s50, v132
	ds_read_b128 v[174:177], v141 offset:32768
	ds_read_b128 v[178:181], v141 offset:33792
	ds_read_b128 v[182:185], v141 offset:34816
	ds_read_b128 v[186:189], v141 offset:35840
	ds_read_b128 v[190:193], v141 offset:36864
	ds_read_b128 v[194:197], v141 offset:37888
	ds_read_b128 v[198:201], v141 offset:38912
	ds_read_b128 v[204:207], v141 offset:39936
	global_load_lds_dwordx4 v130, s[0:1]
	v_add_u32_e32 v130, s50, v134
	s_mov_b32 m0, s26
	s_nop 0
	global_load_lds_dwordx4 v130, s[0:1]
	s_waitcnt vmcnt(8)
	s_waitcnt lgkmcnt(0)
	s_setprio 1
	s_barrier
	v_mfma_f32_16x16x32_bf16 v[126:129], v[142:145], v[174:177], v[126:129]
	v_mfma_f32_16x16x32_bf16 v[126:129], v[146:149], v[178:181], v[126:129]
	v_mfma_f32_16x16x32_bf16 v[122:125], v[150:153], v[174:177], v[122:125]
	v_mfma_f32_16x16x32_bf16 v[122:125], v[154:157], v[178:181], v[122:125]
	v_mfma_f32_16x16x32_bf16 v[118:121], v[142:145], v[182:185], v[118:121]
	v_mfma_f32_16x16x32_bf16 v[118:121], v[146:149], v[186:189], v[118:121]
	v_mfma_f32_16x16x32_bf16 v[110:113], v[150:153], v[182:185], v[110:113]
	v_mfma_f32_16x16x32_bf16 v[110:113], v[154:157], v[186:189], v[110:113]
	v_mfma_f32_16x16x32_bf16 v[102:105], v[142:145], v[190:193], v[102:105]
	v_mfma_f32_16x16x32_bf16 v[102:105], v[146:149], v[194:197], v[102:105]
	v_mfma_f32_16x16x32_bf16 v[94:97], v[150:153], v[190:193], v[94:97]
	v_mfma_f32_16x16x32_bf16 v[94:97], v[154:157], v[194:197], v[94:97]
	v_mfma_f32_16x16x32_bf16 v[86:89], v[142:145], v[198:201], v[86:89]
	v_mfma_f32_16x16x32_bf16 v[86:89], v[146:149], v[204:207], v[86:89]
	v_mfma_f32_16x16x32_bf16 v[78:81], v[150:153], v[198:201], v[78:81]
	v_mfma_f32_16x16x32_bf16 v[78:81], v[154:157], v[204:207], v[78:81]
	s_setprio 0
	s_setprio 1
	v_mfma_f32_16x16x32_bf16 v[114:117], v[158:161], v[174:177], v[114:117]
	v_mfma_f32_16x16x32_bf16 v[114:117], v[162:165], v[178:181], v[114:117]
	v_mfma_f32_16x16x32_bf16 v[106:109], v[166:169], v[174:177], v[106:109]
	v_mfma_f32_16x16x32_bf16 v[106:109], v[170:173], v[178:181], v[106:109]
	v_mfma_f32_16x16x32_bf16 v[98:101], v[158:161], v[182:185], v[98:101]
	v_mfma_f32_16x16x32_bf16 v[98:101], v[162:165], v[186:189], v[98:101]
	v_mfma_f32_16x16x32_bf16 v[90:93], v[166:169], v[182:185], v[90:93]
	v_mfma_f32_16x16x32_bf16 v[90:93], v[170:173], v[186:189], v[90:93]
	v_mfma_f32_16x16x32_bf16 v[82:85], v[158:161], v[190:193], v[82:85]
	v_mfma_f32_16x16x32_bf16 v[82:85], v[162:165], v[194:197], v[82:85]
	v_mfma_f32_16x16x32_bf16 v[74:77], v[166:169], v[190:193], v[74:77]
	v_mfma_f32_16x16x32_bf16 v[74:77], v[170:173], v[194:197], v[74:77]
	v_mfma_f32_16x16x32_bf16 v[70:73], v[158:161], v[198:201], v[70:73]
	v_mfma_f32_16x16x32_bf16 v[70:73], v[162:165], v[204:207], v[70:73]
	v_mfma_f32_16x16x32_bf16 v[66:69], v[166:169], v[198:201], v[66:69]
	v_mfma_f32_16x16x32_bf16 v[66:69], v[170:173], v[204:207], v[66:69]
	s_setprio 0
	s_barrier
	s_or_b32 s50, s49, 0x80
	s_mov_b32 m0, s28
	v_add_u32_e32 v130, s50, v133
	ds_read_b128 v[174:177], v141 offset:49152
	ds_read_b128 v[178:181], v141 offset:50176
	ds_read_b128 v[182:185], v141 offset:51200
	ds_read_b128 v[186:189], v141 offset:52224
	ds_read_b128 v[190:193], v141 offset:53248
	ds_read_b128 v[194:197], v141 offset:54272
	ds_read_b128 v[198:201], v141 offset:55296
	ds_read_b128 v[204:207], v141 offset:56320
	global_load_lds_dwordx4 v130, s[2:3]
	v_add_u32_e32 v130, s50, v135
	s_mov_b32 m0, s29
	s_add_i32 s49, s49, 0x160080
	global_load_lds_dwordx4 v130, s[2:3]
	v_add_u32_e32 v130, s49, v133
	s_mov_b32 m0, s35
	s_nop 0
	global_load_lds_dwordx4 v130, s[2:3]
	v_add_u32_e32 v130, s49, v135
	s_mov_b32 m0, s36
	s_nop 0
	global_load_lds_dwordx4 v130, s[2:3]
	v_add_u32_e32 v130, s48, v132
	s_mov_b32 m0, s30
	s_nop 0
	global_load_lds_dwordx4 v130, s[0:1]
	v_add_u32_e32 v130, s48, v134
	s_mov_b32 m0, s31
	s_nop 0
	global_load_lds_dwordx4 v130, s[0:1]
	s_waitcnt vmcnt(8)
	s_waitcnt lgkmcnt(0)
	s_setprio 1
	s_barrier
	v_mfma_f32_16x16x32_bf16 v[62:65], v[142:145], v[174:177], v[62:65]
	v_mfma_f32_16x16x32_bf16 v[62:65], v[146:149], v[178:181], v[62:65]
	v_mfma_f32_16x16x32_bf16 v[58:61], v[150:153], v[174:177], v[58:61]
	v_mfma_f32_16x16x32_bf16 v[58:61], v[154:157], v[178:181], v[58:61]
	v_mfma_f32_16x16x32_bf16 v[54:57], v[142:145], v[182:185], v[54:57]
	v_mfma_f32_16x16x32_bf16 v[54:57], v[146:149], v[186:189], v[54:57]
	v_mfma_f32_16x16x32_bf16 v[46:49], v[150:153], v[182:185], v[46:49]
	v_mfma_f32_16x16x32_bf16 v[46:49], v[154:157], v[186:189], v[46:49]
	v_mfma_f32_16x16x32_bf16 v[38:41], v[142:145], v[190:193], v[38:41]
	v_mfma_f32_16x16x32_bf16 v[38:41], v[146:149], v[194:197], v[38:41]
	v_mfma_f32_16x16x32_bf16 v[30:33], v[150:153], v[190:193], v[30:33]
	v_mfma_f32_16x16x32_bf16 v[30:33], v[154:157], v[194:197], v[30:33]
	v_mfma_f32_16x16x32_bf16 v[22:25], v[142:145], v[198:201], v[22:25]
	v_mfma_f32_16x16x32_bf16 v[22:25], v[146:149], v[204:207], v[22:25]
	v_mfma_f32_16x16x32_bf16 v[14:17], v[150:153], v[198:201], v[14:17]
	v_mfma_f32_16x16x32_bf16 v[14:17], v[154:157], v[204:207], v[14:17]
	s_setprio 0
	s_setprio 1
	v_mfma_f32_16x16x32_bf16 v[50:53], v[158:161], v[174:177], v[50:53]
	v_mfma_f32_16x16x32_bf16 v[50:53], v[162:165], v[178:181], v[50:53]
	v_mfma_f32_16x16x32_bf16 v[42:45], v[166:169], v[174:177], v[42:45]
	v_mfma_f32_16x16x32_bf16 v[42:45], v[170:173], v[178:181], v[42:45]
	v_mfma_f32_16x16x32_bf16 v[34:37], v[158:161], v[182:185], v[34:37]
	v_mfma_f32_16x16x32_bf16 v[34:37], v[162:165], v[186:189], v[34:37]
	v_mfma_f32_16x16x32_bf16 v[26:29], v[166:169], v[182:185], v[26:29]
	v_mfma_f32_16x16x32_bf16 v[26:29], v[170:173], v[186:189], v[26:29]
	v_mfma_f32_16x16x32_bf16 v[18:21], v[158:161], v[190:193], v[18:21]
	v_mfma_f32_16x16x32_bf16 v[18:21], v[162:165], v[194:197], v[18:21]
	v_mfma_f32_16x16x32_bf16 v[10:13], v[166:169], v[190:193], v[10:13]
	v_mfma_f32_16x16x32_bf16 v[10:13], v[170:173], v[194:197], v[10:13]
	v_mfma_f32_16x16x32_bf16 v[6:9], v[158:161], v[198:201], v[6:9]
	v_mfma_f32_16x16x32_bf16 v[6:9], v[162:165], v[204:207], v[6:9]
	v_mfma_f32_16x16x32_bf16 v[2:5], v[166:169], v[198:201], v[2:5]
	v_mfma_f32_16x16x32_bf16 v[2:5], v[170:173], v[204:207], v[2:5]
	s_setprio 0
	s_barrier
	s_add_i32 s47, s47, 2
	s_addk_i32 s45, 0x100
	s_addk_i32 s46, 0x100
	s_cmpk_gt_u32 s47, 0x55
.LBB0_784:
	v_add_u32_e32 v130, s17, v137
	ds_read_b128 v[142:145], v130
	ds_read_b128 v[146:149], v130 offset:1024
	ds_read_b128 v[150:153], v130 offset:2048
	ds_read_b128 v[154:157], v130 offset:3072
	v_add_u32_e32 v130, s20, v137
	ds_read_b128 v[158:161], v130
	ds_read_b128 v[162:165], v130 offset:1024
	ds_read_b128 v[166:169], v130 offset:2048
	ds_read_b128 v[170:173], v130 offset:3072
	s_add_i32 s48, s45, 0xffea0080
	s_cmpk_eq_i32 s47, 0x54
	s_cselect_b32 s50, s43, s48
	s_cselect_b32 s49, s44, s46
	s_or_b32 s48, s50, 0x80
	v_add_u32_e32 v130, s45, v140
	s_add_i32 m0, s23, 0xc000
	ds_read_b128 v[174:177], v141
	ds_read_b128 v[178:181], v141 offset:1024
	ds_read_b128 v[182:185], v141 offset:2048
	ds_read_b128 v[186:189], v141 offset:3072
	ds_read_b128 v[190:193], v141 offset:4096
	ds_read_b128 v[194:197], v141 offset:5120
	ds_read_b128 v[198:201], v141 offset:6144
	ds_read_b128 v[204:207], v141 offset:7168
	global_load_lds_dwordx4 v130, s[0:1]
	v_add_u32_e32 v130, s45, v139
	s_add_i32 m0, s23, 0xe000
	s_nop 0
	global_load_lds_dwordx4 v130, s[0:1]
	s_waitcnt vmcnt(8)
	s_waitcnt lgkmcnt(0)
	s_setprio 1
	s_barrier
	v_mfma_f32_16x16x32_bf16 v[126:129], v[142:145], v[174:177], v[126:129]
	v_mfma_f32_16x16x32_bf16 v[126:129], v[146:149], v[178:181], v[126:129]
	v_mfma_f32_16x16x32_bf16 v[122:125], v[150:153], v[174:177], v[122:125]
	v_mfma_f32_16x16x32_bf16 v[122:125], v[154:157], v[178:181], v[122:125]
	v_mfma_f32_16x16x32_bf16 v[118:121], v[142:145], v[182:185], v[118:121]
	v_mfma_f32_16x16x32_bf16 v[118:121], v[146:149], v[186:189], v[118:121]
	v_mfma_f32_16x16x32_bf16 v[110:113], v[150:153], v[182:185], v[110:113]
	v_mfma_f32_16x16x32_bf16 v[110:113], v[154:157], v[186:189], v[110:113]
	v_mfma_f32_16x16x32_bf16 v[102:105], v[142:145], v[190:193], v[102:105]
	v_mfma_f32_16x16x32_bf16 v[102:105], v[146:149], v[194:197], v[102:105]
	v_mfma_f32_16x16x32_bf16 v[94:97], v[150:153], v[190:193], v[94:97]
	v_mfma_f32_16x16x32_bf16 v[94:97], v[154:157], v[194:197], v[94:97]
	v_mfma_f32_16x16x32_bf16 v[86:89], v[142:145], v[198:201], v[86:89]
	v_mfma_f32_16x16x32_bf16 v[86:89], v[146:149], v[204:207], v[86:89]
	v_mfma_f32_16x16x32_bf16 v[78:81], v[150:153], v[198:201], v[78:81]
	v_mfma_f32_16x16x32_bf16 v[78:81], v[154:157], v[204:207], v[78:81]
	s_setprio 0
	s_setprio 1
	v_mfma_f32_16x16x32_bf16 v[114:117], v[158:161], v[174:177], v[114:117]
	v_mfma_f32_16x16x32_bf16 v[114:117], v[162:165], v[178:181], v[114:117]
	v_mfma_f32_16x16x32_bf16 v[106:109], v[166:169], v[174:177], v[106:109]
	v_mfma_f32_16x16x32_bf16 v[106:109], v[170:173], v[178:181], v[106:109]
	v_mfma_f32_16x16x32_bf16 v[98:101], v[158:161], v[182:185], v[98:101]
	v_mfma_f32_16x16x32_bf16 v[98:101], v[162:165], v[186:189], v[98:101]
	v_mfma_f32_16x16x32_bf16 v[90:93], v[166:169], v[182:185], v[90:93]
	v_mfma_f32_16x16x32_bf16 v[90:93], v[170:173], v[186:189], v[90:93]
	v_mfma_f32_16x16x32_bf16 v[82:85], v[158:161], v[190:193], v[82:85]
	v_mfma_f32_16x16x32_bf16 v[82:85], v[162:165], v[194:197], v[82:85]
	v_mfma_f32_16x16x32_bf16 v[74:77], v[166:169], v[190:193], v[74:77]
	v_mfma_f32_16x16x32_bf16 v[74:77], v[170:173], v[194:197], v[74:77]
	v_mfma_f32_16x16x32_bf16 v[70:73], v[158:161], v[198:201], v[70:73]
	v_mfma_f32_16x16x32_bf16 v[70:73], v[162:165], v[204:207], v[70:73]
	v_mfma_f32_16x16x32_bf16 v[66:69], v[166:169], v[198:201], v[66:69]
	v_mfma_f32_16x16x32_bf16 v[66:69], v[170:173], v[204:207], v[66:69]
	s_setprio 0
	s_barrier
	s_mov_b32 m0, s18
	v_add_u32_e32 v130, s49, v133
	ds_read_b128 v[174:177], v141 offset:16384
	ds_read_b128 v[178:181], v141 offset:17408
	ds_read_b128 v[182:185], v141 offset:18432
	ds_read_b128 v[186:189], v141 offset:19456
	ds_read_b128 v[190:193], v141 offset:20480
	ds_read_b128 v[194:197], v141 offset:21504
	ds_read_b128 v[198:201], v141 offset:22528
	ds_read_b128 v[204:207], v141 offset:23552
	global_load_lds_dwordx4 v130, s[2:3]
	v_add_u32_e32 v130, s49, v135
	s_mov_b32 m0, s19
	s_add_i32 s51, s49, 0x160000
	global_load_lds_dwordx4 v130, s[2:3]
	v_add_u32_e32 v130, s51, v133
	s_mov_b32 m0, s21
	s_nop 0
	global_load_lds_dwordx4 v130, s[2:3]
	v_add_u32_e32 v130, s51, v135
	s_mov_b32 m0, s22
	s_nop 0
	global_load_lds_dwordx4 v130, s[2:3]
	v_add_u32_e32 v130, s50, v132
	s_mov_b32 m0, s23
	s_nop 0
	global_load_lds_dwordx4 v130, s[0:1]
	v_add_u32_e32 v130, s50, v134
	s_mov_b32 m0, s24
	s_nop 0
	global_load_lds_dwordx4 v130, s[0:1]
	s_waitcnt vmcnt(8)
	s_waitcnt lgkmcnt(0)
	s_setprio 1
	s_barrier
	v_mfma_f32_16x16x32_bf16 v[62:65], v[142:145], v[174:177], v[62:65]
	v_mfma_f32_16x16x32_bf16 v[62:65], v[146:149], v[178:181], v[62:65]
	v_mfma_f32_16x16x32_bf16 v[58:61], v[150:153], v[174:177], v[58:61]
	v_mfma_f32_16x16x32_bf16 v[58:61], v[154:157], v[178:181], v[58:61]
	v_mfma_f32_16x16x32_bf16 v[54:57], v[142:145], v[182:185], v[54:57]
	v_mfma_f32_16x16x32_bf16 v[54:57], v[146:149], v[186:189], v[54:57]
	v_mfma_f32_16x16x32_bf16 v[46:49], v[150:153], v[182:185], v[46:49]
	v_mfma_f32_16x16x32_bf16 v[46:49], v[154:157], v[186:189], v[46:49]
	v_mfma_f32_16x16x32_bf16 v[38:41], v[142:145], v[190:193], v[38:41]
	v_mfma_f32_16x16x32_bf16 v[38:41], v[146:149], v[194:197], v[38:41]
	v_mfma_f32_16x16x32_bf16 v[30:33], v[150:153], v[190:193], v[30:33]
	v_mfma_f32_16x16x32_bf16 v[30:33], v[154:157], v[194:197], v[30:33]
	v_mfma_f32_16x16x32_bf16 v[22:25], v[142:145], v[198:201], v[22:25]
	v_mfma_f32_16x16x32_bf16 v[22:25], v[146:149], v[204:207], v[22:25]
	v_mfma_f32_16x16x32_bf16 v[14:17], v[150:153], v[198:201], v[14:17]
	v_mfma_f32_16x16x32_bf16 v[14:17], v[154:157], v[204:207], v[14:17]
	s_setprio 0
	s_setprio 1
	v_mfma_f32_16x16x32_bf16 v[50:53], v[158:161], v[174:177], v[50:53]
	v_mfma_f32_16x16x32_bf16 v[50:53], v[162:165], v[178:181], v[50:53]
	v_mfma_f32_16x16x32_bf16 v[42:45], v[166:169], v[174:177], v[42:45]
	v_mfma_f32_16x16x32_bf16 v[42:45], v[170:173], v[178:181], v[42:45]
	v_mfma_f32_16x16x32_bf16 v[34:37], v[158:161], v[182:185], v[34:37]
	v_mfma_f32_16x16x32_bf16 v[34:37], v[162:165], v[186:189], v[34:37]
	v_mfma_f32_16x16x32_bf16 v[26:29], v[166:169], v[182:185], v[26:29]
	v_mfma_f32_16x16x32_bf16 v[26:29], v[170:173], v[186:189], v[26:29]
	v_mfma_f32_16x16x32_bf16 v[18:21], v[158:161], v[190:193], v[18:21]
	v_mfma_f32_16x16x32_bf16 v[18:21], v[162:165], v[194:197], v[18:21]
	v_mfma_f32_16x16x32_bf16 v[10:13], v[166:169], v[190:193], v[10:13]
	v_mfma_f32_16x16x32_bf16 v[10:13], v[170:173], v[194:197], v[10:13]
	v_mfma_f32_16x16x32_bf16 v[6:9], v[158:161], v[198:201], v[6:9]
	v_mfma_f32_16x16x32_bf16 v[6:9], v[162:165], v[204:207], v[6:9]
	v_mfma_f32_16x16x32_bf16 v[2:5], v[166:169], v[198:201], v[2:5]
	v_mfma_f32_16x16x32_bf16 v[2:5], v[170:173], v[204:207], v[2:5]
	s_setprio 0
	s_barrier
	v_add_u32_e32 v130, s27, v137
	ds_read_b128 v[142:145], v130
	ds_read_b128 v[146:149], v130 offset:1024
	ds_read_b128 v[150:153], v130 offset:2048
	ds_read_b128 v[154:157], v130 offset:3072
	v_add_u32_e32 v130, s34, v137
	ds_read_b128 v[158:161], v130
	ds_read_b128 v[162:165], v130 offset:1024
	ds_read_b128 v[166:169], v130 offset:2048
	ds_read_b128 v[170:173], v130 offset:3072
	s_add_i32 s50, s50, 0x160000
	s_mov_b32 m0, s25
	v_add_u32_e32 v130, s50, v132
	ds_read_b128 v[174:177], v141 offset:32768
	ds_read_b128 v[178:181], v141 offset:33792
	ds_read_b128 v[182:185], v141 offset:34816
	ds_read_b128 v[186:189], v141 offset:35840
	ds_read_b128 v[190:193], v141 offset:36864
	ds_read_b128 v[194:197], v141 offset:37888
	ds_read_b128 v[198:201], v141 offset:38912
	ds_read_b128 v[204:207], v141 offset:39936
	global_load_lds_dwordx4 v130, s[0:1]
	v_add_u32_e32 v130, s50, v134
	s_mov_b32 m0, s26
	s_nop 0
	global_load_lds_dwordx4 v130, s[0:1]
	s_waitcnt vmcnt(8)
	s_waitcnt lgkmcnt(0)
	s_setprio 1
	s_barrier
	v_mfma_f32_16x16x32_bf16 v[126:129], v[142:145], v[174:177], v[126:129]
	v_mfma_f32_16x16x32_bf16 v[126:129], v[146:149], v[178:181], v[126:129]
	v_mfma_f32_16x16x32_bf16 v[122:125], v[150:153], v[174:177], v[122:125]
	v_mfma_f32_16x16x32_bf16 v[122:125], v[154:157], v[178:181], v[122:125]
	v_mfma_f32_16x16x32_bf16 v[118:121], v[142:145], v[182:185], v[118:121]
	v_mfma_f32_16x16x32_bf16 v[118:121], v[146:149], v[186:189], v[118:121]
	v_mfma_f32_16x16x32_bf16 v[110:113], v[150:153], v[182:185], v[110:113]
	v_mfma_f32_16x16x32_bf16 v[110:113], v[154:157], v[186:189], v[110:113]
	v_mfma_f32_16x16x32_bf16 v[102:105], v[142:145], v[190:193], v[102:105]
	v_mfma_f32_16x16x32_bf16 v[102:105], v[146:149], v[194:197], v[102:105]
	v_mfma_f32_16x16x32_bf16 v[94:97], v[150:153], v[190:193], v[94:97]
	v_mfma_f32_16x16x32_bf16 v[94:97], v[154:157], v[194:197], v[94:97]
	v_mfma_f32_16x16x32_bf16 v[86:89], v[142:145], v[198:201], v[86:89]
	v_mfma_f32_16x16x32_bf16 v[86:89], v[146:149], v[204:207], v[86:89]
	v_mfma_f32_16x16x32_bf16 v[78:81], v[150:153], v[198:201], v[78:81]
	v_mfma_f32_16x16x32_bf16 v[78:81], v[154:157], v[204:207], v[78:81]
	s_setprio 0
	s_setprio 1
	v_mfma_f32_16x16x32_bf16 v[114:117], v[158:161], v[174:177], v[114:117]
	v_mfma_f32_16x16x32_bf16 v[114:117], v[162:165], v[178:181], v[114:117]
	v_mfma_f32_16x16x32_bf16 v[106:109], v[166:169], v[174:177], v[106:109]
	v_mfma_f32_16x16x32_bf16 v[106:109], v[170:173], v[178:181], v[106:109]
	v_mfma_f32_16x16x32_bf16 v[98:101], v[158:161], v[182:185], v[98:101]
	v_mfma_f32_16x16x32_bf16 v[98:101], v[162:165], v[186:189], v[98:101]
	v_mfma_f32_16x16x32_bf16 v[90:93], v[166:169], v[182:185], v[90:93]
	v_mfma_f32_16x16x32_bf16 v[90:93], v[170:173], v[186:189], v[90:93]
	v_mfma_f32_16x16x32_bf16 v[82:85], v[158:161], v[190:193], v[82:85]
	v_mfma_f32_16x16x32_bf16 v[82:85], v[162:165], v[194:197], v[82:85]
	v_mfma_f32_16x16x32_bf16 v[74:77], v[166:169], v[190:193], v[74:77]
	v_mfma_f32_16x16x32_bf16 v[74:77], v[170:173], v[194:197], v[74:77]
	v_mfma_f32_16x16x32_bf16 v[70:73], v[158:161], v[198:201], v[70:73]
	v_mfma_f32_16x16x32_bf16 v[70:73], v[162:165], v[204:207], v[70:73]
	v_mfma_f32_16x16x32_bf16 v[66:69], v[166:169], v[198:201], v[66:69]
	v_mfma_f32_16x16x32_bf16 v[66:69], v[170:173], v[204:207], v[66:69]
	s_setprio 0
	s_barrier
	s_or_b32 s50, s49, 0x80
	s_mov_b32 m0, s28
	v_add_u32_e32 v130, s50, v133
	ds_read_b128 v[174:177], v141 offset:49152
	ds_read_b128 v[178:181], v141 offset:50176
	ds_read_b128 v[182:185], v141 offset:51200
	ds_read_b128 v[186:189], v141 offset:52224
	ds_read_b128 v[190:193], v141 offset:53248
	ds_read_b128 v[194:197], v141 offset:54272
	ds_read_b128 v[198:201], v141 offset:55296
	ds_read_b128 v[204:207], v141 offset:56320
	global_load_lds_dwordx4 v130, s[2:3]
	v_add_u32_e32 v130, s50, v135
	s_mov_b32 m0, s29
	s_add_i32 s49, s49, 0x160080
	global_load_lds_dwordx4 v130, s[2:3]
	v_add_u32_e32 v130, s49, v133
	s_mov_b32 m0, s35
	s_nop 0
	global_load_lds_dwordx4 v130, s[2:3]
	v_add_u32_e32 v130, s49, v135
	s_mov_b32 m0, s36
	s_nop 0
	global_load_lds_dwordx4 v130, s[2:3]
	v_add_u32_e32 v130, s48, v132
	s_mov_b32 m0, s30
	s_nop 0
	global_load_lds_dwordx4 v130, s[0:1]
	v_add_u32_e32 v130, s48, v134
	s_mov_b32 m0, s31
	s_nop 0
	global_load_lds_dwordx4 v130, s[0:1]
	s_add_i32 s47, s47, 2
	s_addk_i32 s45, 0x100
	s_addk_i32 s46, 0x100
	s_cmpk_gt_u32 s47, 0x55
	s_waitcnt vmcnt(8)
	s_waitcnt lgkmcnt(0)
	s_setprio 1
	s_barrier
	v_mfma_f32_16x16x32_bf16 v[62:65], v[142:145], v[174:177], v[62:65]
	v_mfma_f32_16x16x32_bf16 v[62:65], v[146:149], v[178:181], v[62:65]
	v_mfma_f32_16x16x32_bf16 v[58:61], v[150:153], v[174:177], v[58:61]
	v_mfma_f32_16x16x32_bf16 v[58:61], v[154:157], v[178:181], v[58:61]
	v_mfma_f32_16x16x32_bf16 v[54:57], v[142:145], v[182:185], v[54:57]
	v_mfma_f32_16x16x32_bf16 v[54:57], v[146:149], v[186:189], v[54:57]
	v_mfma_f32_16x16x32_bf16 v[46:49], v[150:153], v[182:185], v[46:49]
	v_mfma_f32_16x16x32_bf16 v[46:49], v[154:157], v[186:189], v[46:49]
	v_mfma_f32_16x16x32_bf16 v[38:41], v[142:145], v[190:193], v[38:41]
	v_mfma_f32_16x16x32_bf16 v[38:41], v[146:149], v[194:197], v[38:41]
	v_mfma_f32_16x16x32_bf16 v[30:33], v[150:153], v[190:193], v[30:33]
	v_mfma_f32_16x16x32_bf16 v[30:33], v[154:157], v[194:197], v[30:33]
	v_mfma_f32_16x16x32_bf16 v[22:25], v[142:145], v[198:201], v[22:25]
	v_mfma_f32_16x16x32_bf16 v[22:25], v[146:149], v[204:207], v[22:25]
	v_mfma_f32_16x16x32_bf16 v[14:17], v[150:153], v[198:201], v[14:17]
	v_mfma_f32_16x16x32_bf16 v[14:17], v[154:157], v[204:207], v[14:17]
	s_setprio 0
	s_setprio 1
	v_mfma_f32_16x16x32_bf16 v[50:53], v[158:161], v[174:177], v[50:53]
	v_mfma_f32_16x16x32_bf16 v[50:53], v[162:165], v[178:181], v[50:53]
	v_mfma_f32_16x16x32_bf16 v[42:45], v[166:169], v[174:177], v[42:45]
	v_mfma_f32_16x16x32_bf16 v[42:45], v[170:173], v[178:181], v[42:45]
	v_mfma_f32_16x16x32_bf16 v[34:37], v[158:161], v[182:185], v[34:37]
	v_mfma_f32_16x16x32_bf16 v[34:37], v[162:165], v[186:189], v[34:37]
	v_mfma_f32_16x16x32_bf16 v[26:29], v[166:169], v[182:185], v[26:29]
	v_mfma_f32_16x16x32_bf16 v[26:29], v[170:173], v[186:189], v[26:29]
	v_mfma_f32_16x16x32_bf16 v[18:21], v[158:161], v[190:193], v[18:21]
	v_mfma_f32_16x16x32_bf16 v[18:21], v[162:165], v[194:197], v[18:21]
	v_mfma_f32_16x16x32_bf16 v[10:13], v[166:169], v[190:193], v[10:13]
	v_mfma_f32_16x16x32_bf16 v[10:13], v[170:173], v[194:197], v[10:13]
	v_mfma_f32_16x16x32_bf16 v[6:9], v[158:161], v[198:201], v[6:9]
	v_mfma_f32_16x16x32_bf16 v[6:9], v[162:165], v[204:207], v[6:9]
	v_mfma_f32_16x16x32_bf16 v[2:5], v[166:169], v[198:201], v[2:5]
	v_mfma_f32_16x16x32_bf16 v[2:5], v[170:173], v[204:207], v[2:5]
	s_setprio 0
	s_barrier
	s_cbranch_scc0 .LBB0_784
	s_and_b64 vcc, exec, s[10:11]
	s_cbranch_vccz .LBB0_787
	s_barrier
